# sigmoid/silu: IEEE div sequences -> v_rcp_f32*num (f32); S5/mLSTM/hyena load prefetching; S5 exchange rewrite
# speedup vs baseline: 1.0095x; 1.0095x over previous
; #define OPAQUE(x) asm volatile("" : "+v"(x))
; #define TIDX(p) ((p).wv * 64 + (int)__builtin_amdgcn_mbcnt_hi(~0u, __builtin_amdgcn_mbcnt_lo(~0u, 0u)))
; DI unsigned pack2(float a, float b) { f32x2_t v = {a, b}; bf16x2_t r = __builtin_convertvector(v, bf16x2_t); return __builtin_bit_cast(unsigned, r); }
; DI float sigmoidf_(float x) { return 1.f / (1.f + __expf(-x)); }
; DI bfu* wsb(const PX& p, size_t off) { return (bfu*)(p.ws + off); }
; DI void kstage4(const PX& p, const bfu* __restrict__ A, const bfu* __restrict__ Bt, const int K, const int brow, const int bcol, bfu* shm) {
;   constexpr int HALF = 128, HT = HALF * 64;
;   int tid_ = TIDX(p); OPAQUE(tid_);
;   const int tid = tid_;
;   const int wvb_ = p.wv * 1024;
;   unsigned oa0, oa1, obb0, obb1;
;   { int r_, c_;
;     stage_rc(tid * 16, r_, c_); oa0 = (unsigned)(r_ * K + c_) * 2u;
;     { const int rho = r_ & 31, pr = (r_ & ~31) + 8 * ((rho & 15) >> 2) + 4 * (rho >> 4) + (rho & 3); obb0 = (unsigned)(pr * K + c_) * 2u; }
;     stage_rc(tid * 16 + 8192, r_, c_); oa1 = (unsigned)(r_ * K + c_) * 2u;
;     { const int rho = r_ & 31, pr = (r_ & ~31) + 8 * ((rho & 15) >> 2) + 4 * (rho >> 4) + (rho & 3); obb1 = (unsigned)(pr * K + c_) * 2u; } }
;     ...
;   KS_(shm + 4 * HT, Bt, bcol, obb0, obb1);
;   KS_(shm + 0 * HT, A, brow, oa0, oa1);
;   KS_(shm + 5 * HT, Bt, bcol + HALF, obb0, obb1);
;   KS_(shm + 1 * HT, A, brow + HALF, oa0, oa1);
;     ...
; }
; template <int EPI, int HM>
; DI void epi256(const PX& p, int l, f32x4 (&acc)[2][2][4][2], int brow, int bcol, int aux, bool src_input) {
;     ...
;           } else if (EPI == EPI_GATE) {
;             uint4 o;
;             o.x = pack2(sigmoidf_(v[0]), sigmoidf_(v[1])); o.y = pack2(sigmoidf_(v[2]), sigmoidf_(v[3]));
;             o.z = pack2(sigmoidf_(v[4]), sigmoidf_(v[5])); o.w = pack2(sigmoidf_(v[6]), sigmoidf_(v[7]));
;             *(uint4*)(wsb(p, OFF_BIG + B_ZML) + (size_t)row * 2048 + col0) = o;
.LBB0_267:
	s_or_b64 exec, exec, s[24:25]
	v_mov_b32_e32 v0, v188
	s_cmp_eq_u32 s7, 1
	v_ashrrev_i32_e32 v67, 31, v0
	v_lshrrev_b32_e32 v67, 26, v67
	v_lshlrev_b32_e32 v66, 4, v0
	v_add_u32_e32 v67, v0, v67
	v_bfe_i32 v0, v0, 27, 1
	v_lshrrev_b32_e32 v0, 22, v0
	v_add_u32_e32 v0, v66, v0
	v_and_b32_e32 v0, 0xfffffc00, v0
	v_sub_u32_e32 v0, v66, v0
	s_mov_b32 s12, 0x2f618100
	v_lshrrev_b32_e32 v68, 4, v0
	s_cselect_b32 s24, s12, 0x39818100
	s_mov_b32 s12, 0x1d88000
	v_bitop3_b32 v0, v68, v0, 32 bitop3:0x6c
	s_cselect_b32 s25, s12, 0x1f08000
	s_and_b64 s[12:13], s[4:5], exec
	v_ashrrev_i32_e32 v69, 31, v0
	s_cselect_b32 s73, 0x2c018100, s24
	v_ashrrev_i32_e32 v67, 6, v67
	v_lshrrev_b32_e32 v69, 26, v69
	s_add_u32 s13, s96, s73
	v_lshlrev_b32_e32 v68, 3, v67
	v_add_u32_e32 v69, v0, v69
	s_addc_u32 s62, s97, 0
	v_and_b32_e32 v68, -16, v68
	v_ashrrev_i32_e32 v70, 6, v69
	v_and_b32_e32 v69, 0xc0, v69
	s_and_b64 s[4:5], s[4:5], exec
	v_add_u32_e32 v68, v70, v68
	v_lshlrev_b32_e32 v67, 5, v67
	v_sub_u32_e32 v0, v0, v69
	s_cselect_b32 s4, 0x1c08000, s25
	v_and_b32_e32 v67, 32, v67
	v_ashrrev_i16_sdwa v0, v210, sext(v0) dst_sel:DWORD dst_unused:UNUSED_PAD src0_sel:DWORD src1_sel:BYTE_0
	s_movk_i32 s24, 0x300
	v_lshlrev_b32_e32 v69, 1, v68
	v_lshrrev_b32_e32 v71, 2, v68
	v_and_b32_e32 v70, 3, v70
	s_mov_b32 s25, 0xffffe0
	v_add_u32_sdwa v0, v67, sext(v0) dst_sel:DWORD dst_unused:UNUSED_PAD src0_sel:DWORD src1_sel:WORD_0
	v_mul_lo_u32 v67, v68, s24
	v_and_b32_e32 v69, 24, v69
	v_and_b32_e32 v71, 4, v71
	v_and_or_b32 v68, v68, s25, v70
	v_or3_b32 v68, v68, v69, v71
	v_mul_u32_u24_e32 v68, 0x300, v68
	v_add_u32_e32 v66, 0x2000, v66
	v_add_lshl_u32 v67, v0, v67, 1
	v_add_lshl_u32 v0, v68, v0, 1
	v_ashrrev_i32_e32 v68, 31, v66
	v_lshrrev_b32_e32 v68, 22, v68
	v_add_u32_e32 v68, v66, v68
	v_ashrrev_i32_e32 v68, 10, v68
	v_mul_i32_i24_e32 v69, 0x400, v68
	v_sub_u32_e32 v66, v66, v69
	v_lshrrev_b32_e32 v69, 4, v66
	v_bitop3_b32 v66, v69, v66, 32 bitop3:0x6c
	v_ashrrev_i32_e32 v70, 31, v66
	v_lshrrev_b32_e32 v70, 26, v70
	v_lshlrev_b32_e32 v69, 3, v68
	v_add_u32_e32 v70, v66, v70
	v_and_b32_e32 v69, -16, v69
	v_ashrrev_i32_e32 v71, 6, v70
	v_and_b32_e32 v70, 0xc0, v70
	s_lshl_b32 s12, s4, 1
	v_add_u32_e32 v69, v71, v69
	v_lshlrev_b32_e32 v68, 5, v68
	v_sub_u32_e32 v66, v66, v70
	s_add_u32 s4, s96, s12
	v_and_b32_e32 v68, 32, v68
	v_ashrrev_i16_sdwa v66, v210, sext(v66) dst_sel:DWORD dst_unused:UNUSED_PAD src0_sel:DWORD src1_sel:BYTE_0
	v_lshlrev_b32_e32 v70, 1, v69
	v_lshrrev_b32_e32 v72, 2, v69
	v_and_b32_e32 v71, 3, v71
	s_addc_u32 s5, s97, 0
	v_add_u32_sdwa v66, v68, sext(v66) dst_sel:DWORD dst_unused:UNUSED_PAD src0_sel:DWORD src1_sel:WORD_0
	v_mul_lo_u32 v68, v69, s24
	v_and_b32_e32 v70, 24, v70
	v_and_b32_e32 v72, 4, v72
	v_and_or_b32 v69, v69, s25, v71
	v_readlane_b32 s36, v253, 31
	v_or3_b32 v69, v69, v70, v72
	s_add_u32 s24, s4, s68
	s_mul_hi_u32 s25, s36, 0x600
	v_mul_u32_u24_e32 v69, 0x300, v69
	s_addc_u32 s25, s5, s25
	s_mov_b32 m0, s33
	s_mul_i32 s26, s6, 0x600
	v_add_lshl_u32 v68, v66, v68, 1
	v_add_lshl_u32 v66, v69, v66, 1
	global_load_lds_dwordx4 v0, s[24:25]
	s_mov_b32 m0, s64
	s_add_u32 s26, s13, s26
	global_load_lds_dwordx4 v66, s[24:25]
	s_addc_u32 s27, s62, 0
	s_mov_b32 m0, s82
	s_add_u32 s60, s4, s70
	global_load_lds_dwordx4 v67, s[26:27]
	s_mov_b32 m0, s77
	s_addc_u32 s61, s5, s69
	global_load_lds_dwordx4 v68, s[26:27]
	s_mov_b32 m0, s65
	v_mul_f32_e32 v62, 0xbfb8aa3b, v62
	v_mul_f32_e32 v63, 0xbfb8aa3b, v63
	global_load_lds_dwordx4 v0, s[60:61]
	s_mov_b32 m0, s66
	s_add_u32 s4, s13, s71
	v_exp_f32_e32 v62, v62
	v_exp_f32_e32 v63, v63
	global_load_lds_dwordx4 v66, s[60:61]
	s_addc_u32 s5, s62, 0
	s_mov_b32 m0, s67
	v_mov_b32_e32 v0, v188
	global_load_lds_dwordx4 v67, s[4:5]
	s_mov_b32 m0, s72
	v_pk_add_f32 v[62:63], v[62:63], 1.0 op_sel_hi:[1,0]
	global_load_lds_dwordx4 v68, s[4:5]
	v_mul_f32_e32 v58, 0xbfb8aa3b, v58
	v_ashrrev_i32_e32 v66, 2, v0
	v_and_b32_e32 v66, 0xffffffc0, v66
	v_and_or_b32 v67, v0, 15, s6
	v_add_u32_e32 v66, v67, v66
	v_rcp_f32_e32 v68, v63
	v_mul_f32_e32 v59, 0xbfb8aa3b, v59
	v_exp_f32_e32 v58, v58
	v_exp_f32_e32 v59, v59
	s_nop 0
	v_mul_f32_e32 v63, 1.0, v68
	v_rcp_f32_e32 v68, v62
	v_pk_add_f32 v[58:59], v[58:59], 1.0 op_sel_hi:[1,0]
	v_lshrrev_b32_e32 v0, 1, v0
	v_and_b32_e32 v0, 0x78, v0
	v_mul_f32_e32 v62, 1.0, v68
	v_cvt_pk_bf16_f32 v62, v62, v63
	v_mul_f32_e32 v63, 0xbfb8aa3b, v64
	v_exp_f32_e32 v64, v63
	v_mul_f32_e32 v63, 0xbfb8aa3b, v65
	v_exp_f32_e32 v65, v63
	v_or_b32_e32 v0, s36, v0
	v_readlane_b32 s37, v253, 32
	v_readlane_b32 s36, v254, 2
	v_pk_add_f32 v[64:65], v[64:65], 1.0 op_sel_hi:[1,0]
	v_readlane_b32 s37, v254, 3
	v_rcp_f32_e32 v67, v65
	v_mov_b32_e32 v76, v188
	v_mul_f32_e32 v63, 1.0, v67
	v_rcp_f32_e32 v67, v64
	s_nop 0
	v_mul_f32_e32 v64, 1.0, v67
	v_cvt_pk_bf16_f32 v63, v64, v63
	v_rcp_f32_e32 v65, v59
	s_nop 0
	v_mul_f32_e32 v59, 1.0, v65
	v_rcp_f32_e32 v65, v58
	s_nop 0
	v_mul_f32_e32 v58, 1.0, v65
	v_cvt_pk_bf16_f32 v64, v58, v59
	v_mul_f32_e32 v58, 0xbfb8aa3b, v60
	v_mul_f32_e32 v59, 0xbfb8aa3b, v61
	v_exp_f32_e32 v58, v58
	v_exp_f32_e32 v59, v59
	s_nop 0
	v_pk_add_f32 v[58:59], v[58:59], 1.0 op_sel_hi:[1,0]
	s_nop 0
	v_rcp_f32_e32 v61, v59
	s_nop 0
	v_mul_f32_e32 v59, 1.0, v61
	v_rcp_f32_e32 v61, v58
	s_nop 0
	v_mul_f32_e32 v58, 1.0, v61
	v_lshlrev_b64 v[60:61], 1, v[0:1]
	v_mul_f32_e32 v0, 0xbfb8aa3b, v54
	v_exp_f32_e32 v54, v0
	v_mul_f32_e32 v0, 0xbfb8aa3b, v55
	v_exp_f32_e32 v55, v0
	v_ashrrev_i32_e32 v67, 31, v66
	v_cvt_pk_bf16_f32 v65, v58, v59
	v_lshlrev_b64 v[58:59], 12, v[66:67]
	v_lshl_add_u64 v[58:59], s[36:37], 0, v[58:59]
	v_pk_add_f32 v[54:55], v[54:55], 1.0 op_sel_hi:[1,0]
; DI unsigned pack2(float a, float b) { f32x2_t v = {a, b}; bf16x2_t r = __builtin_convertvector(v, bf16x2_t); return __builtin_bit_cast(unsigned, r); }
; DI bfu* wsb(const PX& p, size_t off) { return (bfu*)(p.ws + off); }
; DI float sigmoidf_(float x) { return 1.f / (1.f + __expf(-x)); }
; template <int EPI, int HM>
; DI void epi256(const PX& p, int l, f32x4 (&acc)[2][2][4][2], int brow, int bcol, int aux, bool src_input) {
;     ...
;           } else if (EPI == EPI_GATE) {
;             uint4 o;
;             o.x = pack2(sigmoidf_(v[0]), sigmoidf_(v[1])); o.y = pack2(sigmoidf_(v[2]), sigmoidf_(v[3]));
;             o.z = pack2(sigmoidf_(v[4]), sigmoidf_(v[5])); o.w = pack2(sigmoidf_(v[6]), sigmoidf_(v[7]));
;             *(uint4*)(wsb(p, OFF_BIG + B_ZML) + (size_t)row * 2048 + col0) = o;
	v_lshl_add_u64 v[58:59], v[58:59], 0, v[60:61]
	s_nop 4
	global_store_dwordx4 v[58:59], v[62:65], off
	s_nop 1
	v_rcp_f32_e32 v63, v55
	v_or_b32_e32 v62, 16, v66
	v_mul_f32_e32 v0, 1.0, v63
	v_rcp_f32_e32 v63, v54
	s_nop 0
	v_mul_f32_e32 v54, 1.0, v63
	v_cvt_pk_bf16_f32 v54, v54, v0
	v_mul_f32_e32 v0, 0xbfb8aa3b, v56
	v_exp_f32_e32 v56, v0
	v_mul_f32_e32 v0, 0xbfb8aa3b, v57
	v_exp_f32_e32 v57, v0
	s_nop 0
	v_pk_add_f32 v[56:57], v[56:57], 1.0 op_sel_hi:[1,0]
	s_nop 0
	v_rcp_f32_e32 v55, v57
	s_nop 0
	v_mul_f32_e32 v0, 1.0, v55
	v_rcp_f32_e32 v57, v56
	s_nop 0
	v_mul_f32_e32 v55, 1.0, v57
	v_cvt_pk_bf16_f32 v55, v55, v0
	v_mul_f32_e32 v0, 0xbfb8aa3b, v50
	v_exp_f32_e32 v50, v0
	v_mul_f32_e32 v0, 0xbfb8aa3b, v51
	v_exp_f32_e32 v51, v0
	s_nop 0
	v_pk_add_f32 v[50:51], v[50:51], 1.0 op_sel_hi:[1,0]
	s_nop 0
	v_rcp_f32_e32 v56, v51
	s_nop 0
	v_mul_f32_e32 v0, 1.0, v56
	v_rcp_f32_e32 v56, v50
	s_nop 0
	v_mul_f32_e32 v50, 1.0, v56
	v_cvt_pk_bf16_f32 v56, v50, v0
	v_mul_f32_e32 v0, 0xbfb8aa3b, v52
	v_exp_f32_e32 v50, v0
	v_mul_f32_e32 v0, 0xbfb8aa3b, v53
	v_exp_f32_e32 v51, v0
	s_nop 0
	v_pk_add_f32 v[50:51], v[50:51], 1.0 op_sel_hi:[1,0]
	s_nop 0
	v_rcp_f32_e32 v52, v51
	s_nop 0
	v_mul_f32_e32 v0, 1.0, v52
	v_rcp_f32_e32 v52, v50
	s_nop 0
	v_mul_f32_e32 v50, 1.0, v52
	v_cvt_pk_bf16_f32 v57, v50, v0
	v_mul_f32_e32 v0, 0xbfb8aa3b, v46
	v_exp_f32_e32 v46, v0
	v_mul_f32_e32 v0, 0xbfb8aa3b, v47
	v_exp_f32_e32 v47, v0
	v_ashrrev_i32_e32 v63, 31, v62
	v_lshlrev_b64 v[50:51], 12, v[62:63]
	v_lshl_add_u64 v[50:51], s[36:37], 0, v[50:51]
	v_pk_add_f32 v[46:47], v[46:47], 1.0 op_sel_hi:[1,0]
	v_lshl_add_u64 v[50:51], v[50:51], 0, v[60:61]
	v_rcp_f32_e32 v53, v47
	global_store_dwordx4 v[50:51], v[54:57], off
	v_or_b32_e32 v52, 32, v66
	s_nop 0
	v_mul_f32_e32 v0, 1.0, v53
	v_rcp_f32_e32 v53, v46
	s_nop 0
	v_mul_f32_e32 v46, 1.0, v53
	v_cvt_pk_bf16_f32 v46, v46, v0
	v_mul_f32_e32 v0, 0xbfb8aa3b, v48
	v_exp_f32_e32 v48, v0
	v_mul_f32_e32 v0, 0xbfb8aa3b, v49
	v_exp_f32_e32 v49, v0
	s_nop 0
	v_pk_add_f32 v[48:49], v[48:49], 1.0 op_sel_hi:[1,0]
	s_nop 0
	v_rcp_f32_e32 v47, v49
	s_nop 0
	v_mul_f32_e32 v0, 1.0, v47
	v_rcp_f32_e32 v49, v48
	s_nop 0
	v_mul_f32_e32 v47, 1.0, v49
	v_cvt_pk_bf16_f32 v47, v47, v0
	v_mul_f32_e32 v0, 0xbfb8aa3b, v42
	v_exp_f32_e32 v42, v0
	v_mul_f32_e32 v0, 0xbfb8aa3b, v43
	v_exp_f32_e32 v43, v0
	s_nop 0
	v_pk_add_f32 v[42:43], v[42:43], 1.0 op_sel_hi:[1,0]
	s_nop 0
	v_rcp_f32_e32 v48, v43
	s_nop 0
	v_mul_f32_e32 v0, 1.0, v48
	v_rcp_f32_e32 v48, v42
	s_nop 0
	v_mul_f32_e32 v42, 1.0, v48
	v_cvt_pk_bf16_f32 v48, v42, v0
	v_mul_f32_e32 v0, 0xbfb8aa3b, v44
	v_exp_f32_e32 v42, v0
	v_mul_f32_e32 v0, 0xbfb8aa3b, v45
	v_exp_f32_e32 v43, v0
	s_nop 0
	v_pk_add_f32 v[42:43], v[42:43], 1.0 op_sel_hi:[1,0]
	s_nop 0
	v_rcp_f32_e32 v44, v43
	s_nop 0
	v_mul_f32_e32 v0, 1.0, v44
	v_rcp_f32_e32 v44, v42
	s_nop 0
	v_mul_f32_e32 v42, 1.0, v44
	v_cvt_pk_bf16_f32 v49, v42, v0
	v_mul_f32_e32 v0, 0xbfb8aa3b, v38
	v_exp_f32_e32 v38, v0
	v_mul_f32_e32 v0, 0xbfb8aa3b, v39
	v_exp_f32_e32 v39, v0
	v_ashrrev_i32_e32 v53, 31, v52
	v_lshlrev_b64 v[42:43], 12, v[52:53]
	v_lshl_add_u64 v[42:43], s[36:37], 0, v[42:43]
	v_pk_add_f32 v[38:39], v[38:39], 1.0 op_sel_hi:[1,0]
	v_lshl_add_u64 v[42:43], v[42:43], 0, v[60:61]
	v_rcp_f32_e32 v45, v39
	global_store_dwordx4 v[42:43], v[46:49], off
	v_or_b32_e32 v44, 48, v66
	s_nop 0
	v_mul_f32_e32 v0, 1.0, v45
	v_rcp_f32_e32 v45, v38
	s_nop 0
	v_mul_f32_e32 v38, 1.0, v45
	v_cvt_pk_bf16_f32 v38, v38, v0
	v_mul_f32_e32 v0, 0xbfb8aa3b, v40
	v_exp_f32_e32 v40, v0
	v_mul_f32_e32 v0, 0xbfb8aa3b, v41
	v_exp_f32_e32 v41, v0
	s_nop 0
	v_pk_add_f32 v[40:41], v[40:41], 1.0 op_sel_hi:[1,0]
	s_nop 0
	v_rcp_f32_e32 v39, v41
	s_nop 0
	v_mul_f32_e32 v0, 1.0, v39
	v_rcp_f32_e32 v41, v40
	s_nop 0
	v_mul_f32_e32 v39, 1.0, v41
	v_cvt_pk_bf16_f32 v39, v39, v0
	v_mul_f32_e32 v0, 0xbfb8aa3b, v34
	v_exp_f32_e32 v34, v0
	v_mul_f32_e32 v0, 0xbfb8aa3b, v35
	v_exp_f32_e32 v35, v0
	s_nop 0
	v_pk_add_f32 v[34:35], v[34:35], 1.0 op_sel_hi:[1,0]
	s_nop 0
	v_rcp_f32_e32 v40, v35
	s_nop 0
	v_mul_f32_e32 v0, 1.0, v40
	v_rcp_f32_e32 v40, v34
	s_nop 0
	v_mul_f32_e32 v34, 1.0, v40
	v_cvt_pk_bf16_f32 v40, v34, v0
	v_mul_f32_e32 v0, 0xbfb8aa3b, v36
	v_exp_f32_e32 v34, v0
	v_mul_f32_e32 v0, 0xbfb8aa3b, v37
	v_exp_f32_e32 v35, v0
	s_nop 0
	v_pk_add_f32 v[34:35], v[34:35], 1.0 op_sel_hi:[1,0]
	s_nop 0
	v_rcp_f32_e32 v36, v35
	s_nop 0
	v_mul_f32_e32 v0, 1.0, v36
	v_rcp_f32_e32 v36, v34
	s_nop 0
	v_mul_f32_e32 v34, 1.0, v36
	v_cvt_pk_bf16_f32 v41, v34, v0
	v_mul_f32_e32 v0, 0xbfb8aa3b, v30
	v_exp_f32_e32 v30, v0
	v_mul_f32_e32 v0, 0xbfb8aa3b, v31
	v_exp_f32_e32 v31, v0
	v_ashrrev_i32_e32 v45, 31, v44
	v_lshlrev_b64 v[34:35], 12, v[44:45]
	v_lshl_add_u64 v[34:35], s[36:37], 0, v[34:35]
	v_pk_add_f32 v[30:31], v[30:31], 1.0 op_sel_hi:[1,0]
	v_lshl_add_u64 v[34:35], v[34:35], 0, v[60:61]
	v_rcp_f32_e32 v36, v31
	global_store_dwordx4 v[34:35], v[38:41], off
	v_mul_f32_e32 v0, 1.0, v36
	v_rcp_f32_e32 v36, v30
	s_nop 0
	v_mul_f32_e32 v30, 1.0, v36
	v_cvt_pk_bf16_f32 v30, v30, v0
	v_mul_f32_e32 v0, 0xbfb8aa3b, v32
	v_exp_f32_e32 v32, v0
	v_mul_f32_e32 v0, 0xbfb8aa3b, v33
	v_exp_f32_e32 v33, v0
	s_nop 0
	v_pk_add_f32 v[32:33], v[32:33], 1.0 op_sel_hi:[1,0]
	s_nop 0
; DI unsigned pack2(float a, float b) { f32x2_t v = {a, b}; bf16x2_t r = __builtin_convertvector(v, bf16x2_t); return __builtin_bit_cast(unsigned, r); }
; DI bfu* wsb(const PX& p, size_t off) { return (bfu*)(p.ws + off); }
; DI float sigmoidf_(float x) { return 1.f / (1.f + __expf(-x)); }
; template <int EPI, int HM>
; DI void epi256(const PX& p, int l, f32x4 (&acc)[2][2][4][2], int brow, int bcol, int aux, bool src_input) {
;     ...
;           } else if (EPI == EPI_GATE) {
;             uint4 o;
;             o.x = pack2(sigmoidf_(v[0]), sigmoidf_(v[1])); o.y = pack2(sigmoidf_(v[2]), sigmoidf_(v[3]));
;             o.z = pack2(sigmoidf_(v[4]), sigmoidf_(v[5])); o.w = pack2(sigmoidf_(v[6]), sigmoidf_(v[7]));
;             *(uint4*)(wsb(p, OFF_BIG + B_ZML) + (size_t)row * 2048 + col0) = o;
	v_rcp_f32_e32 v31, v33
	s_nop 0
	v_mul_f32_e32 v0, 1.0, v31
	v_rcp_f32_e32 v33, v32
	s_nop 0
	v_mul_f32_e32 v31, 1.0, v33
	v_cvt_pk_bf16_f32 v31, v31, v0
	v_mul_f32_e32 v0, 0xbfb8aa3b, v26
	v_exp_f32_e32 v26, v0
	v_mul_f32_e32 v0, 0xbfb8aa3b, v27
	v_exp_f32_e32 v27, v0
	s_nop 0
	v_pk_add_f32 v[26:27], v[26:27], 1.0 op_sel_hi:[1,0]
	s_nop 0
	v_rcp_f32_e32 v32, v27
	s_nop 0
	v_mul_f32_e32 v0, 1.0, v32
	v_rcp_f32_e32 v32, v26
	s_nop 0
	v_mul_f32_e32 v26, 1.0, v32
	v_cvt_pk_bf16_f32 v32, v26, v0
	v_mul_f32_e32 v0, 0xbfb8aa3b, v28
	v_exp_f32_e32 v26, v0
	v_mul_f32_e32 v0, 0xbfb8aa3b, v29
	v_exp_f32_e32 v27, v0
	s_nop 0
	v_pk_add_f32 v[26:27], v[26:27], 1.0 op_sel_hi:[1,0]
	s_nop 0
	v_rcp_f32_e32 v28, v27
	s_nop 0
	v_mul_f32_e32 v0, 1.0, v28
	v_rcp_f32_e32 v28, v26
	s_nop 0
	v_mul_f32_e32 v26, 1.0, v28
	v_cvt_pk_bf16_f32 v33, v26, v0
	v_mul_f32_e32 v0, 0xbfb8aa3b, v22
	v_exp_f32_e32 v22, v0
	v_mul_f32_e32 v0, 0xbfb8aa3b, v23
	v_exp_f32_e32 v23, v0
	global_store_dwordx4 v[58:59], v[30:33], off offset:256
	v_pk_add_f32 v[22:23], v[22:23], 1.0 op_sel_hi:[1,0]
	s_nop 0
	v_rcp_f32_e32 v26, v23
	s_nop 0
	v_mul_f32_e32 v0, 1.0, v26
	v_rcp_f32_e32 v26, v22
	s_nop 0
	v_mul_f32_e32 v22, 1.0, v26
	v_cvt_pk_bf16_f32 v22, v22, v0
	v_mul_f32_e32 v0, 0xbfb8aa3b, v24
	v_exp_f32_e32 v24, v0
	v_mul_f32_e32 v0, 0xbfb8aa3b, v25
	v_exp_f32_e32 v25, v0
	s_nop 0
	v_pk_add_f32 v[24:25], v[24:25], 1.0 op_sel_hi:[1,0]
	s_nop 0
	v_rcp_f32_e32 v23, v25
	s_nop 0
	v_mul_f32_e32 v0, 1.0, v23
	v_rcp_f32_e32 v25, v24
	s_nop 0
	v_mul_f32_e32 v23, 1.0, v25
	v_cvt_pk_bf16_f32 v23, v23, v0
	v_mul_f32_e32 v0, 0xbfb8aa3b, v18
	v_exp_f32_e32 v18, v0
	v_mul_f32_e32 v0, 0xbfb8aa3b, v19
	v_exp_f32_e32 v19, v0
	s_nop 0
	v_pk_add_f32 v[18:19], v[18:19], 1.0 op_sel_hi:[1,0]
	s_nop 0
	v_rcp_f32_e32 v24, v19
	s_nop 0
	v_mul_f32_e32 v0, 1.0, v24
	v_rcp_f32_e32 v24, v18
	s_nop 0
	v_mul_f32_e32 v18, 1.0, v24
	v_cvt_pk_bf16_f32 v24, v18, v0
	v_mul_f32_e32 v0, 0xbfb8aa3b, v20
	v_exp_f32_e32 v18, v0
	v_mul_f32_e32 v0, 0xbfb8aa3b, v21
	v_exp_f32_e32 v19, v0
	s_nop 0
	v_pk_add_f32 v[18:19], v[18:19], 1.0 op_sel_hi:[1,0]
	s_nop 0
	v_rcp_f32_e32 v20, v19
	s_nop 0
	v_mul_f32_e32 v0, 1.0, v20
	v_rcp_f32_e32 v20, v18
	s_nop 0
	v_mul_f32_e32 v18, 1.0, v20
	v_cvt_pk_bf16_f32 v25, v18, v0
	v_mul_f32_e32 v0, 0xbfb8aa3b, v14
	v_exp_f32_e32 v14, v0
	v_mul_f32_e32 v0, 0xbfb8aa3b, v15
	v_exp_f32_e32 v15, v0
	global_store_dwordx4 v[50:51], v[22:25], off offset:256
	v_pk_add_f32 v[14:15], v[14:15], 1.0 op_sel_hi:[1,0]
	s_nop 0
	v_rcp_f32_e32 v18, v15
	s_nop 0
	v_mul_f32_e32 v0, 1.0, v18
	v_rcp_f32_e32 v18, v14
	s_nop 0
	v_mul_f32_e32 v14, 1.0, v18
	v_cvt_pk_bf16_f32 v14, v14, v0
	v_mul_f32_e32 v0, 0xbfb8aa3b, v16
	v_exp_f32_e32 v16, v0
	v_mul_f32_e32 v0, 0xbfb8aa3b, v17
	v_exp_f32_e32 v17, v0
	s_nop 0
	v_pk_add_f32 v[16:17], v[16:17], 1.0 op_sel_hi:[1,0]
	s_nop 0
	v_rcp_f32_e32 v15, v17
	s_nop 0
	v_mul_f32_e32 v0, 1.0, v15
	v_rcp_f32_e32 v17, v16
	s_nop 0
	v_mul_f32_e32 v15, 1.0, v17
	v_cvt_pk_bf16_f32 v15, v15, v0
	v_mul_f32_e32 v0, 0xbfb8aa3b, v10
	v_exp_f32_e32 v10, v0
	v_mul_f32_e32 v0, 0xbfb8aa3b, v11
	v_exp_f32_e32 v11, v0
	s_nop 0
	v_pk_add_f32 v[10:11], v[10:11], 1.0 op_sel_hi:[1,0]
	s_nop 0
	v_rcp_f32_e32 v16, v11
	s_nop 0
	v_mul_f32_e32 v0, 1.0, v16
	v_rcp_f32_e32 v16, v10
	s_nop 0
	v_mul_f32_e32 v10, 1.0, v16
	v_cvt_pk_bf16_f32 v16, v10, v0
	v_mul_f32_e32 v0, 0xbfb8aa3b, v12
	v_exp_f32_e32 v10, v0
	v_mul_f32_e32 v0, 0xbfb8aa3b, v13
	v_exp_f32_e32 v11, v0
	s_nop 0
	v_pk_add_f32 v[10:11], v[10:11], 1.0 op_sel_hi:[1,0]
	s_nop 0
	v_rcp_f32_e32 v12, v11
	s_nop 0
	v_mul_f32_e32 v0, 1.0, v12
	v_rcp_f32_e32 v12, v10
	s_nop 0
	v_mul_f32_e32 v10, 1.0, v12
	v_cvt_pk_bf16_f32 v17, v10, v0
	v_mul_f32_e32 v0, 0xbfb8aa3b, v6
	v_exp_f32_e32 v6, v0
	v_mul_f32_e32 v0, 0xbfb8aa3b, v7
	v_exp_f32_e32 v7, v0
	global_store_dwordx4 v[42:43], v[14:17], off offset:256
	v_pk_add_f32 v[6:7], v[6:7], 1.0 op_sel_hi:[1,0]
	s_nop 0
	v_rcp_f32_e32 v10, v7
	s_nop 0
	v_mul_f32_e32 v0, 1.0, v10
	v_rcp_f32_e32 v10, v6
	s_nop 0
	v_mul_f32_e32 v6, 1.0, v10
	v_cvt_pk_bf16_f32 v6, v6, v0
	v_mul_f32_e32 v0, 0xbfb8aa3b, v8
	v_exp_f32_e32 v8, v0
	v_mul_f32_e32 v0, 0xbfb8aa3b, v9
	v_exp_f32_e32 v9, v0
	s_nop 0
	v_pk_add_f32 v[8:9], v[8:9], 1.0 op_sel_hi:[1,0]
	s_nop 0
	v_rcp_f32_e32 v7, v9
	s_nop 0
	v_mul_f32_e32 v0, 1.0, v7
	v_rcp_f32_e32 v9, v8
	s_nop 0
	v_mul_f32_e32 v7, 1.0, v9
	v_cvt_pk_bf16_f32 v7, v7, v0
	v_mul_f32_e32 v0, 0xbfb8aa3b, v2
	v_exp_f32_e32 v2, v0
	v_mul_f32_e32 v0, 0xbfb8aa3b, v3
	v_exp_f32_e32 v3, v0
	s_nop 0
	v_pk_add_f32 v[2:3], v[2:3], 1.0 op_sel_hi:[1,0]
	s_nop 0
	v_rcp_f32_e32 v8, v3
	s_nop 0
	v_mul_f32_e32 v0, 1.0, v8
	v_rcp_f32_e32 v8, v2
	s_nop 0
	v_mul_f32_e32 v2, 1.0, v8
	v_cvt_pk_bf16_f32 v8, v2, v0
	v_mul_f32_e32 v0, 0xbfb8aa3b, v4
	v_exp_f32_e32 v2, v0
	v_mul_f32_e32 v0, 0xbfb8aa3b, v5
	v_exp_f32_e32 v3, v0
	s_nop 0
	v_pk_add_f32 v[2:3], v[2:3], 1.0 op_sel_hi:[1,0]
	s_nop 0
	v_rcp_f32_e32 v4, v3
	s_nop 0
	v_mul_f32_e32 v0, 1.0, v4
	v_rcp_f32_e32 v4, v2
	s_nop 0
	v_mul_f32_e32 v2, 1.0, v4
	v_cvt_pk_bf16_f32 v9, v2, v0
	global_store_dwordx4 v[34:35], v[6:9], off offset:256
	s_nop 0
	v_ashrrev_i32_e32 v0, 8, v76
	v_cmp_eq_u32_e32 vcc, 1, v0
	s_and_saveexec_b64 s[62:63], vcc
	s_cbranch_execz .LBB0_269
	s_barrier

; #define OPAQUE(x) asm volatile("" : "+v"(x))
; #define TIDX(p) ((p).wv * 64 + (int)__builtin_amdgcn_mbcnt_hi(~0u, __builtin_amdgcn_mbcnt_lo(~0u, 0u)))
; DI unsigned pack2(float a, float b) { f32x2_t v = {a, b}; bf16x2_t r = __builtin_convertvector(v, bf16x2_t); return __builtin_bit_cast(unsigned, r); }
; DI float sigmoidf_(float x) { return 1.f / (1.f + __expf(-x)); }
; DI bfu* wsb(const PX& p, size_t off) { return (bfu*)(p.ws + off); }
; DI void kstage4(const PX& p, const bfu* __restrict__ A, const bfu* __restrict__ Bt, const int K, const int brow, const int bcol, bfu* shm) {
;   constexpr int HALF = 128, HT = HALF * 64;
;   int tid_ = TIDX(p); OPAQUE(tid_);
;   const int tid = tid_;
;   const int wvb_ = p.wv * 1024;
;   unsigned oa0, oa1, obb0, obb1;
;   { int r_, c_;
;     stage_rc(tid * 16, r_, c_); oa0 = (unsigned)(r_ * K + c_) * 2u;
;     { const int rho = r_ & 31, pr = (r_ & ~31) + 8 * ((rho & 15) >> 2) + 4 * (rho >> 4) + (rho & 3); obb0 = (unsigned)(pr * K + c_) * 2u; }
;     stage_rc(tid * 16 + 8192, r_, c_); oa1 = (unsigned)(r_ * K + c_) * 2u;
;     { const int rho = r_ & 31, pr = (r_ & ~31) + 8 * ((rho & 15) >> 2) + 4 * (rho >> 4) + (rho & 3); obb1 = (unsigned)(pr * K + c_) * 2u; } }
;     ...
;   KS_(shm + 4 * HT, Bt, bcol, obb0, obb1);
;   KS_(shm + 0 * HT, A, brow, oa0, oa1);
;   KS_(shm + 5 * HT, Bt, bcol + HALF, obb0, obb1);
;   KS_(shm + 1 * HT, A, brow + HALF, oa0, oa1);
;     ...
; }
; template <int EPI, int HM>
; DI void epi256(const PX& p, int l, f32x4 (&acc)[2][2][4][2], int brow, int bcol, int aux, bool src_input) {
;     ...
;           } else if (EPI == EPI_GATE) {
;             uint4 o;
;             o.x = pack2(sigmoidf_(v[0]), sigmoidf_(v[1])); o.y = pack2(sigmoidf_(v[2]), sigmoidf_(v[3]));
;             o.z = pack2(sigmoidf_(v[4]), sigmoidf_(v[5])); o.w = pack2(sigmoidf_(v[6]), sigmoidf_(v[7]));
;             *(uint4*)(wsb(p, OFF_BIG + B_ZML) + (size_t)row * 2048 + col0) = o;
.LBB0_307:
	s_or_b64 exec, exec, s[62:63]
	v_mov_b32_e32 v0, v188
	s_movk_i32 s36, 0x300
	v_ashrrev_i32_e32 v131, 31, v0
	v_lshrrev_b32_e32 v131, 26, v131
	v_lshlrev_b32_e32 v130, 4, v0
	v_add_u32_e32 v131, v0, v131
	v_bfe_i32 v0, v0, 27, 1
	v_lshrrev_b32_e32 v0, 22, v0
	v_add_u32_e32 v0, v130, v0
	v_and_b32_e32 v0, 0xfffffc00, v0
	v_sub_u32_e32 v0, v130, v0
	v_lshrrev_b32_e32 v132, 4, v0
	v_bitop3_b32 v0, v132, v0, 32 bitop3:0x6c
	v_ashrrev_i32_e32 v133, 31, v0
	v_ashrrev_i32_e32 v131, 6, v131
	v_lshrrev_b32_e32 v133, 26, v133
	v_lshlrev_b32_e32 v132, 3, v131
	v_add_u32_e32 v133, v0, v133
	v_and_b32_e32 v132, -16, v132
	v_ashrrev_i32_e32 v134, 6, v133
	v_and_b32_e32 v133, 0xc0, v133
	v_add_u32_e32 v132, v134, v132
	v_lshlrev_b32_e32 v131, 5, v131
	v_sub_u32_e32 v0, v0, v133
	v_and_b32_e32 v131, 32, v131
	v_ashrrev_i16_sdwa v0, v210, sext(v0) dst_sel:DWORD dst_unused:UNUSED_PAD src0_sel:DWORD src1_sel:BYTE_0
	v_lshlrev_b32_e32 v133, 1, v132
	v_lshrrev_b32_e32 v135, 2, v132
	v_and_b32_e32 v134, 3, v134
	s_mov_b32 s37, 0xffffe0
	v_add_u32_sdwa v0, v131, sext(v0) dst_sel:DWORD dst_unused:UNUSED_PAD src0_sel:DWORD src1_sel:WORD_0
	v_mul_lo_u32 v131, v132, s36
	v_and_b32_e32 v133, 24, v133
	v_and_b32_e32 v135, 4, v135
	v_and_or_b32 v132, v132, s37, v134
	v_or3_b32 v132, v132, v133, v135
	v_mul_u32_u24_e32 v132, 0x300, v132
	v_add_u32_e32 v130, 0x2000, v130
	v_add_lshl_u32 v131, v0, v131, 1
	v_add_lshl_u32 v0, v132, v0, 1
	v_ashrrev_i32_e32 v132, 31, v130
	v_lshrrev_b32_e32 v132, 22, v132
	v_add_u32_e32 v132, v130, v132
	v_ashrrev_i32_e32 v132, 10, v132
	s_cmp_eq_u32 s70, 1
	s_mov_b32 s0, 0x2f618100
	v_mul_i32_i24_e32 v133, 0x400, v132
	s_cselect_b32 s6, s0, 0x39818100
	s_mov_b32 s0, 0x1d88000
	v_sub_u32_e32 v130, v130, v133
	s_cselect_b32 s62, s0, 0x1f08000
	s_and_b64 s[0:1], s[4:5], exec
	v_lshrrev_b32_e32 v133, 4, v130
	s_cselect_b32 s1, 0x2c018100, s6
	v_bitop3_b32 v130, v133, v130, 32 bitop3:0x6c
	s_add_u32 s0, s96, s1
	v_ashrrev_i32_e32 v134, 31, v130
	s_addc_u32 s76, s97, 0
	v_lshrrev_b32_e32 v134, 26, v134
	s_and_b64 s[4:5], s[4:5], exec
	v_lshlrev_b32_e32 v133, 3, v132
	v_add_u32_e32 v134, v130, v134
	s_cselect_b32 s4, 0x1c08000, s62
	v_and_b32_e32 v133, -16, v133
	v_ashrrev_i32_e32 v135, 6, v134
	v_and_b32_e32 v134, 0xc0, v134
	s_lshl_b32 s6, s4, 1
	v_add_u32_e32 v133, v135, v133
	v_lshlrev_b32_e32 v132, 5, v132
	v_sub_u32_e32 v130, v130, v134
	s_add_u32 s4, s96, s6
	v_and_b32_e32 v132, 32, v132
	v_ashrrev_i16_sdwa v130, v210, sext(v130) dst_sel:DWORD dst_unused:UNUSED_PAD src0_sel:DWORD src1_sel:BYTE_0
	v_lshlrev_b32_e32 v134, 1, v133
	v_lshrrev_b32_e32 v136, 2, v133
	v_and_b32_e32 v135, 3, v135
	s_addc_u32 s5, s97, 0
	v_add_u32_sdwa v130, v132, sext(v130) dst_sel:DWORD dst_unused:UNUSED_PAD src0_sel:DWORD src1_sel:WORD_0
	v_mul_lo_u32 v132, v133, s36
	v_and_b32_e32 v134, 24, v134
	v_and_b32_e32 v136, 4, v136
	v_and_or_b32 v133, v133, s37, v135
	v_or3_b32 v133, v133, v134, v136
	s_add_u32 s62, s4, s9
	v_mul_u32_u24_e32 v133, 0x300, v133
	s_addc_u32 s63, s5, s43
	s_mov_b32 m0, s33
	v_add_lshl_u32 v132, v130, v132, 1
	v_add_lshl_u32 v130, v133, v130, 1
	global_load_lds_dwordx4 v0, s[62:63]
	s_mov_b32 m0, s64
	s_add_u32 s68, s0, s45
	global_load_lds_dwordx4 v130, s[62:63]
	s_mov_b32 s39, s69
	s_addc_u32 s69, s76, s69
	s_mov_b32 m0, s82
	s_add_u32 s74, s4, s17
	global_load_lds_dwordx4 v131, s[68:69]
	s_mov_b32 m0, s3
	s_addc_u32 s75, s5, s16
	global_load_lds_dwordx4 v132, s[68:69]
	s_mov_b32 m0, s65
	s_add_u32 s4, s0, s13
	global_load_lds_dwordx4 v0, s[74:75]
	s_mov_b32 m0, s66
	s_addc_u32 s5, s76, s12
	global_load_lds_dwordx4 v130, s[74:75]
	s_mov_b32 m0, s67
	v_mov_b32_e32 v0, v188
	global_load_lds_dwordx4 v131, s[4:5]
	s_mov_b32 m0, s72
	v_readlane_b32 s36, v254, 2
	global_load_lds_dwordx4 v132, s[4:5]
	v_readlane_b32 s37, v254, 3
	v_ashrrev_i32_e32 v130, 2, v0
	v_and_or_b32 v131, v0, 15, s8
	v_lshrrev_b32_e32 v0, 1, v0
	v_and_b32_e32 v0, 0x78, v0
	v_or_b32_e32 v132, s10, v0
	v_mul_f32_e32 v0, 0xbfb8aa3b, v126
	v_exp_f32_e32 v126, v0
	v_mul_f32_e32 v0, 0xbfb8aa3b, v127
	v_exp_f32_e32 v127, v0
	v_and_b32_e32 v130, 0xffffffc0, v130
	v_add_u32_e32 v130, v131, v130
	v_ashrrev_i32_e32 v133, 31, v132
	v_pk_add_f32 v[126:127], v[126:127], 1.0 op_sel_hi:[1,0]
	v_mov_b32_e32 v144, v188
	v_rcp_f32_e32 v131, v127
	s_mov_b32 s44, s45
	v_mul_f32_e32 v0, 1.0, v131
	v_rcp_f32_e32 v131, v126
	s_nop 0
	v_mul_f32_e32 v126, 1.0, v131
	v_cvt_pk_bf16_f32 v126, v126, v0
	v_mul_f32_e32 v0, 0xbfb8aa3b, v128
	v_exp_f32_e32 v128, v0
	v_mul_f32_e32 v0, 0xbfb8aa3b, v129
	v_exp_f32_e32 v129, v0
	s_nop 0
	v_pk_add_f32 v[128:129], v[128:129], 1.0 op_sel_hi:[1,0]
	s_nop 0
	v_rcp_f32_e32 v127, v129
	s_nop 0
	v_mul_f32_e32 v0, 1.0, v127
	v_rcp_f32_e32 v129, v128
	s_nop 0
	v_mul_f32_e32 v127, 1.0, v129
	v_cvt_pk_bf16_f32 v127, v127, v0
	v_mul_f32_e32 v0, 0xbfb8aa3b, v122
	v_exp_f32_e32 v122, v0
	v_mul_f32_e32 v0, 0xbfb8aa3b, v123
	v_exp_f32_e32 v123, v0
	s_nop 0
	v_pk_add_f32 v[122:123], v[122:123], 1.0 op_sel_hi:[1,0]
	s_nop 0
	v_rcp_f32_e32 v128, v123
	s_nop 0
	v_mul_f32_e32 v0, 1.0, v128
	v_rcp_f32_e32 v128, v122
	s_nop 0
	v_mul_f32_e32 v122, 1.0, v128
	v_cvt_pk_bf16_f32 v128, v122, v0
	v_mul_f32_e32 v0, 0xbfb8aa3b, v124
	v_exp_f32_e32 v122, v0
	v_mul_f32_e32 v0, 0xbfb8aa3b, v125
	v_exp_f32_e32 v123, v0
	s_nop 0
	v_pk_add_f32 v[122:123], v[122:123], 1.0 op_sel_hi:[1,0]
	s_nop 0
	v_rcp_f32_e32 v124, v123
	s_nop 0
	v_mul_f32_e32 v0, 1.0, v124
	v_rcp_f32_e32 v124, v122
	s_nop 0
	v_mul_f32_e32 v122, 1.0, v124
	v_cvt_pk_bf16_f32 v129, v122, v0
	v_mul_f32_e32 v0, 0xbfb8aa3b, v118
	v_exp_f32_e32 v118, v0
	v_mul_f32_e32 v0, 0xbfb8aa3b, v119
	v_exp_f32_e32 v119, v0
; DI unsigned pack2(float a, float b) { f32x2_t v = {a, b}; bf16x2_t r = __builtin_convertvector(v, bf16x2_t); return __builtin_bit_cast(unsigned, r); }
; DI float sigmoidf_(float x) { return 1.f / (1.f + __expf(-x)); }
; DI bfu* wsb(const PX& p, size_t off) { return (bfu*)(p.ws + off); }
; template <int EPI, int HM>
; DI void epi256(const PX& p, int l, f32x4 (&acc)[2][2][4][2], int brow, int bcol, int aux, bool src_input) {
;     ...
;           } else if (EPI == EPI_GATE) {
;             uint4 o;
;             o.x = pack2(sigmoidf_(v[0]), sigmoidf_(v[1])); o.y = pack2(sigmoidf_(v[2]), sigmoidf_(v[3]));
;             o.z = pack2(sigmoidf_(v[4]), sigmoidf_(v[5])); o.w = pack2(sigmoidf_(v[6]), sigmoidf_(v[7]));
;             *(uint4*)(wsb(p, OFF_BIG + B_ZML) + (size_t)row * 2048 + col0) = o;
	v_ashrrev_i32_e32 v131, 31, v130
	v_lshlrev_b64 v[122:123], 12, v[130:131]
	v_lshl_add_u64 v[124:125], s[36:37], 0, v[122:123]
	v_lshlrev_b64 v[122:123], 1, v[132:133]
	v_pk_add_f32 v[118:119], v[118:119], 1.0 op_sel_hi:[1,0]
	v_lshl_add_u64 v[124:125], v[124:125], 0, v[122:123]
	s_nop 4
	global_store_dwordx4 v[124:125], v[126:129], off
	s_nop 1
	v_rcp_f32_e32 v127, v119
	v_or_b32_e32 v126, 16, v130
	v_mul_f32_e32 v0, 1.0, v127
	v_rcp_f32_e32 v127, v118
	s_nop 0
	v_mul_f32_e32 v118, 1.0, v127
	v_cvt_pk_bf16_f32 v118, v118, v0
	v_mul_f32_e32 v0, 0xbfb8aa3b, v120
	v_exp_f32_e32 v120, v0
	v_mul_f32_e32 v0, 0xbfb8aa3b, v121
	v_exp_f32_e32 v121, v0
	s_nop 0
	v_pk_add_f32 v[120:121], v[120:121], 1.0 op_sel_hi:[1,0]
	s_nop 0
	v_rcp_f32_e32 v119, v121
	s_nop 0
	v_mul_f32_e32 v0, 1.0, v119
	v_rcp_f32_e32 v121, v120
	s_nop 0
	v_mul_f32_e32 v119, 1.0, v121
	v_cvt_pk_bf16_f32 v119, v119, v0
	v_mul_f32_e32 v0, 0xbfb8aa3b, v114
	v_exp_f32_e32 v114, v0
	v_mul_f32_e32 v0, 0xbfb8aa3b, v115
	v_exp_f32_e32 v115, v0
	s_nop 0
	v_pk_add_f32 v[114:115], v[114:115], 1.0 op_sel_hi:[1,0]
	s_nop 0
	v_rcp_f32_e32 v120, v115
	s_nop 0
	v_mul_f32_e32 v0, 1.0, v120
	v_rcp_f32_e32 v120, v114
	s_nop 0
	v_mul_f32_e32 v114, 1.0, v120
	v_cvt_pk_bf16_f32 v120, v114, v0
	v_mul_f32_e32 v0, 0xbfb8aa3b, v116
	v_exp_f32_e32 v114, v0
	v_mul_f32_e32 v0, 0xbfb8aa3b, v117
	v_exp_f32_e32 v115, v0
	s_nop 0
	v_pk_add_f32 v[114:115], v[114:115], 1.0 op_sel_hi:[1,0]
	s_nop 0
	v_rcp_f32_e32 v116, v115
	s_nop 0
	v_mul_f32_e32 v0, 1.0, v116
	v_rcp_f32_e32 v116, v114
	s_nop 0
	v_mul_f32_e32 v114, 1.0, v116
	v_cvt_pk_bf16_f32 v121, v114, v0
	v_mul_f32_e32 v0, 0xbfb8aa3b, v110
	v_exp_f32_e32 v110, v0
	v_mul_f32_e32 v0, 0xbfb8aa3b, v111
	v_exp_f32_e32 v111, v0
	v_ashrrev_i32_e32 v127, 31, v126
	v_lshlrev_b64 v[114:115], 12, v[126:127]
	v_lshl_add_u64 v[114:115], s[36:37], 0, v[114:115]
	v_pk_add_f32 v[110:111], v[110:111], 1.0 op_sel_hi:[1,0]
	v_lshl_add_u64 v[114:115], v[114:115], 0, v[122:123]
	v_rcp_f32_e32 v117, v111
	global_store_dwordx4 v[114:115], v[118:121], off
	v_or_b32_e32 v116, 32, v130
	s_nop 0
	v_mul_f32_e32 v0, 1.0, v117
	v_rcp_f32_e32 v117, v110
	s_nop 0
	v_mul_f32_e32 v110, 1.0, v117
	v_cvt_pk_bf16_f32 v110, v110, v0
	v_mul_f32_e32 v0, 0xbfb8aa3b, v112
	v_exp_f32_e32 v112, v0
	v_mul_f32_e32 v0, 0xbfb8aa3b, v113
	v_exp_f32_e32 v113, v0
	s_nop 0
	v_pk_add_f32 v[112:113], v[112:113], 1.0 op_sel_hi:[1,0]
	s_nop 0
	v_rcp_f32_e32 v111, v113
	s_nop 0
	v_mul_f32_e32 v0, 1.0, v111
	v_rcp_f32_e32 v113, v112
	s_nop 0
	v_mul_f32_e32 v111, 1.0, v113
	v_cvt_pk_bf16_f32 v111, v111, v0
	v_mul_f32_e32 v0, 0xbfb8aa3b, v106
	v_exp_f32_e32 v106, v0
	v_mul_f32_e32 v0, 0xbfb8aa3b, v107
	v_exp_f32_e32 v107, v0
	s_nop 0
	v_pk_add_f32 v[106:107], v[106:107], 1.0 op_sel_hi:[1,0]
	s_nop 0
	v_rcp_f32_e32 v112, v107
	s_nop 0
	v_mul_f32_e32 v0, 1.0, v112
	v_rcp_f32_e32 v112, v106
	s_nop 0
	v_mul_f32_e32 v106, 1.0, v112
	v_cvt_pk_bf16_f32 v112, v106, v0
	v_mul_f32_e32 v0, 0xbfb8aa3b, v108
	v_exp_f32_e32 v106, v0
	v_mul_f32_e32 v0, 0xbfb8aa3b, v109
	v_exp_f32_e32 v107, v0
	s_nop 0
	v_pk_add_f32 v[106:107], v[106:107], 1.0 op_sel_hi:[1,0]
	s_nop 0
	v_rcp_f32_e32 v108, v107
	s_nop 0
	v_mul_f32_e32 v0, 1.0, v108
	v_rcp_f32_e32 v108, v106
	s_nop 0
	v_mul_f32_e32 v106, 1.0, v108
	v_cvt_pk_bf16_f32 v113, v106, v0
	v_mul_f32_e32 v0, 0xbfb8aa3b, v102
	v_exp_f32_e32 v102, v0
	v_mul_f32_e32 v0, 0xbfb8aa3b, v103
	v_exp_f32_e32 v103, v0
	v_ashrrev_i32_e32 v117, 31, v116
	v_lshlrev_b64 v[106:107], 12, v[116:117]
	v_lshl_add_u64 v[106:107], s[36:37], 0, v[106:107]
	v_pk_add_f32 v[102:103], v[102:103], 1.0 op_sel_hi:[1,0]
	v_lshl_add_u64 v[106:107], v[106:107], 0, v[122:123]
	v_rcp_f32_e32 v109, v103
	global_store_dwordx4 v[106:107], v[110:113], off
	v_or_b32_e32 v108, 48, v130
	s_nop 0
	v_mul_f32_e32 v0, 1.0, v109
	v_rcp_f32_e32 v109, v102
	s_nop 0
	v_mul_f32_e32 v102, 1.0, v109
	v_cvt_pk_bf16_f32 v102, v102, v0
	v_mul_f32_e32 v0, 0xbfb8aa3b, v104
	v_exp_f32_e32 v104, v0
	v_mul_f32_e32 v0, 0xbfb8aa3b, v105
	v_exp_f32_e32 v105, v0
	s_nop 0
	v_pk_add_f32 v[104:105], v[104:105], 1.0 op_sel_hi:[1,0]
	s_nop 0
	v_rcp_f32_e32 v103, v105
	s_nop 0
	v_mul_f32_e32 v0, 1.0, v103
	v_rcp_f32_e32 v105, v104
	s_nop 0
	v_mul_f32_e32 v103, 1.0, v105
	v_cvt_pk_bf16_f32 v103, v103, v0
	v_mul_f32_e32 v0, 0xbfb8aa3b, v98
	v_exp_f32_e32 v98, v0
	v_mul_f32_e32 v0, 0xbfb8aa3b, v99
	v_exp_f32_e32 v99, v0
	s_nop 0
	v_pk_add_f32 v[98:99], v[98:99], 1.0 op_sel_hi:[1,0]
	s_nop 0
	v_rcp_f32_e32 v104, v99
	s_nop 0
	v_mul_f32_e32 v0, 1.0, v104
	v_rcp_f32_e32 v104, v98
	s_nop 0
	v_mul_f32_e32 v98, 1.0, v104
	v_cvt_pk_bf16_f32 v104, v98, v0
	v_mul_f32_e32 v0, 0xbfb8aa3b, v100
	v_exp_f32_e32 v98, v0
	v_mul_f32_e32 v0, 0xbfb8aa3b, v101
	v_exp_f32_e32 v99, v0
	s_nop 0
	v_pk_add_f32 v[98:99], v[98:99], 1.0 op_sel_hi:[1,0]
	s_nop 0
	v_rcp_f32_e32 v100, v99
	s_nop 0
	v_mul_f32_e32 v0, 1.0, v100
	v_rcp_f32_e32 v100, v98
	s_nop 0
	v_mul_f32_e32 v98, 1.0, v100
	v_cvt_pk_bf16_f32 v105, v98, v0
	v_mul_f32_e32 v0, 0xbfb8aa3b, v94
	v_exp_f32_e32 v94, v0
	v_mul_f32_e32 v0, 0xbfb8aa3b, v95
	v_exp_f32_e32 v95, v0
	v_ashrrev_i32_e32 v109, 31, v108
	v_lshlrev_b64 v[98:99], 12, v[108:109]
	v_lshl_add_u64 v[98:99], s[36:37], 0, v[98:99]
	v_pk_add_f32 v[94:95], v[94:95], 1.0 op_sel_hi:[1,0]
	v_lshl_add_u64 v[98:99], v[98:99], 0, v[122:123]
	v_rcp_f32_e32 v100, v95
	global_store_dwordx4 v[98:99], v[102:105], off
	v_mul_f32_e32 v0, 1.0, v100
	v_rcp_f32_e32 v100, v94
	s_nop 0
	v_mul_f32_e32 v94, 1.0, v100
	v_cvt_pk_bf16_f32 v94, v94, v0
	v_mul_f32_e32 v0, 0xbfb8aa3b, v96
	v_exp_f32_e32 v96, v0
	v_mul_f32_e32 v0, 0xbfb8aa3b, v97
	v_exp_f32_e32 v97, v0
	s_nop 0
; DI unsigned pack2(float a, float b) { f32x2_t v = {a, b}; bf16x2_t r = __builtin_convertvector(v, bf16x2_t); return __builtin_bit_cast(unsigned, r); }
; DI float sigmoidf_(float x) { return 1.f / (1.f + __expf(-x)); }
; DI bfu* wsb(const PX& p, size_t off) { return (bfu*)(p.ws + off); }
; template <int EPI, int HM>
; DI void epi256(const PX& p, int l, f32x4 (&acc)[2][2][4][2], int brow, int bcol, int aux, bool src_input) {
;     ...
;           } else if (EPI == EPI_GATE) {
;             uint4 o;
;             o.x = pack2(sigmoidf_(v[0]), sigmoidf_(v[1])); o.y = pack2(sigmoidf_(v[2]), sigmoidf_(v[3]));
;             o.z = pack2(sigmoidf_(v[4]), sigmoidf_(v[5])); o.w = pack2(sigmoidf_(v[6]), sigmoidf_(v[7]));
;             *(uint4*)(wsb(p, OFF_BIG + B_ZML) + (size_t)row * 2048 + col0) = o;
	v_pk_add_f32 v[96:97], v[96:97], 1.0 op_sel_hi:[1,0]
	s_nop 0
	v_rcp_f32_e32 v95, v97
	s_nop 0
	v_mul_f32_e32 v0, 1.0, v95
	v_rcp_f32_e32 v97, v96
	s_nop 0
	v_mul_f32_e32 v95, 1.0, v97
	v_cvt_pk_bf16_f32 v95, v95, v0
	v_mul_f32_e32 v0, 0xbfb8aa3b, v90
	v_exp_f32_e32 v90, v0
	v_mul_f32_e32 v0, 0xbfb8aa3b, v91
	v_exp_f32_e32 v91, v0
	s_nop 0
	v_pk_add_f32 v[90:91], v[90:91], 1.0 op_sel_hi:[1,0]
	s_nop 0
	v_rcp_f32_e32 v96, v91
	s_nop 0
	v_mul_f32_e32 v0, 1.0, v96
	v_rcp_f32_e32 v96, v90
	s_nop 0
	v_mul_f32_e32 v90, 1.0, v96
	v_cvt_pk_bf16_f32 v96, v90, v0
	v_mul_f32_e32 v0, 0xbfb8aa3b, v92
	v_exp_f32_e32 v90, v0
	v_mul_f32_e32 v0, 0xbfb8aa3b, v93
	v_exp_f32_e32 v91, v0
	s_nop 0
	v_pk_add_f32 v[90:91], v[90:91], 1.0 op_sel_hi:[1,0]
	s_nop 0
	v_rcp_f32_e32 v92, v91
	s_nop 0
	v_mul_f32_e32 v0, 1.0, v92
	v_rcp_f32_e32 v92, v90
	s_nop 0
	v_mul_f32_e32 v90, 1.0, v92
	v_cvt_pk_bf16_f32 v97, v90, v0
	v_mul_f32_e32 v0, 0xbfb8aa3b, v86
	v_exp_f32_e32 v86, v0
	v_mul_f32_e32 v0, 0xbfb8aa3b, v87
	v_exp_f32_e32 v87, v0
	global_store_dwordx4 v[124:125], v[94:97], off offset:256
	v_pk_add_f32 v[86:87], v[86:87], 1.0 op_sel_hi:[1,0]
	s_nop 0
	v_rcp_f32_e32 v90, v87
	s_nop 0
	v_mul_f32_e32 v0, 1.0, v90
	v_rcp_f32_e32 v90, v86
	s_nop 0
	v_mul_f32_e32 v86, 1.0, v90
	v_cvt_pk_bf16_f32 v86, v86, v0
	v_mul_f32_e32 v0, 0xbfb8aa3b, v88
	v_exp_f32_e32 v88, v0
	v_mul_f32_e32 v0, 0xbfb8aa3b, v89
	v_exp_f32_e32 v89, v0
	s_nop 0
	v_pk_add_f32 v[88:89], v[88:89], 1.0 op_sel_hi:[1,0]
	s_nop 0
	v_rcp_f32_e32 v87, v89
	s_nop 0
	v_mul_f32_e32 v0, 1.0, v87
	v_rcp_f32_e32 v89, v88
	s_nop 0
	v_mul_f32_e32 v87, 1.0, v89
	v_cvt_pk_bf16_f32 v87, v87, v0
	v_mul_f32_e32 v0, 0xbfb8aa3b, v82
	v_exp_f32_e32 v82, v0
	v_mul_f32_e32 v0, 0xbfb8aa3b, v83
	v_exp_f32_e32 v83, v0
	s_nop 0
	v_pk_add_f32 v[82:83], v[82:83], 1.0 op_sel_hi:[1,0]
	s_nop 0
	v_rcp_f32_e32 v88, v83
	s_nop 0
	v_mul_f32_e32 v0, 1.0, v88
	v_rcp_f32_e32 v88, v82
	s_nop 0
	v_mul_f32_e32 v82, 1.0, v88
	v_cvt_pk_bf16_f32 v88, v82, v0
	v_mul_f32_e32 v0, 0xbfb8aa3b, v84
	v_exp_f32_e32 v82, v0
	v_mul_f32_e32 v0, 0xbfb8aa3b, v85
	v_exp_f32_e32 v83, v0
	s_nop 0
	v_pk_add_f32 v[82:83], v[82:83], 1.0 op_sel_hi:[1,0]
	s_nop 0
	v_rcp_f32_e32 v84, v83
	s_nop 0
	v_mul_f32_e32 v0, 1.0, v84
	v_rcp_f32_e32 v84, v82
	s_nop 0
	v_mul_f32_e32 v82, 1.0, v84
	v_cvt_pk_bf16_f32 v89, v82, v0
	v_mul_f32_e32 v0, 0xbfb8aa3b, v78
	v_exp_f32_e32 v78, v0
	v_mul_f32_e32 v0, 0xbfb8aa3b, v79
	v_exp_f32_e32 v79, v0
	global_store_dwordx4 v[114:115], v[86:89], off offset:256
	v_pk_add_f32 v[78:79], v[78:79], 1.0 op_sel_hi:[1,0]
	s_nop 0
	v_rcp_f32_e32 v82, v79
	s_nop 0
	v_mul_f32_e32 v0, 1.0, v82
	v_rcp_f32_e32 v82, v78
	s_nop 0
	v_mul_f32_e32 v78, 1.0, v82
	v_cvt_pk_bf16_f32 v78, v78, v0
	v_mul_f32_e32 v0, 0xbfb8aa3b, v80
	v_exp_f32_e32 v80, v0
	v_mul_f32_e32 v0, 0xbfb8aa3b, v81
	v_exp_f32_e32 v81, v0
	s_nop 0
	v_pk_add_f32 v[80:81], v[80:81], 1.0 op_sel_hi:[1,0]
	s_nop 0
	v_rcp_f32_e32 v79, v81
	s_nop 0
	v_mul_f32_e32 v0, 1.0, v79
	v_rcp_f32_e32 v81, v80
	s_nop 0
	v_mul_f32_e32 v79, 1.0, v81
	v_cvt_pk_bf16_f32 v79, v79, v0
	v_mul_f32_e32 v0, 0xbfb8aa3b, v74
	v_exp_f32_e32 v74, v0
	v_mul_f32_e32 v0, 0xbfb8aa3b, v75
	v_exp_f32_e32 v75, v0
	s_nop 0
	v_pk_add_f32 v[74:75], v[74:75], 1.0 op_sel_hi:[1,0]
	s_nop 0
	v_rcp_f32_e32 v80, v75
	s_nop 0
	v_mul_f32_e32 v0, 1.0, v80
	v_rcp_f32_e32 v80, v74
	s_nop 0
	v_mul_f32_e32 v74, 1.0, v80
	v_cvt_pk_bf16_f32 v80, v74, v0
	v_mul_f32_e32 v0, 0xbfb8aa3b, v76
	v_exp_f32_e32 v74, v0
	v_mul_f32_e32 v0, 0xbfb8aa3b, v77
	v_exp_f32_e32 v75, v0
	s_nop 0
	v_pk_add_f32 v[74:75], v[74:75], 1.0 op_sel_hi:[1,0]
	s_nop 0
	v_rcp_f32_e32 v76, v75
	s_nop 0
	v_mul_f32_e32 v0, 1.0, v76
	v_rcp_f32_e32 v76, v74
	s_nop 0
	v_mul_f32_e32 v74, 1.0, v76
	v_cvt_pk_bf16_f32 v81, v74, v0
	v_mul_f32_e32 v0, 0xbfb8aa3b, v70
	v_exp_f32_e32 v70, v0
	v_mul_f32_e32 v0, 0xbfb8aa3b, v71
	v_exp_f32_e32 v71, v0
	global_store_dwordx4 v[106:107], v[78:81], off offset:256
	v_pk_add_f32 v[70:71], v[70:71], 1.0 op_sel_hi:[1,0]
	s_nop 0
	v_rcp_f32_e32 v74, v71
	s_nop 0
	v_mul_f32_e32 v0, 1.0, v74
	v_rcp_f32_e32 v74, v70
	s_nop 0
	v_mul_f32_e32 v70, 1.0, v74
	v_cvt_pk_bf16_f32 v70, v70, v0
	v_mul_f32_e32 v0, 0xbfb8aa3b, v72
	v_exp_f32_e32 v72, v0
	v_mul_f32_e32 v0, 0xbfb8aa3b, v73
	v_exp_f32_e32 v73, v0
	s_nop 0
	v_pk_add_f32 v[72:73], v[72:73], 1.0 op_sel_hi:[1,0]
	s_nop 0
	v_rcp_f32_e32 v71, v73
	s_nop 0
	v_mul_f32_e32 v0, 1.0, v71
	v_rcp_f32_e32 v73, v72
	s_nop 0
	v_mul_f32_e32 v71, 1.0, v73
	v_cvt_pk_bf16_f32 v71, v71, v0
	v_mul_f32_e32 v0, 0xbfb8aa3b, v66
	v_exp_f32_e32 v66, v0
	v_mul_f32_e32 v0, 0xbfb8aa3b, v67
	v_exp_f32_e32 v67, v0
	s_nop 0
	v_pk_add_f32 v[66:67], v[66:67], 1.0 op_sel_hi:[1,0]
	s_nop 0
	v_rcp_f32_e32 v72, v67
	s_nop 0
	v_mul_f32_e32 v0, 1.0, v72
	v_rcp_f32_e32 v72, v66
	s_nop 0
	v_mul_f32_e32 v66, 1.0, v72
	v_cvt_pk_bf16_f32 v72, v66, v0
	v_mul_f32_e32 v0, 0xbfb8aa3b, v68
	v_exp_f32_e32 v66, v0
	v_mul_f32_e32 v0, 0xbfb8aa3b, v69
	v_exp_f32_e32 v67, v0
	s_nop 0
	v_pk_add_f32 v[66:67], v[66:67], 1.0 op_sel_hi:[1,0]
	s_nop 0
	v_rcp_f32_e32 v68, v67
	s_nop 0
	v_mul_f32_e32 v0, 1.0, v68
	v_rcp_f32_e32 v68, v66
	s_nop 0
	v_mul_f32_e32 v66, 1.0, v68
	v_cvt_pk_bf16_f32 v73, v66, v0
	v_mul_f32_e32 v0, 0xbfb8aa3b, v62
	v_exp_f32_e32 v62, v0
	v_mul_f32_e32 v0, 0xbfb8aa3b, v63
	v_exp_f32_e32 v63, v0
	global_store_dwordx4 v[98:99], v[70:73], off offset:256
	v_add_u32_e32 v66, 0x80, v130
	v_pk_add_f32 v[62:63], v[62:63], 1.0 op_sel_hi:[1,0]
	s_nop 0
	v_rcp_f32_e32 v67, v63
	s_nop 0
	v_mul_f32_e32 v0, 1.0, v67
	v_rcp_f32_e32 v67, v62
	s_nop 0
	v_mul_f32_e32 v62, 1.0, v67
	v_cvt_pk_bf16_f32 v62, v62, v0
	v_mul_f32_e32 v0, 0xbfb8aa3b, v64
	v_exp_f32_e32 v64, v0
; DI unsigned pack2(float a, float b) { f32x2_t v = {a, b}; bf16x2_t r = __builtin_convertvector(v, bf16x2_t); return __builtin_bit_cast(unsigned, r); }
; DI float sigmoidf_(float x) { return 1.f / (1.f + __expf(-x)); }
; DI bfu* wsb(const PX& p, size_t off) { return (bfu*)(p.ws + off); }
; template <int EPI, int HM>
; DI void epi256(const PX& p, int l, f32x4 (&acc)[2][2][4][2], int brow, int bcol, int aux, bool src_input) {
;     ...
;           } else if (EPI == EPI_GATE) {
;             uint4 o;
;             o.x = pack2(sigmoidf_(v[0]), sigmoidf_(v[1])); o.y = pack2(sigmoidf_(v[2]), sigmoidf_(v[3]));
;             o.z = pack2(sigmoidf_(v[4]), sigmoidf_(v[5])); o.w = pack2(sigmoidf_(v[6]), sigmoidf_(v[7]));
;             *(uint4*)(wsb(p, OFF_BIG + B_ZML) + (size_t)row * 2048 + col0) = o;
	v_mul_f32_e32 v0, 0xbfb8aa3b, v65
	v_exp_f32_e32 v65, v0
	s_nop 0
	v_pk_add_f32 v[64:65], v[64:65], 1.0 op_sel_hi:[1,0]
	s_nop 0
	v_rcp_f32_e32 v63, v65
	s_nop 0
	v_mul_f32_e32 v0, 1.0, v63
	v_rcp_f32_e32 v65, v64
	s_nop 0
	v_mul_f32_e32 v63, 1.0, v65
	v_cvt_pk_bf16_f32 v63, v63, v0
	v_mul_f32_e32 v0, 0xbfb8aa3b, v58
	v_exp_f32_e32 v58, v0
	v_mul_f32_e32 v0, 0xbfb8aa3b, v59
	v_exp_f32_e32 v59, v0
	s_nop 0
	v_pk_add_f32 v[58:59], v[58:59], 1.0 op_sel_hi:[1,0]
	s_nop 0
	v_rcp_f32_e32 v64, v59
	s_nop 0
	v_mul_f32_e32 v0, 1.0, v64
	v_rcp_f32_e32 v64, v58
	s_nop 0
	v_mul_f32_e32 v58, 1.0, v64
	v_cvt_pk_bf16_f32 v64, v58, v0
	v_mul_f32_e32 v0, 0xbfb8aa3b, v60
	v_exp_f32_e32 v58, v0
	v_mul_f32_e32 v0, 0xbfb8aa3b, v61
	v_exp_f32_e32 v59, v0
	s_nop 0
	v_pk_add_f32 v[58:59], v[58:59], 1.0 op_sel_hi:[1,0]
	s_nop 0
	v_rcp_f32_e32 v60, v59
	s_nop 0
	v_mul_f32_e32 v0, 1.0, v60
	v_rcp_f32_e32 v60, v58
	s_nop 0
	v_mul_f32_e32 v58, 1.0, v60
	v_cvt_pk_bf16_f32 v65, v58, v0
	v_mul_f32_e32 v0, 0xbfb8aa3b, v54
	v_exp_f32_e32 v54, v0
	v_mul_f32_e32 v0, 0xbfb8aa3b, v55
	v_exp_f32_e32 v55, v0
	v_ashrrev_i32_e32 v67, 31, v66
	v_lshlrev_b64 v[58:59], 12, v[66:67]
	v_lshl_add_u64 v[58:59], s[36:37], 0, v[58:59]
	v_pk_add_f32 v[54:55], v[54:55], 1.0 op_sel_hi:[1,0]
	v_lshl_add_u64 v[58:59], v[58:59], 0, v[122:123]
	v_rcp_f32_e32 v61, v55
	global_store_dwordx4 v[58:59], v[62:65], off
	v_add_u32_e32 v60, 0x90, v130
	s_nop 0
	v_mul_f32_e32 v0, 1.0, v61
	v_rcp_f32_e32 v61, v54
	s_nop 0
	v_mul_f32_e32 v54, 1.0, v61
	v_cvt_pk_bf16_f32 v54, v54, v0
	v_mul_f32_e32 v0, 0xbfb8aa3b, v56
	v_exp_f32_e32 v56, v0
	v_mul_f32_e32 v0, 0xbfb8aa3b, v57
	v_exp_f32_e32 v57, v0
	s_nop 0
	v_pk_add_f32 v[56:57], v[56:57], 1.0 op_sel_hi:[1,0]
	s_nop 0
	v_rcp_f32_e32 v55, v57
	s_nop 0
	v_mul_f32_e32 v0, 1.0, v55
	v_rcp_f32_e32 v57, v56
	s_nop 0
	v_mul_f32_e32 v55, 1.0, v57
	v_cvt_pk_bf16_f32 v55, v55, v0
	v_mul_f32_e32 v0, 0xbfb8aa3b, v50
	v_exp_f32_e32 v50, v0
	v_mul_f32_e32 v0, 0xbfb8aa3b, v51
	v_exp_f32_e32 v51, v0
	s_nop 0
	v_pk_add_f32 v[50:51], v[50:51], 1.0 op_sel_hi:[1,0]
	s_nop 0
	v_rcp_f32_e32 v56, v51
	s_nop 0
	v_mul_f32_e32 v0, 1.0, v56
	v_rcp_f32_e32 v56, v50
	s_nop 0
	v_mul_f32_e32 v50, 1.0, v56
	v_cvt_pk_bf16_f32 v56, v50, v0
	v_mul_f32_e32 v0, 0xbfb8aa3b, v52
	v_exp_f32_e32 v50, v0
	v_mul_f32_e32 v0, 0xbfb8aa3b, v53
	v_exp_f32_e32 v51, v0
	s_nop 0
	v_pk_add_f32 v[50:51], v[50:51], 1.0 op_sel_hi:[1,0]
	s_nop 0
	v_rcp_f32_e32 v52, v51
	s_nop 0
	v_mul_f32_e32 v0, 1.0, v52
	v_rcp_f32_e32 v52, v50
	s_nop 0
	v_mul_f32_e32 v50, 1.0, v52
	v_cvt_pk_bf16_f32 v57, v50, v0
	v_mul_f32_e32 v0, 0xbfb8aa3b, v46
	v_exp_f32_e32 v46, v0
	v_mul_f32_e32 v0, 0xbfb8aa3b, v47
	v_exp_f32_e32 v47, v0
	v_ashrrev_i32_e32 v61, 31, v60
	v_lshlrev_b64 v[50:51], 12, v[60:61]
	v_lshl_add_u64 v[50:51], s[36:37], 0, v[50:51]
	v_pk_add_f32 v[46:47], v[46:47], 1.0 op_sel_hi:[1,0]
	v_lshl_add_u64 v[50:51], v[50:51], 0, v[122:123]
	v_rcp_f32_e32 v53, v47
	global_store_dwordx4 v[50:51], v[54:57], off
	v_add_u32_e32 v52, 0xa0, v130
	s_nop 0
	v_mul_f32_e32 v0, 1.0, v53
	v_rcp_f32_e32 v53, v46
	s_nop 0
	v_mul_f32_e32 v46, 1.0, v53
	v_cvt_pk_bf16_f32 v46, v46, v0
	v_mul_f32_e32 v0, 0xbfb8aa3b, v48
	v_exp_f32_e32 v48, v0
	v_mul_f32_e32 v0, 0xbfb8aa3b, v49
	v_exp_f32_e32 v49, v0
	s_nop 0
	v_pk_add_f32 v[48:49], v[48:49], 1.0 op_sel_hi:[1,0]
	s_nop 0
	v_rcp_f32_e32 v47, v49
	s_nop 0
	v_mul_f32_e32 v0, 1.0, v47
	v_rcp_f32_e32 v49, v48
	s_nop 0
	v_mul_f32_e32 v47, 1.0, v49
	v_cvt_pk_bf16_f32 v47, v47, v0
	v_mul_f32_e32 v0, 0xbfb8aa3b, v42
	v_exp_f32_e32 v42, v0
	v_mul_f32_e32 v0, 0xbfb8aa3b, v43
	v_exp_f32_e32 v43, v0
	s_nop 0
	v_pk_add_f32 v[42:43], v[42:43], 1.0 op_sel_hi:[1,0]
	s_nop 0
	v_rcp_f32_e32 v48, v43
	s_nop 0
	v_mul_f32_e32 v0, 1.0, v48
	v_rcp_f32_e32 v48, v42
	s_nop 0
	v_mul_f32_e32 v42, 1.0, v48
	v_cvt_pk_bf16_f32 v48, v42, v0
	v_mul_f32_e32 v0, 0xbfb8aa3b, v44
	v_exp_f32_e32 v42, v0
	v_mul_f32_e32 v0, 0xbfb8aa3b, v45
	v_exp_f32_e32 v43, v0
	s_nop 0
	v_pk_add_f32 v[42:43], v[42:43], 1.0 op_sel_hi:[1,0]
	s_nop 0
	v_rcp_f32_e32 v44, v43
	s_nop 0
	v_mul_f32_e32 v0, 1.0, v44
	v_rcp_f32_e32 v44, v42
	s_nop 0
	v_mul_f32_e32 v42, 1.0, v44
	v_cvt_pk_bf16_f32 v49, v42, v0
	v_mul_f32_e32 v0, 0xbfb8aa3b, v38
	v_exp_f32_e32 v38, v0
	v_mul_f32_e32 v0, 0xbfb8aa3b, v39
	v_exp_f32_e32 v39, v0
	v_ashrrev_i32_e32 v53, 31, v52
	v_lshlrev_b64 v[42:43], 12, v[52:53]
	v_lshl_add_u64 v[42:43], s[36:37], 0, v[42:43]
	v_pk_add_f32 v[38:39], v[38:39], 1.0 op_sel_hi:[1,0]
	v_lshl_add_u64 v[42:43], v[42:43], 0, v[122:123]
	v_rcp_f32_e32 v45, v39
	global_store_dwordx4 v[42:43], v[46:49], off
	v_add_u32_e32 v44, 0xb0, v130
	s_nop 0
	v_mul_f32_e32 v0, 1.0, v45
	v_rcp_f32_e32 v45, v38
	s_nop 0
	v_mul_f32_e32 v38, 1.0, v45
	v_cvt_pk_bf16_f32 v38, v38, v0
	v_mul_f32_e32 v0, 0xbfb8aa3b, v40
	v_exp_f32_e32 v40, v0
	v_mul_f32_e32 v0, 0xbfb8aa3b, v41
	v_exp_f32_e32 v41, v0
	s_nop 0
	v_pk_add_f32 v[40:41], v[40:41], 1.0 op_sel_hi:[1,0]
	s_nop 0
	v_rcp_f32_e32 v39, v41
	s_nop 0
	v_mul_f32_e32 v0, 1.0, v39
	v_rcp_f32_e32 v41, v40
	s_nop 0
	v_mul_f32_e32 v39, 1.0, v41
	v_cvt_pk_bf16_f32 v39, v39, v0
	v_mul_f32_e32 v0, 0xbfb8aa3b, v34
	v_exp_f32_e32 v34, v0
	v_mul_f32_e32 v0, 0xbfb8aa3b, v35
	v_exp_f32_e32 v35, v0
	s_nop 0
	v_pk_add_f32 v[34:35], v[34:35], 1.0 op_sel_hi:[1,0]
	s_nop 0
	v_rcp_f32_e32 v40, v35
	s_nop 0
	v_mul_f32_e32 v0, 1.0, v40
	v_rcp_f32_e32 v40, v34
	s_nop 0
	v_mul_f32_e32 v34, 1.0, v40
	v_cvt_pk_bf16_f32 v40, v34, v0
	v_mul_f32_e32 v0, 0xbfb8aa3b, v36
	v_exp_f32_e32 v34, v0
	v_mul_f32_e32 v0, 0xbfb8aa3b, v37
	v_exp_f32_e32 v35, v0
	s_nop 0
	v_pk_add_f32 v[34:35], v[34:35], 1.0 op_sel_hi:[1,0]
	s_nop 0
	v_rcp_f32_e32 v36, v35
; DI unsigned pack2(float a, float b) { f32x2_t v = {a, b}; bf16x2_t r = __builtin_convertvector(v, bf16x2_t); return __builtin_bit_cast(unsigned, r); }
; DI float sigmoidf_(float x) { return 1.f / (1.f + __expf(-x)); }
; DI bfu* wsb(const PX& p, size_t off) { return (bfu*)(p.ws + off); }
; template <int EPI, int HM>
; DI void epi256(const PX& p, int l, f32x4 (&acc)[2][2][4][2], int brow, int bcol, int aux, bool src_input) {
;     ...
;           } else if (EPI == EPI_GATE) {
;             uint4 o;
;             o.x = pack2(sigmoidf_(v[0]), sigmoidf_(v[1])); o.y = pack2(sigmoidf_(v[2]), sigmoidf_(v[3]));
;             o.z = pack2(sigmoidf_(v[4]), sigmoidf_(v[5])); o.w = pack2(sigmoidf_(v[6]), sigmoidf_(v[7]));
;             *(uint4*)(wsb(p, OFF_BIG + B_ZML) + (size_t)row * 2048 + col0) = o;
	s_nop 0
	v_mul_f32_e32 v0, 1.0, v36
	v_rcp_f32_e32 v36, v34
	s_nop 0
	v_mul_f32_e32 v34, 1.0, v36
	v_cvt_pk_bf16_f32 v41, v34, v0
	v_mul_f32_e32 v0, 0xbfb8aa3b, v30
	v_exp_f32_e32 v30, v0
	v_mul_f32_e32 v0, 0xbfb8aa3b, v31
	v_exp_f32_e32 v31, v0
	v_ashrrev_i32_e32 v45, 31, v44
	v_lshlrev_b64 v[34:35], 12, v[44:45]
	v_lshl_add_u64 v[34:35], s[36:37], 0, v[34:35]
	v_pk_add_f32 v[30:31], v[30:31], 1.0 op_sel_hi:[1,0]
	v_lshl_add_u64 v[34:35], v[34:35], 0, v[122:123]
	v_rcp_f32_e32 v36, v31
	global_store_dwordx4 v[34:35], v[38:41], off
	v_mul_f32_e32 v0, 1.0, v36
	v_rcp_f32_e32 v36, v30
	s_nop 0
	v_mul_f32_e32 v30, 1.0, v36
	v_cvt_pk_bf16_f32 v30, v30, v0
	v_mul_f32_e32 v0, 0xbfb8aa3b, v32
	v_exp_f32_e32 v32, v0
	v_mul_f32_e32 v0, 0xbfb8aa3b, v33
	v_exp_f32_e32 v33, v0
	s_nop 0
	v_pk_add_f32 v[32:33], v[32:33], 1.0 op_sel_hi:[1,0]
	s_nop 0
	v_rcp_f32_e32 v31, v33
	s_nop 0
	v_mul_f32_e32 v0, 1.0, v31
	v_rcp_f32_e32 v33, v32
	s_nop 0
	v_mul_f32_e32 v31, 1.0, v33
	v_cvt_pk_bf16_f32 v31, v31, v0
	v_mul_f32_e32 v0, 0xbfb8aa3b, v26
	v_exp_f32_e32 v26, v0
	v_mul_f32_e32 v0, 0xbfb8aa3b, v27
	v_exp_f32_e32 v27, v0
	s_nop 0
	v_pk_add_f32 v[26:27], v[26:27], 1.0 op_sel_hi:[1,0]
	s_nop 0
	v_rcp_f32_e32 v32, v27
	s_nop 0
	v_mul_f32_e32 v0, 1.0, v32
	v_rcp_f32_e32 v32, v26
	s_nop 0
	v_mul_f32_e32 v26, 1.0, v32
	v_cvt_pk_bf16_f32 v32, v26, v0
	v_mul_f32_e32 v0, 0xbfb8aa3b, v28
	v_exp_f32_e32 v26, v0
	v_mul_f32_e32 v0, 0xbfb8aa3b, v29
	v_exp_f32_e32 v27, v0
	s_nop 0
	v_pk_add_f32 v[26:27], v[26:27], 1.0 op_sel_hi:[1,0]
	s_nop 0
	v_rcp_f32_e32 v28, v27
	s_nop 0
	v_mul_f32_e32 v0, 1.0, v28
	v_rcp_f32_e32 v28, v26
	s_nop 0
	v_mul_f32_e32 v26, 1.0, v28
	v_cvt_pk_bf16_f32 v33, v26, v0
	v_mul_f32_e32 v0, 0xbfb8aa3b, v22
	v_exp_f32_e32 v22, v0
	v_mul_f32_e32 v0, 0xbfb8aa3b, v23
	v_exp_f32_e32 v23, v0
	global_store_dwordx4 v[58:59], v[30:33], off offset:256
	v_pk_add_f32 v[22:23], v[22:23], 1.0 op_sel_hi:[1,0]
	s_nop 0
	v_rcp_f32_e32 v26, v23
	s_nop 0
	v_mul_f32_e32 v0, 1.0, v26
	v_rcp_f32_e32 v26, v22
	s_nop 0
	v_mul_f32_e32 v22, 1.0, v26
	v_cvt_pk_bf16_f32 v22, v22, v0
	v_mul_f32_e32 v0, 0xbfb8aa3b, v24
	v_exp_f32_e32 v24, v0
	v_mul_f32_e32 v0, 0xbfb8aa3b, v25
	v_exp_f32_e32 v25, v0
	s_nop 0
	v_pk_add_f32 v[24:25], v[24:25], 1.0 op_sel_hi:[1,0]
	s_nop 0
	v_rcp_f32_e32 v23, v25
	s_nop 0
	v_mul_f32_e32 v0, 1.0, v23
	v_rcp_f32_e32 v25, v24
	s_nop 0
	v_mul_f32_e32 v23, 1.0, v25
	v_cvt_pk_bf16_f32 v23, v23, v0
	v_mul_f32_e32 v0, 0xbfb8aa3b, v18
	v_exp_f32_e32 v18, v0
	v_mul_f32_e32 v0, 0xbfb8aa3b, v19
	v_exp_f32_e32 v19, v0
	s_nop 0
	v_pk_add_f32 v[18:19], v[18:19], 1.0 op_sel_hi:[1,0]
	s_nop 0
	v_rcp_f32_e32 v24, v19
	s_nop 0
	v_mul_f32_e32 v0, 1.0, v24
	v_rcp_f32_e32 v24, v18
	s_nop 0
	v_mul_f32_e32 v18, 1.0, v24
	v_cvt_pk_bf16_f32 v24, v18, v0
	v_mul_f32_e32 v0, 0xbfb8aa3b, v20
	v_exp_f32_e32 v18, v0
	v_mul_f32_e32 v0, 0xbfb8aa3b, v21
	v_exp_f32_e32 v19, v0
	s_nop 0
	v_pk_add_f32 v[18:19], v[18:19], 1.0 op_sel_hi:[1,0]
	s_nop 0
	v_rcp_f32_e32 v20, v19
	s_nop 0
	v_mul_f32_e32 v0, 1.0, v20
	v_rcp_f32_e32 v20, v18
	s_nop 0
	v_mul_f32_e32 v18, 1.0, v20
	v_cvt_pk_bf16_f32 v25, v18, v0
	v_mul_f32_e32 v0, 0xbfb8aa3b, v14
	v_exp_f32_e32 v14, v0
	v_mul_f32_e32 v0, 0xbfb8aa3b, v15
	v_exp_f32_e32 v15, v0
	global_store_dwordx4 v[50:51], v[22:25], off offset:256
	v_pk_add_f32 v[14:15], v[14:15], 1.0 op_sel_hi:[1,0]
	s_nop 0
	v_rcp_f32_e32 v18, v15
	s_nop 0
	v_mul_f32_e32 v0, 1.0, v18
	v_rcp_f32_e32 v18, v14
	s_nop 0
	v_mul_f32_e32 v14, 1.0, v18
	v_cvt_pk_bf16_f32 v14, v14, v0
	v_mul_f32_e32 v0, 0xbfb8aa3b, v16
	v_exp_f32_e32 v16, v0
	v_mul_f32_e32 v0, 0xbfb8aa3b, v17
	v_exp_f32_e32 v17, v0
	s_nop 0
	v_pk_add_f32 v[16:17], v[16:17], 1.0 op_sel_hi:[1,0]
	s_nop 0
	v_rcp_f32_e32 v15, v17
	s_nop 0
	v_mul_f32_e32 v0, 1.0, v15
	v_rcp_f32_e32 v17, v16
	s_nop 0
	v_mul_f32_e32 v15, 1.0, v17
	v_cvt_pk_bf16_f32 v15, v15, v0
	v_mul_f32_e32 v0, 0xbfb8aa3b, v10
	v_exp_f32_e32 v10, v0
	v_mul_f32_e32 v0, 0xbfb8aa3b, v11
	v_exp_f32_e32 v11, v0
	s_nop 0
	v_pk_add_f32 v[10:11], v[10:11], 1.0 op_sel_hi:[1,0]
	s_nop 0
	v_rcp_f32_e32 v16, v11
	s_nop 0
	v_mul_f32_e32 v0, 1.0, v16
	v_rcp_f32_e32 v16, v10
	s_nop 0
	v_mul_f32_e32 v10, 1.0, v16
	v_cvt_pk_bf16_f32 v16, v10, v0
	v_mul_f32_e32 v0, 0xbfb8aa3b, v12
	v_exp_f32_e32 v10, v0
	v_mul_f32_e32 v0, 0xbfb8aa3b, v13
	v_exp_f32_e32 v11, v0
	s_nop 0
	v_pk_add_f32 v[10:11], v[10:11], 1.0 op_sel_hi:[1,0]
	s_nop 0
	v_rcp_f32_e32 v12, v11
	s_nop 0
	v_mul_f32_e32 v0, 1.0, v12
	v_rcp_f32_e32 v12, v10
	s_nop 0
	v_mul_f32_e32 v10, 1.0, v12
	v_cvt_pk_bf16_f32 v17, v10, v0
	v_mul_f32_e32 v0, 0xbfb8aa3b, v6
	v_exp_f32_e32 v6, v0
	v_mul_f32_e32 v0, 0xbfb8aa3b, v7
	v_exp_f32_e32 v7, v0
	global_store_dwordx4 v[42:43], v[14:17], off offset:256
	v_pk_add_f32 v[6:7], v[6:7], 1.0 op_sel_hi:[1,0]
	s_nop 0
	v_rcp_f32_e32 v10, v7
	s_nop 0
	v_mul_f32_e32 v0, 1.0, v10
	v_rcp_f32_e32 v10, v6
	s_nop 0
	v_mul_f32_e32 v6, 1.0, v10
	v_cvt_pk_bf16_f32 v6, v6, v0
	v_mul_f32_e32 v0, 0xbfb8aa3b, v8
	v_exp_f32_e32 v8, v0
	v_mul_f32_e32 v0, 0xbfb8aa3b, v9
	v_exp_f32_e32 v9, v0
	s_nop 0
	v_pk_add_f32 v[8:9], v[8:9], 1.0 op_sel_hi:[1,0]
	s_nop 0
	v_rcp_f32_e32 v7, v9
	s_nop 0
	v_mul_f32_e32 v0, 1.0, v7
	v_rcp_f32_e32 v9, v8
	s_nop 0
	v_mul_f32_e32 v7, 1.0, v9
	v_cvt_pk_bf16_f32 v7, v7, v0
	v_mul_f32_e32 v0, 0xbfb8aa3b, v2
	v_exp_f32_e32 v2, v0
	v_mul_f32_e32 v0, 0xbfb8aa3b, v3
	v_exp_f32_e32 v3, v0
	s_nop 0
	v_pk_add_f32 v[2:3], v[2:3], 1.0 op_sel_hi:[1,0]
	s_nop 0
	v_rcp_f32_e32 v8, v3
	s_nop 0
	v_mul_f32_e32 v0, 1.0, v8
	v_rcp_f32_e32 v8, v2
	s_nop 0
	v_mul_f32_e32 v2, 1.0, v8
	v_cvt_pk_bf16_f32 v8, v2, v0
	v_mul_f32_e32 v0, 0xbfb8aa3b, v4
	v_exp_f32_e32 v2, v0
	v_mul_f32_e32 v0, 0xbfb8aa3b, v5
	v_exp_f32_e32 v3, v0
	s_nop 0
	v_pk_add_f32 v[2:3], v[2:3], 1.0 op_sel_hi:[1,0]
	s_nop 0
	v_rcp_f32_e32 v4, v3
	s_nop 0
	v_mul_f32_e32 v0, 1.0, v4
	v_rcp_f32_e32 v4, v2
	s_nop 0
	v_mul_f32_e32 v2, 1.0, v4
	v_cvt_pk_bf16_f32 v9, v2, v0
	global_store_dwordx4 v[34:35], v[6:9], off offset:256
	s_nop 0
	v_ashrrev_i32_e32 v0, 8, v144
	v_cmp_eq_u32_e32 vcc, 1, v0
	s_and_saveexec_b64 s[76:77], vcc
	s_cbranch_execz .LBB0_309
	s_barrier

; DI unsigned pack2(float a, float b) { f32x2_t v = {a, b}; bf16x2_t r = __builtin_convertvector(v, bf16x2_t); return __builtin_bit_cast(unsigned, r); }
; DI float lo16(unsigned u) { return __uint_as_float(u << 16); }
; DI float hi16(unsigned u) { return __uint_as_float(u & 0xffff0000u); }
; DI bfu* wsb(const PX& p, size_t off) { return (bfu*)(p.ws + off); }
; DI float sigmoidf_(float x) { return 1.f / (1.f + __expf(-x)); }
; template <int EPI, int HM>
; DI void epi256(const PX& p, int l, f32x4 (&acc)[2][2][4][2], int brow, int bcol, int aux, bool src_input) {
;     ...
;             const float* gbp = p.in[30] + l * 768 + col0;
;             const f32x4 g0 = *(const f32x4*)gbp, g1 = *(const f32x4*)(gbp + 4);
;             const float gb[8] = {g0[0], g0[1], g0[2], g0[3], g1[0], g1[1], g1[2], g1[3]};
;             const uint4 z = *(const uint4*)(wsb(p, OFF_BIG + B_YF) + (size_t)row * 768 + col0);
;             const unsigned zz[4] = {z.x, z.y, z.z, z.w};
;             unsigned oo[4];
; #pragma unroll
;             for (int q = 0; q < 4; q++)
;               oo[q] = pack2(lo16(zz[q]) * sigmoidf_(v[2 * q] + gb[2 * q]), hi16(zz[q]) * sigmoidf_(v[2 * q + 1] + gb[2 * q + 1]));
;             *(uint4*)(wsb(p, OFF_BIG + B_YB) + (size_t)row * 768 + col0) = make_uint4(oo[0], oo[1], oo[2], oo[3]);
.LBB0_354:
	s_or_b64 exec, exec, s[10:11]
	v_mov_b32_e32 v130, v188
	s_nop 0
	v_ashrrev_i32_e32 v0, 2, v130
	v_and_or_b32 v131, v130, 15, s1
	v_lshrrev_b32_e32 v130, 1, v130
	v_and_b32_e32 v130, 0x78, v130
	v_or_b32_e32 v132, s0, v130
	v_and_b32_e32 v0, 0xffffffc0, v0
	v_ashrrev_i32_e32 v133, 31, v132
	v_add_u32_e32 v0, v131, v0
	v_lshl_add_u64 v[130:131], v[132:133], 2, s[6:7]
	global_load_dwordx4 v[138:141], v[130:131], off offset:16
	global_load_dwordx4 v[142:145], v[130:131], off
	v_readlane_b32 s0, v254, 4
	v_readlane_b32 s1, v254, 5
	v_lshlrev_b64 v[132:133], 1, v[132:133]
	s_waitcnt vmcnt(0)
	v_add_f32_e32 v122, v122, v138
	v_mov_b64_e32 v[134:135], s[0:1]
	v_mad_i64_i32 v[136:137], s[0:1], v0, s81, v[134:135]
	v_lshl_add_u64 v[136:137], v[136:137], 0, v[132:133]
	global_load_dwordx4 v[146:149], v[136:137], off
	v_add_f32_e32 v126, v126, v142
	v_add_f32_e32 v127, v127, v143
	v_mul_f32_e32 v126, 0xbfb8aa3b, v126
	v_mul_f32_e32 v127, 0xbfb8aa3b, v127
	v_exp_f32_e32 v126, v126
	v_exp_f32_e32 v127, v127
	v_add_f32_e32 v129, v129, v145
	v_mul_f32_e32 v129, 0xbfb8aa3b, v129
	v_exp_f32_e32 v129, v129
	v_pk_add_f32 v[126:127], v[126:127], 1.0 op_sel_hi:[1,0]
	v_add_f32_e32 v123, v123, v139
	v_rcp_f32_e32 v143, v127
	v_mul_f32_e32 v122, 0xbfb8aa3b, v122
	v_mul_f32_e32 v123, 0xbfb8aa3b, v123
	v_exp_f32_e32 v122, v122
	v_exp_f32_e32 v123, v123
	v_add_f32_e32 v125, v125, v141
	v_mul_f32_e32 v125, 0xbfb8aa3b, v125
	v_exp_f32_e32 v125, v125
	v_pk_add_f32 v[122:123], v[122:123], 1.0 op_sel_hi:[1,0]
	s_waitcnt vmcnt(0)
	v_lshlrev_b32_e32 v150, 16, v146
	v_and_b32_e32 v151, 0xffff0000, v146
	v_mul_f32_e32 v127, 1.0, v143
	v_rcp_f32_e32 v143, v126
	s_nop 0
	v_mul_f32_e32 v126, 1.0, v143
	v_pk_mul_f32 v[126:127], v[126:127], v[150:151]
	v_or_b32_e32 v150, 16, v0
	v_cvt_pk_bf16_f32 v142, v126, v127
	v_add_f32_e32 v127, v128, v144
	v_mul_f32_e32 v127, 0xbfb8aa3b, v127
	v_exp_f32_e32 v128, v127
	v_lshlrev_b32_e32 v126, 16, v147
	v_and_b32_e32 v127, 0xffff0000, v147
	v_pk_add_f32 v[128:129], v[128:129], 1.0 op_sel_hi:[1,0]
	s_nop 0
	v_rcp_f32_e32 v144, v129
	s_nop 0
	v_mul_f32_e32 v129, 1.0, v144
	v_rcp_f32_e32 v144, v128
	s_nop 0
	v_mul_f32_e32 v128, 1.0, v144
	v_pk_mul_f32 v[126:127], v[128:129], v[126:127]
	v_rcp_f32_e32 v129, v123
	v_cvt_pk_bf16_f32 v143, v126, v127
	v_lshlrev_b32_e32 v126, 16, v148
	v_and_b32_e32 v127, 0xffff0000, v148
	v_mul_f32_e32 v123, 1.0, v129
	v_rcp_f32_e32 v129, v122
	s_nop 0
	v_mul_f32_e32 v122, 1.0, v129
	v_pk_mul_f32 v[122:123], v[122:123], v[126:127]
	s_nop 0
	v_cvt_pk_bf16_f32 v144, v122, v123
	v_add_f32_e32 v123, v124, v140
	v_mul_f32_e32 v123, 0xbfb8aa3b, v123
	v_exp_f32_e32 v124, v123
	v_lshlrev_b32_e32 v122, 16, v149
	v_and_b32_e32 v123, 0xffff0000, v149
	v_pk_add_f32 v[124:125], v[124:125], 1.0 op_sel_hi:[1,0]
	s_nop 0
	v_rcp_f32_e32 v127, v125
	s_nop 0
	v_mul_f32_e32 v125, 1.0, v127
	v_rcp_f32_e32 v127, v124
	v_readlane_b32 s0, v254, 6
	v_readlane_b32 s1, v254, 7
	v_mul_f32_e32 v124, 1.0, v127
	v_pk_mul_f32 v[122:123], v[124:125], v[122:123]
	s_nop 0
	v_cvt_pk_bf16_f32 v145, v122, v123
	v_mov_b64_e32 v[122:123], s[0:1]
	v_mad_i64_i32 v[124:125], s[0:1], v0, s81, v[122:123]
	v_lshl_add_u64 v[126:127], v[124:125], 0, v[132:133]
	global_store_dwordx4 v[126:127], v[142:145], off
	global_load_dwordx4 v[138:141], v[130:131], off offset:16
	s_nop 0
	global_load_dwordx4 v[142:145], v[130:131], off
	v_mad_i64_i32 v[124:125], s[0:1], v150, s81, v[134:135]
	v_lshl_add_u64 v[124:125], v[124:125], 0, v[132:133]
	global_load_dwordx4 v[146:149], v[124:125], off
	s_waitcnt vmcnt(0)
	v_add_f32_e32 v114, v114, v138
	v_add_f32_e32 v118, v118, v142
	v_add_f32_e32 v119, v119, v143
	v_mul_f32_e32 v118, 0xbfb8aa3b, v118
	v_mul_f32_e32 v119, 0xbfb8aa3b, v119
	v_exp_f32_e32 v118, v118
	v_exp_f32_e32 v119, v119
	v_lshlrev_b32_e32 v128, 16, v146
	v_and_b32_e32 v129, 0xffff0000, v146
	v_add_f32_e32 v115, v115, v139
	v_pk_add_f32 v[118:119], v[118:119], 1.0 op_sel_hi:[1,0]
	v_mul_f32_e32 v114, 0xbfb8aa3b, v114
	v_rcp_f32_e32 v143, v119
	v_mul_f32_e32 v115, 0xbfb8aa3b, v115
	v_exp_f32_e32 v114, v114
	v_exp_f32_e32 v115, v115
	s_nop 0
	v_mul_f32_e32 v119, 1.0, v143
	v_rcp_f32_e32 v143, v118
	v_pk_add_f32 v[114:115], v[114:115], 1.0 op_sel_hi:[1,0]
	v_add_f32_e32 v117, v117, v141
	v_mul_f32_e32 v117, 0xbfb8aa3b, v117
	v_mul_f32_e32 v118, 1.0, v143
	v_pk_mul_f32 v[118:119], v[118:119], v[128:129]
	v_lshlrev_b32_e32 v128, 16, v147
	v_cvt_pk_bf16_f32 v118, v118, v119
	v_add_f32_e32 v119, v120, v144
	v_mul_f32_e32 v119, 0xbfb8aa3b, v119
	v_exp_f32_e32 v120, v119
	v_add_f32_e32 v119, v121, v145
	v_mul_f32_e32 v119, 0xbfb8aa3b, v119
	v_exp_f32_e32 v121, v119
	v_and_b32_e32 v129, 0xffff0000, v147
	v_exp_f32_e32 v117, v117
	v_or_b32_e32 v146, 32, v0
	v_pk_add_f32 v[120:121], v[120:121], 1.0 op_sel_hi:[1,0]
	s_nop 0
	v_rcp_f32_e32 v142, v121
	s_nop 0
	v_mul_f32_e32 v121, 1.0, v142
	v_rcp_f32_e32 v142, v120
	s_nop 0
	v_mul_f32_e32 v120, 1.0, v142
	v_pk_mul_f32 v[120:121], v[120:121], v[128:129]
	v_rcp_f32_e32 v129, v115
	v_cvt_pk_bf16_f32 v119, v120, v121
	v_lshlrev_b32_e32 v120, 16, v148
	v_and_b32_e32 v121, 0xffff0000, v148
	v_mul_f32_e32 v115, 1.0, v129
	v_rcp_f32_e32 v129, v114
	s_nop 0
	v_mul_f32_e32 v114, 1.0, v129
	v_pk_mul_f32 v[114:115], v[114:115], v[120:121]
	s_nop 0
	v_cvt_pk_bf16_f32 v120, v114, v115
	v_add_f32_e32 v115, v116, v140
	v_mul_f32_e32 v115, 0xbfb8aa3b, v115
	v_exp_f32_e32 v116, v115
	v_lshlrev_b32_e32 v114, 16, v149
	v_and_b32_e32 v115, 0xffff0000, v149
	v_pk_add_f32 v[116:117], v[116:117], 1.0 op_sel_hi:[1,0]
	s_nop 0
	v_rcp_f32_e32 v128, v117
	s_nop 0
	v_mul_f32_e32 v117, 1.0, v128
	v_rcp_f32_e32 v128, v116
	s_nop 0
	v_mul_f32_e32 v116, 1.0, v128
	v_pk_mul_f32 v[114:115], v[116:117], v[114:115]
	s_nop 0
	v_cvt_pk_bf16_f32 v121, v114, v115
	v_mad_i64_i32 v[114:115], s[0:1], v150, s81, v[122:123]
	v_lshl_add_u64 v[116:117], v[114:115], 0, v[132:133]
	global_store_dwordx4 v[116:117], v[118:121], off
	global_load_dwordx4 v[118:121], v[130:131], off offset:16
	s_nop 0
	global_load_dwordx4 v[138:141], v[130:131], off
	v_mad_i64_i32 v[114:115], s[0:1], v146, s81, v[134:135]
	v_lshl_add_u64 v[114:115], v[114:115], 0, v[132:133]
	global_load_dwordx4 v[142:145], v[114:115], off
	s_waitcnt vmcnt(0)
; DI unsigned pack2(float a, float b) { f32x2_t v = {a, b}; bf16x2_t r = __builtin_convertvector(v, bf16x2_t); return __builtin_bit_cast(unsigned, r); }
; DI float lo16(unsigned u) { return __uint_as_float(u << 16); }
; DI float hi16(unsigned u) { return __uint_as_float(u & 0xffff0000u); }
; DI bfu* wsb(const PX& p, size_t off) { return (bfu*)(p.ws + off); }
; DI float sigmoidf_(float x) { return 1.f / (1.f + __expf(-x)); }
; template <int EPI, int HM>
; DI void epi256(const PX& p, int l, f32x4 (&acc)[2][2][4][2], int brow, int bcol, int aux, bool src_input) {
;     ...
;             const float* gbp = p.in[30] + l * 768 + col0;
;             const f32x4 g0 = *(const f32x4*)gbp, g1 = *(const f32x4*)(gbp + 4);
;             const float gb[8] = {g0[0], g0[1], g0[2], g0[3], g1[0], g1[1], g1[2], g1[3]};
;             const uint4 z = *(const uint4*)(wsb(p, OFF_BIG + B_YF) + (size_t)row * 768 + col0);
;             const unsigned zz[4] = {z.x, z.y, z.z, z.w};
;             unsigned oo[4];
; #pragma unroll
;             for (int q = 0; q < 4; q++)
;               oo[q] = pack2(lo16(zz[q]) * sigmoidf_(v[2 * q] + gb[2 * q]), hi16(zz[q]) * sigmoidf_(v[2 * q + 1] + gb[2 * q + 1]));
;             *(uint4*)(wsb(p, OFF_BIG + B_YB) + (size_t)row * 768 + col0) = make_uint4(oo[0], oo[1], oo[2], oo[3]);
	v_add_f32_e32 v106, v106, v118
	v_add_f32_e32 v110, v110, v138
	v_add_f32_e32 v111, v111, v139
	v_mul_f32_e32 v110, 0xbfb8aa3b, v110
	v_mul_f32_e32 v111, 0xbfb8aa3b, v111
	v_exp_f32_e32 v110, v110
	v_exp_f32_e32 v111, v111
	v_lshlrev_b32_e32 v128, 16, v142
	v_and_b32_e32 v129, 0xffff0000, v142
	v_add_f32_e32 v113, v113, v141
	v_pk_add_f32 v[110:111], v[110:111], 1.0 op_sel_hi:[1,0]
	v_mul_f32_e32 v113, 0xbfb8aa3b, v113
	v_rcp_f32_e32 v139, v111
	v_exp_f32_e32 v113, v113
	v_add_f32_e32 v107, v107, v119
	v_mul_f32_e32 v106, 0xbfb8aa3b, v106
	v_mul_f32_e32 v111, 1.0, v139
	v_rcp_f32_e32 v139, v110
	v_mul_f32_e32 v107, 0xbfb8aa3b, v107
	v_exp_f32_e32 v106, v106
	v_exp_f32_e32 v107, v107
	s_nop 0
	v_mul_f32_e32 v110, 1.0, v139
	v_pk_mul_f32 v[110:111], v[110:111], v[128:129]
	v_pk_add_f32 v[106:107], v[106:107], 1.0 op_sel_hi:[1,0]
	v_cvt_pk_bf16_f32 v138, v110, v111
	v_add_f32_e32 v111, v112, v140
	v_mul_f32_e32 v111, 0xbfb8aa3b, v111
	v_exp_f32_e32 v112, v111
	v_lshlrev_b32_e32 v110, 16, v143
	v_and_b32_e32 v111, 0xffff0000, v143
	v_add_f32_e32 v109, v109, v121
	v_pk_add_f32 v[112:113], v[112:113], 1.0 op_sel_hi:[1,0]
	v_mul_f32_e32 v109, 0xbfb8aa3b, v109
	v_rcp_f32_e32 v129, v113
	v_exp_f32_e32 v109, v109
	s_nop 0
	v_mul_f32_e32 v113, 1.0, v129
	v_rcp_f32_e32 v129, v112
	s_nop 0
	v_mul_f32_e32 v112, 1.0, v129
	v_pk_mul_f32 v[110:111], v[112:113], v[110:111]
	v_rcp_f32_e32 v113, v107
	v_cvt_pk_bf16_f32 v139, v110, v111
	v_lshlrev_b32_e32 v110, 16, v144
	v_and_b32_e32 v111, 0xffff0000, v144
	v_mul_f32_e32 v107, 1.0, v113
	v_rcp_f32_e32 v113, v106
	s_nop 0
	v_mul_f32_e32 v106, 1.0, v113
	v_pk_mul_f32 v[106:107], v[106:107], v[110:111]
	s_nop 0
	v_cvt_pk_bf16_f32 v140, v106, v107
	v_add_f32_e32 v107, v108, v120
	v_mul_f32_e32 v107, 0xbfb8aa3b, v107
	v_exp_f32_e32 v108, v107
	v_lshlrev_b32_e32 v106, 16, v145
	v_and_b32_e32 v107, 0xffff0000, v145
	v_pk_add_f32 v[108:109], v[108:109], 1.0 op_sel_hi:[1,0]
	s_nop 0
	v_rcp_f32_e32 v111, v109
	s_nop 0
	v_mul_f32_e32 v109, 1.0, v111
	v_rcp_f32_e32 v111, v108
	s_nop 0
	v_mul_f32_e32 v108, 1.0, v111
	v_pk_mul_f32 v[106:107], v[108:109], v[106:107]
	v_or_b32_e32 v112, 48, v0
	v_cvt_pk_bf16_f32 v141, v106, v107
	v_mad_i64_i32 v[106:107], s[0:1], v146, s81, v[122:123]
	v_lshl_add_u64 v[110:111], v[106:107], 0, v[132:133]
	global_store_dwordx4 v[110:111], v[138:141], off
	global_load_dwordx4 v[118:121], v[130:131], off offset:16
	s_nop 0
	global_load_dwordx4 v[138:141], v[130:131], off
	v_mad_i64_i32 v[106:107], s[0:1], v112, s81, v[134:135]
	v_lshl_add_u64 v[108:109], v[106:107], 0, v[132:133]
	global_load_dwordx4 v[142:145], v[108:109], off
	s_waitcnt vmcnt(0)
	v_add_f32_e32 v98, v98, v118
	v_add_f32_e32 v102, v102, v138
	v_add_f32_e32 v103, v103, v139
	v_mul_f32_e32 v102, 0xbfb8aa3b, v102
	v_mul_f32_e32 v103, 0xbfb8aa3b, v103
	v_exp_f32_e32 v102, v102
	v_exp_f32_e32 v103, v103
	v_lshlrev_b32_e32 v106, 16, v142
	v_and_b32_e32 v107, 0xffff0000, v142
	v_add_f32_e32 v99, v99, v119
	v_pk_add_f32 v[102:103], v[102:103], 1.0 op_sel_hi:[1,0]
	v_mul_f32_e32 v98, 0xbfb8aa3b, v98
	v_rcp_f32_e32 v128, v103
	v_mul_f32_e32 v99, 0xbfb8aa3b, v99
	v_exp_f32_e32 v98, v98
	v_exp_f32_e32 v99, v99
	s_nop 0
	v_mul_f32_e32 v103, 1.0, v128
	v_rcp_f32_e32 v128, v102
	v_pk_add_f32 v[98:99], v[98:99], 1.0 op_sel_hi:[1,0]
	v_add_f32_e32 v101, v101, v121
	v_mul_f32_e32 v101, 0xbfb8aa3b, v101
	v_mul_f32_e32 v102, 1.0, v128
	v_pk_mul_f32 v[102:103], v[102:103], v[106:107]
	v_lshlrev_b32_e32 v106, 16, v143
	v_cvt_pk_bf16_f32 v102, v102, v103
	v_add_f32_e32 v103, v104, v140
	v_mul_f32_e32 v103, 0xbfb8aa3b, v103
	v_exp_f32_e32 v104, v103
	v_add_f32_e32 v103, v105, v141
	v_mul_f32_e32 v103, 0xbfb8aa3b, v103
	v_exp_f32_e32 v105, v103
	v_and_b32_e32 v107, 0xffff0000, v143
	v_exp_f32_e32 v101, v101
	v_pk_add_f32 v[104:105], v[104:105], 1.0 op_sel_hi:[1,0]
	s_nop 0
	v_rcp_f32_e32 v113, v105
	s_nop 0
	v_mul_f32_e32 v105, 1.0, v113
	v_rcp_f32_e32 v113, v104
	s_nop 0
	v_mul_f32_e32 v104, 1.0, v113
	v_pk_mul_f32 v[104:105], v[104:105], v[106:107]
	v_rcp_f32_e32 v107, v99
	v_cvt_pk_bf16_f32 v103, v104, v105
	v_lshlrev_b32_e32 v104, 16, v144
	v_and_b32_e32 v105, 0xffff0000, v144
	v_mul_f32_e32 v99, 1.0, v107
	v_rcp_f32_e32 v107, v98
	s_nop 0
	v_mul_f32_e32 v98, 1.0, v107
	v_pk_mul_f32 v[98:99], v[98:99], v[104:105]
	s_nop 0
	v_cvt_pk_bf16_f32 v104, v98, v99
	v_add_f32_e32 v99, v100, v120
	v_mul_f32_e32 v99, 0xbfb8aa3b, v99
	v_exp_f32_e32 v100, v99
	v_lshlrev_b32_e32 v98, 16, v145
	v_and_b32_e32 v99, 0xffff0000, v145
	v_pk_add_f32 v[100:101], v[100:101], 1.0 op_sel_hi:[1,0]
	s_nop 0
	v_rcp_f32_e32 v106, v101
	s_nop 0
	v_mul_f32_e32 v101, 1.0, v106
	v_rcp_f32_e32 v106, v100
	s_nop 0
	v_mul_f32_e32 v100, 1.0, v106
	v_pk_mul_f32 v[98:99], v[100:101], v[98:99]
	s_nop 0
	v_cvt_pk_bf16_f32 v105, v98, v99
	v_mad_i64_i32 v[98:99], s[0:1], v112, s81, v[122:123]
	v_lshl_add_u64 v[106:107], v[98:99], 0, v[132:133]
	global_store_dwordx4 v[106:107], v[102:105], off
	global_load_dwordx4 v[98:101], v[130:131], off offset:528
	s_nop 0
	global_load_dwordx4 v[102:105], v[130:131], off offset:512
	global_load_dwordx4 v[118:121], v[136:137], off offset:256
	s_waitcnt vmcnt(0)
; DI unsigned pack2(float a, float b) { f32x2_t v = {a, b}; bf16x2_t r = __builtin_convertvector(v, bf16x2_t); return __builtin_bit_cast(unsigned, r); }
; DI float lo16(unsigned u) { return __uint_as_float(u << 16); }
; DI float hi16(unsigned u) { return __uint_as_float(u & 0xffff0000u); }
; DI bfu* wsb(const PX& p, size_t off) { return (bfu*)(p.ws + off); }
; DI float sigmoidf_(float x) { return 1.f / (1.f + __expf(-x)); }
; template <int EPI, int HM>
; DI void epi256(const PX& p, int l, f32x4 (&acc)[2][2][4][2], int brow, int bcol, int aux, bool src_input) {
;     ...
;             const float* gbp = p.in[30] + l * 768 + col0;
;             const f32x4 g0 = *(const f32x4*)gbp, g1 = *(const f32x4*)(gbp + 4);
;             const float gb[8] = {g0[0], g0[1], g0[2], g0[3], g1[0], g1[1], g1[2], g1[3]};
;             const uint4 z = *(const uint4*)(wsb(p, OFF_BIG + B_YF) + (size_t)row * 768 + col0);
;             const unsigned zz[4] = {z.x, z.y, z.z, z.w};
;             unsigned oo[4];
; #pragma unroll
;             for (int q = 0; q < 4; q++)
;               oo[q] = pack2(lo16(zz[q]) * sigmoidf_(v[2 * q] + gb[2 * q]), hi16(zz[q]) * sigmoidf_(v[2 * q + 1] + gb[2 * q + 1]));
;             *(uint4*)(wsb(p, OFF_BIG + B_YB) + (size_t)row * 768 + col0) = make_uint4(oo[0], oo[1], oo[2], oo[3]);
	v_add_f32_e32 v90, v90, v98
	v_add_f32_e32 v94, v94, v102
	v_add_f32_e32 v95, v95, v103
	v_mul_f32_e32 v94, 0xbfb8aa3b, v94
	v_mul_f32_e32 v95, 0xbfb8aa3b, v95
	v_exp_f32_e32 v94, v94
	v_exp_f32_e32 v95, v95
	v_lshlrev_b32_e32 v112, 16, v118
	v_and_b32_e32 v113, 0xffff0000, v118
	v_add_f32_e32 v91, v91, v99
	v_pk_add_f32 v[94:95], v[94:95], 1.0 op_sel_hi:[1,0]
	v_mul_f32_e32 v90, 0xbfb8aa3b, v90
	v_rcp_f32_e32 v103, v95
	v_mul_f32_e32 v91, 0xbfb8aa3b, v91
	v_exp_f32_e32 v90, v90
	v_exp_f32_e32 v91, v91
	s_nop 0
	v_mul_f32_e32 v95, 1.0, v103
	v_rcp_f32_e32 v103, v94
	v_pk_add_f32 v[90:91], v[90:91], 1.0 op_sel_hi:[1,0]
	v_add_f32_e32 v93, v93, v101
	v_mul_f32_e32 v94, 1.0, v103
	v_pk_mul_f32 v[94:95], v[94:95], v[112:113]
	v_rcp_f32_e32 v99, v91
	v_cvt_pk_bf16_f32 v94, v94, v95
	v_add_f32_e32 v95, v96, v104
	v_mul_f32_e32 v95, 0xbfb8aa3b, v95
	v_exp_f32_e32 v96, v95
	v_add_f32_e32 v95, v97, v105
	v_mul_f32_e32 v95, 0xbfb8aa3b, v95
	v_exp_f32_e32 v97, v95
	v_lshlrev_b32_e32 v102, 16, v119
	v_and_b32_e32 v103, 0xffff0000, v119
	v_mul_f32_e32 v93, 0xbfb8aa3b, v93
	v_pk_add_f32 v[96:97], v[96:97], 1.0 op_sel_hi:[1,0]
	v_exp_f32_e32 v93, v93
	s_nop 0
	v_rcp_f32_e32 v104, v97
	s_nop 0
	v_mul_f32_e32 v97, 1.0, v104
	v_rcp_f32_e32 v104, v96
	s_nop 0
	v_mul_f32_e32 v96, 1.0, v104
	v_pk_mul_f32 v[96:97], v[96:97], v[102:103]
	v_mul_f32_e32 v91, 1.0, v99
	v_rcp_f32_e32 v99, v90
	v_cvt_pk_bf16_f32 v95, v96, v97
	v_lshlrev_b32_e32 v96, 16, v120
	v_and_b32_e32 v97, 0xffff0000, v120
	v_mul_f32_e32 v90, 1.0, v99
	v_pk_mul_f32 v[90:91], v[90:91], v[96:97]
	s_nop 0
	v_cvt_pk_bf16_f32 v96, v90, v91
	v_add_f32_e32 v91, v92, v100
	v_mul_f32_e32 v91, 0xbfb8aa3b, v91
	v_exp_f32_e32 v92, v91
	v_lshlrev_b32_e32 v90, 16, v121
	v_and_b32_e32 v91, 0xffff0000, v121
	v_pk_add_f32 v[92:93], v[92:93], 1.0 op_sel_hi:[1,0]
	s_nop 0
	v_rcp_f32_e32 v98, v93
	s_nop 0
	v_mul_f32_e32 v93, 1.0, v98
	v_rcp_f32_e32 v98, v92
	s_nop 0
	v_mul_f32_e32 v92, 1.0, v98
	v_pk_mul_f32 v[90:91], v[92:93], v[90:91]
	s_nop 0
	v_cvt_pk_bf16_f32 v97, v90, v91
	global_store_dwordx4 v[126:127], v[94:97], off offset:256
	global_load_dwordx4 v[90:93], v[130:131], off offset:528
	s_nop 0
	global_load_dwordx4 v[94:97], v[130:131], off offset:512
	global_load_dwordx4 v[98:101], v[124:125], off offset:256
	s_waitcnt vmcnt(0)
	v_add_f32_e32 v82, v82, v90
	v_add_f32_e32 v86, v86, v94
	v_add_f32_e32 v87, v87, v95
	v_mul_f32_e32 v86, 0xbfb8aa3b, v86
	v_mul_f32_e32 v87, 0xbfb8aa3b, v87
	v_exp_f32_e32 v86, v86
	v_exp_f32_e32 v87, v87
	v_lshlrev_b32_e32 v102, 16, v98
	v_and_b32_e32 v103, 0xffff0000, v98
	v_add_f32_e32 v83, v83, v91
	v_pk_add_f32 v[86:87], v[86:87], 1.0 op_sel_hi:[1,0]
	v_mul_f32_e32 v82, 0xbfb8aa3b, v82
	v_rcp_f32_e32 v95, v87
	v_mul_f32_e32 v83, 0xbfb8aa3b, v83
	v_exp_f32_e32 v82, v82
	v_exp_f32_e32 v83, v83
	s_nop 0
	v_mul_f32_e32 v87, 1.0, v95
	v_rcp_f32_e32 v95, v86
	v_pk_add_f32 v[82:83], v[82:83], 1.0 op_sel_hi:[1,0]
	v_add_f32_e32 v85, v85, v93
	v_mul_f32_e32 v86, 1.0, v95
	v_pk_mul_f32 v[86:87], v[86:87], v[102:103]
	v_lshlrev_b32_e32 v94, 16, v99
	v_cvt_pk_bf16_f32 v86, v86, v87
	v_add_f32_e32 v87, v88, v96
	v_mul_f32_e32 v87, 0xbfb8aa3b, v87
	v_exp_f32_e32 v88, v87
	v_add_f32_e32 v87, v89, v97
	v_mul_f32_e32 v87, 0xbfb8aa3b, v87
	v_exp_f32_e32 v89, v87
	v_and_b32_e32 v95, 0xffff0000, v99
	v_rcp_f32_e32 v91, v83
	v_mul_f32_e32 v85, 0xbfb8aa3b, v85
	v_pk_add_f32 v[88:89], v[88:89], 1.0 op_sel_hi:[1,0]
	v_exp_f32_e32 v85, v85
	s_nop 0
	v_rcp_f32_e32 v96, v89
	s_nop 0
	v_mul_f32_e32 v89, 1.0, v96
	v_rcp_f32_e32 v96, v88
	s_nop 0
	v_mul_f32_e32 v88, 1.0, v96
	v_pk_mul_f32 v[88:89], v[88:89], v[94:95]
	v_mul_f32_e32 v83, 1.0, v91
	v_rcp_f32_e32 v91, v82
	v_cvt_pk_bf16_f32 v87, v88, v89
	v_lshlrev_b32_e32 v88, 16, v100
	v_and_b32_e32 v89, 0xffff0000, v100
	v_mul_f32_e32 v82, 1.0, v91
	v_pk_mul_f32 v[82:83], v[82:83], v[88:89]
	s_nop 0
	v_cvt_pk_bf16_f32 v88, v82, v83
	v_add_f32_e32 v83, v84, v92
	v_mul_f32_e32 v83, 0xbfb8aa3b, v83
	v_exp_f32_e32 v84, v83
	v_lshlrev_b32_e32 v82, 16, v101
	v_and_b32_e32 v83, 0xffff0000, v101
	v_pk_add_f32 v[84:85], v[84:85], 1.0 op_sel_hi:[1,0]
	s_nop 0
	v_rcp_f32_e32 v90, v85
	s_nop 0
	v_mul_f32_e32 v85, 1.0, v90
	v_rcp_f32_e32 v90, v84
	s_nop 0
	v_mul_f32_e32 v84, 1.0, v90
	v_pk_mul_f32 v[82:83], v[84:85], v[82:83]
	s_nop 0
	v_cvt_pk_bf16_f32 v89, v82, v83
	global_store_dwordx4 v[116:117], v[86:89], off offset:256
	global_load_dwordx4 v[82:85], v[130:131], off offset:528
	s_nop 0
	global_load_dwordx4 v[86:89], v[130:131], off offset:512
	global_load_dwordx4 v[90:93], v[114:115], off offset:256
	s_waitcnt vmcnt(0)
; DI unsigned pack2(float a, float b) { f32x2_t v = {a, b}; bf16x2_t r = __builtin_convertvector(v, bf16x2_t); return __builtin_bit_cast(unsigned, r); }
; DI float lo16(unsigned u) { return __uint_as_float(u << 16); }
; DI float hi16(unsigned u) { return __uint_as_float(u & 0xffff0000u); }
; DI bfu* wsb(const PX& p, size_t off) { return (bfu*)(p.ws + off); }
; DI float sigmoidf_(float x) { return 1.f / (1.f + __expf(-x)); }
; template <int EPI, int HM>
; DI void epi256(const PX& p, int l, f32x4 (&acc)[2][2][4][2], int brow, int bcol, int aux, bool src_input) {
;     ...
;             const float* gbp = p.in[30] + l * 768 + col0;
;             const f32x4 g0 = *(const f32x4*)gbp, g1 = *(const f32x4*)(gbp + 4);
;             const float gb[8] = {g0[0], g0[1], g0[2], g0[3], g1[0], g1[1], g1[2], g1[3]};
;             const uint4 z = *(const uint4*)(wsb(p, OFF_BIG + B_YF) + (size_t)row * 768 + col0);
;             const unsigned zz[4] = {z.x, z.y, z.z, z.w};
;             unsigned oo[4];
; #pragma unroll
;             for (int q = 0; q < 4; q++)
;               oo[q] = pack2(lo16(zz[q]) * sigmoidf_(v[2 * q] + gb[2 * q]), hi16(zz[q]) * sigmoidf_(v[2 * q + 1] + gb[2 * q + 1]));
;             *(uint4*)(wsb(p, OFF_BIG + B_YB) + (size_t)row * 768 + col0) = make_uint4(oo[0], oo[1], oo[2], oo[3]);
	v_add_f32_e32 v74, v74, v82
	v_add_f32_e32 v78, v78, v86
	v_add_f32_e32 v79, v79, v87
	v_mul_f32_e32 v78, 0xbfb8aa3b, v78
	v_mul_f32_e32 v79, 0xbfb8aa3b, v79
	v_exp_f32_e32 v78, v78
	v_exp_f32_e32 v79, v79
	v_lshlrev_b32_e32 v94, 16, v90
	v_and_b32_e32 v95, 0xffff0000, v90
	v_add_f32_e32 v75, v75, v83
	v_pk_add_f32 v[78:79], v[78:79], 1.0 op_sel_hi:[1,0]
	v_mul_f32_e32 v74, 0xbfb8aa3b, v74
	v_rcp_f32_e32 v87, v79
	v_mul_f32_e32 v75, 0xbfb8aa3b, v75
	v_exp_f32_e32 v74, v74
	v_exp_f32_e32 v75, v75
	s_nop 0
	v_mul_f32_e32 v79, 1.0, v87
	v_rcp_f32_e32 v87, v78
	v_pk_add_f32 v[74:75], v[74:75], 1.0 op_sel_hi:[1,0]
	v_add_f32_e32 v77, v77, v85
	v_mul_f32_e32 v78, 1.0, v87
	v_pk_mul_f32 v[78:79], v[78:79], v[94:95]
	v_lshlrev_b32_e32 v86, 16, v91
	v_cvt_pk_bf16_f32 v78, v78, v79
	v_add_f32_e32 v79, v80, v88
	v_mul_f32_e32 v79, 0xbfb8aa3b, v79
	v_exp_f32_e32 v80, v79
	v_add_f32_e32 v79, v81, v89
	v_mul_f32_e32 v79, 0xbfb8aa3b, v79
	v_exp_f32_e32 v81, v79
	v_and_b32_e32 v87, 0xffff0000, v91
	v_rcp_f32_e32 v83, v75
	v_mul_f32_e32 v77, 0xbfb8aa3b, v77
	v_pk_add_f32 v[80:81], v[80:81], 1.0 op_sel_hi:[1,0]
	v_exp_f32_e32 v77, v77
	s_nop 0
	v_rcp_f32_e32 v88, v81
	s_nop 0
	v_mul_f32_e32 v81, 1.0, v88
	v_rcp_f32_e32 v88, v80
	s_nop 0
	v_mul_f32_e32 v80, 1.0, v88
	v_pk_mul_f32 v[80:81], v[80:81], v[86:87]
	v_mul_f32_e32 v75, 1.0, v83
	v_rcp_f32_e32 v83, v74
	v_cvt_pk_bf16_f32 v79, v80, v81
	v_lshlrev_b32_e32 v80, 16, v92
	v_and_b32_e32 v81, 0xffff0000, v92
	v_mul_f32_e32 v74, 1.0, v83
	v_pk_mul_f32 v[74:75], v[74:75], v[80:81]
	s_nop 0
	v_cvt_pk_bf16_f32 v80, v74, v75
	v_add_f32_e32 v75, v76, v84
	v_mul_f32_e32 v75, 0xbfb8aa3b, v75
	v_exp_f32_e32 v76, v75
	v_lshlrev_b32_e32 v74, 16, v93
	v_and_b32_e32 v75, 0xffff0000, v93
	v_pk_add_f32 v[76:77], v[76:77], 1.0 op_sel_hi:[1,0]
	s_nop 0
	v_rcp_f32_e32 v82, v77
	s_nop 0
	v_mul_f32_e32 v77, 1.0, v82
	v_rcp_f32_e32 v82, v76
	s_nop 0
	v_mul_f32_e32 v76, 1.0, v82
	v_pk_mul_f32 v[74:75], v[76:77], v[74:75]
	s_nop 0
	v_cvt_pk_bf16_f32 v81, v74, v75
	global_store_dwordx4 v[110:111], v[78:81], off offset:256
	global_load_dwordx4 v[74:77], v[130:131], off offset:528
	s_nop 0
	global_load_dwordx4 v[78:81], v[130:131], off offset:512
	global_load_dwordx4 v[82:85], v[108:109], off offset:256
	s_waitcnt vmcnt(0)
	v_add_f32_e32 v66, v66, v74
	v_add_f32_e32 v70, v70, v78
	v_add_f32_e32 v71, v71, v79
	v_mul_f32_e32 v70, 0xbfb8aa3b, v70
	v_mul_f32_e32 v71, 0xbfb8aa3b, v71
	v_exp_f32_e32 v70, v70
	v_exp_f32_e32 v71, v71
	v_lshlrev_b32_e32 v86, 16, v82
	v_and_b32_e32 v87, 0xffff0000, v82
	v_add_f32_e32 v67, v67, v75
	v_pk_add_f32 v[70:71], v[70:71], 1.0 op_sel_hi:[1,0]
	v_mul_f32_e32 v66, 0xbfb8aa3b, v66
	v_rcp_f32_e32 v79, v71
	v_mul_f32_e32 v67, 0xbfb8aa3b, v67
	v_exp_f32_e32 v66, v66
	v_exp_f32_e32 v67, v67
	s_nop 0
	v_mul_f32_e32 v71, 1.0, v79
	v_rcp_f32_e32 v79, v70
	v_pk_add_f32 v[66:67], v[66:67], 1.0 op_sel_hi:[1,0]
	v_add_f32_e32 v69, v69, v77
	v_mul_f32_e32 v70, 1.0, v79
	v_pk_mul_f32 v[70:71], v[70:71], v[86:87]
	v_lshlrev_b32_e32 v78, 16, v83
	v_cvt_pk_bf16_f32 v70, v70, v71
	v_add_f32_e32 v71, v72, v80
	v_mul_f32_e32 v71, 0xbfb8aa3b, v71
	v_exp_f32_e32 v72, v71
	v_add_f32_e32 v71, v73, v81
	v_mul_f32_e32 v71, 0xbfb8aa3b, v71
	v_exp_f32_e32 v73, v71
	v_and_b32_e32 v79, 0xffff0000, v83
	v_rcp_f32_e32 v75, v67
	v_mul_f32_e32 v69, 0xbfb8aa3b, v69
	v_pk_add_f32 v[72:73], v[72:73], 1.0 op_sel_hi:[1,0]
	v_exp_f32_e32 v69, v69
	s_nop 0
	v_rcp_f32_e32 v80, v73
	s_nop 0
	v_mul_f32_e32 v73, 1.0, v80
	v_rcp_f32_e32 v80, v72
	s_nop 0
	v_mul_f32_e32 v72, 1.0, v80
	v_pk_mul_f32 v[72:73], v[72:73], v[78:79]
	v_mul_f32_e32 v67, 1.0, v75
	v_rcp_f32_e32 v75, v66
	v_cvt_pk_bf16_f32 v71, v72, v73
	v_lshlrev_b32_e32 v72, 16, v84
	v_and_b32_e32 v73, 0xffff0000, v84
	v_mul_f32_e32 v66, 1.0, v75
	v_pk_mul_f32 v[66:67], v[66:67], v[72:73]
	v_add_u32_e32 v82, 0x80, v0
	v_cvt_pk_bf16_f32 v72, v66, v67
	v_add_f32_e32 v67, v68, v76
	v_mul_f32_e32 v67, 0xbfb8aa3b, v67
	v_exp_f32_e32 v68, v67
	v_lshlrev_b32_e32 v66, 16, v85
	v_and_b32_e32 v67, 0xffff0000, v85
	v_pk_add_f32 v[68:69], v[68:69], 1.0 op_sel_hi:[1,0]
	s_nop 0
	v_rcp_f32_e32 v74, v69
	s_nop 0
	v_mul_f32_e32 v69, 1.0, v74
	v_rcp_f32_e32 v74, v68
	s_nop 0
	v_mul_f32_e32 v68, 1.0, v74
	v_pk_mul_f32 v[66:67], v[68:69], v[66:67]
	s_nop 0
	v_cvt_pk_bf16_f32 v73, v66, v67
	global_store_dwordx4 v[106:107], v[70:73], off offset:256
	global_load_dwordx4 v[68:71], v[130:131], off offset:16
	s_nop 0
	global_load_dwordx4 v[72:75], v[130:131], off
	v_mad_i64_i32 v[66:67], s[0:1], v82, s81, v[134:135]
	v_lshl_add_u64 v[66:67], v[66:67], 0, v[132:133]
	global_load_dwordx4 v[76:79], v[66:67], off
	s_waitcnt vmcnt(0)
; DI unsigned pack2(float a, float b) { f32x2_t v = {a, b}; bf16x2_t r = __builtin_convertvector(v, bf16x2_t); return __builtin_bit_cast(unsigned, r); }
; DI float lo16(unsigned u) { return __uint_as_float(u << 16); }
; DI float hi16(unsigned u) { return __uint_as_float(u & 0xffff0000u); }
; DI bfu* wsb(const PX& p, size_t off) { return (bfu*)(p.ws + off); }
; DI float sigmoidf_(float x) { return 1.f / (1.f + __expf(-x)); }
; template <int EPI, int HM>
; DI void epi256(const PX& p, int l, f32x4 (&acc)[2][2][4][2], int brow, int bcol, int aux, bool src_input) {
;     ...
;             const float* gbp = p.in[30] + l * 768 + col0;
;             const f32x4 g0 = *(const f32x4*)gbp, g1 = *(const f32x4*)(gbp + 4);
;             const float gb[8] = {g0[0], g0[1], g0[2], g0[3], g1[0], g1[1], g1[2], g1[3]};
;             const uint4 z = *(const uint4*)(wsb(p, OFF_BIG + B_YF) + (size_t)row * 768 + col0);
;             const unsigned zz[4] = {z.x, z.y, z.z, z.w};
;             unsigned oo[4];
; #pragma unroll
;             for (int q = 0; q < 4; q++)
;               oo[q] = pack2(lo16(zz[q]) * sigmoidf_(v[2 * q] + gb[2 * q]), hi16(zz[q]) * sigmoidf_(v[2 * q + 1] + gb[2 * q + 1]));
;             *(uint4*)(wsb(p, OFF_BIG + B_YB) + (size_t)row * 768 + col0) = make_uint4(oo[0], oo[1], oo[2], oo[3]);
	v_add_f32_e32 v58, v58, v68
	v_add_f32_e32 v62, v62, v72
	v_add_f32_e32 v63, v63, v73
	v_mul_f32_e32 v62, 0xbfb8aa3b, v62
	v_mul_f32_e32 v63, 0xbfb8aa3b, v63
	v_exp_f32_e32 v62, v62
	v_exp_f32_e32 v63, v63
	v_lshlrev_b32_e32 v80, 16, v76
	v_and_b32_e32 v81, 0xffff0000, v76
	v_add_f32_e32 v59, v59, v69
	v_pk_add_f32 v[62:63], v[62:63], 1.0 op_sel_hi:[1,0]
	v_mul_f32_e32 v58, 0xbfb8aa3b, v58
	v_rcp_f32_e32 v73, v63
	v_mul_f32_e32 v59, 0xbfb8aa3b, v59
	v_exp_f32_e32 v58, v58
	v_exp_f32_e32 v59, v59
	s_nop 0
	v_mul_f32_e32 v63, 1.0, v73
	v_rcp_f32_e32 v73, v62
	v_pk_add_f32 v[58:59], v[58:59], 1.0 op_sel_hi:[1,0]
	v_add_f32_e32 v61, v61, v71
	v_mul_f32_e32 v62, 1.0, v73
	v_pk_mul_f32 v[62:63], v[62:63], v[80:81]
	v_lshlrev_b32_e32 v72, 16, v77
	v_cvt_pk_bf16_f32 v62, v62, v63
	v_add_f32_e32 v63, v64, v74
	v_mul_f32_e32 v63, 0xbfb8aa3b, v63
	v_exp_f32_e32 v64, v63
	v_add_f32_e32 v63, v65, v75
	v_mul_f32_e32 v63, 0xbfb8aa3b, v63
	v_exp_f32_e32 v65, v63
	v_and_b32_e32 v73, 0xffff0000, v77
	v_rcp_f32_e32 v69, v59
	v_mul_f32_e32 v61, 0xbfb8aa3b, v61
	v_pk_add_f32 v[64:65], v[64:65], 1.0 op_sel_hi:[1,0]
	v_exp_f32_e32 v61, v61
	s_nop 0
	v_rcp_f32_e32 v74, v65
	s_nop 0
	v_mul_f32_e32 v65, 1.0, v74
	v_rcp_f32_e32 v74, v64
	s_nop 0
	v_mul_f32_e32 v64, 1.0, v74
	v_pk_mul_f32 v[64:65], v[64:65], v[72:73]
	v_mul_f32_e32 v59, 1.0, v69
	v_rcp_f32_e32 v69, v58
	v_cvt_pk_bf16_f32 v63, v64, v65
	v_lshlrev_b32_e32 v64, 16, v78
	v_and_b32_e32 v65, 0xffff0000, v78
	v_mul_f32_e32 v58, 1.0, v69
	v_pk_mul_f32 v[58:59], v[58:59], v[64:65]
	v_add_u32_e32 v78, 0x90, v0
	v_cvt_pk_bf16_f32 v64, v58, v59
	v_add_f32_e32 v59, v60, v70
	v_mul_f32_e32 v59, 0xbfb8aa3b, v59
	v_exp_f32_e32 v60, v59
	v_lshlrev_b32_e32 v58, 16, v79
	v_and_b32_e32 v59, 0xffff0000, v79
	v_pk_add_f32 v[60:61], v[60:61], 1.0 op_sel_hi:[1,0]
	s_nop 0
	v_rcp_f32_e32 v68, v61
	s_nop 0
	v_mul_f32_e32 v61, 1.0, v68
	v_rcp_f32_e32 v68, v60
	s_nop 0
	v_mul_f32_e32 v60, 1.0, v68
	v_pk_mul_f32 v[58:59], v[60:61], v[58:59]
	s_nop 0
	v_cvt_pk_bf16_f32 v65, v58, v59
	v_mad_i64_i32 v[58:59], s[0:1], v82, s81, v[122:123]
	v_lshl_add_u64 v[60:61], v[58:59], 0, v[132:133]
	global_store_dwordx4 v[60:61], v[62:65], off
	global_load_dwordx4 v[62:65], v[130:131], off offset:16
	s_nop 0
	global_load_dwordx4 v[68:71], v[130:131], off
	v_mad_i64_i32 v[58:59], s[0:1], v78, s81, v[134:135]
	v_lshl_add_u64 v[58:59], v[58:59], 0, v[132:133]
	global_load_dwordx4 v[72:75], v[58:59], off
	s_waitcnt vmcnt(0)
	v_add_f32_e32 v50, v50, v62
	v_add_f32_e32 v54, v54, v68
	v_add_f32_e32 v55, v55, v69
	v_mul_f32_e32 v54, 0xbfb8aa3b, v54
	v_mul_f32_e32 v55, 0xbfb8aa3b, v55
	v_exp_f32_e32 v54, v54
	v_exp_f32_e32 v55, v55
	v_lshlrev_b32_e32 v76, 16, v72
	v_and_b32_e32 v77, 0xffff0000, v72
	v_add_f32_e32 v57, v57, v71
	v_pk_add_f32 v[54:55], v[54:55], 1.0 op_sel_hi:[1,0]
	v_mul_f32_e32 v57, 0xbfb8aa3b, v57
	v_rcp_f32_e32 v69, v55
	v_exp_f32_e32 v57, v57
	v_add_f32_e32 v51, v51, v63
	v_mul_f32_e32 v50, 0xbfb8aa3b, v50
	v_mul_f32_e32 v55, 1.0, v69
	v_rcp_f32_e32 v69, v54
	v_mul_f32_e32 v51, 0xbfb8aa3b, v51
	v_exp_f32_e32 v50, v50
	v_exp_f32_e32 v51, v51
	s_nop 0
	v_mul_f32_e32 v54, 1.0, v69
	v_pk_mul_f32 v[54:55], v[54:55], v[76:77]
	v_pk_add_f32 v[50:51], v[50:51], 1.0 op_sel_hi:[1,0]
	v_cvt_pk_bf16_f32 v68, v54, v55
	v_add_f32_e32 v55, v56, v70
	v_mul_f32_e32 v55, 0xbfb8aa3b, v55
	v_exp_f32_e32 v56, v55
	v_lshlrev_b32_e32 v54, 16, v73
	v_and_b32_e32 v55, 0xffff0000, v73
	v_add_f32_e32 v53, v53, v65
	v_pk_add_f32 v[56:57], v[56:57], 1.0 op_sel_hi:[1,0]
	v_mul_f32_e32 v53, 0xbfb8aa3b, v53
	v_rcp_f32_e32 v70, v57
	v_exp_f32_e32 v53, v53
	s_nop 0
	v_mul_f32_e32 v57, 1.0, v70
	v_rcp_f32_e32 v70, v56
	s_nop 0
	v_mul_f32_e32 v56, 1.0, v70
	v_pk_mul_f32 v[54:55], v[56:57], v[54:55]
	v_rcp_f32_e32 v57, v51
	v_cvt_pk_bf16_f32 v69, v54, v55
	v_lshlrev_b32_e32 v54, 16, v74
	v_and_b32_e32 v55, 0xffff0000, v74
	v_mul_f32_e32 v51, 1.0, v57
	v_rcp_f32_e32 v57, v50
	s_nop 0
	v_mul_f32_e32 v50, 1.0, v57
	v_pk_mul_f32 v[50:51], v[50:51], v[54:55]
	s_nop 0
	v_cvt_pk_bf16_f32 v70, v50, v51
	v_add_f32_e32 v51, v52, v64
	v_mul_f32_e32 v51, 0xbfb8aa3b, v51
	v_exp_f32_e32 v52, v51
	v_lshlrev_b32_e32 v50, 16, v75
	v_and_b32_e32 v51, 0xffff0000, v75
	v_pk_add_f32 v[52:53], v[52:53], 1.0 op_sel_hi:[1,0]
	s_nop 0
	v_rcp_f32_e32 v55, v53
	s_nop 0
	v_mul_f32_e32 v53, 1.0, v55
	v_rcp_f32_e32 v55, v52
	s_nop 0
	v_mul_f32_e32 v52, 1.0, v55
	v_pk_mul_f32 v[50:51], v[52:53], v[50:51]
	v_add_u32_e32 v56, 0xa0, v0
	v_cvt_pk_bf16_f32 v71, v50, v51
	v_mad_i64_i32 v[50:51], s[0:1], v78, s81, v[122:123]
	v_lshl_add_u64 v[54:55], v[50:51], 0, v[132:133]
	global_store_dwordx4 v[54:55], v[68:71], off
	global_load_dwordx4 v[62:65], v[130:131], off offset:16
	s_nop 0
	global_load_dwordx4 v[68:71], v[130:131], off
	v_mad_i64_i32 v[50:51], s[0:1], v56, s81, v[134:135]
	v_lshl_add_u64 v[52:53], v[50:51], 0, v[132:133]
	global_load_dwordx4 v[72:75], v[52:53], off
	v_add_u32_e32 v0, 0xb0, v0
	s_waitcnt vmcnt(0)
; DI unsigned pack2(float a, float b) { f32x2_t v = {a, b}; bf16x2_t r = __builtin_convertvector(v, bf16x2_t); return __builtin_bit_cast(unsigned, r); }
; DI float lo16(unsigned u) { return __uint_as_float(u << 16); }
; DI float hi16(unsigned u) { return __uint_as_float(u & 0xffff0000u); }
; DI bfu* wsb(const PX& p, size_t off) { return (bfu*)(p.ws + off); }
; DI float sigmoidf_(float x) { return 1.f / (1.f + __expf(-x)); }
; template <int EPI, int HM>
; DI void epi256(const PX& p, int l, f32x4 (&acc)[2][2][4][2], int brow, int bcol, int aux, bool src_input) {
;     ...
;             const float* gbp = p.in[30] + l * 768 + col0;
;             const f32x4 g0 = *(const f32x4*)gbp, g1 = *(const f32x4*)(gbp + 4);
;             const float gb[8] = {g0[0], g0[1], g0[2], g0[3], g1[0], g1[1], g1[2], g1[3]};
;             const uint4 z = *(const uint4*)(wsb(p, OFF_BIG + B_YF) + (size_t)row * 768 + col0);
;             const unsigned zz[4] = {z.x, z.y, z.z, z.w};
;             unsigned oo[4];
; #pragma unroll
;             for (int q = 0; q < 4; q++)
;               oo[q] = pack2(lo16(zz[q]) * sigmoidf_(v[2 * q] + gb[2 * q]), hi16(zz[q]) * sigmoidf_(v[2 * q + 1] + gb[2 * q + 1]));
;             *(uint4*)(wsb(p, OFF_BIG + B_YB) + (size_t)row * 768 + col0) = make_uint4(oo[0], oo[1], oo[2], oo[3]);
	v_add_f32_e32 v42, v42, v62
	v_add_f32_e32 v46, v46, v68
	v_add_f32_e32 v47, v47, v69
	v_mul_f32_e32 v46, 0xbfb8aa3b, v46
	v_mul_f32_e32 v47, 0xbfb8aa3b, v47
	v_exp_f32_e32 v46, v46
	v_exp_f32_e32 v47, v47
	v_lshlrev_b32_e32 v50, 16, v72
	v_and_b32_e32 v51, 0xffff0000, v72
	v_add_f32_e32 v43, v43, v63
	v_pk_add_f32 v[46:47], v[46:47], 1.0 op_sel_hi:[1,0]
	v_mul_f32_e32 v42, 0xbfb8aa3b, v42
	v_rcp_f32_e32 v68, v47
	v_mul_f32_e32 v43, 0xbfb8aa3b, v43
	v_exp_f32_e32 v42, v42
	v_exp_f32_e32 v43, v43
	s_nop 0
	v_mul_f32_e32 v47, 1.0, v68
	v_rcp_f32_e32 v68, v46
	v_pk_add_f32 v[42:43], v[42:43], 1.0 op_sel_hi:[1,0]
	v_add_f32_e32 v45, v45, v65
	v_mul_f32_e32 v45, 0xbfb8aa3b, v45
	v_mul_f32_e32 v46, 1.0, v68
	v_pk_mul_f32 v[46:47], v[46:47], v[50:51]
	v_lshlrev_b32_e32 v50, 16, v73
	v_cvt_pk_bf16_f32 v46, v46, v47
	v_add_f32_e32 v47, v48, v70
	v_mul_f32_e32 v47, 0xbfb8aa3b, v47
	v_exp_f32_e32 v48, v47
	v_add_f32_e32 v47, v49, v71
	v_mul_f32_e32 v47, 0xbfb8aa3b, v47
	v_exp_f32_e32 v49, v47
	v_and_b32_e32 v51, 0xffff0000, v73
	v_exp_f32_e32 v45, v45
	v_pk_add_f32 v[48:49], v[48:49], 1.0 op_sel_hi:[1,0]
	s_nop 0
	v_rcp_f32_e32 v57, v49
	s_nop 0
	v_mul_f32_e32 v49, 1.0, v57
	v_rcp_f32_e32 v57, v48
	s_nop 0
	v_mul_f32_e32 v48, 1.0, v57
	v_pk_mul_f32 v[48:49], v[48:49], v[50:51]
	v_rcp_f32_e32 v51, v43
	v_cvt_pk_bf16_f32 v47, v48, v49
	v_lshlrev_b32_e32 v48, 16, v74
	v_and_b32_e32 v49, 0xffff0000, v74
	v_mul_f32_e32 v43, 1.0, v51
	v_rcp_f32_e32 v51, v42
	s_nop 0
	v_mul_f32_e32 v42, 1.0, v51
	v_pk_mul_f32 v[42:43], v[42:43], v[48:49]
	s_nop 0
	v_cvt_pk_bf16_f32 v48, v42, v43
	v_add_f32_e32 v43, v44, v64
	v_mul_f32_e32 v43, 0xbfb8aa3b, v43
	v_exp_f32_e32 v44, v43
	v_lshlrev_b32_e32 v42, 16, v75
	v_and_b32_e32 v43, 0xffff0000, v75
	v_pk_add_f32 v[44:45], v[44:45], 1.0 op_sel_hi:[1,0]
	s_nop 0
	v_rcp_f32_e32 v50, v45
	s_nop 0
	v_mul_f32_e32 v45, 1.0, v50
	v_rcp_f32_e32 v50, v44
	s_nop 0
	v_mul_f32_e32 v44, 1.0, v50
	v_pk_mul_f32 v[42:43], v[44:45], v[42:43]
	s_nop 0
	v_cvt_pk_bf16_f32 v49, v42, v43
	v_mad_i64_i32 v[42:43], s[0:1], v56, s81, v[122:123]
	v_lshl_add_u64 v[50:51], v[42:43], 0, v[132:133]
	global_store_dwordx4 v[50:51], v[46:49], off
	global_load_dwordx4 v[42:45], v[130:131], off offset:16
	global_load_dwordx4 v[62:65], v[130:131], off
	v_mad_i64_i32 v[46:47], s[0:1], v0, s81, v[134:135]
	v_lshl_add_u64 v[48:49], v[46:47], 0, v[132:133]
	global_load_dwordx4 v[68:71], v[48:49], off
	s_waitcnt vmcnt(0)
	v_add_f32_e32 v34, v34, v42
	v_add_f32_e32 v38, v38, v62
	v_add_f32_e32 v39, v39, v63
	v_mul_f32_e32 v38, 0xbfb8aa3b, v38
	v_mul_f32_e32 v39, 0xbfb8aa3b, v39
	v_exp_f32_e32 v38, v38
	v_exp_f32_e32 v39, v39
	v_lshlrev_b32_e32 v46, 16, v68
	v_and_b32_e32 v47, 0xffff0000, v68
	v_add_f32_e32 v35, v35, v43
	v_pk_add_f32 v[38:39], v[38:39], 1.0 op_sel_hi:[1,0]
	v_mul_f32_e32 v34, 0xbfb8aa3b, v34
	v_rcp_f32_e32 v57, v39
	v_mul_f32_e32 v35, 0xbfb8aa3b, v35
	v_exp_f32_e32 v34, v34
	v_exp_f32_e32 v35, v35
	s_nop 0
	v_mul_f32_e32 v39, 1.0, v57
	v_rcp_f32_e32 v57, v38
	v_pk_add_f32 v[34:35], v[34:35], 1.0 op_sel_hi:[1,0]
	v_add_f32_e32 v37, v37, v45
	v_mul_f32_e32 v38, 1.0, v57
	v_pk_mul_f32 v[38:39], v[38:39], v[46:47]
	v_rcp_f32_e32 v43, v35
	v_cvt_pk_bf16_f32 v38, v38, v39
	v_add_f32_e32 v39, v40, v64
	v_mul_f32_e32 v39, 0xbfb8aa3b, v39
	v_exp_f32_e32 v40, v39
	v_add_f32_e32 v39, v41, v65
	v_mul_f32_e32 v39, 0xbfb8aa3b, v39
	v_exp_f32_e32 v41, v39
	v_lshlrev_b32_e32 v46, 16, v69
	v_and_b32_e32 v47, 0xffff0000, v69
	v_mul_f32_e32 v37, 0xbfb8aa3b, v37
	v_pk_add_f32 v[40:41], v[40:41], 1.0 op_sel_hi:[1,0]
	v_exp_f32_e32 v37, v37
	s_nop 0
	v_rcp_f32_e32 v56, v41
	s_nop 0
	v_mul_f32_e32 v41, 1.0, v56
	v_rcp_f32_e32 v56, v40
	s_nop 0
	v_mul_f32_e32 v40, 1.0, v56
	v_pk_mul_f32 v[40:41], v[40:41], v[46:47]
	v_mul_f32_e32 v35, 1.0, v43
	v_rcp_f32_e32 v43, v34
	v_cvt_pk_bf16_f32 v39, v40, v41
	v_lshlrev_b32_e32 v40, 16, v70
	v_and_b32_e32 v41, 0xffff0000, v70
	v_mul_f32_e32 v34, 1.0, v43
	v_pk_mul_f32 v[34:35], v[34:35], v[40:41]
	s_nop 0
	v_cvt_pk_bf16_f32 v40, v34, v35
	v_add_f32_e32 v35, v36, v44
	v_mul_f32_e32 v35, 0xbfb8aa3b, v35
	v_exp_f32_e32 v36, v35
	v_lshlrev_b32_e32 v34, 16, v71
	v_and_b32_e32 v35, 0xffff0000, v71
	v_pk_add_f32 v[36:37], v[36:37], 1.0 op_sel_hi:[1,0]
	s_nop 0
	v_rcp_f32_e32 v42, v37
	s_nop 0
	v_mul_f32_e32 v37, 1.0, v42
	v_rcp_f32_e32 v42, v36
	s_nop 0
	v_mul_f32_e32 v36, 1.0, v42
	v_pk_mul_f32 v[34:35], v[36:37], v[34:35]
	s_nop 0
	v_cvt_pk_bf16_f32 v41, v34, v35
	v_mad_i64_i32 v[34:35], s[0:1], v0, s81, v[122:123]
	v_lshl_add_u64 v[46:47], v[34:35], 0, v[132:133]
	global_store_dwordx4 v[46:47], v[38:41], off
	global_load_dwordx4 v[34:37], v[130:131], off offset:528
	s_nop 0
	global_load_dwordx4 v[38:41], v[130:131], off offset:512
	global_load_dwordx4 v[42:45], v[66:67], off offset:256
	s_waitcnt vmcnt(0)
; DI unsigned pack2(float a, float b) { f32x2_t v = {a, b}; bf16x2_t r = __builtin_convertvector(v, bf16x2_t); return __builtin_bit_cast(unsigned, r); }
; DI float lo16(unsigned u) { return __uint_as_float(u << 16); }
; DI float hi16(unsigned u) { return __uint_as_float(u & 0xffff0000u); }
; DI bfu* wsb(const PX& p, size_t off) { return (bfu*)(p.ws + off); }
; DI float sigmoidf_(float x) { return 1.f / (1.f + __expf(-x)); }
; template <int EPI, int HM>
; DI void epi256(const PX& p, int l, f32x4 (&acc)[2][2][4][2], int brow, int bcol, int aux, bool src_input) {
;     ...
;             const float* gbp = p.in[30] + l * 768 + col0;
;             const f32x4 g0 = *(const f32x4*)gbp, g1 = *(const f32x4*)(gbp + 4);
;             const float gb[8] = {g0[0], g0[1], g0[2], g0[3], g1[0], g1[1], g1[2], g1[3]};
;             const uint4 z = *(const uint4*)(wsb(p, OFF_BIG + B_YF) + (size_t)row * 768 + col0);
;             const unsigned zz[4] = {z.x, z.y, z.z, z.w};
;             unsigned oo[4];
; #pragma unroll
;             for (int q = 0; q < 4; q++)
;               oo[q] = pack2(lo16(zz[q]) * sigmoidf_(v[2 * q] + gb[2 * q]), hi16(zz[q]) * sigmoidf_(v[2 * q + 1] + gb[2 * q + 1]));
;             *(uint4*)(wsb(p, OFF_BIG + B_YB) + (size_t)row * 768 + col0) = make_uint4(oo[0], oo[1], oo[2], oo[3]);
	v_add_f32_e32 v0, v30, v38
	v_mul_f32_e32 v0, 0xbfb8aa3b, v0
	v_exp_f32_e32 v30, v0
	v_add_f32_e32 v0, v31, v39
	v_mul_f32_e32 v0, 0xbfb8aa3b, v0
	v_exp_f32_e32 v31, v0
	v_lshlrev_b32_e32 v56, 16, v42
	v_and_b32_e32 v57, 0xffff0000, v42
	v_pk_add_f32 v[30:31], v[30:31], 1.0 op_sel_hi:[1,0]
	s_nop 0
	v_rcp_f32_e32 v38, v31
	s_nop 0
	v_mul_f32_e32 v31, 1.0, v38
	v_rcp_f32_e32 v38, v30
	s_nop 0
	v_mul_f32_e32 v30, 1.0, v38
	v_add_f32_e32 v0, v32, v40
	v_mul_f32_e32 v0, 0xbfb8aa3b, v0
	v_exp_f32_e32 v32, v0
	v_add_f32_e32 v0, v33, v41
	v_mul_f32_e32 v0, 0xbfb8aa3b, v0
	v_exp_f32_e32 v33, v0
	v_pk_mul_f32 v[30:31], v[30:31], v[56:57]
	v_lshlrev_b32_e32 v38, 16, v43
	v_cvt_pk_bf16_f32 v30, v30, v31
	v_pk_add_f32 v[32:33], v[32:33], 1.0 op_sel_hi:[1,0]
	v_and_b32_e32 v39, 0xffff0000, v43
	v_rcp_f32_e32 v31, v33
	s_nop 0
	v_mul_f32_e32 v33, 1.0, v31
	v_rcp_f32_e32 v31, v32
	s_nop 0
	v_mul_f32_e32 v32, 1.0, v31
	v_add_f32_e32 v0, v26, v34
	v_mul_f32_e32 v0, 0xbfb8aa3b, v0
	v_exp_f32_e32 v26, v0
	v_add_f32_e32 v0, v27, v35
	v_mul_f32_e32 v0, 0xbfb8aa3b, v0
	v_exp_f32_e32 v27, v0
	v_pk_mul_f32 v[32:33], v[32:33], v[38:39]
	v_pk_add_f32 v[26:27], v[26:27], 1.0 op_sel_hi:[1,0]
	s_nop 0
	v_rcp_f32_e32 v34, v27
	v_cvt_pk_bf16_f32 v31, v32, v33
	v_lshlrev_b32_e32 v32, 16, v44
	v_and_b32_e32 v33, 0xffff0000, v44
	v_mul_f32_e32 v27, 1.0, v34
	v_rcp_f32_e32 v34, v26
	s_nop 0
	v_mul_f32_e32 v26, 1.0, v34
	v_add_f32_e32 v0, v28, v36
	v_mul_f32_e32 v0, 0xbfb8aa3b, v0
	v_exp_f32_e32 v28, v0
	v_add_f32_e32 v0, v29, v37
	v_mul_f32_e32 v0, 0xbfb8aa3b, v0
	v_exp_f32_e32 v29, v0
	v_pk_mul_f32 v[26:27], v[26:27], v[32:33]
	v_pk_add_f32 v[28:29], v[28:29], 1.0 op_sel_hi:[1,0]
	s_nop 0
	v_rcp_f32_e32 v33, v29
	v_cvt_pk_bf16_f32 v32, v26, v27
	v_lshlrev_b32_e32 v26, 16, v45
	v_and_b32_e32 v27, 0xffff0000, v45
	v_mul_f32_e32 v29, 1.0, v33
	v_rcp_f32_e32 v33, v28
	s_nop 0
	v_mul_f32_e32 v28, 1.0, v33
	v_pk_mul_f32 v[26:27], v[28:29], v[26:27]
	s_nop 0
	v_cvt_pk_bf16_f32 v33, v26, v27
	global_store_dwordx4 v[60:61], v[30:33], off offset:256
	global_load_dwordx4 v[26:29], v[130:131], off offset:528
	global_load_dwordx4 v[34:37], v[130:131], off offset:512
	s_nop 0
	global_load_dwordx4 v[30:33], v[58:59], off offset:256
	s_waitcnt vmcnt(0)
	v_add_f32_e32 v0, v22, v34
	v_mul_f32_e32 v0, 0xbfb8aa3b, v0
	v_exp_f32_e32 v22, v0
	v_add_f32_e32 v0, v23, v35
	v_mul_f32_e32 v0, 0xbfb8aa3b, v0
	v_exp_f32_e32 v23, v0
	v_lshlrev_b32_e32 v38, 16, v30
	v_and_b32_e32 v39, 0xffff0000, v30
	v_pk_add_f32 v[22:23], v[22:23], 1.0 op_sel_hi:[1,0]
	s_nop 0
	v_rcp_f32_e32 v30, v23
	s_nop 0
	v_mul_f32_e32 v23, 1.0, v30
	v_rcp_f32_e32 v30, v22
	s_nop 0
	v_mul_f32_e32 v22, 1.0, v30
	v_add_f32_e32 v0, v24, v36
	v_mul_f32_e32 v0, 0xbfb8aa3b, v0
	v_exp_f32_e32 v24, v0
	v_add_f32_e32 v0, v25, v37
	v_mul_f32_e32 v0, 0xbfb8aa3b, v0
	v_exp_f32_e32 v25, v0
	v_pk_mul_f32 v[22:23], v[22:23], v[38:39]
	v_lshlrev_b32_e32 v30, 16, v31
	v_cvt_pk_bf16_f32 v22, v22, v23
	v_pk_add_f32 v[24:25], v[24:25], 1.0 op_sel_hi:[1,0]
	v_and_b32_e32 v31, 0xffff0000, v31
	v_rcp_f32_e32 v23, v25
	s_nop 0
	v_mul_f32_e32 v25, 1.0, v23
	v_rcp_f32_e32 v23, v24
	s_nop 0
	v_mul_f32_e32 v24, 1.0, v23
	v_add_f32_e32 v0, v18, v26
	v_mul_f32_e32 v0, 0xbfb8aa3b, v0
	v_exp_f32_e32 v18, v0
	v_add_f32_e32 v0, v19, v27
	v_mul_f32_e32 v0, 0xbfb8aa3b, v0
	v_exp_f32_e32 v19, v0
	v_pk_mul_f32 v[24:25], v[24:25], v[30:31]
	v_pk_add_f32 v[18:19], v[18:19], 1.0 op_sel_hi:[1,0]
	s_nop 0
	v_rcp_f32_e32 v26, v19
	v_cvt_pk_bf16_f32 v23, v24, v25
	v_lshlrev_b32_e32 v24, 16, v32
	v_and_b32_e32 v25, 0xffff0000, v32
	v_mul_f32_e32 v19, 1.0, v26
	v_rcp_f32_e32 v26, v18
	s_nop 0
	v_mul_f32_e32 v18, 1.0, v26
	v_add_f32_e32 v0, v20, v28
	v_mul_f32_e32 v0, 0xbfb8aa3b, v0
	v_exp_f32_e32 v20, v0
	v_add_f32_e32 v0, v21, v29
	v_mul_f32_e32 v0, 0xbfb8aa3b, v0
	v_exp_f32_e32 v21, v0
	v_pk_mul_f32 v[18:19], v[18:19], v[24:25]
	v_pk_add_f32 v[20:21], v[20:21], 1.0 op_sel_hi:[1,0]
	s_nop 0
	v_rcp_f32_e32 v25, v21
	v_cvt_pk_bf16_f32 v24, v18, v19
	v_lshlrev_b32_e32 v18, 16, v33
	v_and_b32_e32 v19, 0xffff0000, v33
	v_mul_f32_e32 v21, 1.0, v25
	v_rcp_f32_e32 v25, v20
	s_nop 0
	v_mul_f32_e32 v20, 1.0, v25
	v_pk_mul_f32 v[18:19], v[20:21], v[18:19]
	s_nop 0
	v_cvt_pk_bf16_f32 v25, v18, v19
	global_store_dwordx4 v[54:55], v[22:25], off offset:256
	global_load_dwordx4 v[18:21], v[130:131], off offset:528
	global_load_dwordx4 v[26:29], v[130:131], off offset:512
	s_nop 0
	global_load_dwordx4 v[22:25], v[52:53], off offset:256
	s_waitcnt vmcnt(0)
; DI unsigned pack2(float a, float b) { f32x2_t v = {a, b}; bf16x2_t r = __builtin_convertvector(v, bf16x2_t); return __builtin_bit_cast(unsigned, r); }
; DI float lo16(unsigned u) { return __uint_as_float(u << 16); }
; DI float hi16(unsigned u) { return __uint_as_float(u & 0xffff0000u); }
; DI bfu* wsb(const PX& p, size_t off) { return (bfu*)(p.ws + off); }
; DI float sigmoidf_(float x) { return 1.f / (1.f + __expf(-x)); }
; template <int EPI, int HM>
; DI void epi256(const PX& p, int l, f32x4 (&acc)[2][2][4][2], int brow, int bcol, int aux, bool src_input) {
;     ...
;             const float* gbp = p.in[30] + l * 768 + col0;
;             const f32x4 g0 = *(const f32x4*)gbp, g1 = *(const f32x4*)(gbp + 4);
;             const float gb[8] = {g0[0], g0[1], g0[2], g0[3], g1[0], g1[1], g1[2], g1[3]};
;             const uint4 z = *(const uint4*)(wsb(p, OFF_BIG + B_YF) + (size_t)row * 768 + col0);
;             const unsigned zz[4] = {z.x, z.y, z.z, z.w};
;             unsigned oo[4];
; #pragma unroll
;             for (int q = 0; q < 4; q++)
;               oo[q] = pack2(lo16(zz[q]) * sigmoidf_(v[2 * q] + gb[2 * q]), hi16(zz[q]) * sigmoidf_(v[2 * q + 1] + gb[2 * q + 1]));
;             *(uint4*)(wsb(p, OFF_BIG + B_YB) + (size_t)row * 768 + col0) = make_uint4(oo[0], oo[1], oo[2], oo[3]);
	v_add_f32_e32 v0, v14, v26
	v_mul_f32_e32 v0, 0xbfb8aa3b, v0
	v_exp_f32_e32 v14, v0
	v_add_f32_e32 v0, v15, v27
	v_mul_f32_e32 v0, 0xbfb8aa3b, v0
	v_exp_f32_e32 v15, v0
	v_lshlrev_b32_e32 v30, 16, v22
	v_and_b32_e32 v31, 0xffff0000, v22
	v_pk_add_f32 v[14:15], v[14:15], 1.0 op_sel_hi:[1,0]
	s_nop 0
	v_rcp_f32_e32 v22, v15
	s_nop 0
	v_mul_f32_e32 v15, 1.0, v22
	v_rcp_f32_e32 v22, v14
	s_nop 0
	v_mul_f32_e32 v14, 1.0, v22
	v_add_f32_e32 v0, v16, v28
	v_mul_f32_e32 v0, 0xbfb8aa3b, v0
	v_exp_f32_e32 v16, v0
	v_add_f32_e32 v0, v17, v29
	v_mul_f32_e32 v0, 0xbfb8aa3b, v0
	v_exp_f32_e32 v17, v0
	v_pk_mul_f32 v[14:15], v[14:15], v[30:31]
	v_lshlrev_b32_e32 v22, 16, v23
	v_cvt_pk_bf16_f32 v14, v14, v15
	v_pk_add_f32 v[16:17], v[16:17], 1.0 op_sel_hi:[1,0]
	v_and_b32_e32 v23, 0xffff0000, v23
	v_rcp_f32_e32 v15, v17
	s_nop 0
	v_mul_f32_e32 v17, 1.0, v15
	v_rcp_f32_e32 v15, v16
	s_nop 0
	v_mul_f32_e32 v16, 1.0, v15
	v_add_f32_e32 v0, v10, v18
	v_mul_f32_e32 v0, 0xbfb8aa3b, v0
	v_exp_f32_e32 v10, v0
	v_add_f32_e32 v0, v11, v19
	v_mul_f32_e32 v0, 0xbfb8aa3b, v0
	v_exp_f32_e32 v11, v0
	v_pk_mul_f32 v[16:17], v[16:17], v[22:23]
	v_pk_add_f32 v[10:11], v[10:11], 1.0 op_sel_hi:[1,0]
	s_nop 0
	v_rcp_f32_e32 v18, v11
	v_cvt_pk_bf16_f32 v15, v16, v17
	v_lshlrev_b32_e32 v16, 16, v24
	v_and_b32_e32 v17, 0xffff0000, v24
	v_mul_f32_e32 v11, 1.0, v18
	v_rcp_f32_e32 v18, v10
	s_nop 0
	v_mul_f32_e32 v10, 1.0, v18
	v_add_f32_e32 v0, v12, v20
	v_mul_f32_e32 v0, 0xbfb8aa3b, v0
	v_exp_f32_e32 v12, v0
	v_add_f32_e32 v0, v13, v21
	v_mul_f32_e32 v0, 0xbfb8aa3b, v0
	v_exp_f32_e32 v13, v0
	v_pk_mul_f32 v[10:11], v[10:11], v[16:17]
	v_pk_add_f32 v[12:13], v[12:13], 1.0 op_sel_hi:[1,0]
	s_nop 0
	v_rcp_f32_e32 v17, v13
	v_cvt_pk_bf16_f32 v16, v10, v11
	v_lshlrev_b32_e32 v10, 16, v25
	v_and_b32_e32 v11, 0xffff0000, v25
	v_mul_f32_e32 v13, 1.0, v17
	v_rcp_f32_e32 v17, v12
	s_nop 0
	v_mul_f32_e32 v12, 1.0, v17
	v_pk_mul_f32 v[10:11], v[12:13], v[10:11]
	s_nop 0
	v_cvt_pk_bf16_f32 v17, v10, v11
	global_store_dwordx4 v[50:51], v[14:17], off offset:256
	global_load_dwordx4 v[10:13], v[130:131], off offset:528
	global_load_dwordx4 v[18:21], v[130:131], off offset:512
	s_nop 0
	global_load_dwordx4 v[14:17], v[48:49], off offset:256
	s_waitcnt vmcnt(0)
	v_add_f32_e32 v0, v6, v18
	v_mul_f32_e32 v0, 0xbfb8aa3b, v0
	v_exp_f32_e32 v6, v0
	v_add_f32_e32 v0, v7, v19
	v_mul_f32_e32 v0, 0xbfb8aa3b, v0
	v_exp_f32_e32 v7, v0
	v_lshlrev_b32_e32 v22, 16, v14
	v_and_b32_e32 v23, 0xffff0000, v14
	v_pk_add_f32 v[6:7], v[6:7], 1.0 op_sel_hi:[1,0]
	s_nop 0
	v_rcp_f32_e32 v14, v7
	s_nop 0
	v_mul_f32_e32 v7, 1.0, v14
	v_rcp_f32_e32 v14, v6
	s_nop 0
	v_mul_f32_e32 v6, 1.0, v14
	v_add_f32_e32 v0, v8, v20
	v_mul_f32_e32 v0, 0xbfb8aa3b, v0
	v_exp_f32_e32 v8, v0
	v_add_f32_e32 v0, v9, v21
	v_mul_f32_e32 v0, 0xbfb8aa3b, v0
	v_exp_f32_e32 v9, v0
	v_pk_mul_f32 v[6:7], v[6:7], v[22:23]
	v_lshlrev_b32_e32 v14, 16, v15
	v_cvt_pk_bf16_f32 v6, v6, v7
	v_pk_add_f32 v[8:9], v[8:9], 1.0 op_sel_hi:[1,0]
	v_and_b32_e32 v15, 0xffff0000, v15
	v_rcp_f32_e32 v7, v9
	s_nop 0
	v_mul_f32_e32 v9, 1.0, v7
	v_rcp_f32_e32 v7, v8
	s_nop 0
	v_mul_f32_e32 v8, 1.0, v7
	v_add_f32_e32 v0, v2, v10
	v_mul_f32_e32 v0, 0xbfb8aa3b, v0
	v_exp_f32_e32 v2, v0
	v_add_f32_e32 v0, v3, v11
	v_mul_f32_e32 v0, 0xbfb8aa3b, v0
	v_exp_f32_e32 v3, v0
	v_pk_mul_f32 v[8:9], v[8:9], v[14:15]
	v_pk_add_f32 v[2:3], v[2:3], 1.0 op_sel_hi:[1,0]
	s_nop 0
	v_rcp_f32_e32 v10, v3
	v_cvt_pk_bf16_f32 v7, v8, v9
	v_lshlrev_b32_e32 v8, 16, v16
	v_and_b32_e32 v9, 0xffff0000, v16
	v_mul_f32_e32 v3, 1.0, v10
	v_rcp_f32_e32 v10, v2
	s_nop 0
	v_mul_f32_e32 v2, 1.0, v10
	v_add_f32_e32 v0, v4, v12
	v_mul_f32_e32 v0, 0xbfb8aa3b, v0
	v_exp_f32_e32 v4, v0
	v_add_f32_e32 v0, v5, v13
	v_mul_f32_e32 v0, 0xbfb8aa3b, v0
	v_exp_f32_e32 v5, v0
	v_pk_mul_f32 v[2:3], v[2:3], v[8:9]
	v_pk_add_f32 v[4:5], v[4:5], 1.0 op_sel_hi:[1,0]
	s_nop 0
	v_rcp_f32_e32 v9, v5
	v_cvt_pk_bf16_f32 v8, v2, v3
	v_lshlrev_b32_e32 v2, 16, v17
	v_and_b32_e32 v3, 0xffff0000, v17
	v_mul_f32_e32 v5, 1.0, v9
	v_rcp_f32_e32 v9, v4
	s_mov_b32 s0, s61
	s_mov_b32 s1, s60
	v_mul_f32_e32 v4, 1.0, v9
	v_pk_mul_f32 v[2:3], v[4:5], v[2:3]
	s_and_b64 vcc, exec, s[8:9]
	v_cvt_pk_bf16_f32 v9, v2, v3
	global_store_dwordx4 v[46:47], v[6:9], off offset:256
	s_cbranch_vccnz .LBB0_363

; #define OPAQUE(x) asm volatile("" : "+v"(x))
; #define TIDX(p) ((p).wv * 64 + (int)__builtin_amdgcn_mbcnt_hi(~0u, __builtin_amdgcn_mbcnt_lo(~0u, 0u)))
; DI bfu* wsb(const PX& p, size_t off) { return (bfu*)(p.ws + off); }
; DI float* wsf(const PX& p, size_t off) { return (float*)(p.ws + off); }
; DI void mlstm_job(const PX& p, int l, int job, unsigned char* smem) {
;   int tid_ = TIDX(p); OPAQUE(tid_); const int tid = tid_, lane = tid & 63, w = tid >> 6, lr = lane & 31, lh = lane >> 5;
;   const int b = job >> 3, h = (job >> 1) & 3, dir = job & 1;
;   bfu* sq = (bfu*)smem;
;   bfu* sk = sq + 64 * 200;
;   bfu* swk = sk + 64 * 200;
;   bfu* svT = swk + 192 * 72;
;   bfu* sS = svT + 224 * 72;
;   float* sf = (float*)(sS + 64 * 72);
;   float* rA = sf; float* muA = sf + 128; float* wkA = sf + 256; float* winA = sf + 384; float* emtA = sf + 512;
;   float* scA = sf + 640; float* denA = sf + 656; float* cw = sf + 720;
;   const bfu* Zml = wsb(p, OFF_BIG + B_ZML);
;   const float* Zgt = wsf(p, OFF_BIG + B_ZGT);
;   bfu* H = wsb(p, OFF_BIG + (dir ? B_HB : B_HF));
;   __syncthreads();
;   for (int x = tid; x < 384; x += NTHR) {
;     const int ch = (x < 192) ? h * 192 + x : 768 + h * 192 + (x - 192);
; #pragma unroll
;     for (int j = 0; j < 3; j++) cw[j * 384 + x] = p.in[17][(l * 3 + j) * 1536 + ch];
;     cw[1152 + x] = p.in[18][l * 1536 + ch];
;   }
;   for (int x = tid; x < 32 * 72; x += NTHR) svT[192 * 72 + x] = (x < 72) ? (bfu)0x3F80 : (bfu)0;
;   const float gbi = p.in[19][l * 16 + (dir ? 8 : 0) + h];
;   const float gbf = p.in[19][l * 16 + (dir ? 12 : 4) + h];
;   f32x16 st[6];
; #pragma unroll
;   for (int i = 0; i < 6; i++)
; #pragma unroll
;     for (int r = 0; r < 16; r++) st[i][r] = 0.f;
;   float m = 0.f;
;   float pgi = 0.f, pgf = 0.f;
;   if (w == 0) {
;     const int t = dir ? 255 - lane : lane;
;     const int tok = NLAT + b * 256 + t;
;     pgi = Zgt[(size_t)tok * 16 + (dir ? 8 : 0) + h];
;     pgf = Zgt[(size_t)tok * 16 + (dir ? 12 : 4) + h];
;   }
.LBB0_447:
	s_or_b64 exec, exec, s[8:9]
	v_and_b32_e32 v175, 63, v160
	v_mov_b32_e32 v0, 0x1da00
	v_bfe_u32 v5, v160, 5, 1
	s_and_b64 s[8:9], s[4:5], exec
	v_lshl_or_b32 v178, v175, 2, v0
	v_mov_b32_e32 v0, 0x13400
	v_ashrrev_i32_e32 v2, 2, v160
	s_movk_i32 s16, 0xffe0
	v_ashrrev_i32_e32 v3, 6, v160
	s_mov_b32 s8, 0x32c18100
	v_lshl_or_b32 v179, v175, 1, v0
	v_mul_i32_i24_e32 v0, 0xfffffe72, v175
	s_movk_i32 s37, 0x190
	v_and_b32_e32 v9, 0xffffffe0, v2
	v_bfi_b32 v4, s16, v2, v160
	v_lshlrev_b32_e32 v2, 4, v5
	v_and_b32_e32 v176, 31, v160
	s_cselect_b32 s8, 0x2f618100, s8
	v_mad_u32_u24 v181, v175, s37, v0
	v_bfrev_b32_e32 v0, 0.5
	v_mad_u64_u32 v[164:165], s[16:17], v4, s37, v[2:3]
	v_lshlrev_b32_e32 v4, 5, v3
	s_add_u32 s13, s96, s8
	v_lshl_or_b32 v183, v211, 2, v0
	v_lshlrev_b32_e32 v0, 3, v5
	v_and_or_b32 v10, v4, 32, v176
	v_lshl_or_b32 v185, v5, 2, v9
	v_mov_b32_e32 v5, 0x1b200
	s_movk_i32 s36, 0x90
	s_addc_u32 s20, s97, 0
	s_lshl_b32 s12, s3, 8
	v_mad_u32_u24 v9, v10, s36, v5
	v_or_b32_e32 v5, v4, v176
	s_lshl_b32 s11, s3, 11
	s_add_i32 s12, s12, 0x8000
	s_mul_i32 s3, s0, 0x180
	v_readlane_b32 s8, v254, 2
	v_mul_lo_u32 v5, v5, s36
	s_mov_b32 s16, 0x13400
	v_readlane_b32 s9, v254, 3
	s_add_u32 s74, s8, s3
	v_add3_u32 v187, v5, v2, s16
	v_cmp_eq_u32_e64 s[18:19], 6, v3
	v_cmp_gt_u32_e64 s[16:17], 32, v175
	s_addc_u32 s75, s9, 0
	s_and_b64 s[60:61], s[18:19], s[16:17]
	s_add_u32 s18, s13, s3
	s_movk_i32 s8, 0x18e
	v_mov_b32_e32 v11, 0x1d800
	s_addc_u32 s19, s20, 0
	v_ashrrev_i32_e32 v5, 31, v4
	v_mad_u32_u24 v6, v175, s8, v181
	v_cmp_gt_i32_e64 s[8:9], 7, v3
	v_cmp_gt_i32_e64 s[44:45], 4, v3
	v_cmp_gt_i32_e64 s[14:15], 6, v3
	v_mad_u32_u24 v165, v10, s37, v2
	v_lshl_or_b32 v184, v10, 2, v11
	v_or_b32_e32 v11, 0x1b200, v2
	v_lshl_add_u64 v[2:3], v[4:5], 1, s[18:19]
	v_and_b32_e32 v8, 64, v211
	v_lshl_add_u64 v[166:167], v[2:3], 0, v[0:1]
	v_add_u32_e32 v2, -1, v211
	v_cmp_lt_i32_e64 s[18:19], v2, v8
	v_writelane_b32 v255, s14, 27
	v_or_b32_e32 v229, 3, v185
	v_cndmask_b32_e64 v2, v2, v211, s[18:19]
	v_lshlrev_b32_e32 v190, 2, v2
	v_add_u32_e32 v2, -2, v211
	v_cmp_lt_i32_e64 s[18:19], v2, v8
	v_writelane_b32 v255, s15, 28
	v_or_b32_e32 v230, 2, v185
	v_cndmask_b32_e64 v2, v2, v211, s[18:19]
	v_lshlrev_b32_e32 v191, 2, v2
	v_add_u32_e32 v2, -4, v211
	v_cmp_lt_i32_e64 s[20:21], v2, v8
	v_or_b32_e32 v232, 9, v185
	v_or_b32_e32 v233, 8, v185
	v_cndmask_b32_e64 v2, v2, v211, s[20:21]
	v_lshlrev_b32_e32 v192, 2, v2
	v_add_u32_e32 v2, -8, v211
	v_cmp_lt_i32_e64 s[22:23], v2, v8
	v_or_b32_e32 v234, 11, v185
	v_or_b32_e32 v235, 10, v185
	v_cndmask_b32_e64 v2, v2, v211, s[22:23]
	v_lshlrev_b32_e32 v193, 2, v2
	v_add_u32_e32 v2, -16, v211
	v_cmp_lt_i32_e64 s[24:25], v2, v8
	v_or_b32_e32 v237, 17, v185
	v_or_b32_e32 v238, 16, v185
	v_cndmask_b32_e64 v2, v2, v211, s[24:25]
	v_lshlrev_b32_e32 v194, 2, v2
	v_subrev_u32_e32 v2, 32, v211
	v_cmp_lt_i32_e64 s[26:27], v2, v8
	v_or_b32_e32 v239, 19, v185
	v_or_b32_e32 v240, 18, v185
	v_cndmask_b32_e64 v2, v2, v211, s[26:27]
	v_cmp_gt_i32_e64 s[26:27], v185, v10
	v_or_b32_e32 v242, 25, v185
	v_or_b32_e32 v243, 24, v185
	v_writelane_b32 v255, s26, 10
	v_or_b32_e32 v244, 27, v185
	v_or_b32_e32 v245, 26, v185
	v_writelane_b32 v255, s27, 11
	v_cmp_lt_i32_e64 s[26:27], v185, v10
	v_lshlrev_b32_e32 v195, 2, v2
	v_ashrrev_i32_e32 v2, 3, v160
	v_writelane_b32 v255, s26, 22
	v_add_u32_e32 v5, 0x200, v160
	v_and_b32_e32 v168, -8, v2
	v_writelane_b32 v255, s27, 23
	v_cmp_gt_i32_e64 s[26:27], v229, v10
	v_ashrrev_i32_e32 v5, 3, v5
	v_add_u32_e32 v13, 0x400, v160
	v_writelane_b32 v255, s26, 15
	v_or_b32_e32 v2, 7, v2
	v_lshlrev_b32_e32 v3, 2, v168
	v_writelane_b32 v255, s27, 16
	v_cmp_gt_i32_e64 s[26:27], v230, v10
	v_ashrrev_i32_e32 v13, 3, v13
	v_mul_lo_u32 v220, v2, s36
	v_writelane_b32 v255, s26, 18
	v_or_b32_e32 v2, 7, v5
	v_add_u32_e32 v196, 0x1e140, v3
	v_writelane_b32 v255, s27, 19
	v_cmp_gt_i32_e64 s[26:27], v232, v10
	v_lshlrev_b32_e32 v4, 1, v168
	v_and_b32_e32 v170, -8, v5
	v_writelane_b32 v255, s26, 29
	v_and_b32_e32 v172, -8, v13
	v_add_u32_e32 v202, 0x1e440, v3
	v_writelane_b32 v255, s27, 30
	v_cmp_gt_i32_e64 s[26:27], v233, v10
	v_mul_lo_u32 v224, v2, s36
	v_or_b32_e32 v2, 7, v13
	v_writelane_b32 v255, s26, 31
	v_mul_u32_u24_e32 v3, 0x90, v176
	v_mov_b32_e32 v30, v1
	v_writelane_b32 v255, s27, 32
	v_cmp_gt_i32_e64 s[26:27], v234, v10
	v_mov_b32_e32 v31, v1
	v_lshlrev_b32_e32 v7, 2, v176
; DI void mlstm_job(const PX& p, int l, int job, unsigned char* smem) {
;     ...
;   for (int x = tid; x < 32 * 72; x += NTHR) svT[192 * 72 + x] = (x < 72) ? (bfu)0x3F80 : (bfu)0;
;   const float gbi = p.in[19][l * 16 + (dir ? 8 : 0) + h];
;   const float gbf = p.in[19][l * 16 + (dir ? 12 : 4) + h];
;   f32x16 st[6];
; #pragma unroll
;   for (int i = 0; i < 6; i++)
; #pragma unroll
;     for (int r = 0; r < 16; r++) st[i][r] = 0.f;
;   float m = 0.f;
;   float pgi = 0.f, pgf = 0.f;
;   if (w == 0) {
;     const int t = dir ? 255 - lane : lane;
;     const int tok = NLAT + b * 256 + t;
;     pgi = Zgt[(size_t)tok * 16 + (dir ? 8 : 0) + h];
;     pgf = Zgt[(size_t)tok * 16 + (dir ? 12 : 4) + h];
;   }
	v_writelane_b32 v255, s26, 33
	v_add_u32_e32 v197, v6, v4
	v_lshlrev_b32_e32 v8, 2, v170
	v_writelane_b32 v255, s27, 34
	v_cmp_gt_i32_e64 s[26:27], v235, v10
	v_lshlrev_b32_e32 v12, 1, v170
	v_lshlrev_b32_e32 v14, 2, v172
	v_writelane_b32 v255, s26, 35
	v_lshlrev_b32_e32 v15, 1, v172
	v_mad_u32_u24 v203, v175, s37, v4
	v_writelane_b32 v255, s27, 36
	v_cmp_gt_i32_e64 s[26:27], v237, v10
	v_mul_lo_u32 v228, v2, s36
	v_mul_u32_u24_e32 v2, 0x190, v176
	v_writelane_b32 v255, s26, 37
	v_add3_u32 v247, v0, v0, v3
	v_or_b32_e32 v249, 32, v176
	v_writelane_b32 v255, s27, 38
	v_cmp_gt_i32_e64 s[26:27], v238, v10
	v_mov_b32_e32 v4, 0x1e040
	v_mov_b32_e32 v16, v1
	v_writelane_b32 v255, s26, 39
	v_mov_b32_e32 v17, v1
	v_mov_b32_e32 v18, v1
	v_writelane_b32 v255, s27, 40
	v_cmp_gt_i32_e64 s[26:27], v239, v10
	v_mov_b32_e32 v19, v1
	v_mov_b32_e32 v20, v1
	v_writelane_b32 v255, s26, 41
	v_mov_b32_e32 v21, v1
	v_mov_b32_e32 v22, v1
	v_writelane_b32 v255, s27, 42
	v_cmp_gt_i32_e64 s[26:27], v240, v10
	v_mov_b32_e32 v23, v1
	v_mov_b32_e32 v24, v1
	v_writelane_b32 v255, s26, 43
	v_mov_b32_e32 v25, v1
	v_mov_b32_e32 v26, v1
	v_writelane_b32 v255, s27, 44
	v_cmp_gt_i32_e64 s[26:27], v242, v10
	v_mov_b32_e32 v27, v1
	v_mov_b32_e32 v28, v1
	v_writelane_b32 v255, s26, 45
	v_mov_b32_e32 v29, v1
	v_mov_b64_e32 v[46:47], v[30:31]
	v_writelane_b32 v255, s27, 46
	v_cmp_gt_i32_e64 s[26:27], v243, v10
	v_mov_b64_e32 v[62:63], v[30:31]
	v_mov_b64_e32 v[78:79], v[30:31]
	v_writelane_b32 v255, s26, 47
	v_mov_b64_e32 v[94:95], v[30:31]
	v_mov_b64_e32 v[110:111], v[30:31]
	v_writelane_b32 v255, s27, 48
	v_cmp_gt_i32_e64 s[26:27], v244, v10
	s_mov_b32 s10, 0
	v_or_b32_e32 v182, 0x1dc00, v7
	v_writelane_b32 v255, s26, 49
	v_cmp_eq_u32_e64 s[14:15], 0, v175
	v_add_u32_e32 v189, 0x1e040, v7
	v_writelane_b32 v255, s27, 50
	v_cmp_gt_i32_e64 s[26:27], v245, v10
	v_cmp_gt_u32_e64 s[18:19], 2, v175
	v_cmp_gt_u32_e64 s[20:21], 4, v175
	v_writelane_b32 v255, s26, 51
	v_cmp_gt_u32_e64 s[22:23], 8, v175
	v_cmp_gt_u32_e64 s[24:25], 16, v175
	v_writelane_b32 v255, s27, 52
	v_readlane_b32 s26, v253, 31
	v_readlane_b32 s27, v253, 32
	s_lshl_b32 s26, s1, 2
	v_writelane_b32 v253, s26, 31
	v_ashrrev_i32_e32 v169, 31, v168
	v_ashrrev_i32_e32 v171, 31, v170
	v_add_u32_e32 v198, 0x1e140, v8
	v_add_u32_e32 v199, v6, v12
	v_ashrrev_i32_e32 v173, 31, v172
	v_add_u32_e32 v200, 0x1e140, v14
	v_add_u32_e32 v201, v6, v15
	v_mul_lo_u32 v219, v168, s36
	v_add_u32_e32 v221, 0x1e440, v8
	v_mad_u32_u24 v222, v175, s37, v12
	v_mul_lo_u32 v223, v170, s36
	v_add_u32_e32 v225, 0x1e440, v14
	v_mad_u32_u24 v226, v175, s37, v15
	v_mul_lo_u32 v227, v172, s36
	s_mov_b64 s[36:37], s[60:61]
	v_lshl_add_u32 v231, v185, 1, v9
	v_lshl_add_u32 v236, v233, 1, v9
	v_lshl_add_u32 v241, v238, 1, v9
	v_lshl_add_u32 v246, v243, 1, v9
	v_add_u32_e32 v248, 0xc800, v247
	v_lshl_add_u32 v250, v249, 2, v4
	v_or_b32_e32 v251, 0x1de00, v7
	s_xor_b64 s[76:77], vcc, -1
	v_writelane_b32 v253, s27, 32
	s_lshl_b32 s60, s0, 2
	s_lshl_b32 s68, s2, 2
	v_add_u32_e32 v215, v0, v2
	v_add_u32_e32 v216, v11, v3
	v_mov_b64_e32 v[44:45], v[28:29]
	v_mov_b64_e32 v[42:43], v[26:27]
	v_mov_b64_e32 v[40:41], v[24:25]
	v_mov_b64_e32 v[38:39], v[22:23]
	v_mov_b64_e32 v[36:37], v[20:21]
	v_mov_b64_e32 v[34:35], v[18:19]
	v_mov_b64_e32 v[32:33], v[16:17]
	v_mov_b64_e32 v[60:61], v[28:29]
	v_mov_b64_e32 v[58:59], v[26:27]
	v_mov_b64_e32 v[56:57], v[24:25]
	v_mov_b64_e32 v[54:55], v[22:23]
	v_mov_b64_e32 v[52:53], v[20:21]
	v_mov_b64_e32 v[50:51], v[18:19]
	v_mov_b64_e32 v[48:49], v[16:17]
	v_mov_b64_e32 v[76:77], v[28:29]
	v_mov_b64_e32 v[74:75], v[26:27]
	v_mov_b64_e32 v[72:73], v[24:25]
	v_mov_b64_e32 v[70:71], v[22:23]
	v_mov_b64_e32 v[68:69], v[20:21]
	v_mov_b64_e32 v[66:67], v[18:19]
	v_mov_b64_e32 v[64:65], v[16:17]
	v_mov_b64_e32 v[92:93], v[28:29]
	v_mov_b64_e32 v[90:91], v[26:27]
	v_mov_b64_e32 v[88:89], v[24:25]
	v_mov_b64_e32 v[86:87], v[22:23]
	v_mov_b64_e32 v[84:85], v[20:21]
	v_mov_b64_e32 v[82:83], v[18:19]
	v_mov_b64_e32 v[80:81], v[16:17]
	v_mov_b64_e32 v[108:109], v[28:29]
	v_mov_b64_e32 v[106:107], v[26:27]
	v_mov_b64_e32 v[104:105], v[24:25]
	v_mov_b64_e32 v[102:103], v[22:23]
	v_mov_b64_e32 v[100:101], v[20:21]
	v_mov_b64_e32 v[98:99], v[18:19]
	v_mov_b64_e32 v[96:97], v[16:17]
	s_mov_b32 s13, 0
	s_waitcnt vmcnt(0)
	v_lshl_add_u32 v208, v211, 4, s82
	v_add_u32_e32 v208, 0x21100, v208
	s_branch .LBB0_449

; DI void mlstm_job(const PX& p, int l, int job, unsigned char* smem) {
;     ...
; #pragma unroll 1
;   for (int cc = 0; cc < 36; cc++) {
;     const int seg = cc >= 4;
;     const int c = seg ? cc - 4 : cc;
;     const int Lseg = seg ? 2048 : 256;
;     const int RL = seg ? 64 : 256;
;     const int tokbase = seg ? b * 2048 : NLAT + b * 256;
;     {
;       const int par = cc & 1;
;       if (w == 0) {
;         const float gi = pgi + gbi;
;         const float gf = pgf + gbf;
;         const float lf = fminf(gf, 0.f) - log1pf(expf(-fabsf(gf)));
;         float bc = lf;
; #pragma unroll
;         for (int o = 1; o < 64; o <<= 1) { const float v = __shfl_up(bc, o); if (lane >= o) bc += v; }
;         const float rr = gi - bc;
;         float M = rr;
; #pragma unroll
;         for (int o = 1; o < 64; o <<= 1) { const float v = __shfl_up(M, o); if (lane >= o) M = fmaxf(M, v); }
;     ...
;         if (which < 2) {
;           const bfu* zp = Zml + (size_t)tok * 3072 + which * 768 + h * 192 + d8;
;           const int tm = t & (RL - 1);
;           const uint4 mid = *(const uint4*)zp;
;           const uint4 lft = *(const uint4*)(zp - ((tm != 0) ? 3072 : 0));
;           const uint4 rgt = *(const uint4*)(zp + ((tm != RL - 1) ? 3072 : 0));
.LBB0_449:
	s_and_b32 s0, s13, 1
	s_add_i32 s2, s10, 0xffffff00
	s_cmp_gt_u32 s13, 3
	s_movk_i32 s3, 0x800
	s_cselect_b32 s26, s2, s10
	s_cselect_b32 s3, s3, 0x100
	s_cselect_b32 s2, s11, s12
	s_cselect_b32 s1, 63, 0xff
	v_or_b32_e32 v0, s26, v175
	v_xad_u32 v2, v0, -1, s3
	v_cndmask_b32_e64 v0, v2, v0, s[4:5]
	v_add_u32_e32 v4, s2, v0
	v_mov_b64_e32 v[2:3], s[74:75]
	s_movk_i32 s2, 0x1800
	v_mad_i64_i32 v[124:125], s[26:27], v4, s2, v[2:3]
	v_and_b32_e32 v0, s1, v0
	v_cmp_eq_u32_e32 vcc, 0, v0
	v_mov_b32_e32 v2, 0xffffe800
	v_lshl_add_u64 v[14:15], v[168:169], 1, v[124:125]
	v_cndmask_b32_e64 v127, -1, 0, vcc
	v_cndmask_b32_e64 v126, v2, 0, vcc
	v_lshl_add_u64 v[154:155], v[14:15], 0, v[126:127]
	v_cmp_eq_u32_e64 s[2:3], s1, v0
	s_nop 1
	v_cndmask_b32_e64 v0, v214, 0, s[2:3]
	v_lshl_add_u64 v[156:157], v[14:15], 0, v[0:1]
	s_add_i32 m0, s82, 0x21100
	s_nop 0
	global_load_lds_dwordx4 v[14:15], off
	s_add_i32 m0, s82, 0x23100
	s_nop 0
	global_load_lds_dwordx4 v[154:155], off
	s_add_i32 m0, s82, 0x25100
	s_nop 0
	global_load_lds_dwordx4 v[156:157], off
	s_and_saveexec_b64 s[62:63], s[6:7]
	s_cbranch_execz .LBB0_452
	s_nop 0
	v_add_f32_e32 v0, v174, v180
	s_mov_b32 s2, 0xbfb8aa3b
	v_mul_f32_e64 v2, |v0|, s2
	v_fma_f32 v3, |v0|, s2, -v2
	s_mov_b32 s1, 0xb2a5705f
	v_rndne_f32_e32 v4, v2
	v_fma_f32 v3, |v0|, s1, v3
	v_sub_f32_e32 v2, v2, v4
	v_add_f32_e32 v2, v2, v3
	v_exp_f32_e32 v2, v2
	v_cvt_i32_f32_e32 v3, v4
	s_mov_b32 s26, 0x42ce8ed0
	v_cmp_ngt_f32_e64 vcc, |v0|, s26
	s_mov_b32 s27, 0xc2b17218
	v_ldexp_f32 v2, v2, v3
	v_cndmask_b32_e32 v2, 0, v2, vcc
	v_cmp_nlt_f32_e64 vcc, |v0|, s27
	v_min_f32_e32 v4, 0, v0
	s_mov_b32 s1, 0x3f2aaaab
	v_cndmask_b32_e32 v0, v212, v2, vcc
	v_add_f32_e32 v5, 1.0, v0
	v_add_f32_e32 v2, -1.0, v5
	v_sub_f32_e32 v3, v2, v5
	v_add_f32_e32 v3, 1.0, v3
	v_sub_f32_e32 v2, v0, v2
	v_add_f32_e32 v6, v2, v3
	v_frexp_mant_f32_e32 v7, v5
	v_cvt_f64_f32_e32 v[2:3], v5
	v_frexp_exp_i32_f64_e32 v2, v[2:3]
	v_cmp_gt_f32_e32 vcc, s1, v7
	s_mov_b32 s1, 0x3f317218
	s_mov_b32 s3, 0xc2ce8ed0
	v_subbrev_co_u32_e32 v2, vcc, 0, v2, vcc
	v_sub_u32_e32 v3, 0, v2
	v_ldexp_f32 v5, v5, v3
	v_ldexp_f32 v3, v6, v3
	v_add_f32_e32 v6, -1.0, v5
	v_add_f32_e32 v9, 1.0, v5
	v_add_f32_e32 v7, 1.0, v6
	v_add_f32_e32 v10, -1.0, v9
	v_sub_f32_e32 v7, v5, v7
	v_sub_f32_e32 v5, v5, v10
	v_add_f32_e32 v7, v3, v7
	v_add_f32_e32 v3, v3, v5
	v_add_f32_e32 v5, v9, v3
	v_rcp_f32_e32 v10, v5
	v_add_f32_e32 v8, v6, v7
	v_sub_f32_e32 v6, v6, v8
	v_add_f32_e32 v6, v7, v6
	v_sub_f32_e32 v7, v9, v5
	v_add_f32_e32 v3, v3, v7
	v_mul_f32_e32 v7, v8, v10
	v_mul_f32_e32 v9, v5, v7
	v_fma_f32 v11, v7, v5, -v9
	v_fmac_f32_e32 v11, v7, v3
	v_add_f32_e32 v12, v9, v11
	v_sub_f32_e32 v13, v8, v12
	v_sub_f32_e32 v8, v8, v13
	v_sub_f32_e32 v9, v12, v9
	v_sub_f32_e32 v8, v8, v12
	v_add_f32_e32 v6, v6, v8
	v_sub_f32_e32 v8, v9, v11
	v_add_f32_e32 v6, v8, v6
	v_add_f32_e32 v8, v13, v6
	v_mul_f32_e32 v9, v10, v8
	v_mul_f32_e32 v11, v5, v9
	v_fma_f32 v5, v9, v5, -v11
	v_fmac_f32_e32 v5, v9, v3
	v_sub_f32_e32 v3, v13, v8
	v_add_f32_e32 v3, v6, v3
	v_add_f32_e32 v6, v11, v5
	v_sub_f32_e32 v12, v8, v6
	v_sub_f32_e32 v8, v8, v12
	v_sub_f32_e32 v11, v6, v11
	v_sub_f32_e32 v6, v8, v6
	v_add_f32_e32 v3, v3, v6
	v_sub_f32_e32 v5, v11, v5
	v_cvt_f32_i32_e32 v2, v2
	v_add_f32_e32 v3, v5, v3
	v_add_f32_e32 v5, v7, v9
	v_add_f32_e32 v3, v12, v3
	v_sub_f32_e32 v6, v5, v7
	v_mul_f32_e32 v3, v10, v3
	v_sub_f32_e32 v6, v9, v6
	v_add_f32_e32 v3, v6, v3
	v_mul_f32_e32 v9, 0x3f317218, v2
	v_add_f32_e32 v6, v5, v3
	v_fma_f32 v10, v2, s1, -v9
	v_mul_f32_e32 v7, v6, v6
	v_mov_b32_e32 v8, 0x3ecc95a3
	v_fmac_f32_e32 v10, 0xb102e308, v2
	v_sub_f32_e32 v2, v6, v5
	v_fmamk_f32 v8, v7, 0x3e9b6dac, v8
	v_sub_f32_e32 v2, v3, v2
	v_add_f32_e32 v3, v9, v10
	v_fmaak_f32 v8, v7, v8, 0x3f2aaada
	v_sub_f32_e32 v5, v3, v9
	v_ldexp_f32 v9, v6, 1
	v_mul_f32_e32 v6, v6, v7
	v_mul_f32_e32 v6, v6, v8
	v_add_f32_e32 v7, v9, v6
	v_sub_f32_e32 v8, v7, v9
	v_ldexp_f32 v2, v2, 1
	v_sub_f32_e32 v6, v6, v8
	v_add_f32_e32 v2, v2, v6
	v_add_f32_e32 v6, v7, v2
	v_sub_f32_e32 v7, v6, v7
	v_sub_f32_e32 v2, v2, v7
	v_add_f32_e32 v7, v3, v6
	v_sub_f32_e32 v8, v7, v3
	v_sub_f32_e32 v9, v7, v8
	v_sub_f32_e32 v5, v10, v5
	v_sub_f32_e32 v3, v3, v9
	v_sub_f32_e32 v6, v6, v8
	v_add_f32_e32 v3, v6, v3
	v_add_f32_e32 v6, v5, v2
	v_sub_f32_e32 v8, v6, v5
	v_sub_f32_e32 v9, v6, v8
	v_sub_f32_e32 v5, v5, v9
	v_sub_f32_e32 v2, v2, v8
	v_add_f32_e32 v3, v6, v3
	v_add_f32_e32 v2, v2, v5
	v_add_f32_e32 v5, v7, v3
	v_sub_f32_e32 v6, v5, v7
	v_sub_f32_e32 v3, v3, v6
	v_add_f32_e32 v2, v2, v3
	s_mov_b32 s1, 0x7f800000
	v_add_f32_e32 v2, v5, v2
	v_cmp_neq_f32_e32 vcc, s1, v0
	s_mov_b32 s1, 0x33800000
	v_lshlrev_b32_e32 v6, 2, v160
	v_cndmask_b32_e32 v2, v212, v2, vcc
	v_cmp_lt_f32_e64 vcc, |v0|, s1
	s_mov_b32 s1, 0x3fb8aa3b
	v_lshl_or_b32 v6, s0, 8, v6
	v_cndmask_b32_e32 v0, v2, v0, vcc
	v_sub_f32_e32 v0, v4, v0
	ds_bpermute_b32 v2, v190, v0
	v_add_u32_e32 v7, 0x1d600, v6
	s_waitcnt lgkmcnt(0)
	v_add_f32_e32 v2, v0, v2
	v_cndmask_b32_e64 v0, v2, v0, s[14:15]
	ds_bpermute_b32 v2, v191, v0
	s_waitcnt lgkmcnt(0)
	v_add_f32_e32 v2, v0, v2
	v_cndmask_b32_e64 v0, v2, v0, s[18:19]
	ds_bpermute_b32 v2, v192, v0
	s_waitcnt lgkmcnt(0)
	v_add_f32_e32 v2, v0, v2
	v_cndmask_b32_e64 v0, v2, v0, s[20:21]
	ds_bpermute_b32 v2, v193, v0
	s_waitcnt lgkmcnt(0)
	v_add_f32_e32 v2, v0, v2
	v_cndmask_b32_e64 v0, v2, v0, s[22:23]
	ds_bpermute_b32 v2, v194, v0
	s_waitcnt lgkmcnt(0)
	v_add_f32_e32 v2, v0, v2
	v_cndmask_b32_e64 v0, v2, v0, s[24:25]
	ds_bpermute_b32 v2, v195, v0
	s_waitcnt lgkmcnt(0)
; DI void mlstm_job(const PX& p, int l, int job, unsigned char* smem) {
;     ...
;         for (int o = 1; o < 64; o <<= 1) { const float v = __shfl_up(bc, o); if (lane >= o) bc += v; }
;         const float rr = gi - bc;
;         float M = rr;
; #pragma unroll
;         for (int o = 1; o < 64; o <<= 1) { const float v = __shfl_up(M, o); if (lane >= o) M = fmaxf(M, v); }
;         const float mu = fmaxf(m, M);
;         const float b63 = __shfl(bc, 63), mu63 = __shfl(mu, 63);
;         rA[par * 64 + lane] = rr;
;         muA[par * 64 + lane] = mu;
;         wkA[par * 64 + lane] = expf(rr - mu63);
;         winA[par * 64 + lane] = expf(m - mu);
;         emtA[par * 64 + lane] = expf(-(bc + mu));
;         if (lane == 0) { scA[par * 4] = expf(m - mu63); scA[par * 4 + 1] = b63 + mu63; }
;       }
;       __syncthreads();
;       if (w == 0 && cc + 1 < 36) {
;         const int sg = (cc + 1) >= 4;
;         const int pos = (sg ? cc + 1 - 4 : cc + 1) * 64 + lane;
;         const int Ls = sg ? 2048 : 256;
;         const int t = dir ? Ls - 1 - pos : pos;
;         const int tok = (sg ? b * 2048 : NLAT + b * 256) + t;
;         pgi = Zgt[(size_t)tok * 16 + (dir ? 8 : 0) + h];
;         pgf = Zgt[(size_t)tok * 16 + (dir ? 12 : 4) + h];
;       }
	v_add_f32_e32 v2, v0, v2
	v_cndmask_b32_e64 v3, v2, v0, s[16:17]
	v_add_f32_e32 v0, v161, v177
	v_sub_f32_e32 v4, v0, v3
	ds_bpermute_b32 v0, v190, v4
	ds_write_b32 v7, v4
	s_waitcnt lgkmcnt(1)
	v_max_f32_e32 v0, v0, v0
	v_max_f32_e32 v0, v4, v0
	v_cndmask_b32_e64 v0, v0, v4, s[14:15]
	ds_bpermute_b32 v2, v191, v0
	s_waitcnt lgkmcnt(0)
	v_max_f32_e32 v2, v2, v2
	v_max_f32_e32 v2, v0, v2
	v_cndmask_b32_e64 v0, v2, v0, s[18:19]
	ds_bpermute_b32 v2, v192, v0
	s_waitcnt lgkmcnt(0)
	v_max_f32_e32 v2, v2, v2
	v_max_f32_e32 v2, v0, v2
	v_cndmask_b32_e64 v0, v2, v0, s[20:21]
	ds_bpermute_b32 v2, v193, v0
	s_waitcnt lgkmcnt(0)
	v_max_f32_e32 v2, v2, v2
	v_max_f32_e32 v2, v0, v2
	v_cndmask_b32_e64 v0, v2, v0, s[22:23]
	ds_bpermute_b32 v2, v194, v0
	s_waitcnt lgkmcnt(0)
	v_max_f32_e32 v2, v2, v2
	v_max_f32_e32 v2, v0, v2
	v_cndmask_b32_e64 v0, v2, v0, s[24:25]
	ds_bpermute_b32 v2, v195, v0
	v_max_f32_e32 v5, v0, v0
	s_waitcnt lgkmcnt(0)
	v_max_f32_e32 v2, v2, v2
	v_max_f32_e32 v2, v5, v2
	v_cndmask_b32_e64 v0, v2, v0, s[16:17]
	v_max_f32_e32 v0, v0, v0
	v_max_f32_e32 v2, v163, v163
	v_max_f32_e32 v5, v2, v0
	ds_bpermute_b32 v0, v183, v5
	v_sub_f32_e32 v7, v163, v5
	ds_bpermute_b32 v2, v183, v3
	v_add_f32_e32 v3, v3, v5
	s_waitcnt lgkmcnt(1)
	v_sub_f32_e32 v8, v4, v0
	v_mul_f32_e32 v9, 0x3fb8aa3b, v8
	v_fma_f32 v10, v8, s1, -v9
	v_rndne_f32_e32 v11, v9
	v_fmac_f32_e32 v10, 0x32a5705f, v8
	v_sub_f32_e32 v9, v9, v11
	v_add_f32_e32 v9, v9, v10
	v_exp_f32_e32 v9, v9
	v_cvt_i32_f32_e32 v10, v11
	v_add_u32_e32 v4, 0x1d800, v6
	ds_write_b32 v4, v5
	v_cmp_ngt_f32_e32 vcc, s3, v8
	v_ldexp_f32 v4, v9, v10
	v_mul_f32_e32 v9, 0x3fb8aa3b, v7
	v_fma_f32 v10, v7, s1, -v9
	v_rndne_f32_e32 v11, v9
	v_fmac_f32_e32 v10, 0x32a5705f, v7
	v_sub_f32_e32 v9, v9, v11
	v_add_f32_e32 v9, v9, v10
	v_exp_f32_e32 v9, v9
	v_cvt_i32_f32_e32 v10, v11
	s_mov_b32 s1, 0x42b17218
	v_cndmask_b32_e32 v4, 0, v4, vcc
	v_cmp_nlt_f32_e32 vcc, s1, v8
	v_add_u32_e32 v8, 0x1da00, v6
	v_mul_f32_e32 v5, 0xbfb8aa3b, v3
	v_cndmask_b32_e32 v4, v212, v4, vcc
	ds_write_b32 v8, v4
	v_ldexp_f32 v4, v9, v10
	v_fma_f32 v8, v3, s2, -v5
	v_rndne_f32_e32 v9, v5
	v_fmac_f32_e32 v8, 0xb2a5705f, v3
	v_sub_f32_e32 v5, v5, v9
	v_add_f32_e32 v5, v5, v8
	v_exp_f32_e32 v5, v5
	v_cvt_i32_f32_e32 v8, v9
	v_cmp_ngt_f32_e32 vcc, s3, v7
	s_nop 1
	v_cndmask_b32_e32 v4, 0, v4, vcc
	v_cmp_nlt_f32_e32 vcc, s1, v7
	v_add_u32_e32 v7, 0x1dc00, v6
	s_nop 0
	v_cndmask_b32_e32 v4, v212, v4, vcc
	ds_write_b32 v7, v4
	v_ldexp_f32 v4, v5, v8
	v_cmp_nlt_f32_e32 vcc, s26, v3
	s_nop 1
	v_cndmask_b32_e32 v4, 0, v4, vcc
	v_cmp_ngt_f32_e32 vcc, s27, v3
	s_nop 1
	v_cndmask_b32_e32 v3, v212, v4, vcc
	v_add_u32_e32 v4, 0x1de00, v6
	ds_write_b32 v4, v3
	s_and_b64 exec, exec, s[14:15]
	s_cbranch_execz .LBB0_452
	v_sub_f32_e32 v4, v163, v0
	v_mul_f32_e32 v3, 0x3fb8aa3b, v4
	s_mov_b32 s1, 0x3fb8aa3b
	v_fma_f32 v5, v4, s1, -v3
	v_rndne_f32_e32 v6, v3
	v_fmac_f32_e32 v5, 0x32a5705f, v4
	v_sub_f32_e32 v3, v3, v6
	v_add_f32_e32 v3, v3, v5
	v_exp_f32_e32 v5, v3
	v_cvt_i32_f32_e32 v6, v6
	s_mov_b32 s2, 0xc2ce8ed0
	s_lshl_b32 s1, s0, 4
	s_waitcnt lgkmcnt(4)
	v_add_f32_e32 v3, v2, v0
	v_ldexp_f32 v0, v5, v6
	v_cmp_ngt_f32_e32 vcc, s2, v4
	s_mov_b32 s2, 0x42b17218
	s_or_b32 s1, s1, 0x1e000
	v_cndmask_b32_e32 v0, 0, v0, vcc
	v_cmp_nlt_f32_e32 vcc, s2, v4
	s_nop 1
	v_cndmask_b32_e32 v2, v212, v0, vcc
	v_mov_b32_e32 v0, s1
	ds_write_b64 v0, v[2:3]
.LBB0_452:
	s_or_b64 exec, exec, s[62:63]
	s_cmp_lg_u32 s13, 35
	s_cselect_b64 s[2:3], -1, 0
	s_and_b64 s[2:3], s[76:77], s[2:3]
	s_waitcnt lgkmcnt(0)
	s_barrier
	s_waitcnt vmcnt(0)
	s_and_saveexec_b64 s[62:63], s[2:3]
	s_cbranch_execz .LBB0_454
	s_cmp_gt_u32 s13, 2
	s_cselect_b32 s1, -3, 1
	s_movk_i32 s2, 0x7ff
	s_cselect_b32 s2, s2, 0xff
	s_cselect_b32 s3, s11, s12
	s_add_i32 s1, s1, s13
	v_lshl_or_b32 v0, s1, 6, v160
	v_sub_u32_e32 v2, s2, v0
	v_cndmask_b32_e64 v0, v2, v0, s[4:5]
	v_add_u32_e32 v2, s3, v0
	v_ashrrev_i32_e32 v3, 31, v2
	v_readlane_b32 s2, v254, 14
	v_lshlrev_b64 v[2:3], 6, v[2:3]
	v_readlane_b32 s3, v254, 15
	s_nop 1
	v_lshl_add_u64 v[2:3], s[2:3], 0, v[2:3]
	v_readlane_b32 s2, v253, 31
	v_readlane_b32 s3, v253, 32
	s_mov_b32 s61, s3
	s_mov_b32 s69, s3
	v_lshl_add_u64 v[4:5], v[2:3], 0, s[2:3]
	v_lshl_add_u64 v[4:5], v[4:5], 0, s[60:61]
	v_lshl_add_u64 v[2:3], v[2:3], 0, s[68:69]
	v_lshl_add_u64 v[2:3], v[2:3], 0, s[60:61]
	global_load_dword v177, v[4:5], off
	global_load_dword v180, v[2:3], off
; DI float lo16(unsigned u) { return __uint_as_float(u << 16); }
; DI void mlstm_job(const PX& p, int l, int job, unsigned char* smem) {
;     ...
;       const float dec = scA[par * 4];
;       const float mnew = scA[par * 4 + 1];
; #pragma unroll
;       for (int i = 0; i < 9; i++) {
;         const int u = tid + NTHR * i;
;         const int which = i / 3;
;         const int rem = u - which * 1536;
;         const int tau = rem & 63;
;         const int d8 = (rem >> 6) * 8;
;         const int pos = c * 64 + tau;
;         const int t = dir ? Lseg - 1 - pos : pos;
;         const int tok = tokbase + t;
;         if (which < 2) {
;           const bfu* zp = Zml + (size_t)tok * 3072 + which * 768 + h * 192 + d8;
;           const int tm = t & (RL - 1);
;           const uint4 mid = *(const uint4*)zp;
;           const uint4 lft = *(const uint4*)(zp - ((tm != 0) ? 3072 : 0));
;           const uint4 rgt = *(const uint4*)(zp + ((tm != RL - 1) ? 3072 : 0));
;           const float lvf = (tm != 0) ? 1.f : 0.f, rvf = (tm != RL - 1) ? 1.f : 0.f;
;           const unsigned ml_[4] = {lft.x, lft.y, lft.z, lft.w};
;           const unsigned mm_[4] = {mid.x, mid.y, mid.z, mid.w};
;           const unsigned mr_[4] = {rgt.x, rgt.y, rgt.z, rgt.w};
;           const float* cwx = cw + which * 192 + d8;
;           float v[8];
; #pragma unroll
;           for (int e = 0; e < 8; e++) {
;             const float a = (e & 1) ? hi16(ml_[e >> 1]) : lo16(ml_[e >> 1]);
;             const float bm = (e & 1) ? hi16(mm_[e >> 1]) : lo16(mm_[e >> 1]);
;             const float cr = (e & 1) ? hi16(mr_[e >> 1]) : lo16(mr_[e >> 1]);
;             float s = cwx[e] * (a * lvf) + cwx[384 + e] * bm + cwx[768 + e] * (cr * rvf) + cwx[1152 + e];
;             s = s / (1.f + __expf(-s));
;             v[e] = s;
;           }
;           if (which == 0) {
;             uint4 o;
;             o.x = pack2(v[0], v[1]); o.y = pack2(v[2], v[3]); o.z = pack2(v[4], v[5]); o.w = pack2(v[6], v[7]);
;             *(uint4*)(sq + tau * 200 + d8) = o;
;           } else {
;             const float wk = wkA[par * 64 + tau];
; #pragma unroll
;             for (int e = 0; e < 8; e++) v[e] *= 0.07216878364870323f;
;             uint4 o;
;             o.x = pack2(v[0], v[1]); o.y = pack2(v[2], v[3]); o.z = pack2(v[4], v[5]); o.w = pack2(v[6], v[7]);
;             *(uint4*)(sk + tau * 200 + d8) = o;
; #pragma unroll
.LBB0_454:
	s_or_b64 exec, exec, s[62:63]
	s_lshl_b32 s1, s0, 4
	s_or_b32 s1, s1, 0x1e000
	s_add_i32 s2, s10, 0xffffff00
	s_cmp_gt_u32 s13, 3
	s_movk_i32 s3, 0x800
	v_mov_b32_e32 v0, s1
	s_cselect_b32 s26, s2, s10
	s_cselect_b32 s69, s3, 0x100
	ds_read_b64 v[162:163], v0
	v_or_b32_e32 v0, s26, v175
	v_xad_u32 v2, v0, -1, s69
	s_cselect_b32 s61, s11, s12
	v_cndmask_b32_e64 v0, v2, v0, s[4:5]
	v_add_u32_e32 v4, s61, v0
	v_mov_b64_e32 v[2:3], s[74:75]
	s_movk_i32 s1, 0x1800
	v_mad_i64_i32 v[124:125], s[2:3], v4, s1, v[2:3]
	s_cselect_b32 s1, 63, 0xff
	v_and_b32_e32 v0, s1, v0
	v_cmp_eq_u32_e32 vcc, 0, v0
	v_mov_b32_e32 v2, 0xffffe800
	v_lshl_add_u64 v[14:15], v[168:169], 1, v[124:125]
	v_cndmask_b32_e64 v127, -1, 0, vcc
	v_cndmask_b32_e64 v126, v2, 0, vcc
	v_lshl_add_u64 v[120:121], v[14:15], 0, v[126:127]
	ds_read_b128 v[2:5], v208
	ds_read_b128 v[6:9], v208 offset:8192
	v_cmp_eq_u32_e64 s[62:63], s1, v0
	v_cndmask_b32_e64 v118, 1.0, 0, vcc
	s_lshl_b32 s27, s0, 8
	v_cndmask_b32_e64 v0, v214, 0, s[62:63]
	v_lshl_add_u64 v[122:123], v[14:15], 0, v[0:1]
	ds_read_b128 v[10:13], v208 offset:16384
	s_waitcnt lgkmcnt(0)
	s_add_i32 m0, s82, 0x21080
	s_nop 0
	global_load_lds_dwordx4 v[14:15], off offset:128
	s_add_i32 m0, s82, 0x23080
	s_nop 0
	global_load_lds_dwordx4 v[154:155], off offset:128
	s_add_i32 m0, s82, 0x25080
	s_nop 0
	global_load_lds_dwordx4 v[156:157], off offset:128
	ds_read_b128 v[128:131], v196
	ds_read_b128 v[112:115], v196 offset:16
	v_cndmask_b32_e64 v116, 1.0, 0, s[62:63]
	v_add_u32_e32 v117, s27, v178
	s_mov_b32 s2, 0x3d93cd3a
	s_nop 0
	v_lshlrev_b32_e32 v136, 16, v2
	s_nop 0
	v_lshlrev_b32_e32 v132, 16, v6
	v_and_b32_e32 v133, 0xffff0000, v6
	v_pk_mul_f32 v[138:139], v[118:119], v[132:133] op_sel_hi:[0,1]
	ds_read_b128 v[132:135], v196 offset:1536
	v_and_b32_e32 v137, 0xffff0000, v2
	s_nop 0
	v_lshlrev_b32_e32 v140, 16, v10
	v_and_b32_e32 v141, 0xffff0000, v10
	s_waitcnt lgkmcnt(0)
	v_pk_mul_f32 v[132:133], v[132:133], v[136:137]
	s_nop 0
	v_pk_fma_f32 v[128:129], v[138:139], v[128:129], v[132:133]
	ds_read_b128 v[136:139], v196 offset:3072
	v_pk_mul_f32 v[132:133], v[116:117], v[140:141] op_sel_hi:[0,1]
	ds_read_b128 v[140:143], v196 offset:4608
	s_waitcnt lgkmcnt(1)
	v_pk_fma_f32 v[128:129], v[132:133], v[136:137], v[128:129]
	s_waitcnt lgkmcnt(0)
	v_pk_add_f32 v[128:129], v[140:141], v[128:129]
	s_nop 0
	v_mul_f32_e32 v2, 0xbfb8aa3b, v128
	v_exp_f32_e32 v132, v2
	v_mul_f32_e32 v2, 0xbfb8aa3b, v129
	v_exp_f32_e32 v133, v2
	s_nop 0
	v_pk_add_f32 v[132:133], v[132:133], 1.0 op_sel_hi:[1,0]
	s_nop 0
	v_rcp_f32_e32 v6, v133
	s_nop 0
	v_mul_f32_e32 v119, v129, v6
	v_rcp_f32_e32 v6, v132
	s_nop 0
	v_mul_f32_e32 v128, v128, v6
	v_lshlrev_b32_e32 v6, 16, v7
	v_lshlrev_b32_e32 v2, 16, v3
	v_and_b32_e32 v7, 0xffff0000, v7
	v_and_b32_e32 v3, 0xffff0000, v3
	v_lshlrev_b32_e32 v10, 16, v11
	v_and_b32_e32 v11, 0xffff0000, v11
	v_pk_mul_f32 v[6:7], v[118:119], v[6:7] op_sel_hi:[0,1]
	v_pk_mul_f32 v[2:3], v[134:135], v[2:3]
	ds_read_b128 v[132:135], v196 offset:1552
	v_pk_fma_f32 v[2:3], v[6:7], v[130:131], v[2:3]
	v_pk_mul_f32 v[6:7], v[116:117], v[10:11] op_sel_hi:[0,1]
	v_pk_fma_f32 v[2:3], v[6:7], v[138:139], v[2:3]
	ds_read_b128 v[136:139], v196 offset:3088
	v_pk_add_f32 v[2:3], v[142:143], v[2:3]
	ds_read_b128 v[140:143], v196 offset:4624
	v_mul_f32_e32 v6, 0xbfb8aa3b, v2
	v_mul_f32_e32 v7, 0xbfb8aa3b, v3
	v_exp_f32_e32 v6, v6
	v_exp_f32_e32 v7, v7
	s_nop 0
	v_pk_add_f32 v[6:7], v[6:7], 1.0 op_sel_hi:[1,0]
	s_nop 0
	v_rcp_f32_e32 v11, v7
	s_nop 0
	v_mul_f32_e32 v129, v3, v11
	v_rcp_f32_e32 v7, v6
	s_nop 0
	v_mul_f32_e32 v130, v2, v7
	v_lshlrev_b32_e32 v10, 16, v8
	v_lshlrev_b32_e32 v6, 16, v4
	v_and_b32_e32 v11, 0xffff0000, v8
	v_and_b32_e32 v7, 0xffff0000, v4
	v_lshlrev_b32_e32 v2, 16, v12
	v_and_b32_e32 v3, 0xffff0000, v12
	v_pk_mul_f32 v[10:11], v[118:119], v[10:11] op_sel_hi:[0,1]
	s_waitcnt lgkmcnt(2)
	v_pk_mul_f32 v[6:7], v[132:133], v[6:7]
	v_pk_mul_f32 v[2:3], v[116:117], v[2:3] op_sel_hi:[0,1]
	v_pk_fma_f32 v[6:7], v[10:11], v[112:113], v[6:7]
	s_waitcnt lgkmcnt(1)
	v_pk_fma_f32 v[2:3], v[2:3], v[136:137], v[6:7]
	s_waitcnt lgkmcnt(0)
	v_pk_add_f32 v[2:3], v[140:141], v[2:3]
	s_nop 0
	v_mul_f32_e32 v4, 0xbfb8aa3b, v2
	v_exp_f32_e32 v6, v4
	v_mul_f32_e32 v4, 0xbfb8aa3b, v3
	v_exp_f32_e32 v7, v4
	s_nop 0
	v_pk_add_f32 v[6:7], v[6:7], 1.0 op_sel_hi:[1,0]
	s_nop 0
	v_rcp_f32_e32 v8, v7
	s_nop 0
	v_mul_f32_e32 v8, v3, v8
	v_rcp_f32_e32 v4, v6
	s_nop 0
	v_mul_f32_e32 v10, v2, v4
	v_lshlrev_b32_e32 v2, 16, v9
	v_lshlrev_b32_e32 v4, 16, v5
	v_and_b32_e32 v3, 0xffff0000, v9
	v_and_b32_e32 v5, 0xffff0000, v5
	v_lshlrev_b32_e32 v6, 16, v13
	v_and_b32_e32 v7, 0xffff0000, v13
	v_pk_mul_f32 v[2:3], v[118:119], v[2:3] op_sel_hi:[0,1]
	v_pk_mul_f32 v[4:5], v[134:135], v[4:5]
	s_nop 0
	v_pk_fma_f32 v[2:3], v[2:3], v[114:115], v[4:5]
	v_pk_mul_f32 v[4:5], v[116:117], v[6:7] op_sel_hi:[0,1]
	v_pk_fma_f32 v[2:3], v[4:5], v[138:139], v[2:3]
	s_nop 0
	v_pk_add_f32 v[2:3], v[142:143], v[2:3]
	s_nop 0
	v_mul_f32_e32 v4, 0xbfb8aa3b, v2
	v_mul_f32_e32 v5, 0xbfb8aa3b, v3
	v_exp_f32_e32 v4, v4
	v_exp_f32_e32 v5, v5
	s_nop 0
	v_pk_add_f32 v[4:5], v[4:5], 1.0 op_sel_hi:[1,0]
	s_nop 0
	v_rcp_f32_e32 v7, v5
	s_nop 0
	v_mul_f32_e32 v5, v3, v7
	v_rcp_f32_e32 v6, v4
	s_nop 0
	v_mul_f32_e32 v6, v2, v6
	v_cvt_pk_bf16_f32 v2, v128, v119
	v_cvt_pk_bf16_f32 v3, v130, v129
	v_cvt_pk_bf16_f32 v4, v10, v8
	v_cvt_pk_bf16_f32 v5, v6, v5
	ds_write_b128 v197, v[2:5]
	v_lshl_add_u64 v[4:5], v[170:171], 1, v[124:125]
	v_lshl_add_u64 v[10:11], v[4:5], 0, v[126:127]
	s_waitcnt vmcnt(0)
; DI float lo16(unsigned u) { return __uint_as_float(u << 16); }
; DI void mlstm_job(const PX& p, int l, int job, unsigned char* smem) {
;     ...
;       for (int i = 0; i < 9; i++) {
;         const int u = tid + NTHR * i;
;         const int which = i / 3;
;         const int rem = u - which * 1536;
;         const int tau = rem & 63;
;         const int d8 = (rem >> 6) * 8;
;         const int pos = c * 64 + tau;
;         const int t = dir ? Lseg - 1 - pos : pos;
;         const int tok = tokbase + t;
;         if (which < 2) {
;           const bfu* zp = Zml + (size_t)tok * 3072 + which * 768 + h * 192 + d8;
;           const int tm = t & (RL - 1);
;           const uint4 mid = *(const uint4*)zp;
;           const uint4 lft = *(const uint4*)(zp - ((tm != 0) ? 3072 : 0));
;           const uint4 rgt = *(const uint4*)(zp + ((tm != RL - 1) ? 3072 : 0));
;           const float lvf = (tm != 0) ? 1.f : 0.f, rvf = (tm != RL - 1) ? 1.f : 0.f;
;           const unsigned ml_[4] = {lft.x, lft.y, lft.z, lft.w};
;           const unsigned mm_[4] = {mid.x, mid.y, mid.z, mid.w};
;           const unsigned mr_[4] = {rgt.x, rgt.y, rgt.z, rgt.w};
;           const float* cwx = cw + which * 192 + d8;
;           float v[8];
; #pragma unroll
;           for (int e = 0; e < 8; e++) {
;             const float a = (e & 1) ? hi16(ml_[e >> 1]) : lo16(ml_[e >> 1]);
;             const float bm = (e & 1) ? hi16(mm_[e >> 1]) : lo16(mm_[e >> 1]);
;             const float cr = (e & 1) ? hi16(mr_[e >> 1]) : lo16(mr_[e >> 1]);
;             float s = cwx[e] * (a * lvf) + cwx[384 + e] * bm + cwx[768 + e] * (cr * rvf) + cwx[1152 + e];
;             s = s / (1.f + __expf(-s));
;             v[e] = s;
;           }
;           if (which == 0) {
;             uint4 o;
;             o.x = pack2(v[0], v[1]); o.y = pack2(v[2], v[3]); o.z = pack2(v[4], v[5]); o.w = pack2(v[6], v[7]);
;             *(uint4*)(sq + tau * 200 + d8) = o;
;           } else {
;             const float wk = wkA[par * 64 + tau];
; #pragma unroll
;             for (int e = 0; e < 8; e++) v[e] *= 0.07216878364870323f;
;             uint4 o;
;             o.x = pack2(v[0], v[1]); o.y = pack2(v[2], v[3]); o.z = pack2(v[4], v[5]); o.w = pack2(v[6], v[7]);
;             *(uint4*)(sk + tau * 200 + d8) = o;
; #pragma unroll
;             for (int e = 0; e < 8; e++) swk[(d8 + e) * 72 + tau] = f2bf(wk * v[e]);
;           }
	ds_read_b128 v[6:9], v208
	ds_read_b128 v[112:115], v208 offset:8192
	v_lshl_add_u64 v[12:13], v[4:5], 0, v[0:1]
	ds_read_b128 v[128:131], v208 offset:16384
	s_waitcnt lgkmcnt(0)
	s_add_i32 m0, s82, 0x21000
	s_nop 0
	global_load_lds_dwordx4 v[14:15], off offset:256
	s_add_i32 m0, s82, 0x23000
	s_nop 0
	global_load_lds_dwordx4 v[154:155], off offset:256
	s_add_i32 m0, s82, 0x25000
	s_nop 0
	global_load_lds_dwordx4 v[156:157], off offset:256
	ds_read_b128 v[132:135], v198
	ds_read_b128 v[136:139], v198 offset:16
	ds_read_b128 v[140:143], v198 offset:1536
	s_nop 0
	v_lshlrev_b32_e32 v144, 16, v6
	s_nop 0
	v_lshlrev_b32_e32 v2, 16, v112
	v_and_b32_e32 v3, 0xffff0000, v112
	v_and_b32_e32 v145, 0xffff0000, v6
	s_nop 0
	v_lshlrev_b32_e32 v148, 16, v128
	v_and_b32_e32 v149, 0xffff0000, v128
	v_pk_mul_f32 v[2:3], v[118:119], v[2:3] op_sel_hi:[0,1]
	s_waitcnt lgkmcnt(0)
	v_pk_mul_f32 v[140:141], v[140:141], v[144:145]
	ds_read_b128 v[144:147], v198 offset:3072
	v_pk_fma_f32 v[2:3], v[2:3], v[132:133], v[140:141]
	v_pk_mul_f32 v[132:133], v[116:117], v[148:149] op_sel_hi:[0,1]
	ds_read_b128 v[148:151], v198 offset:4608
	s_waitcnt lgkmcnt(1)
	v_pk_fma_f32 v[2:3], v[132:133], v[144:145], v[2:3]
	s_waitcnt lgkmcnt(0)
	v_pk_add_f32 v[2:3], v[148:149], v[2:3]
	s_nop 0
	v_mul_f32_e32 v6, 0xbfb8aa3b, v2
	v_exp_f32_e32 v132, v6
	v_mul_f32_e32 v6, 0xbfb8aa3b, v3
	v_exp_f32_e32 v133, v6
	s_nop 0
	v_pk_add_f32 v[132:133], v[132:133], 1.0 op_sel_hi:[1,0]
	s_nop 0
	v_rcp_f32_e32 v112, v133
	s_nop 0
	v_mul_f32_e32 v119, v3, v112
	v_rcp_f32_e32 v6, v132
	s_nop 0
	v_mul_f32_e32 v128, v2, v6
	v_lshlrev_b32_e32 v2, 16, v113
	v_lshlrev_b32_e32 v6, 16, v7
	v_and_b32_e32 v3, 0xffff0000, v113
	v_and_b32_e32 v7, 0xffff0000, v7
	v_lshlrev_b32_e32 v112, 16, v129
	v_and_b32_e32 v113, 0xffff0000, v129
	v_pk_mul_f32 v[2:3], v[118:119], v[2:3] op_sel_hi:[0,1]
	v_pk_mul_f32 v[6:7], v[142:143], v[6:7]
	ds_read_b128 v[140:143], v198 offset:3088
	v_pk_fma_f32 v[2:3], v[2:3], v[134:135], v[6:7]
	v_pk_mul_f32 v[6:7], v[116:117], v[112:113] op_sel_hi:[0,1]
	v_pk_fma_f32 v[2:3], v[6:7], v[146:147], v[2:3]
	ds_read_b128 v[144:147], v198 offset:4624
	v_pk_add_f32 v[2:3], v[150:151], v[2:3]
	s_nop 0
	v_mul_f32_e32 v6, 0xbfb8aa3b, v2
	v_mul_f32_e32 v7, 0xbfb8aa3b, v3
	v_exp_f32_e32 v6, v6
	v_exp_f32_e32 v7, v7
	s_nop 0
	v_pk_add_f32 v[6:7], v[6:7], 1.0 op_sel_hi:[1,0]
	s_nop 0
	v_rcp_f32_e32 v113, v7
	s_nop 0
	v_mul_f32_e32 v129, v3, v113
	v_rcp_f32_e32 v7, v6
	s_nop 0
	ds_read_b128 v[132:135], v198 offset:1552
	v_mul_f32_e32 v148, v2, v7
	v_lshlrev_b32_e32 v2, 16, v114
	v_lshlrev_b32_e32 v6, 16, v8
	v_and_b32_e32 v3, 0xffff0000, v114
	v_and_b32_e32 v7, 0xffff0000, v8
	v_lshlrev_b32_e32 v112, 16, v130
	v_and_b32_e32 v113, 0xffff0000, v130
	v_pk_mul_f32 v[2:3], v[118:119], v[2:3] op_sel_hi:[0,1]
	s_waitcnt lgkmcnt(0)
	v_pk_mul_f32 v[6:7], v[132:133], v[6:7]
	s_nop 0
	v_pk_fma_f32 v[2:3], v[2:3], v[136:137], v[6:7]
	v_pk_mul_f32 v[6:7], v[116:117], v[112:113] op_sel_hi:[0,1]
	v_pk_fma_f32 v[2:3], v[6:7], v[140:141], v[2:3]
	s_nop 0
	v_pk_add_f32 v[2:3], v[144:145], v[2:3]
	s_nop 0
	v_mul_f32_e32 v6, 0xbfb8aa3b, v2
	v_mul_f32_e32 v7, 0xbfb8aa3b, v3
	v_exp_f32_e32 v6, v6
	v_exp_f32_e32 v7, v7
	s_nop 0
	v_pk_add_f32 v[6:7], v[6:7], 1.0 op_sel_hi:[1,0]
	s_nop 0
	v_rcp_f32_e32 v112, v7
	s_nop 0
	v_mul_f32_e32 v112, v3, v112
	v_rcp_f32_e32 v7, v6
	s_nop 0
	v_mul_f32_e32 v113, v2, v7
	v_lshlrev_b32_e32 v2, 16, v115
	v_lshlrev_b32_e32 v6, 16, v9
	v_and_b32_e32 v3, 0xffff0000, v115
	v_and_b32_e32 v7, 0xffff0000, v9
	v_lshlrev_b32_e32 v8, 16, v131
	v_and_b32_e32 v9, 0xffff0000, v131
	v_pk_mul_f32 v[2:3], v[118:119], v[2:3] op_sel_hi:[0,1]
	v_pk_mul_f32 v[6:7], v[134:135], v[6:7]
	s_nop 0
	v_pk_fma_f32 v[2:3], v[2:3], v[138:139], v[6:7]
	v_pk_mul_f32 v[6:7], v[116:117], v[8:9] op_sel_hi:[0,1]
	v_pk_fma_f32 v[2:3], v[6:7], v[142:143], v[2:3]
	s_nop 0
	v_pk_add_f32 v[2:3], v[146:147], v[2:3]
	s_nop 0
	v_mul_f32_e32 v6, 0xbfb8aa3b, v2
	v_mul_f32_e32 v7, 0xbfb8aa3b, v3
	v_exp_f32_e32 v6, v6
	v_exp_f32_e32 v7, v7
	s_nop 0
	v_pk_add_f32 v[6:7], v[6:7], 1.0 op_sel_hi:[1,0]
	s_nop 0
	v_rcp_f32_e32 v9, v7
	s_nop 0
	v_mul_f32_e32 v3, v3, v9
	v_rcp_f32_e32 v8, v6
	s_nop 0
	v_mul_f32_e32 v2, v2, v8
	v_cvt_pk_bf16_f32 v6, v128, v119
	v_cvt_pk_bf16_f32 v7, v148, v129
	v_cvt_pk_bf16_f32 v8, v113, v112
	v_cvt_pk_bf16_f32 v9, v2, v3
	v_lshl_add_u64 v[2:3], v[172:173], 1, v[124:125]
	ds_write_b128 v199, v[6:9]
	v_lshl_add_u64 v[6:7], v[2:3], 0, v[126:127]
	s_waitcnt vmcnt(0)
	ds_read_b128 v[112:115], v208
	ds_read_b128 v[124:127], v208 offset:8192
	v_lshl_add_u64 v[8:9], v[2:3], 0, v[0:1]
	ds_read_b128 v[128:131], v208 offset:16384
	s_waitcnt lgkmcnt(0)
	s_add_i32 m0, s82, 0x20b00
	s_nop 0
	global_load_lds_dwordx4 v[14:15], off offset:1536
	s_add_i32 m0, s82, 0x22b00
	s_nop 0
	global_load_lds_dwordx4 v[154:155], off offset:1536
	s_add_i32 m0, s82, 0x24b00
	s_nop 0
	global_load_lds_dwordx4 v[156:157], off offset:1536
	ds_read_b128 v[132:135], v200
	ds_read_b128 v[136:139], v200 offset:16
	s_nop 0
	v_lshlrev_b32_e32 v144, 16, v112
	s_nop 0
	v_lshlrev_b32_e32 v140, 16, v124
	v_and_b32_e32 v141, 0xffff0000, v124
	v_pk_mul_f32 v[146:147], v[118:119], v[140:141] op_sel_hi:[0,1]
	ds_read_b128 v[140:143], v200 offset:1536
	v_and_b32_e32 v145, 0xffff0000, v112
	s_nop 0
	v_lshlrev_b32_e32 v148, 16, v128
	v_and_b32_e32 v149, 0xffff0000, v128
	s_waitcnt lgkmcnt(0)
	v_pk_mul_f32 v[140:141], v[140:141], v[144:145]
	s_nop 0
	v_pk_fma_f32 v[132:133], v[146:147], v[132:133], v[140:141]
	ds_read_b128 v[144:147], v200 offset:3072
	v_pk_mul_f32 v[140:141], v[116:117], v[148:149] op_sel_hi:[0,1]
	ds_read_b128 v[148:151], v200 offset:4608
	s_waitcnt lgkmcnt(1)
; DI unsigned pack2(float a, float b) { f32x2_t v = {a, b}; bf16x2_t r = __builtin_convertvector(v, bf16x2_t); return __builtin_bit_cast(unsigned, r); }
; DI float lo16(unsigned u) { return __uint_as_float(u << 16); }
; DI float hi16(unsigned u) { return __uint_as_float(u & 0xffff0000u); }
; DI void mlstm_job(const PX& p, int l, int job, unsigned char* smem) {
;     ...
;         if (which < 2) {
;           const bfu* zp = Zml + (size_t)tok * 3072 + which * 768 + h * 192 + d8;
;           const int tm = t & (RL - 1);
;           const uint4 mid = *(const uint4*)zp;
;           const uint4 lft = *(const uint4*)(zp - ((tm != 0) ? 3072 : 0));
;           const uint4 rgt = *(const uint4*)(zp + ((tm != RL - 1) ? 3072 : 0));
;           const float lvf = (tm != 0) ? 1.f : 0.f, rvf = (tm != RL - 1) ? 1.f : 0.f;
;           const unsigned ml_[4] = {lft.x, lft.y, lft.z, lft.w};
;           const unsigned mm_[4] = {mid.x, mid.y, mid.z, mid.w};
;           const unsigned mr_[4] = {rgt.x, rgt.y, rgt.z, rgt.w};
;           const float* cwx = cw + which * 192 + d8;
;           float v[8];
; #pragma unroll
;           for (int e = 0; e < 8; e++) {
;             const float a = (e & 1) ? hi16(ml_[e >> 1]) : lo16(ml_[e >> 1]);
;             const float bm = (e & 1) ? hi16(mm_[e >> 1]) : lo16(mm_[e >> 1]);
;             const float cr = (e & 1) ? hi16(mr_[e >> 1]) : lo16(mr_[e >> 1]);
;             float s = cwx[e] * (a * lvf) + cwx[384 + e] * bm + cwx[768 + e] * (cr * rvf) + cwx[1152 + e];
;             s = s / (1.f + __expf(-s));
;             v[e] = s;
;           }
;           if (which == 0) {
;             uint4 o;
;             o.x = pack2(v[0], v[1]); o.y = pack2(v[2], v[3]); o.z = pack2(v[4], v[5]); o.w = pack2(v[6], v[7]);
;             *(uint4*)(sq + tau * 200 + d8) = o;
;           } else {
;             const float wk = wkA[par * 64 + tau];
; #pragma unroll
;             for (int e = 0; e < 8; e++) v[e] *= 0.07216878364870323f;
;             uint4 o;
;             o.x = pack2(v[0], v[1]); o.y = pack2(v[2], v[3]); o.z = pack2(v[4], v[5]); o.w = pack2(v[6], v[7]);
;             *(uint4*)(sk + tau * 200 + d8) = o;
; #pragma unroll
;             for (int e = 0; e < 8; e++) swk[(d8 + e) * 72 + tau] = f2bf(wk * v[e]);
;           }
	v_pk_fma_f32 v[132:133], v[140:141], v[144:145], v[132:133]
	s_waitcnt lgkmcnt(0)
	v_pk_add_f32 v[132:133], v[148:149], v[132:133]
	s_nop 0
	v_mul_f32_e32 v0, 0xbfb8aa3b, v132
	v_exp_f32_e32 v140, v0
	v_mul_f32_e32 v0, 0xbfb8aa3b, v133
	v_exp_f32_e32 v141, v0
	s_nop 0
	v_pk_add_f32 v[140:141], v[140:141], 1.0 op_sel_hi:[1,0]
	s_nop 0
	v_rcp_f32_e32 v112, v141
	s_nop 0
	v_mul_f32_e32 v0, v133, v112
	v_rcp_f32_e32 v119, v140
	s_nop 0
	v_mul_f32_e32 v119, v132, v119
	v_lshlrev_b32_e32 v124, 16, v125
	v_lshlrev_b32_e32 v112, 16, v113
	v_and_b32_e32 v125, 0xffff0000, v125
	v_and_b32_e32 v113, 0xffff0000, v113
	v_lshlrev_b32_e32 v128, 16, v129
	v_and_b32_e32 v129, 0xffff0000, v129
	v_pk_mul_f32 v[124:125], v[118:119], v[124:125] op_sel_hi:[0,1]
	v_pk_mul_f32 v[112:113], v[142:143], v[112:113]
	ds_read_b128 v[140:143], v200 offset:3088
	v_pk_fma_f32 v[112:113], v[124:125], v[134:135], v[112:113]
	v_pk_mul_f32 v[124:125], v[116:117], v[128:129] op_sel_hi:[0,1]
	v_pk_fma_f32 v[112:113], v[124:125], v[146:147], v[112:113]
	ds_read_b128 v[144:147], v200 offset:4624
	v_pk_add_f32 v[112:113], v[150:151], v[112:113]
	s_nop 0
	v_mul_f32_e32 v124, 0xbfb8aa3b, v112
	v_mul_f32_e32 v125, 0xbfb8aa3b, v113
	v_exp_f32_e32 v124, v124
	v_exp_f32_e32 v125, v125
	s_nop 0
	v_pk_add_f32 v[124:125], v[124:125], 1.0 op_sel_hi:[1,0]
	s_nop 0
	v_rcp_f32_e32 v129, v125
	s_nop 0
	v_mul_f32_e32 v148, v113, v129
	v_rcp_f32_e32 v125, v124
	s_nop 0
	ds_read_b128 v[132:135], v200 offset:1552
	v_mul_f32_e32 v149, v112, v125
	v_lshlrev_b32_e32 v112, 16, v126
	v_lshlrev_b32_e32 v124, 16, v114
	v_and_b32_e32 v113, 0xffff0000, v126
	v_and_b32_e32 v125, 0xffff0000, v114
	v_lshlrev_b32_e32 v128, 16, v130
	v_and_b32_e32 v129, 0xffff0000, v130
	v_pk_mul_f32 v[112:113], v[118:119], v[112:113] op_sel_hi:[0,1]
	s_waitcnt lgkmcnt(0)
	v_pk_mul_f32 v[124:125], v[132:133], v[124:125]
	s_nop 0
	v_pk_fma_f32 v[112:113], v[112:113], v[136:137], v[124:125]
	v_pk_mul_f32 v[124:125], v[116:117], v[128:129] op_sel_hi:[0,1]
	v_pk_fma_f32 v[112:113], v[124:125], v[140:141], v[112:113]
	s_nop 0
	v_pk_add_f32 v[112:113], v[144:145], v[112:113]
	s_nop 0
	v_mul_f32_e32 v114, 0xbfb8aa3b, v112
	v_exp_f32_e32 v124, v114
	v_mul_f32_e32 v114, 0xbfb8aa3b, v113
	v_exp_f32_e32 v125, v114
	s_nop 0
	v_pk_add_f32 v[124:125], v[124:125], 1.0 op_sel_hi:[1,0]
	s_nop 0
	v_rcp_f32_e32 v126, v125
	s_nop 0
	v_mul_f32_e32 v126, v113, v126
	v_rcp_f32_e32 v114, v124
	s_nop 0
	v_mul_f32_e32 v128, v112, v114
	v_lshlrev_b32_e32 v112, 16, v127
	v_lshlrev_b32_e32 v114, 16, v115
	v_and_b32_e32 v113, 0xffff0000, v127
	v_and_b32_e32 v115, 0xffff0000, v115
	v_lshlrev_b32_e32 v124, 16, v131
	v_and_b32_e32 v125, 0xffff0000, v131
	v_pk_mul_f32 v[112:113], v[118:119], v[112:113] op_sel_hi:[0,1]
	v_pk_mul_f32 v[114:115], v[134:135], v[114:115]
	s_nop 0
	v_pk_fma_f32 v[112:113], v[112:113], v[138:139], v[114:115]
	v_pk_mul_f32 v[114:115], v[116:117], v[124:125] op_sel_hi:[0,1]
	v_pk_fma_f32 v[112:113], v[114:115], v[142:143], v[112:113]
	s_nop 0
	v_pk_add_f32 v[112:113], v[146:147], v[112:113]
	s_nop 0
	v_mul_f32_e32 v114, 0xbfb8aa3b, v112
	v_mul_f32_e32 v115, 0xbfb8aa3b, v113
	v_exp_f32_e32 v114, v114
	v_exp_f32_e32 v115, v115
	s_nop 0
	v_pk_add_f32 v[114:115], v[114:115], 1.0 op_sel_hi:[1,0]
	s_nop 0
	v_rcp_f32_e32 v125, v115
	s_nop 0
	v_mul_f32_e32 v115, v113, v125
	v_rcp_f32_e32 v124, v114
	s_nop 0
	v_mul_f32_e32 v124, v112, v124
	v_cvt_pk_bf16_f32 v112, v119, v0
	v_cvt_pk_bf16_f32 v113, v149, v148
	v_cvt_pk_bf16_f32 v114, v128, v126
	v_cvt_pk_bf16_f32 v115, v124, v115
	ds_write_b128 v201, v[112:115]
	s_waitcnt vmcnt(0)
	ds_read_b128 v[112:115], v208
	ds_read_b128 v[124:127], v208 offset:8192
	s_nop 0
	ds_read_b128 v[120:123], v208 offset:16384
	s_waitcnt lgkmcnt(0)
	s_add_i32 m0, s82, 0x20a80
	s_nop 0
	global_load_lds_dwordx4 v[14:15], off offset:1664
	s_add_i32 m0, s82, 0x22a80
	s_nop 0
	global_load_lds_dwordx4 v[154:155], off offset:1664
	s_add_i32 m0, s82, 0x24a80
	s_nop 0
	global_load_lds_dwordx4 v[156:157], off offset:1664
	s_nop 0
	v_lshlrev_b32_e32 v130, 16, v112
	s_nop 0
	v_lshlrev_b32_e32 v128, 16, v124
	s_nop 0
	v_lshlrev_b32_e32 v132, 16, v120
	v_and_b32_e32 v129, 0xffff0000, v124
	v_and_b32_e32 v131, 0xffff0000, v112
	v_and_b32_e32 v133, 0xffff0000, v120
	v_lshlrev_b32_e32 v136, 16, v125
	v_lshlrev_b32_e32 v138, 16, v113
	v_lshlrev_b32_e32 v140, 16, v121
	v_and_b32_e32 v137, 0xffff0000, v125
	v_and_b32_e32 v139, 0xffff0000, v113
	v_and_b32_e32 v141, 0xffff0000, v121
	v_lshlrev_b32_e32 v142, 16, v126
	v_lshlrev_b32_e32 v144, 16, v114
	v_lshlrev_b32_e32 v146, 16, v122
	v_and_b32_e32 v143, 0xffff0000, v126
	v_and_b32_e32 v145, 0xffff0000, v114
	v_and_b32_e32 v147, 0xffff0000, v122
	v_lshlrev_b32_e32 v148, 16, v127
	v_lshlrev_b32_e32 v150, 16, v115
	v_lshlrev_b32_e32 v152, 16, v123
	v_and_b32_e32 v149, 0xffff0000, v127
	v_and_b32_e32 v151, 0xffff0000, v115
	v_and_b32_e32 v153, 0xffff0000, v123
	ds_read_b32 v0, v117
	ds_read_b128 v[112:115], v202
	ds_read_b128 v[120:123], v202 offset:16
	ds_read_b128 v[124:127], v202 offset:1536
	v_pk_mul_f32 v[128:129], v[118:119], v[128:129] op_sel_hi:[0,1]
	s_waitcnt lgkmcnt(0)
	v_pk_mul_f32 v[124:125], v[124:125], v[130:131]
	s_nop 0
	v_pk_fma_f32 v[112:113], v[128:129], v[112:113], v[124:125]
	ds_read_b128 v[128:131], v202 offset:3072
	v_pk_mul_f32 v[124:125], v[116:117], v[132:133] op_sel_hi:[0,1]
	ds_read_b128 v[132:135], v202 offset:4608
	s_waitcnt lgkmcnt(1)
	v_pk_fma_f32 v[112:113], v[124:125], v[128:129], v[112:113]
	s_waitcnt lgkmcnt(0)
; DI unsigned pack2(float a, float b) { f32x2_t v = {a, b}; bf16x2_t r = __builtin_convertvector(v, bf16x2_t); return __builtin_bit_cast(unsigned, r); }
; DI float lo16(unsigned u) { return __uint_as_float(u << 16); }
; DI float hi16(unsigned u) { return __uint_as_float(u & 0xffff0000u); }
; DI void mlstm_job(const PX& p, int l, int job, unsigned char* smem) {
;     ...
;         if (which < 2) {
;           const bfu* zp = Zml + (size_t)tok * 3072 + which * 768 + h * 192 + d8;
;           const int tm = t & (RL - 1);
;           const uint4 mid = *(const uint4*)zp;
;           const uint4 lft = *(const uint4*)(zp - ((tm != 0) ? 3072 : 0));
;           const uint4 rgt = *(const uint4*)(zp + ((tm != RL - 1) ? 3072 : 0));
;           const float lvf = (tm != 0) ? 1.f : 0.f, rvf = (tm != RL - 1) ? 1.f : 0.f;
;           const unsigned ml_[4] = {lft.x, lft.y, lft.z, lft.w};
;           const unsigned mm_[4] = {mid.x, mid.y, mid.z, mid.w};
;           const unsigned mr_[4] = {rgt.x, rgt.y, rgt.z, rgt.w};
;           const float* cwx = cw + which * 192 + d8;
;           float v[8];
; #pragma unroll
;           for (int e = 0; e < 8; e++) {
;             const float a = (e & 1) ? hi16(ml_[e >> 1]) : lo16(ml_[e >> 1]);
;             const float bm = (e & 1) ? hi16(mm_[e >> 1]) : lo16(mm_[e >> 1]);
;             const float cr = (e & 1) ? hi16(mr_[e >> 1]) : lo16(mr_[e >> 1]);
;             float s = cwx[e] * (a * lvf) + cwx[384 + e] * bm + cwx[768 + e] * (cr * rvf) + cwx[1152 + e];
;             s = s / (1.f + __expf(-s));
;             v[e] = s;
;           }
;           if (which == 0) {
;             uint4 o;
;             o.x = pack2(v[0], v[1]); o.y = pack2(v[2], v[3]); o.z = pack2(v[4], v[5]); o.w = pack2(v[6], v[7]);
;             *(uint4*)(sq + tau * 200 + d8) = o;
;           } else {
;             const float wk = wkA[par * 64 + tau];
; #pragma unroll
;             for (int e = 0; e < 8; e++) v[e] *= 0.07216878364870323f;
;             uint4 o;
;             o.x = pack2(v[0], v[1]); o.y = pack2(v[2], v[3]); o.z = pack2(v[4], v[5]); o.w = pack2(v[6], v[7]);
;             *(uint4*)(sk + tau * 200 + d8) = o;
; #pragma unroll
;             for (int e = 0; e < 8; e++) swk[(d8 + e) * 72 + tau] = f2bf(wk * v[e]);
;           }
	v_pk_add_f32 v[112:113], v[132:133], v[112:113]
	s_nop 0
	v_mul_f32_e32 v119, 0xbfb8aa3b, v112
	v_exp_f32_e32 v124, v119
	v_mul_f32_e32 v119, 0xbfb8aa3b, v113
	v_exp_f32_e32 v125, v119
	s_nop 0
	v_pk_add_f32 v[124:125], v[124:125], 1.0 op_sel_hi:[1,0]
	s_nop 0
	v_rcp_f32_e32 v128, v125
	s_nop 0
	v_mul_f32_e32 v113, v113, v128
	v_rcp_f32_e32 v125, v124
	s_nop 0
	v_mul_f32_e32 v112, v112, v125
	v_pk_mul_f32 v[132:133], v[112:113], s[2:3] op_sel_hi:[1,0]
	v_pk_mul_f32 v[112:113], v[118:119], v[136:137] op_sel_hi:[0,1]
	v_pk_mul_f32 v[124:125], v[126:127], v[138:139]
	s_nop 0
	v_pk_fma_f32 v[112:113], v[112:113], v[114:115], v[124:125]
	v_pk_mul_f32 v[114:115], v[116:117], v[140:141] op_sel_hi:[0,1]
	v_pk_fma_f32 v[112:113], v[114:115], v[130:131], v[112:113]
	ds_read_b128 v[128:131], v202 offset:4624
	v_pk_add_f32 v[112:113], v[134:135], v[112:113]
	s_nop 0
	v_mul_f32_e32 v114, 0xbfb8aa3b, v112
	v_mul_f32_e32 v115, 0xbfb8aa3b, v113
	v_exp_f32_e32 v114, v114
	v_exp_f32_e32 v115, v115
	s_nop 0
	v_pk_add_f32 v[114:115], v[114:115], 1.0 op_sel_hi:[1,0]
	s_nop 0
	v_rcp_f32_e32 v124, v115
	s_nop 0
	v_mul_f32_e32 v113, v113, v124
	v_rcp_f32_e32 v119, v114
	s_nop 0
	v_mul_f32_e32 v112, v112, v119
	v_pk_mul_f32 v[134:135], v[112:113], s[2:3] op_sel_hi:[1,0]
	ds_read_b128 v[112:115], v202 offset:1552
	v_pk_mul_f32 v[124:125], v[118:119], v[142:143] op_sel_hi:[0,1]
	s_waitcnt lgkmcnt(0)
	v_pk_mul_f32 v[112:113], v[112:113], v[144:145]
	s_nop 0
	v_pk_fma_f32 v[112:113], v[124:125], v[120:121], v[112:113]
	ds_read_b128 v[124:127], v202 offset:3088
	v_pk_mul_f32 v[120:121], v[116:117], v[146:147] op_sel_hi:[0,1]
	v_pk_mul_f32 v[114:115], v[114:115], v[150:151]
	s_waitcnt lgkmcnt(0)
	v_pk_fma_f32 v[112:113], v[120:121], v[124:125], v[112:113]
	s_nop 0
	v_pk_add_f32 v[112:113], v[128:129], v[112:113]
	s_nop 0
	v_mul_f32_e32 v119, 0xbfb8aa3b, v112
	v_exp_f32_e32 v120, v119
	v_mul_f32_e32 v119, 0xbfb8aa3b, v113
	v_exp_f32_e32 v121, v119
	s_nop 0
	v_pk_add_f32 v[120:121], v[120:121], 1.0 op_sel_hi:[1,0]
	s_nop 0
	v_rcp_f32_e32 v124, v121
	s_nop 0
	v_mul_f32_e32 v113, v113, v124
	v_rcp_f32_e32 v121, v120
	s_nop 0
	v_mul_f32_e32 v112, v112, v121
	v_pk_mul_f32 v[120:121], v[112:113], s[2:3] op_sel_hi:[1,0]
	v_pk_mul_f32 v[112:113], v[118:119], v[148:149] op_sel_hi:[0,1]
	v_pk_fma_f32 v[112:113], v[112:113], v[122:123], v[114:115]
	v_pk_mul_f32 v[114:115], v[116:117], v[152:153] op_sel_hi:[0,1]
	v_pk_fma_f32 v[112:113], v[114:115], v[126:127], v[112:113]
	s_nop 0
	v_pk_add_f32 v[112:113], v[130:131], v[112:113]
	s_nop 0
	v_mul_f32_e32 v114, 0xbfb8aa3b, v112
	v_mul_f32_e32 v115, 0xbfb8aa3b, v113
	v_exp_f32_e32 v114, v114
	v_exp_f32_e32 v115, v115
	s_nop 0
	v_pk_add_f32 v[114:115], v[114:115], 1.0 op_sel_hi:[1,0]
	s_nop 0
	v_rcp_f32_e32 v122, v115
	s_nop 0
	v_mul_f32_e32 v113, v113, v122
	v_rcp_f32_e32 v119, v114
	s_nop 0
	v_mul_f32_e32 v112, v112, v119
	v_pk_mul_f32 v[122:123], v[112:113], s[2:3] op_sel_hi:[1,0]
	v_cvt_pk_bf16_f32 v112, v132, v133
	v_cvt_pk_bf16_f32 v113, v134, v135
	v_cvt_pk_bf16_f32 v114, v120, v121
	v_cvt_pk_bf16_f32 v115, v122, v123
	ds_write_b128 v203, v[112:115] offset:25600
	v_mul_f32_e32 v112, v132, v0
	v_cvt_pk_bf16_f32 v112, v112, s0
	v_add_u32_e32 v113, v181, v219
	ds_write_b16 v113, v112 offset:51200
	v_mul_f32_e32 v112, v133, v0
	v_cvt_pk_bf16_f32 v112, v112, s0
	ds_write_b16 v113, v112 offset:51344
	v_mul_f32_e32 v112, v134, v0
	v_cvt_pk_bf16_f32 v112, v112, s0
	ds_write_b16 v113, v112 offset:51488
	v_mul_f32_e32 v112, v135, v0
	v_cvt_pk_bf16_f32 v112, v112, s0
	ds_write_b16 v113, v112 offset:51632
	v_mul_f32_e32 v112, v120, v0
	v_cvt_pk_bf16_f32 v112, v112, s0
	ds_write_b16 v113, v112 offset:51776
	v_mul_f32_e32 v112, v121, v0
	v_cvt_pk_bf16_f32 v112, v112, s0
	ds_write_b16 v113, v112 offset:51920
	v_mul_f32_e32 v112, v0, v122
	v_cvt_pk_bf16_f32 v112, v112, s0
	v_mul_f32_e32 v0, v0, v123
	ds_write_b16 v113, v112 offset:52064
	v_cvt_pk_bf16_f32 v0, v0, s0
	v_add_u32_e32 v112, v181, v220
	ds_write_b16 v112, v0 offset:51200
	s_waitcnt vmcnt(0)
	ds_read_b128 v[112:115], v208
	ds_read_b128 v[120:123], v208 offset:8192
	s_nop 0
	ds_read_b128 v[10:13], v208 offset:16384
	s_waitcnt lgkmcnt(0)
	s_add_i32 m0, s82, 0x20a00
	s_nop 0
	global_load_lds_dwordx4 v[14:15], off offset:1792
	s_add_i32 m0, s82, 0x22a00
	s_nop 0
	global_load_lds_dwordx4 v[154:155], off offset:1792
	s_add_i32 m0, s82, 0x24a00
	s_nop 0
	global_load_lds_dwordx4 v[156:157], off offset:1792
	s_nop 0
	v_lshlrev_b32_e32 v126, 16, v112
	s_nop 0
	v_lshlrev_b32_e32 v124, 16, v120
	s_nop 0
	v_lshlrev_b32_e32 v128, 16, v10
	v_and_b32_e32 v125, 0xffff0000, v120
	v_and_b32_e32 v127, 0xffff0000, v112
	v_and_b32_e32 v129, 0xffff0000, v10
	v_lshlrev_b32_e32 v132, 16, v121
	v_lshlrev_b32_e32 v134, 16, v113
	v_lshlrev_b32_e32 v136, 16, v11
	v_and_b32_e32 v133, 0xffff0000, v121
	v_and_b32_e32 v135, 0xffff0000, v113
	v_and_b32_e32 v137, 0xffff0000, v11
	v_lshlrev_b32_e32 v138, 16, v122
	v_lshlrev_b32_e32 v140, 16, v114
	v_lshlrev_b32_e32 v142, 16, v12
	v_and_b32_e32 v139, 0xffff0000, v122
	v_and_b32_e32 v141, 0xffff0000, v114
	v_and_b32_e32 v143, 0xffff0000, v12
	v_lshlrev_b32_e32 v144, 16, v123
	v_lshlrev_b32_e32 v146, 16, v115
	v_lshlrev_b32_e32 v148, 16, v13
	v_and_b32_e32 v145, 0xffff0000, v123
	v_and_b32_e32 v147, 0xffff0000, v115
	v_and_b32_e32 v149, 0xffff0000, v13
	ds_read_b32 v0, v117
	ds_read_b128 v[10:13], v221
	ds_read_b128 v[112:115], v221 offset:16
	ds_read_b128 v[120:123], v221 offset:1536
	v_pk_mul_f32 v[124:125], v[118:119], v[124:125] op_sel_hi:[0,1]
	s_waitcnt lgkmcnt(0)
; DI unsigned pack2(float a, float b) { f32x2_t v = {a, b}; bf16x2_t r = __builtin_convertvector(v, bf16x2_t); return __builtin_bit_cast(unsigned, r); }
; DI float lo16(unsigned u) { return __uint_as_float(u << 16); }
; DI float hi16(unsigned u) { return __uint_as_float(u & 0xffff0000u); }
; DI void mlstm_job(const PX& p, int l, int job, unsigned char* smem) {
;     ...
;         if (which < 2) {
;           const bfu* zp = Zml + (size_t)tok * 3072 + which * 768 + h * 192 + d8;
;           const int tm = t & (RL - 1);
;           const uint4 mid = *(const uint4*)zp;
;           const uint4 lft = *(const uint4*)(zp - ((tm != 0) ? 3072 : 0));
;           const uint4 rgt = *(const uint4*)(zp + ((tm != RL - 1) ? 3072 : 0));
;           const float lvf = (tm != 0) ? 1.f : 0.f, rvf = (tm != RL - 1) ? 1.f : 0.f;
;           const unsigned ml_[4] = {lft.x, lft.y, lft.z, lft.w};
;           const unsigned mm_[4] = {mid.x, mid.y, mid.z, mid.w};
;           const unsigned mr_[4] = {rgt.x, rgt.y, rgt.z, rgt.w};
;           const float* cwx = cw + which * 192 + d8;
;           float v[8];
; #pragma unroll
;           for (int e = 0; e < 8; e++) {
;             const float a = (e & 1) ? hi16(ml_[e >> 1]) : lo16(ml_[e >> 1]);
;             const float bm = (e & 1) ? hi16(mm_[e >> 1]) : lo16(mm_[e >> 1]);
;             const float cr = (e & 1) ? hi16(mr_[e >> 1]) : lo16(mr_[e >> 1]);
;             float s = cwx[e] * (a * lvf) + cwx[384 + e] * bm + cwx[768 + e] * (cr * rvf) + cwx[1152 + e];
;             s = s / (1.f + __expf(-s));
;             v[e] = s;
;           }
;           if (which == 0) {
;             uint4 o;
;             o.x = pack2(v[0], v[1]); o.y = pack2(v[2], v[3]); o.z = pack2(v[4], v[5]); o.w = pack2(v[6], v[7]);
;             *(uint4*)(sq + tau * 200 + d8) = o;
;           } else {
;             const float wk = wkA[par * 64 + tau];
; #pragma unroll
;             for (int e = 0; e < 8; e++) v[e] *= 0.07216878364870323f;
;             uint4 o;
;             o.x = pack2(v[0], v[1]); o.y = pack2(v[2], v[3]); o.z = pack2(v[4], v[5]); o.w = pack2(v[6], v[7]);
;             *(uint4*)(sk + tau * 200 + d8) = o;
; #pragma unroll
;             for (int e = 0; e < 8; e++) swk[(d8 + e) * 72 + tau] = f2bf(wk * v[e]);
;           }
	v_pk_mul_f32 v[120:121], v[120:121], v[126:127]
	s_nop 0
	v_pk_fma_f32 v[10:11], v[124:125], v[10:11], v[120:121]
	ds_read_b128 v[124:127], v221 offset:3072
	v_pk_mul_f32 v[120:121], v[116:117], v[128:129] op_sel_hi:[0,1]
	ds_read_b128 v[128:131], v221 offset:4608
	s_waitcnt lgkmcnt(1)
	v_pk_fma_f32 v[10:11], v[120:121], v[124:125], v[10:11]
	s_waitcnt lgkmcnt(0)
	v_pk_add_f32 v[10:11], v[128:129], v[10:11]
	s_nop 0
	v_mul_f32_e32 v119, 0xbfb8aa3b, v10
	v_exp_f32_e32 v120, v119
	v_mul_f32_e32 v119, 0xbfb8aa3b, v11
	v_exp_f32_e32 v121, v119
	s_nop 0
	v_pk_add_f32 v[120:121], v[120:121], 1.0 op_sel_hi:[1,0]
	s_nop 0
	v_rcp_f32_e32 v124, v121
	s_nop 0
	v_mul_f32_e32 v11, v11, v124
	v_rcp_f32_e32 v121, v120
	s_nop 0
	v_mul_f32_e32 v10, v10, v121
	v_pk_mul_f32 v[128:129], v[10:11], s[2:3] op_sel_hi:[1,0]
	v_pk_mul_f32 v[10:11], v[118:119], v[132:133] op_sel_hi:[0,1]
	v_pk_mul_f32 v[120:121], v[122:123], v[134:135]
	s_nop 0
	v_pk_fma_f32 v[10:11], v[10:11], v[12:13], v[120:121]
	v_pk_mul_f32 v[12:13], v[116:117], v[136:137] op_sel_hi:[0,1]
	v_pk_fma_f32 v[10:11], v[12:13], v[126:127], v[10:11]
	ds_read_b128 v[124:127], v221 offset:4624
	v_pk_add_f32 v[10:11], v[130:131], v[10:11]
	s_nop 0
	v_mul_f32_e32 v12, 0xbfb8aa3b, v10
	v_mul_f32_e32 v13, 0xbfb8aa3b, v11
	v_exp_f32_e32 v12, v12
	v_exp_f32_e32 v13, v13
	s_nop 0
	v_pk_add_f32 v[12:13], v[12:13], 1.0 op_sel_hi:[1,0]
	s_nop 0
	v_rcp_f32_e32 v120, v13
	s_nop 0
	v_mul_f32_e32 v11, v11, v120
	v_rcp_f32_e32 v119, v12
	s_nop 0
	v_mul_f32_e32 v10, v10, v119
	v_pk_mul_f32 v[130:131], v[10:11], s[2:3] op_sel_hi:[1,0]
	ds_read_b128 v[10:13], v221 offset:1552
	v_pk_mul_f32 v[120:121], v[118:119], v[138:139] op_sel_hi:[0,1]
	s_waitcnt lgkmcnt(0)
	v_pk_mul_f32 v[10:11], v[10:11], v[140:141]
	s_nop 0
	v_pk_fma_f32 v[10:11], v[120:121], v[112:113], v[10:11]
	ds_read_b128 v[120:123], v221 offset:3088
	v_pk_mul_f32 v[112:113], v[116:117], v[142:143] op_sel_hi:[0,1]
	v_pk_mul_f32 v[12:13], v[12:13], v[146:147]
	s_waitcnt lgkmcnt(0)
	v_pk_fma_f32 v[10:11], v[112:113], v[120:121], v[10:11]
	s_nop 0
	v_pk_add_f32 v[10:11], v[124:125], v[10:11]
	s_nop 0
	v_mul_f32_e32 v112, 0xbfb8aa3b, v10
	v_mul_f32_e32 v113, 0xbfb8aa3b, v11
	v_exp_f32_e32 v112, v112
	v_exp_f32_e32 v113, v113
	s_nop 0
	v_pk_add_f32 v[112:113], v[112:113], 1.0 op_sel_hi:[1,0]
	s_nop 0
	v_rcp_f32_e32 v120, v113
	s_nop 0
	v_mul_f32_e32 v11, v11, v120
	v_rcp_f32_e32 v119, v112
	s_nop 0
	v_mul_f32_e32 v10, v10, v119
	v_pk_mul_f32 v[112:113], v[10:11], s[2:3] op_sel_hi:[1,0]
	v_pk_mul_f32 v[10:11], v[118:119], v[144:145] op_sel_hi:[0,1]
	v_pk_fma_f32 v[10:11], v[10:11], v[114:115], v[12:13]
	v_pk_mul_f32 v[12:13], v[116:117], v[148:149] op_sel_hi:[0,1]
	v_pk_fma_f32 v[10:11], v[12:13], v[122:123], v[10:11]
	s_nop 0
	v_pk_add_f32 v[10:11], v[126:127], v[10:11]
	s_nop 0
	v_mul_f32_e32 v12, 0xbfb8aa3b, v10
	v_mul_f32_e32 v13, 0xbfb8aa3b, v11
	v_exp_f32_e32 v12, v12
	v_exp_f32_e32 v13, v13
	s_nop 0
	v_pk_add_f32 v[12:13], v[12:13], 1.0 op_sel_hi:[1,0]
	s_nop 0
	v_rcp_f32_e32 v115, v13
	s_nop 0
	v_mul_f32_e32 v11, v11, v115
	v_rcp_f32_e32 v114, v12
	s_nop 0
	v_mul_f32_e32 v10, v10, v114
	v_pk_mul_f32 v[114:115], v[10:11], s[2:3] op_sel_hi:[1,0]
	v_cvt_pk_bf16_f32 v10, v128, v129
	v_cvt_pk_bf16_f32 v11, v130, v131
	v_cvt_pk_bf16_f32 v12, v112, v113
	v_cvt_pk_bf16_f32 v13, v114, v115
	ds_write_b128 v222, v[10:13] offset:25600
	v_mul_f32_e32 v10, v128, v0
	v_cvt_pk_bf16_f32 v10, v10, s0
	v_add_u32_e32 v11, v181, v223
	ds_write_b16 v11, v10 offset:51200
	v_mul_f32_e32 v10, v129, v0
	v_cvt_pk_bf16_f32 v10, v10, s0
	ds_write_b16 v11, v10 offset:51344
	v_mul_f32_e32 v10, v130, v0
	v_cvt_pk_bf16_f32 v10, v10, s0
	ds_write_b16 v11, v10 offset:51488
	v_mul_f32_e32 v10, v131, v0
	v_cvt_pk_bf16_f32 v10, v10, s0
	ds_write_b16 v11, v10 offset:51632
	v_mul_f32_e32 v10, v112, v0
	v_cvt_pk_bf16_f32 v10, v10, s0
	ds_write_b16 v11, v10 offset:51776
	v_mul_f32_e32 v10, v113, v0
	v_cvt_pk_bf16_f32 v10, v10, s0
	ds_write_b16 v11, v10 offset:51920
	v_mul_f32_e32 v10, v0, v114
	v_cvt_pk_bf16_f32 v10, v10, s0
	v_mul_f32_e32 v0, v0, v115
	ds_write_b16 v11, v10 offset:52064
	v_cvt_pk_bf16_f32 v0, v0, s0
	v_add_u32_e32 v10, v181, v224
	ds_write_b16 v10, v0 offset:51200
	s_waitcnt vmcnt(0)
	ds_read_b128 v[10:13], v208
	ds_read_b128 v[112:115], v208 offset:8192
	s_nop 0
	ds_read_b128 v[6:9], v208 offset:16384
	s_waitcnt lgkmcnt(0)
	s_add_i32 m0, s82, 0x20500
	s_nop 0
	global_load_lds_dwordx4 v[14:15], off offset:3072
	s_add_i32 m0, s82, 0x22480
	s_nop 0
	global_load_lds_dwordx4 v[14:15], off offset:3200
	s_add_i32 m0, s82, 0x24400
	s_nop 0
	global_load_lds_dwordx4 v[14:15], off offset:3328
	s_nop 0
	v_lshlrev_b32_e32 v122, 16, v10
	s_nop 0
	v_lshlrev_b32_e32 v120, 16, v112
	s_nop 0
	v_lshlrev_b32_e32 v124, 16, v6
	v_and_b32_e32 v121, 0xffff0000, v112
	v_and_b32_e32 v123, 0xffff0000, v10
	v_and_b32_e32 v125, 0xffff0000, v6
	v_lshlrev_b32_e32 v128, 16, v113
	v_lshlrev_b32_e32 v130, 16, v11
	v_lshlrev_b32_e32 v132, 16, v7
	v_and_b32_e32 v129, 0xffff0000, v113
	v_and_b32_e32 v131, 0xffff0000, v11
	v_and_b32_e32 v133, 0xffff0000, v7
	v_lshlrev_b32_e32 v134, 16, v114
	v_lshlrev_b32_e32 v136, 16, v12
	v_lshlrev_b32_e32 v138, 16, v8
	v_and_b32_e32 v135, 0xffff0000, v114
	v_and_b32_e32 v137, 0xffff0000, v12
	v_and_b32_e32 v139, 0xffff0000, v8
	v_lshlrev_b32_e32 v140, 16, v115
	v_lshlrev_b32_e32 v142, 16, v13
	v_lshlrev_b32_e32 v144, 16, v9
	v_and_b32_e32 v141, 0xffff0000, v115
	v_and_b32_e32 v143, 0xffff0000, v13
	v_and_b32_e32 v145, 0xffff0000, v9
	ds_read_b32 v0, v117
	ds_read_b128 v[6:9], v225
	ds_read_b128 v[10:13], v225 offset:16
	ds_read_b128 v[112:115], v225 offset:1536
	v_pk_mul_f32 v[120:121], v[118:119], v[120:121] op_sel_hi:[0,1]
	s_waitcnt lgkmcnt(0)
; DI void mlstm_job(const PX& p, int l, int job, unsigned char* smem) {
;     ...
;         if (which < 2) {
;           const bfu* zp = Zml + (size_t)tok * 3072 + which * 768 + h * 192 + d8;
;           const int tm = t & (RL - 1);
;           const uint4 mid = *(const uint4*)zp;
;           const uint4 lft = *(const uint4*)(zp - ((tm != 0) ? 3072 : 0));
;           const uint4 rgt = *(const uint4*)(zp + ((tm != RL - 1) ? 3072 : 0));
;           const float lvf = (tm != 0) ? 1.f : 0.f, rvf = (tm != RL - 1) ? 1.f : 0.f;
;           const unsigned ml_[4] = {lft.x, lft.y, lft.z, lft.w};
;           const unsigned mm_[4] = {mid.x, mid.y, mid.z, mid.w};
;           const unsigned mr_[4] = {rgt.x, rgt.y, rgt.z, rgt.w};
;           const float* cwx = cw + which * 192 + d8;
;           float v[8];
; #pragma unroll
;           for (int e = 0; e < 8; e++) {
;             const float a = (e & 1) ? hi16(ml_[e >> 1]) : lo16(ml_[e >> 1]);
;             const float bm = (e & 1) ? hi16(mm_[e >> 1]) : lo16(mm_[e >> 1]);
;             const float cr = (e & 1) ? hi16(mr_[e >> 1]) : lo16(mr_[e >> 1]);
;             float s = cwx[e] * (a * lvf) + cwx[384 + e] * bm + cwx[768 + e] * (cr * rvf) + cwx[1152 + e];
;             s = s / (1.f + __expf(-s));
;             v[e] = s;
;           }
;           if (which == 0) {
;             uint4 o;
;             o.x = pack2(v[0], v[1]); o.y = pack2(v[2], v[3]); o.z = pack2(v[4], v[5]); o.w = pack2(v[6], v[7]);
;             *(uint4*)(sq + tau * 200 + d8) = o;
;           } else {
;             const float wk = wkA[par * 64 + tau];
; #pragma unroll
;             for (int e = 0; e < 8; e++) v[e] *= 0.07216878364870323f;
;             uint4 o;
;             o.x = pack2(v[0], v[1]); o.y = pack2(v[2], v[3]); o.z = pack2(v[4], v[5]); o.w = pack2(v[6], v[7]);
;             *(uint4*)(sk + tau * 200 + d8) = o;
; #pragma unroll
;             for (int e = 0; e < 8; e++) swk[(d8 + e) * 72 + tau] = f2bf(wk * v[e]);
;           }
;         } else {
;           const bfu* zp = Zml + (size_t)tok * 3072 + 1536 + h * 192 + d8;
;           const uint4 mid = *(const uint4*)zp;
;           const unsigned mm_[4] = {mid.x, mid.y, mid.z, mid.w};
; #pragma unroll
;           for (int e = 0; e < 8; e++) svT[(d8 + e) * 72 + tau] = (bfu)((e & 1) ? (mm_[e >> 1] >> 16) : (mm_[e >> 1] & 0xffffu));
;         }
;       }
;       __syncthreads();
;       f32x16 num[2];
	v_pk_mul_f32 v[112:113], v[112:113], v[122:123]
	s_nop 0
	v_pk_fma_f32 v[6:7], v[120:121], v[6:7], v[112:113]
	ds_read_b128 v[120:123], v225 offset:3072
	v_pk_mul_f32 v[112:113], v[116:117], v[124:125] op_sel_hi:[0,1]
	ds_read_b128 v[124:127], v225 offset:4608
	s_waitcnt lgkmcnt(1)
	v_pk_fma_f32 v[6:7], v[112:113], v[120:121], v[6:7]
	s_waitcnt lgkmcnt(0)
	v_pk_add_f32 v[6:7], v[124:125], v[6:7]
	s_nop 0
	v_mul_f32_e32 v112, 0xbfb8aa3b, v6
	v_mul_f32_e32 v113, 0xbfb8aa3b, v7
	v_exp_f32_e32 v112, v112
	v_exp_f32_e32 v113, v113
	s_nop 0
	v_pk_add_f32 v[112:113], v[112:113], 1.0 op_sel_hi:[1,0]
	s_nop 0
	v_rcp_f32_e32 v119, v113
	s_nop 0
	v_mul_f32_e32 v7, v7, v119
	v_rcp_f32_e32 v117, v112
	s_nop 0
	v_mul_f32_e32 v6, v6, v117
	v_pk_mul_f32 v[124:125], v[6:7], s[2:3] op_sel_hi:[1,0]
	v_pk_mul_f32 v[6:7], v[118:119], v[128:129] op_sel_hi:[0,1]
	v_pk_mul_f32 v[112:113], v[114:115], v[130:131]
	s_nop 0
	v_pk_fma_f32 v[6:7], v[6:7], v[8:9], v[112:113]
	v_pk_mul_f32 v[8:9], v[116:117], v[132:133] op_sel_hi:[0,1]
	v_pk_fma_f32 v[6:7], v[8:9], v[122:123], v[6:7]
	ds_read_b128 v[120:123], v225 offset:4624
	v_pk_add_f32 v[6:7], v[126:127], v[6:7]
	s_nop 0
	v_mul_f32_e32 v8, 0xbfb8aa3b, v6
	v_mul_f32_e32 v9, 0xbfb8aa3b, v7
	v_exp_f32_e32 v8, v8
	v_exp_f32_e32 v9, v9
	s_nop 0
	v_pk_add_f32 v[8:9], v[8:9], 1.0 op_sel_hi:[1,0]
	s_nop 0
	v_rcp_f32_e32 v113, v9
	s_nop 0
	v_mul_f32_e32 v7, v7, v113
	v_rcp_f32_e32 v112, v8
	s_nop 0
	v_mul_f32_e32 v6, v6, v112
	v_pk_mul_f32 v[126:127], v[6:7], s[2:3] op_sel_hi:[1,0]
	ds_read_b128 v[6:9], v225 offset:1552
	v_pk_mul_f32 v[112:113], v[118:119], v[134:135] op_sel_hi:[0,1]
	s_waitcnt lgkmcnt(0)
	v_pk_mul_f32 v[6:7], v[6:7], v[136:137]
	s_nop 0
	v_pk_fma_f32 v[6:7], v[112:113], v[10:11], v[6:7]
	ds_read_b128 v[112:115], v225 offset:3088
	v_pk_mul_f32 v[10:11], v[116:117], v[138:139] op_sel_hi:[0,1]
	v_pk_mul_f32 v[8:9], v[8:9], v[142:143]
	s_waitcnt lgkmcnt(0)
	v_pk_fma_f32 v[6:7], v[10:11], v[112:113], v[6:7]
	s_nop 0
	v_pk_add_f32 v[6:7], v[120:121], v[6:7]
	s_nop 0
	v_mul_f32_e32 v10, 0xbfb8aa3b, v6
	v_mul_f32_e32 v11, 0xbfb8aa3b, v7
	v_exp_f32_e32 v10, v10
	v_exp_f32_e32 v11, v11
	s_nop 0
	v_pk_add_f32 v[10:11], v[10:11], 1.0 op_sel_hi:[1,0]
	s_nop 0
	v_rcp_f32_e32 v113, v11
	s_nop 0
	v_mul_f32_e32 v7, v7, v113
	v_rcp_f32_e32 v112, v10
	s_nop 0
	v_mul_f32_e32 v6, v6, v112
	v_pk_mul_f32 v[10:11], v[6:7], s[2:3] op_sel_hi:[1,0]
	v_pk_mul_f32 v[6:7], v[118:119], v[140:141] op_sel_hi:[0,1]
	v_pk_fma_f32 v[6:7], v[6:7], v[12:13], v[8:9]
	v_pk_mul_f32 v[8:9], v[116:117], v[144:145] op_sel_hi:[0,1]
	v_pk_fma_f32 v[6:7], v[8:9], v[114:115], v[6:7]
	s_nop 0
	v_pk_add_f32 v[6:7], v[122:123], v[6:7]
	s_nop 0
	v_mul_f32_e32 v8, 0xbfb8aa3b, v6
	v_mul_f32_e32 v9, 0xbfb8aa3b, v7
	v_exp_f32_e32 v8, v8
	v_exp_f32_e32 v9, v9
	s_nop 0
	v_pk_add_f32 v[8:9], v[8:9], 1.0 op_sel_hi:[1,0]
	s_nop 0
	v_rcp_f32_e32 v13, v9
	s_nop 0
	v_mul_f32_e32 v7, v7, v13
	v_rcp_f32_e32 v12, v8
	s_nop 0
	v_mul_f32_e32 v6, v6, v12
	v_pk_mul_f32 v[12:13], v[6:7], s[2:3] op_sel_hi:[1,0]
	v_cvt_pk_bf16_f32 v6, v124, v125
	v_cvt_pk_bf16_f32 v7, v126, v127
	v_cvt_pk_bf16_f32 v8, v10, v11
	v_cvt_pk_bf16_f32 v9, v12, v13
	ds_write_b128 v226, v[6:9] offset:25600
	v_mul_f32_e32 v6, v124, v0
	v_cvt_pk_bf16_f32 v6, v6, s0
	v_add_u32_e32 v7, v181, v227
	ds_write_b16 v7, v6 offset:51200
	v_mul_f32_e32 v6, v125, v0
	v_cvt_pk_bf16_f32 v6, v6, s0
	ds_write_b16 v7, v6 offset:51344
	v_mul_f32_e32 v6, v126, v0
	v_cvt_pk_bf16_f32 v6, v6, s0
	ds_write_b16 v7, v6 offset:51488
	v_mul_f32_e32 v6, v127, v0
	v_cvt_pk_bf16_f32 v6, v6, s0
	ds_write_b16 v7, v6 offset:51632
	v_mul_f32_e32 v6, v10, v0
	v_cvt_pk_bf16_f32 v6, v6, s0
	ds_write_b16 v7, v6 offset:51776
	v_mul_f32_e32 v6, v11, v0
	v_cvt_pk_bf16_f32 v6, v6, s0
	ds_write_b16 v7, v6 offset:51920
	v_mul_f32_e32 v6, v0, v12
	v_cvt_pk_bf16_f32 v6, v6, s0
	v_mul_f32_e32 v0, v0, v13
	ds_write_b16 v7, v6 offset:52064
	v_cvt_pk_bf16_f32 v0, v0, s0
	v_add_u32_e32 v6, v181, v228
	ds_write_b16 v6, v0 offset:51200
	s_waitcnt vmcnt(0)
	ds_read_b128 v[6:9], v208
	v_add_u32_e32 v0, v179, v219
	s_waitcnt lgkmcnt(0)
	ds_write_b16 v0, v6
	ds_write_b16_d16_hi v0, v6 offset:144
	ds_write_b16 v0, v7 offset:288
	ds_write_b16_d16_hi v0, v7 offset:432
	ds_write_b16 v0, v8 offset:576
	ds_write_b16_d16_hi v0, v8 offset:720
	ds_write_b16 v0, v9 offset:864
	ds_read_b128 v[4:7], v208 offset:8192
	v_add_u32_e32 v0, v179, v220
	ds_write_b16_d16_hi v0, v9
	v_add_u32_e32 v0, v179, v223
	s_waitcnt lgkmcnt(0)
	ds_write_b16 v0, v4
	ds_write_b16_d16_hi v0, v4 offset:144
	ds_write_b16 v0, v5 offset:288
	ds_write_b16_d16_hi v0, v5 offset:432
	ds_write_b16 v0, v6 offset:576
	ds_write_b16_d16_hi v0, v6 offset:720
	ds_write_b16 v0, v7 offset:864
	ds_read_b128 v[2:5], v208 offset:16384
	v_add_u32_e32 v0, v179, v224
	ds_write_b16_d16_hi v0, v7
	v_add_u32_e32 v0, v179, v227
	s_waitcnt lgkmcnt(0)
	ds_write_b16 v0, v2
	ds_write_b16_d16_hi v0, v2 offset:144
	ds_write_b16 v0, v3 offset:288
	ds_write_b16_d16_hi v0, v3 offset:432
	ds_write_b16 v0, v4 offset:576
	ds_write_b16_d16_hi v0, v4 offset:720
	ds_write_b16 v0, v5 offset:864
	v_add_u32_e32 v0, v179, v228
	v_mov_b32_e32 v14, v1
	v_mov_b32_e32 v15, v1
	ds_write_b16_d16_hi v0, v5
	v_mov_b32_e32 v0, v1
	v_mov_b32_e32 v2, v1
	v_mov_b32_e32 v3, v1
	v_mov_b32_e32 v4, v1
	v_mov_b32_e32 v5, v1
	v_mov_b32_e32 v6, v1
	v_mov_b32_e32 v7, v1
	v_mov_b32_e32 v8, v1
	v_mov_b32_e32 v9, v1
	v_mov_b32_e32 v10, v1
	v_mov_b32_e32 v11, v1
	v_mov_b32_e32 v12, v1
	v_mov_b32_e32 v13, v1
	v_mov_b64_e32 v[126:127], v[14:15]
	v_mov_b64_e32 v[142:143], v[14:15]
	v_mov_b64_e32 v[124:125], v[12:13]
	v_mov_b64_e32 v[122:123], v[10:11]
	v_mov_b64_e32 v[120:121], v[8:9]
	v_mov_b64_e32 v[118:119], v[6:7]
	v_mov_b64_e32 v[116:117], v[4:5]
	v_mov_b64_e32 v[114:115], v[2:3]
	v_mov_b64_e32 v[112:113], v[0:1]
	v_mov_b64_e32 v[140:141], v[12:13]
	v_mov_b64_e32 v[138:139], v[10:11]
	v_mov_b64_e32 v[136:137], v[8:9]
	v_mov_b64_e32 v[134:135], v[6:7]
	v_mov_b64_e32 v[132:133], v[4:5]
	v_mov_b64_e32 v[130:131], v[2:3]
	v_mov_b64_e32 v[128:129], v[0:1]
	s_waitcnt lgkmcnt(0)
	s_barrier
; DI unsigned pack2(float a, float b) { f32x2_t v = {a, b}; bf16x2_t r = __builtin_convertvector(v, bf16x2_t); return __builtin_bit_cast(unsigned, r); }
; DI f32x16 mfma32(bf16x8 a, bf16x8 b, f32x16 c) { return __builtin_amdgcn_mfma_f32_32x32x16_bf16(a, b, c, 0, 0, 0); }
; DI void mlstm_job(const PX& p, int l, int job, unsigned char* smem) {
;     ...
;       if (w < 7) {
; #pragma unroll
;         for (int i = 0; i < 6; i++) {
; #pragma unroll
;           for (int s2 = 0; s2 < 2; s2++) {
;             uint4 pk;
;             pk.x = pack2(st[i][8 * s2 + 0], st[i][8 * s2 + 1]);
;             pk.y = pack2(st[i][8 * s2 + 2], st[i][8 * s2 + 3]);
;             pk.z = pack2(st[i][8 * s2 + 4], st[i][8 * s2 + 5]);
;             pk.w = pack2(st[i][8 * s2 + 6], st[i][8 * s2 + 7]);
;             const bf16x8 aop = u4_to_bf8(pk);
; #pragma unroll
;             for (int ti = 0; ti < 2; ti++) {
;               const bfu* qp = sq + (ti * 32 + lr) * 200 + 32 * i + 16 * s2 + 4 * lh;
;               const uint2 lo = *(const uint2*)qp;
;               const uint2 hi = *(const uint2*)(qp + 8);
;               const uint4 bq = make_uint4(lo.x, lo.y, hi.x, hi.y);
;               num[ti] = mfma32(aop, u4_to_bf8(bq), num[ti]);
;             }
;           }
;         }
; #pragma unroll
;         for (int ti = 0; ti < 2; ti++) {
;           const float wi = winA[par * 64 + ti * 32 + lr];
; #pragma unroll
;           for (int r = 0; r < 16; r++) num[ti][r] *= wi;
;         }
	s_and_saveexec_b64 s[62:63], s[8:9]
	s_cbranch_execz .LBB0_456
	v_add_u32_e32 v0, 0x3000, v215
	ds_read2_b64 v[6:9], v215 offset1:2
	ds_read2_b64 v[10:13], v0 offset0:64 offset1:66
	ds_read2_b64 v[144:147], v215 offset0:4 offset1:6
	ds_read2_b64 v[148:151], v0 offset0:68 offset1:70
	v_cvt_pk_bf16_f32 v2, v96, v97
	v_cvt_pk_bf16_f32 v3, v98, v99
	v_cvt_pk_bf16_f32 v4, v100, v101
	v_cvt_pk_bf16_f32 v5, v102, v103
	s_waitcnt lgkmcnt(3)
	s_nop 0
	v_mfma_f32_32x32x16_bf16 v[128:143], v[2:5], v[6:9], 0
	ds_read2_b64 v[6:9], v215 offset0:8 offset1:10
	s_waitcnt lgkmcnt(3)
	v_mfma_f32_32x32x16_bf16 v[112:127], v[2:5], v[10:13], 0
	ds_read2_b64 v[10:13], v0 offset0:72 offset1:74
	v_cvt_pk_bf16_f32 v2, v104, v105
	v_cvt_pk_bf16_f32 v3, v106, v107
	v_cvt_pk_bf16_f32 v4, v108, v109
	v_cvt_pk_bf16_f32 v5, v110, v111
	s_waitcnt lgkmcnt(3)
	s_nop 0
	v_mfma_f32_32x32x16_bf16 v[128:143], v[2:5], v[144:147], v[128:143]
	ds_read2_b64 v[144:147], v215 offset0:12 offset1:14
	s_waitcnt lgkmcnt(3)
	v_mfma_f32_32x32x16_bf16 v[112:127], v[2:5], v[148:151], v[112:127]
	ds_read2_b64 v[148:151], v0 offset0:76 offset1:78
	v_cvt_pk_bf16_f32 v2, v80, v81
	v_cvt_pk_bf16_f32 v3, v82, v83
	v_cvt_pk_bf16_f32 v4, v84, v85
	v_cvt_pk_bf16_f32 v5, v86, v87
	s_waitcnt lgkmcnt(3)
	s_nop 0
	v_mfma_f32_32x32x16_bf16 v[128:143], v[2:5], v[6:9], v[128:143]
	ds_read2_b64 v[6:9], v215 offset0:16 offset1:18
	s_waitcnt lgkmcnt(3)
	v_mfma_f32_32x32x16_bf16 v[112:127], v[2:5], v[10:13], v[112:127]
	ds_read2_b64 v[10:13], v0 offset0:80 offset1:82
	v_cvt_pk_bf16_f32 v2, v88, v89
	v_cvt_pk_bf16_f32 v3, v90, v91
	v_cvt_pk_bf16_f32 v4, v92, v93
	v_cvt_pk_bf16_f32 v5, v94, v95
	s_waitcnt lgkmcnt(3)
	s_nop 0
	v_mfma_f32_32x32x16_bf16 v[128:143], v[2:5], v[144:147], v[128:143]
	ds_read2_b64 v[144:147], v215 offset0:20 offset1:22
	s_waitcnt lgkmcnt(3)
	v_mfma_f32_32x32x16_bf16 v[112:127], v[2:5], v[148:151], v[112:127]
	ds_read2_b64 v[148:151], v0 offset0:84 offset1:86
	v_cvt_pk_bf16_f32 v2, v64, v65
	v_cvt_pk_bf16_f32 v3, v66, v67
	v_cvt_pk_bf16_f32 v4, v68, v69
	v_cvt_pk_bf16_f32 v5, v70, v71
	s_waitcnt lgkmcnt(3)
	s_nop 0
	v_mfma_f32_32x32x16_bf16 v[128:143], v[2:5], v[6:9], v[128:143]
	ds_read2_b64 v[6:9], v215 offset0:24 offset1:26
	s_waitcnt lgkmcnt(3)
	v_mfma_f32_32x32x16_bf16 v[112:127], v[2:5], v[10:13], v[112:127]
	ds_read2_b64 v[10:13], v0 offset0:88 offset1:90
	v_cvt_pk_bf16_f32 v2, v72, v73
	v_cvt_pk_bf16_f32 v3, v74, v75
	v_cvt_pk_bf16_f32 v4, v76, v77
	v_cvt_pk_bf16_f32 v5, v78, v79
	s_waitcnt lgkmcnt(3)
	s_nop 0
	v_mfma_f32_32x32x16_bf16 v[128:143], v[2:5], v[144:147], v[128:143]
	ds_read2_b64 v[144:147], v215 offset0:28 offset1:30
	s_waitcnt lgkmcnt(3)
	v_mfma_f32_32x32x16_bf16 v[112:127], v[2:5], v[148:151], v[112:127]
	ds_read2_b64 v[148:151], v0 offset0:92 offset1:94
	v_cvt_pk_bf16_f32 v2, v48, v49
	v_cvt_pk_bf16_f32 v3, v50, v51
	v_cvt_pk_bf16_f32 v4, v52, v53
	v_cvt_pk_bf16_f32 v5, v54, v55
	s_waitcnt lgkmcnt(3)
	s_nop 0
	v_mfma_f32_32x32x16_bf16 v[128:143], v[2:5], v[6:9], v[128:143]
	ds_read2_b64 v[6:9], v215 offset0:32 offset1:34
	s_waitcnt lgkmcnt(3)
	v_mfma_f32_32x32x16_bf16 v[112:127], v[2:5], v[10:13], v[112:127]
	ds_read2_b64 v[10:13], v0 offset0:96 offset1:98
	v_cvt_pk_bf16_f32 v2, v56, v57
	v_cvt_pk_bf16_f32 v3, v58, v59
	v_cvt_pk_bf16_f32 v4, v60, v61
	v_cvt_pk_bf16_f32 v5, v62, v63
	s_waitcnt lgkmcnt(3)
	s_nop 0
	v_mfma_f32_32x32x16_bf16 v[128:143], v[2:5], v[144:147], v[128:143]
	ds_read2_b64 v[144:147], v215 offset0:36 offset1:38
	s_waitcnt lgkmcnt(3)
	v_mfma_f32_32x32x16_bf16 v[112:127], v[2:5], v[148:151], v[112:127]
	ds_read2_b64 v[148:151], v0 offset0:100 offset1:102
	v_cvt_pk_bf16_f32 v2, v32, v33
	v_cvt_pk_bf16_f32 v3, v34, v35
	v_cvt_pk_bf16_f32 v4, v36, v37
	v_cvt_pk_bf16_f32 v5, v38, v39
	s_waitcnt lgkmcnt(3)
	s_nop 0
	v_mfma_f32_32x32x16_bf16 v[128:143], v[2:5], v[6:9], v[128:143]
	ds_read2_b64 v[6:9], v215 offset0:40 offset1:42
	s_waitcnt lgkmcnt(3)
	v_mfma_f32_32x32x16_bf16 v[112:127], v[2:5], v[10:13], v[112:127]
	ds_read2_b64 v[10:13], v0 offset0:104 offset1:106
	v_cvt_pk_bf16_f32 v2, v40, v41
	v_cvt_pk_bf16_f32 v3, v42, v43
	v_cvt_pk_bf16_f32 v4, v44, v45
	v_cvt_pk_bf16_f32 v5, v46, v47
	s_waitcnt lgkmcnt(3)
	s_nop 0
	v_mfma_f32_32x32x16_bf16 v[128:143], v[2:5], v[144:147], v[128:143]
	ds_read2_b64 v[144:147], v215 offset0:44 offset1:46
	s_waitcnt lgkmcnt(3)
	v_mfma_f32_32x32x16_bf16 v[112:127], v[2:5], v[148:151], v[112:127]
	ds_read2_b64 v[148:151], v0 offset0:108 offset1:110
	v_cvt_pk_bf16_f32 v2, v16, v17
	v_cvt_pk_bf16_f32 v3, v18, v19
	v_cvt_pk_bf16_f32 v4, v20, v21
	v_cvt_pk_bf16_f32 v5, v22, v23
	s_waitcnt lgkmcnt(3)
	s_nop 0
	v_mfma_f32_32x32x16_bf16 v[128:143], v[2:5], v[6:9], v[128:143]
	s_waitcnt lgkmcnt(2)
	v_mfma_f32_32x32x16_bf16 v[112:127], v[2:5], v[10:13], v[112:127]
	v_cvt_pk_bf16_f32 v2, v24, v25
	v_cvt_pk_bf16_f32 v3, v26, v27
	v_cvt_pk_bf16_f32 v4, v28, v29
	v_cvt_pk_bf16_f32 v5, v30, v31
	s_waitcnt lgkmcnt(1)
	s_nop 0
	v_mfma_f32_32x32x16_bf16 v[128:143], v[2:5], v[144:147], v[128:143]
	s_waitcnt lgkmcnt(0)
	v_mfma_f32_32x32x16_bf16 v[112:127], v[2:5], v[148:151], v[112:127]
	v_add_u32_e32 v0, s27, v182
	ds_read2_b32 v[2:3], v0 offset1:32
	s_waitcnt lgkmcnt(0)
	v_mov_b32_e32 v0, v3
	s_nop 6
	v_mul_f32_e64 v142, v142, v2
	v_mul_f32_e64 v143, v143, v2
	v_pk_mul_f32 v[140:141], v[140:141], v[2:3] op_sel_hi:[1,0]
	v_pk_mul_f32 v[138:139], v[138:139], v[2:3] op_sel_hi:[1,0]
	v_pk_mul_f32 v[136:137], v[136:137], v[2:3] op_sel_hi:[1,0]
	v_pk_mul_f32 v[134:135], v[134:135], v[2:3] op_sel_hi:[1,0]
	v_pk_mul_f32 v[132:133], v[132:133], v[2:3] op_sel_hi:[1,0]
	v_pk_mul_f32 v[130:131], v[130:131], v[2:3] op_sel_hi:[1,0]
	v_pk_mul_f32 v[128:129], v[128:129], v[2:3] op_sel_hi:[1,0]
	v_pk_mul_f32 v[126:127], v[126:127], v[0:1] op_sel_hi:[1,0]
	v_pk_mul_f32 v[124:125], v[124:125], v[0:1] op_sel_hi:[1,0]
	v_pk_mul_f32 v[122:123], v[122:123], v[0:1] op_sel_hi:[1,0]
	v_pk_mul_f32 v[120:121], v[120:121], v[0:1] op_sel_hi:[1,0]
	v_pk_mul_f32 v[118:119], v[118:119], v[0:1] op_sel_hi:[1,0]
	v_pk_mul_f32 v[116:117], v[116:117], v[0:1] op_sel_hi:[1,0]
	v_pk_mul_f32 v[114:115], v[114:115], v[0:1] op_sel_hi:[1,0]
	v_pk_mul_f32 v[112:113], v[112:113], v[0:1] op_sel_hi:[1,0]

; DI unsigned pack2(float a, float b) { f32x2_t v = {a, b}; bf16x2_t r = __builtin_convertvector(v, bf16x2_t); return __builtin_bit_cast(unsigned, r); }
; DI f32x4 mfma16(bf16x8 a, bf16x8 b, f32x4 c) { return __builtin_amdgcn_mfma_f32_16x16x32_bf16(a, b, c, 0, 0, 0); }
; DI void s5_job(const PX& p, int l, int job, unsigned char* smem) {
;     ...
; #pragma unroll
;         for (int s = 0; s < 8; s++) {
;           const bf16x8 ub = u4_to_bf8(ucur[s]);
; #pragma unroll
;           for (int tt = 0; tt < 2; tt++) {
;             f32x4 cr, ci;
; #pragma unroll
;             for (int r = 0; r < 4; r++) {
;               cr[r] = lre[tt][r] * sre[tt][r] - lim[tt][r] * sim[tt][r];
;               ci[r] = lre[tt][r] * sim[tt][r] + lim[tt][r] * sre[tt][r];
;             }
;             sre[tt] = mfma16(Are[tt], ub, cr);
;             sim[tt] = mfma16(Aim[tt], ub, ci);
;           }
;           uint4 pr, pi;
;           pr.x = pack2(sre[0][0], sre[0][1]); pr.y = pack2(sre[0][2], sre[0][3]);
;           pr.z = pack2(sre[1][0], sre[1][1]); pr.w = pack2(sre[1][2], sre[1][3]);
;           pi.x = pack2(sim[0][0], sim[0][1]); pi.y = pack2(sim[0][2], sim[0][3]);
;           pi.z = pack2(sim[1][0], sim[1][1]); pi.w = pack2(sim[1][2], sim[1][3]);
;           f32x4 y = f32x4{0.f, 0.f, 0.f, 0.f};
;           y = mfma16(Cf[0], u4_to_bf8(pr), y);
;           y = mfma16(Cf[1], u4_to_bf8(pi), y);
;           yp[s] = y;
;         }
.LBB0_507:
	v_pk_mul_f32 v[92:93], v[146:147], v[122:123]
	v_pk_mul_f32 v[96:97], v[142:143], v[120:121]
	v_pk_fma_f32 v[94:95], v[144:145], v[118:119], v[92:93] neg_lo:[0,0,1] neg_hi:[0,0,1]
	v_pk_fma_f32 v[92:93], v[140:141], v[116:117], v[96:97] neg_lo:[0,0,1] neg_hi:[0,0,1]
	v_pk_mul_f32 v[100:101], v[144:145], v[122:123]
	v_pk_mul_f32 v[104:105], v[150:151], v[112:113]
	s_nop 0
	v_mfma_f32_16x16x32_bf16 v[96:99], v[12:15], v[40:43], v[92:95]
	s_nop 2
	v_mul_f32_e64 v92, v140, v120
	v_mul_f32_e64 v93, v141, v121
	v_pk_fma_f32 v[94:95], v[146:147], v[118:119], v[100:101]
	v_pk_fma_f32 v[92:93], v[142:143], v[116:117], v[92:93]
	s_nop 1
	v_mfma_f32_16x16x32_bf16 v[100:103], v[16:19], v[40:43], v[92:95]
	s_nop 2
	v_mul_f32_e64 v92, v154, v114
	v_mul_f32_e64 v93, v155, v115
	v_pk_mul_f32 v[114:115], v[152:153], v[114:115]
	v_pk_fma_f32 v[94:95], v[152:153], v[110:111], v[92:93] neg_lo:[0,0,1] neg_hi:[0,0,1]
	v_pk_fma_f32 v[92:93], v[148:149], v[108:109], v[104:105] neg_lo:[0,0,1] neg_hi:[0,0,1]
	v_pk_mul_f32 v[116:117], v[142:143], v[100:101]
	s_nop 0
	v_mfma_f32_16x16x32_bf16 v[104:107], v[4:7], v[40:43], v[92:95]
	s_nop 2
	v_mul_f32_e64 v92, v148, v112
	v_mul_f32_e64 v93, v149, v113
	v_pk_fma_f32 v[94:95], v[154:155], v[110:111], v[114:115]
	v_pk_fma_f32 v[92:93], v[150:151], v[108:109], v[92:93]
	v_cvt_pk_bf16_f32 v112, v100, v101
	v_cvt_pk_bf16_f32 v113, v102, v103
	v_mfma_f32_16x16x32_bf16 v[108:111], v[8:11], v[40:43], v[92:95]
	v_mul_f32_e64 v100, v140, v100
	v_mul_f32_e64 v101, v141, v101
	s_nop 0
	v_cvt_pk_bf16_f32 v92, v96, v97
	v_cvt_pk_bf16_f32 v93, v98, v99
	v_cvt_pk_bf16_f32 v94, v104, v105
	v_cvt_pk_bf16_f32 v95, v106, v107
	s_nop 0
	v_cvt_pk_bf16_f32 v114, v108, v109
	v_cvt_pk_bf16_f32 v115, v110, v111
	v_mfma_f32_16x16x32_bf16 v[92:95], v[20:23], v[92:95], 0
	s_nop 0
	v_mfma_f32_16x16x32_bf16 v[92:95], v[24:27], v[112:115], v[92:95]
	v_mul_f32_e64 v112, v146, v102
	v_mul_f32_e64 v113, v147, v103
	v_pk_mul_f32 v[102:103], v[144:145], v[102:103]
	v_pk_fma_f32 v[114:115], v[144:145], v[98:99], v[112:113] neg_lo:[0,0,1] neg_hi:[0,0,1]
	v_pk_fma_f32 v[112:113], v[140:141], v[96:97], v[116:117] neg_lo:[0,0,1] neg_hi:[0,0,1]
	v_pk_fma_f32 v[98:99], v[146:147], v[98:99], v[102:103]
	v_pk_fma_f32 v[96:97], v[142:143], v[96:97], v[100:101]
	v_pk_mul_f32 v[116:117], v[150:151], v[108:109]
	s_nop 0
	v_mfma_f32_16x16x32_bf16 v[112:115], v[12:15], v[36:39], v[112:115]
	v_mfma_f32_16x16x32_bf16 v[100:103], v[16:19], v[36:39], v[96:99]
	s_nop 2
	v_mul_f32_e64 v96, v154, v110
	v_mul_f32_e64 v97, v155, v111
	v_pk_mul_f32 v[110:111], v[152:153], v[110:111]
	v_pk_fma_f32 v[98:99], v[152:153], v[106:107], v[96:97] neg_lo:[0,0,1] neg_hi:[0,0,1]
	v_pk_fma_f32 v[96:97], v[148:149], v[104:105], v[116:117] neg_lo:[0,0,1] neg_hi:[0,0,1]
	v_pk_mul_f32 v[120:121], v[142:143], v[100:101]
	s_nop 0
	v_mfma_f32_16x16x32_bf16 v[116:119], v[4:7], v[36:39], v[96:99]
	s_nop 2
	v_mul_f32_e64 v96, v148, v108
	v_mul_f32_e64 v97, v149, v109
	v_pk_fma_f32 v[98:99], v[154:155], v[106:107], v[110:111]
	v_pk_fma_f32 v[96:97], v[150:151], v[104:105], v[96:97]
	v_cvt_pk_bf16_f32 v108, v100, v101
	v_cvt_pk_bf16_f32 v109, v102, v103
	v_mfma_f32_16x16x32_bf16 v[104:107], v[8:11], v[36:39], v[96:99]
	v_mul_f32_e64 v100, v140, v100
	v_mul_f32_e64 v101, v141, v101
	v_pk_fma_f32 v[100:101], v[142:143], v[112:113], v[100:101]
	v_cvt_pk_bf16_f32 v96, v112, v113
	v_cvt_pk_bf16_f32 v97, v114, v115
	v_cvt_pk_bf16_f32 v98, v116, v117
	v_cvt_pk_bf16_f32 v99, v118, v119
	s_nop 0
	v_cvt_pk_bf16_f32 v110, v104, v105
	v_cvt_pk_bf16_f32 v111, v106, v107
	v_mfma_f32_16x16x32_bf16 v[96:99], v[20:23], v[96:99], 0
	s_nop 0
	v_mfma_f32_16x16x32_bf16 v[96:99], v[24:27], v[108:111], v[96:99]
	v_mul_f32_e64 v108, v146, v102
	v_mul_f32_e64 v109, v147, v103
	v_pk_mul_f32 v[102:103], v[144:145], v[102:103]
	v_pk_fma_f32 v[110:111], v[144:145], v[114:115], v[108:109] neg_lo:[0,0,1] neg_hi:[0,0,1]
	v_pk_fma_f32 v[102:103], v[146:147], v[114:115], v[102:103]
	v_pk_fma_f32 v[108:109], v[140:141], v[112:113], v[120:121] neg_lo:[0,0,1] neg_hi:[0,0,1]
	v_pk_mul_f32 v[120:121], v[150:151], v[104:105]
	s_nop 0
	v_mfma_f32_16x16x32_bf16 v[112:115], v[16:19], v[56:59], v[100:103]
	s_nop 2
	v_mul_f32_e64 v100, v154, v106
	v_mul_f32_e64 v101, v155, v107
	v_mfma_f32_16x16x32_bf16 v[108:111], v[12:15], v[56:59], v[108:111]
	v_fma_f32 v102, v152, v118, -v100
	v_fma_f32 v103, v153, v119, -v101
	v_pk_fma_f32 v[100:101], v[148:149], v[116:117], v[120:121] neg_lo:[0,0,1] neg_hi:[0,0,1]
	v_pk_mul_f32 v[106:107], v[152:153], v[106:107]
	v_pk_mul_f32 v[124:125], v[142:143], v[112:113]
	v_mfma_f32_16x16x32_bf16 v[120:123], v[4:7], v[56:59], v[100:103]
	s_nop 2
	v_mul_f32_e64 v100, v148, v104
	v_mul_f32_e64 v101, v149, v105
	v_pk_fma_f32 v[102:103], v[154:155], v[118:119], v[106:107]
	v_pk_fma_f32 v[100:101], v[150:151], v[116:117], v[100:101]
	v_cvt_pk_bf16_f32 v116, v112, v113
	v_cvt_pk_bf16_f32 v117, v114, v115
	v_mfma_f32_16x16x32_bf16 v[104:107], v[8:11], v[56:59], v[100:103]
	v_mul_f32_e64 v112, v140, v112
	v_mul_f32_e64 v113, v141, v113
	s_nop 0
	v_cvt_pk_bf16_f32 v100, v108, v109
	v_cvt_pk_bf16_f32 v101, v110, v111
	v_cvt_pk_bf16_f32 v102, v120, v121
	v_cvt_pk_bf16_f32 v103, v122, v123
	s_nop 0
	v_cvt_pk_bf16_f32 v118, v104, v105
	v_cvt_pk_bf16_f32 v119, v106, v107
	v_mfma_f32_16x16x32_bf16 v[100:103], v[20:23], v[100:103], 0
	s_nop 0
	v_mfma_f32_16x16x32_bf16 v[100:103], v[24:27], v[116:119], v[100:103]
	v_mul_f32_e64 v116, v146, v114
	v_mul_f32_e64 v117, v147, v115
	v_pk_fma_f32 v[118:119], v[144:145], v[110:111], v[116:117] neg_lo:[0,0,1] neg_hi:[0,0,1]
	v_pk_fma_f32 v[116:117], v[140:141], v[108:109], v[124:125] neg_lo:[0,0,1] neg_hi:[0,0,1]
; DI unsigned pack2(float a, float b) { f32x2_t v = {a, b}; bf16x2_t r = __builtin_convertvector(v, bf16x2_t); return __builtin_bit_cast(unsigned, r); }
; DI f32x4 mfma16(bf16x8 a, bf16x8 b, f32x4 c) { return __builtin_amdgcn_mfma_f32_16x16x32_bf16(a, b, c, 0, 0, 0); }
; DI void s5_job(const PX& p, int l, int job, unsigned char* smem) {
;     ...
; #pragma unroll
;         for (int s = 0; s < 8; s++) {
;           const bf16x8 ub = u4_to_bf8(ucur[s]);
; #pragma unroll
;           for (int tt = 0; tt < 2; tt++) {
;             f32x4 cr, ci;
; #pragma unroll
;             for (int r = 0; r < 4; r++) {
;               cr[r] = lre[tt][r] * sre[tt][r] - lim[tt][r] * sim[tt][r];
;               ci[r] = lre[tt][r] * sim[tt][r] + lim[tt][r] * sre[tt][r];
;             }
;             sre[tt] = mfma16(Are[tt], ub, cr);
;             sim[tt] = mfma16(Aim[tt], ub, ci);
;           }
;           uint4 pr, pi;
;           pr.x = pack2(sre[0][0], sre[0][1]); pr.y = pack2(sre[0][2], sre[0][3]);
;           pr.z = pack2(sre[1][0], sre[1][1]); pr.w = pack2(sre[1][2], sre[1][3]);
;           pi.x = pack2(sim[0][0], sim[0][1]); pi.y = pack2(sim[0][2], sim[0][3]);
;           pi.z = pack2(sim[1][0], sim[1][1]); pi.w = pack2(sim[1][2], sim[1][3]);
;           f32x4 y = f32x4{0.f, 0.f, 0.f, 0.f};
;           y = mfma16(Cf[0], u4_to_bf8(pr), y);
;           y = mfma16(Cf[1], u4_to_bf8(pi), y);
;           yp[s] = y;
;         }
	v_pk_mul_f32 v[124:125], v[144:145], v[114:115]
	v_pk_fma_f32 v[108:109], v[142:143], v[108:109], v[112:113]
	s_nop 0
	v_mfma_f32_16x16x32_bf16 v[114:117], v[12:15], v[52:55], v[116:119]
	v_mul_f32_e64 v112, v154, v106
	v_mul_f32_e64 v113, v155, v107
	v_pk_fma_f32 v[110:111], v[146:147], v[110:111], v[124:125]
	v_pk_fma_f32 v[126:127], v[152:153], v[122:123], v[112:113] neg_lo:[0,0,1] neg_hi:[0,0,1]
	v_pk_mul_f32 v[118:119], v[150:151], v[104:105]
	v_pk_mul_f32 v[106:107], v[152:153], v[106:107]
	v_pk_fma_f32 v[124:125], v[148:149], v[120:121], v[118:119] neg_lo:[0,0,1] neg_hi:[0,0,1]
	v_pk_mul_f32 v[104:105], v[148:149], v[104:105]
	v_pk_fma_f32 v[106:107], v[154:155], v[122:123], v[106:107]
	v_mfma_f32_16x16x32_bf16 v[124:127], v[4:7], v[52:55], v[124:127]
	v_fma_f32 v104, v150, v120, v104
	v_fma_f32 v105, v151, v121, v105
	v_mfma_f32_16x16x32_bf16 v[108:111], v[16:19], v[52:55], v[108:111]
	s_nop 0
	v_mfma_f32_16x16x32_bf16 v[118:121], v[8:11], v[52:55], v[104:107]
	s_nop 2
	v_cvt_pk_bf16_f32 v104, v114, v115
	v_cvt_pk_bf16_f32 v105, v116, v117
	v_cvt_pk_bf16_f32 v106, v124, v125
	v_cvt_pk_bf16_f32 v107, v126, v127
	v_cvt_pk_bf16_f32 v128, v108, v109
	v_cvt_pk_bf16_f32 v129, v110, v111
	v_mfma_f32_16x16x32_bf16 v[104:107], v[20:23], v[104:107], 0
	v_cvt_pk_bf16_f32 v130, v118, v119
	v_cvt_pk_bf16_f32 v131, v120, v121
	v_pk_mul_f32 v[122:123], v[142:143], v[108:109]
	v_pk_mul_f32 v[112:113], v[146:147], v[110:111]
	v_mfma_f32_16x16x32_bf16 v[104:107], v[24:27], v[128:131], v[104:107]
	v_fma_f32 v128, v140, v114, -v122
	v_fma_f32 v129, v141, v115, -v123
	v_pk_mul_f32 v[122:123], v[144:145], v[110:111]
	v_pk_mul_f32 v[108:109], v[140:141], v[108:109]
	v_pk_fma_f32 v[130:131], v[144:145], v[116:117], v[112:113] neg_lo:[0,0,1] neg_hi:[0,0,1]
	v_pk_fma_f32 v[116:117], v[146:147], v[116:117], v[122:123]
	v_pk_fma_f32 v[114:115], v[142:143], v[114:115], v[108:109]
	v_pk_mul_f32 v[108:109], v[154:155], v[120:121]
	v_pk_mul_f32 v[122:123], v[150:151], v[118:119]
	s_nop 0
	v_mfma_f32_16x16x32_bf16 v[110:113], v[12:15], v[72:75], v[128:131]
	v_mul_f32_e64 v118, v148, v118
	v_mul_f32_e64 v119, v149, v119
	s_nop 0
	v_pk_fma_f32 v[130:131], v[152:153], v[126:127], v[108:109] neg_lo:[0,0,1] neg_hi:[0,0,1]
	v_pk_fma_f32 v[128:129], v[148:149], v[124:125], v[122:123] neg_lo:[0,0,1] neg_hi:[0,0,1]
	v_pk_mul_f32 v[108:109], v[152:153], v[120:121]
	v_pk_fma_f32 v[124:125], v[150:151], v[124:125], v[118:119]
	v_mfma_f32_16x16x32_bf16 v[120:123], v[4:7], v[72:75], v[128:131]
	v_fma_f32 v126, v154, v126, v108
	v_fma_f32 v127, v155, v127, v109
	v_mfma_f32_16x16x32_bf16 v[114:117], v[16:19], v[72:75], v[114:117]
	s_nop 0
	v_mfma_f32_16x16x32_bf16 v[128:131], v[8:11], v[72:75], v[124:127]
	s_nop 2
	v_cvt_pk_bf16_f32 v124, v110, v111
	v_cvt_pk_bf16_f32 v125, v112, v113
	v_cvt_pk_bf16_f32 v126, v120, v121
	v_cvt_pk_bf16_f32 v127, v122, v123
	v_cvt_pk_bf16_f32 v132, v114, v115
	v_cvt_pk_bf16_f32 v133, v116, v117
	v_mfma_f32_16x16x32_bf16 v[124:127], v[20:23], v[124:127], 0
	v_cvt_pk_bf16_f32 v134, v128, v129
	v_cvt_pk_bf16_f32 v135, v130, v131
	v_pk_mul_f32 v[108:109], v[146:147], v[116:117]
	v_pk_mul_f32 v[118:119], v[142:143], v[114:115]
	v_mfma_f32_16x16x32_bf16 v[124:127], v[24:27], v[132:135], v[124:127]
	v_fma_f32 v134, v144, v112, -v108
	v_fma_f32 v135, v145, v113, -v109
	v_pk_mul_f32 v[108:109], v[144:145], v[116:117]
	v_pk_mul_f32 v[114:115], v[140:141], v[114:115]
	v_pk_fma_f32 v[132:133], v[140:141], v[110:111], v[118:119] neg_lo:[0,0,1] neg_hi:[0,0,1]
	v_pk_fma_f32 v[112:113], v[146:147], v[112:113], v[108:109]
	v_pk_fma_f32 v[110:111], v[142:143], v[110:111], v[114:115]
	s_nop 0
	v_mfma_f32_16x16x32_bf16 v[116:119], v[12:15], v[68:71], v[132:135]
	v_mfma_f32_16x16x32_bf16 v[108:111], v[16:19], v[68:71], v[110:113]
	s_nop 1
	v_mul_f32_e64 v132, v150, v128
	v_mul_f32_e64 v133, v151, v129
	v_pk_mul_f32 v[128:129], v[148:149], v[128:129]
	v_pk_mul_f32 v[112:113], v[154:155], v[130:131]
	v_pk_mul_f32 v[130:131], v[152:153], v[130:131]
	v_pk_fma_f32 v[114:115], v[152:153], v[122:123], v[112:113] neg_lo:[0,0,1] neg_hi:[0,0,1]
	v_pk_fma_f32 v[112:113], v[148:149], v[120:121], v[132:133] neg_lo:[0,0,1] neg_hi:[0,0,1]
	v_pk_fma_f32 v[122:123], v[154:155], v[122:123], v[130:131]
	v_pk_fma_f32 v[120:121], v[150:151], v[120:121], v[128:129]
	v_mfma_f32_16x16x32_bf16 v[112:115], v[4:7], v[68:71], v[112:115]
	v_cvt_pk_bf16_f32 v128, v116, v117
	v_cvt_pk_bf16_f32 v129, v118, v119
	v_cvt_pk_bf16_f32 v132, v108, v109
	v_mfma_f32_16x16x32_bf16 v[120:123], v[8:11], v[68:71], v[120:123]
	v_cvt_pk_bf16_f32 v133, v110, v111
	s_nop 2
	v_cvt_pk_bf16_f32 v130, v112, v113
	v_cvt_pk_bf16_f32 v131, v114, v115
	v_pk_mul_f32 v[136:137], v[142:143], v[108:109]
	v_pk_mul_f32 v[108:109], v[140:141], v[108:109]
; DI unsigned pack2(float a, float b) { f32x2_t v = {a, b}; bf16x2_t r = __builtin_convertvector(v, bf16x2_t); return __builtin_bit_cast(unsigned, r); }
; DI f32x4 mfma16(bf16x8 a, bf16x8 b, f32x4 c) { return __builtin_amdgcn_mfma_f32_16x16x32_bf16(a, b, c, 0, 0, 0); }
; DI void s5_job(const PX& p, int l, int job, unsigned char* smem) {
;     ...
;             sre[tt] = mfma16(Are[tt], ub, cr);
;             sim[tt] = mfma16(Aim[tt], ub, ci);
;           }
;           uint4 pr, pi;
;           pr.x = pack2(sre[0][0], sre[0][1]); pr.y = pack2(sre[0][2], sre[0][3]);
;           pr.z = pack2(sre[1][0], sre[1][1]); pr.w = pack2(sre[1][2], sre[1][3]);
;           pi.x = pack2(sim[0][0], sim[0][1]); pi.y = pack2(sim[0][2], sim[0][3]);
;           pi.z = pack2(sim[1][0], sim[1][1]); pi.w = pack2(sim[1][2], sim[1][3]);
;           f32x4 y = f32x4{0.f, 0.f, 0.f, 0.f};
;           y = mfma16(Cf[0], u4_to_bf8(pr), y);
;           y = mfma16(Cf[1], u4_to_bf8(pi), y);
;           yp[s] = y;
;         }
;         if (hf == 1) {
; #pragma unroll
;           for (int s = 0; s < 8; s++)
; #pragma unroll
;             for (int r = 0; r < 4; r++) exb[(s * 4 + r) * 64] = yp[s][r];
;         }
;     ...
;       if (active) {
; #pragma unroll
;         for (int s = 0; s < 8; s++) ucur[s] = unext[s];
	v_mfma_f32_16x16x32_bf16 v[128:131], v[20:23], v[128:131], 0
	v_cvt_pk_bf16_f32 v134, v120, v121
	v_cvt_pk_bf16_f32 v135, v122, v123
	v_pk_fma_f32 v[108:109], v[142:143], v[116:117], v[108:109]
	s_nop 0
	v_mfma_f32_16x16x32_bf16 v[128:131], v[24:27], v[132:135], v[128:131]
	v_mul_f32_e64 v132, v146, v110
	v_mul_f32_e64 v133, v147, v111
	v_pk_mul_f32 v[110:111], v[144:145], v[110:111]
	v_pk_fma_f32 v[134:135], v[144:145], v[118:119], v[132:133] neg_lo:[0,0,1] neg_hi:[0,0,1]
	v_pk_fma_f32 v[132:133], v[140:141], v[116:117], v[136:137] neg_lo:[0,0,1] neg_hi:[0,0,1]
	v_pk_mul_f32 v[116:117], v[154:155], v[122:123]
	v_pk_fma_f32 v[110:111], v[146:147], v[118:119], v[110:111]
	s_nop 0
	v_mfma_f32_16x16x32_bf16 v[136:139], v[12:15], v[88:91], v[132:135]
	v_fma_f32 v118, v152, v114, -v116
	v_fma_f32 v119, v153, v115, -v117
	v_pk_mul_f32 v[122:123], v[152:153], v[122:123]
	v_pk_mul_f32 v[132:133], v[150:151], v[120:121]
	v_pk_fma_f32 v[114:115], v[154:155], v[114:115], v[122:123]
	v_pk_fma_f32 v[116:117], v[148:149], v[112:113], v[132:133] neg_lo:[0,0,1] neg_hi:[0,0,1]
	v_mfma_f32_16x16x32_bf16 v[108:111], v[16:19], v[88:91], v[108:111]
	s_nop 0
	v_mfma_f32_16x16x32_bf16 v[164:167], v[4:7], v[88:91], v[116:119]
	s_nop 2
	v_mul_f32_e64 v116, v148, v120
	v_mul_f32_e64 v117, v149, v121
	s_nop 0
	v_cvt_pk_bf16_f32 v120, v108, v109
	v_pk_fma_f32 v[112:113], v[150:151], v[112:113], v[116:117]
	v_cvt_pk_bf16_f32 v116, v136, v137
	v_cvt_pk_bf16_f32 v117, v138, v139
	v_mfma_f32_16x16x32_bf16 v[112:115], v[8:11], v[88:91], v[112:115]
	v_cvt_pk_bf16_f32 v118, v164, v165
	v_cvt_pk_bf16_f32 v119, v166, v167
	v_cvt_pk_bf16_f32 v121, v110, v111
	s_nop 0
	v_mfma_f32_16x16x32_bf16 v[116:119], v[20:23], v[116:119], 0
	s_nop 2
	v_cvt_pk_bf16_f32 v122, v112, v113
	v_cvt_pk_bf16_f32 v123, v114, v115
	s_nop 1
	v_mfma_f32_16x16x32_bf16 v[132:135], v[24:27], v[120:123], v[116:119]
	v_mul_f32_e64 v120, v142, v108
	v_mul_f32_e64 v121, v143, v109
	v_pk_mul_f32 v[108:109], v[140:141], v[108:109]
	v_pk_mul_f32 v[116:117], v[146:147], v[110:111]
	v_pk_mul_f32 v[110:111], v[144:145], v[110:111]
	v_pk_fma_f32 v[108:109], v[142:143], v[136:137], v[108:109]
	v_pk_fma_f32 v[110:111], v[146:147], v[138:139], v[110:111]
	v_pk_fma_f32 v[118:119], v[144:145], v[138:139], v[116:117] neg_lo:[0,0,1] neg_hi:[0,0,1]
	v_pk_fma_f32 v[116:117], v[140:141], v[136:137], v[120:121] neg_lo:[0,0,1] neg_hi:[0,0,1]
	s_nop 0
	v_mfma_f32_16x16x32_bf16 v[120:123], v[16:19], v[84:87], v[108:111]
	v_mul_f32_e64 v136, v150, v112
	v_mul_f32_e64 v137, v151, v113
	v_pk_mul_f32 v[112:113], v[148:149], v[112:113]
	v_pk_mul_f32 v[108:109], v[154:155], v[114:115]
	v_mfma_f32_16x16x32_bf16 v[116:119], v[12:15], v[84:87], v[116:119]
	v_fma_f32 v110, v152, v166, -v108
	v_fma_f32 v111, v153, v167, -v109
	v_pk_fma_f32 v[108:109], v[148:149], v[164:165], v[136:137] neg_lo:[0,0,1] neg_hi:[0,0,1]
	v_pk_mul_f32 v[114:115], v[152:153], v[114:115]
	v_pk_fma_f32 v[112:113], v[150:151], v[164:165], v[112:113]
	v_mfma_f32_16x16x32_bf16 v[108:111], v[4:7], v[84:87], v[108:111]
	v_fma_f32 v114, v154, v166, v114
	v_fma_f32 v115, v155, v167, v115
	v_cvt_pk_bf16_f32 v136, v116, v117
	v_cvt_pk_bf16_f32 v137, v118, v119
	v_mfma_f32_16x16x32_bf16 v[112:115], v[8:11], v[84:87], v[112:115]
	v_cvt_pk_bf16_f32 v164, v120, v121
	s_nop 1
	v_cvt_pk_bf16_f32 v138, v108, v109
	v_cvt_pk_bf16_f32 v139, v110, v111
	v_cvt_pk_bf16_f32 v165, v122, v123
	s_nop 0
	v_mfma_f32_16x16x32_bf16 v[136:139], v[20:23], v[136:139], 0
	v_cvt_pk_bf16_f32 v166, v112, v113
	v_cvt_pk_bf16_f32 v167, v114, v115
	s_nop 1
	v_mfma_f32_16x16x32_bf16 v[136:139], v[24:27], v[164:167], v[136:139]
	s_waitcnt vmcnt(0)
	v_mov_b64_e32 v[86:87], v[78:79]
	v_mov_b64_e32 v[84:85], v[76:77]
	v_mov_b64_e32 v[90:91], v[82:83]
	v_mov_b64_e32 v[88:89], v[80:81]
	v_mov_b64_e32 v[70:71], v[62:63]
	v_mov_b64_e32 v[68:69], v[60:61]
	v_mov_b64_e32 v[74:75], v[66:67]
	v_mov_b64_e32 v[72:73], v[64:65]
	v_mov_b64_e32 v[54:55], v[46:47]
	v_mov_b64_e32 v[52:53], v[44:45]
	v_mov_b64_e32 v[58:59], v[50:51]
	v_mov_b64_e32 v[56:57], v[48:49]
	v_mov_b64_e32 v[38:39], v[30:31]
	v_mov_b64_e32 v[36:37], v[28:29]
	v_mov_b64_e32 v[42:43], v[34:35]
	v_mov_b64_e32 v[40:41], v[32:33]
	v_mad_u32_u24 v163, v211, 12, v0
	s_and_saveexec_b64 s[16:17], s[8:9]
	s_cbranch_execz .Ls5x_w0
	ds_write_b128 v163, v[92:95]
	ds_write_b128 v163, v[96:99] offset:1024
	ds_write_b128 v163, v[100:103] offset:2048
	ds_write_b128 v163, v[104:107] offset:3072
.Ls5x_w0:
	s_or_b64 exec, exec, s[16:17]
	s_and_saveexec_b64 s[16:17], s[10:11]
	s_cbranch_execz .Ls5x_w1
	ds_write_b128 v163, v[124:127] offset:4096
	ds_write_b128 v163, v[128:131] offset:5120
	ds_write_b128 v163, v[132:135] offset:6144
	ds_write_b128 v163, v[136:139] offset:7168

; DI unsigned pack2(float a, float b) { f32x2_t v = {a, b}; bf16x2_t r = __builtin_convertvector(v, bf16x2_t); return __builtin_bit_cast(unsigned, r); }
; DI void s5_job(const PX& p, int l, int job, unsigned char* smem) {
;     ...
;       __syncthreads();
;       if (active && hf == 0) {
; #pragma unroll
;         for (int s = 0; s < 8; s++) {
;           const int st = blk * 8 + s;
;           const int t = dir ? Lseg - 1 - st : st;
;           float q[4];
; #pragma unroll
;           for (int r = 0; r < 4; r++) q[r] = yp[s][r] + exb[(s * 4 + r) * 64];
;           uint2 o;
;           o.x = pack2(q[0], q[1]); o.y = pack2(q[2], q[3]);
;           *(uint2*)(Y + (size_t)(tokbase + t) * 768) = o;
;         }
;       }
.LBB0_510:
	s_or_b64 exec, exec, s[14:15]
	s_waitcnt lgkmcnt(0)
	s_barrier
	s_and_saveexec_b64 s[14:15], s[10:11]
	s_cbranch_execz .Ls5x_r0
	ds_read_b128 v[168:171], v163
	ds_read_b128 v[172:175], v163 offset:1024
	ds_read_b128 v[176:179], v163 offset:2048
	ds_read_b128 v[180:183], v163 offset:3072
	s_add_i32 s16, s20, -15
	s_add_i32 s21, s19, 8
	s_mov_b32 s17, s16
	v_mov_b32_e32 v3, s21
	v_mov_b32_e32 v184, s17
	v_cndmask_b32_e64 v3, v3, v184, s[6:7]
	v_add_u32_e32 v3, v3, v2
	v_mad_i64_i32 v[164:165], s[22:23], v3, s81, v[158:159]
	s_waitcnt lgkmcnt(3)
	v_pk_add_f32 v[168:169], v[92:93], v[168:169]
	v_pk_add_f32 v[170:171], v[94:95], v[170:171]
	v_cvt_pk_bf16_f32 v168, v168, v169
	v_cvt_pk_bf16_f32 v169, v170, v171
	global_store_dwordx2 v[164:165], v[168:169], off
	s_xor_b32 s21, s16, -2
	s_add_i32 s17, s20, -14
	s_add_i32 s21, s21, s1
	v_mov_b32_e32 v3, s21
	v_mov_b32_e32 v184, s17
	v_cndmask_b32_e64 v3, v3, v184, s[6:7]
	v_add_u32_e32 v3, v3, v2
	v_mad_i64_i32 v[166:167], s[22:23], v3, s81, v[158:159]
	s_waitcnt lgkmcnt(2)
	v_pk_add_f32 v[172:173], v[96:97], v[172:173]
	v_pk_add_f32 v[174:175], v[98:99], v[174:175]
	v_cvt_pk_bf16_f32 v172, v172, v173
	v_cvt_pk_bf16_f32 v173, v174, v175
	global_store_dwordx2 v[166:167], v[172:173], off
	s_xor_b32 s21, s16, -3
	s_add_i32 s17, s20, -13
	s_add_i32 s21, s21, s1
	v_mov_b32_e32 v3, s21
	v_mov_b32_e32 v184, s17
	v_cndmask_b32_e64 v3, v3, v184, s[6:7]
	v_add_u32_e32 v3, v3, v2
	v_mad_i64_i32 v[164:165], s[22:23], v3, s81, v[158:159]
	s_waitcnt lgkmcnt(1)
	v_pk_add_f32 v[176:177], v[100:101], v[176:177]
	v_pk_add_f32 v[178:179], v[102:103], v[178:179]
	v_cvt_pk_bf16_f32 v176, v176, v177
	v_cvt_pk_bf16_f32 v177, v178, v179
	global_store_dwordx2 v[164:165], v[176:177], off
	s_xor_b32 s21, s16, -4
	s_add_i32 s17, s20, -12
	s_add_i32 s21, s21, s1
	v_mov_b32_e32 v3, s21
	v_mov_b32_e32 v184, s17
	v_cndmask_b32_e64 v3, v3, v184, s[6:7]
	v_add_u32_e32 v3, v3, v2
	v_mad_i64_i32 v[166:167], s[22:23], v3, s81, v[158:159]
	s_waitcnt lgkmcnt(0)
	v_pk_add_f32 v[180:181], v[104:105], v[180:181]
	v_pk_add_f32 v[182:183], v[106:107], v[182:183]
	v_cvt_pk_bf16_f32 v180, v180, v181
	v_cvt_pk_bf16_f32 v181, v182, v183
	global_store_dwordx2 v[166:167], v[180:181], off
.Ls5x_r0:
	s_or_b64 exec, exec, s[14:15]
	s_and_b64 s[16:17], s[4:5], s[8:9]
	s_and_saveexec_b64 s[14:15], s[16:17]
	s_cbranch_execz .Ls5x_r1
	ds_read_b128 v[168:171], v163 offset:4096
	ds_read_b128 v[172:175], v163 offset:5120
	ds_read_b128 v[176:179], v163 offset:6144
	ds_read_b128 v[180:183], v163 offset:7168
	s_add_i32 s16, s20, -15
	s_xor_b32 s21, s16, -5
	s_add_i32 s17, s20, -11
	s_add_i32 s21, s21, s1
	v_mov_b32_e32 v3, s21
	v_mov_b32_e32 v184, s17
	v_cndmask_b32_e64 v3, v3, v184, s[6:7]
	v_add_u32_e32 v3, v3, v2
	v_mad_i64_i32 v[164:165], s[22:23], v3, s81, v[158:159]
	s_waitcnt lgkmcnt(3)
	v_pk_add_f32 v[168:169], v[124:125], v[168:169]
	v_pk_add_f32 v[170:171], v[126:127], v[170:171]
	v_cvt_pk_bf16_f32 v168, v168, v169
	v_cvt_pk_bf16_f32 v169, v170, v171
	global_store_dwordx2 v[164:165], v[168:169], off
	s_xor_b32 s21, s16, -6
	s_add_i32 s17, s20, -10
	s_add_i32 s21, s21, s1
	v_mov_b32_e32 v3, s21
	v_mov_b32_e32 v184, s17
	v_cndmask_b32_e64 v3, v3, v184, s[6:7]
	v_add_u32_e32 v3, v3, v2
	v_mad_i64_i32 v[166:167], s[22:23], v3, s81, v[158:159]
	s_waitcnt lgkmcnt(2)
	v_pk_add_f32 v[172:173], v[128:129], v[172:173]
	v_pk_add_f32 v[174:175], v[130:131], v[174:175]
	v_cvt_pk_bf16_f32 v172, v172, v173
	v_cvt_pk_bf16_f32 v173, v174, v175
	global_store_dwordx2 v[166:167], v[172:173], off
	s_xor_b32 s21, s16, -7
	s_add_i32 s17, s20, -9
	s_add_i32 s21, s21, s1
	v_mov_b32_e32 v3, s21
	v_mov_b32_e32 v184, s17
	v_cndmask_b32_e64 v3, v3, v184, s[6:7]
	v_add_u32_e32 v3, v3, v2
	v_mad_i64_i32 v[164:165], s[22:23], v3, s81, v[158:159]
	s_waitcnt lgkmcnt(1)
	v_pk_add_f32 v[176:177], v[132:133], v[176:177]
	v_pk_add_f32 v[178:179], v[134:135], v[178:179]
	v_cvt_pk_bf16_f32 v176, v176, v177
	v_cvt_pk_bf16_f32 v177, v178, v179
	global_store_dwordx2 v[164:165], v[176:177], off
	s_xor_b32 s21, s16, -8
	s_add_i32 s17, s20, -8
	s_add_i32 s21, s21, s1
	v_mov_b32_e32 v3, s21
	v_mov_b32_e32 v184, s17
	v_cndmask_b32_e64 v3, v3, v184, s[6:7]
	v_add_u32_e32 v3, v3, v2
	v_mad_i64_i32 v[166:167], s[22:23], v3, s81, v[158:159]
	s_waitcnt lgkmcnt(0)
	v_pk_add_f32 v[180:181], v[136:137], v[180:181]
	v_pk_add_f32 v[182:183], v[138:139], v[182:183]
	v_cvt_pk_bf16_f32 v180, v180, v181
	v_cvt_pk_bf16_f32 v181, v182, v183
	global_store_dwordx2 v[166:167], v[180:181], off
.Ls5x_r1:
	s_or_b64 exec, exec, s[14:15]
	s_branch .LBB0_503

; DI float bf2f(bfu v) { return __uint_as_float(((unsigned)v) << 16); }
; DI unsigned pack2(float a, float b) { f32x2_t v = {a, b}; bf16x2_t r = __builtin_convertvector(v, bf16x2_t); return __builtin_bit_cast(unsigned, r); }
; DI float lo16(unsigned u) { return __uint_as_float(u << 16); }
; DI float hi16(unsigned u) { return __uint_as_float(u & 0xffff0000u); }
; template <int L>
; DI void hyena_job(const PX& p, int l, int c, unsigned char* smem) {
;     ...
; #pragma unroll
;   for (int ui = 0; ui < (16 * (L / 8)) / NTHR; ui++) {
;     const int u = tid + ui * NTHR;
;     const int b = u / (L / 8), s8 = (u % (L / 8)) * 8;
;     const bfu* zr = zv + b * L;
;     const uint4 mid = *(const uint4*)(zr + s8);
;     const bool lv = (s8 % RL != 0), rv = ((s8 + 8) % RL != 0);
;     const float lft = bf2f(zr[lv ? s8 - 1 : s8]) * (lv ? 1.f : 0.f);
;     const float rgt = bf2f(zr[rv ? s8 + 8 : s8]) * (rv ? 1.f : 0.f);
;     float z[10];
;     z[0] = lft; z[9] = rgt;
;     z[1] = lo16(mid.x); z[2] = hi16(mid.x); z[3] = lo16(mid.y); z[4] = hi16(mid.y);
;     z[5] = lo16(mid.z); z[6] = hi16(mid.z); z[7] = lo16(mid.w); z[8] = hi16(mid.w);
;     float o[8];
; #pragma unroll
;     for (int e = 0; e < 8; e++) o[e] = wv[0] * z[e] + wv[1] * z[e + 1] + wv[2] * z[e + 2] + wv[3];
;     uint4 pk;
;     pk.x = pack2(o[0], o[1]); pk.y = pack2(o[2], o[3]); pk.z = pack2(o[4], o[5]); pk.w = pack2(o[6], o[7]);
;     *(uint4*)(U + b * USTR + s8) = pk;
;   }
.LBB0_557:
	s_or_b64 exec, exec, s[4:5]
	v_ashrrev_i32_e32 v2, 31, v125
	v_add_u32_sdwa v2, v125, v2 dst_sel:DWORD dst_unused:UNUSED_PAD src0_sel:DWORD src1_sel:BYTE_3
	s_waitcnt vmcnt(0)
	v_ashrrev_i32_e32 v9, 8, v2
	s_mul_i32 s2, s62, 0x12000
	v_readlane_b32 s4, v253, 29
	v_mul_i32_i24_e32 v2, 0x100, v9
	s_mul_hi_i32 s1, s62, 0x12000
	v_readlane_b32 s5, v253, 30
	s_add_u32 s22, s4, s2
	v_sub_u32_e32 v24, v125, v2
	v_lshlrev_b32_e32 v4, 11, v9
	s_addc_u32 s23, s5, s1
	v_lshlrev_b32_e32 v146, 4, v125
	v_mov_b32_e32 v147, 0
	v_lshl_add_u64 v[146:147], s[22:23], 0, v[146:147]
	v_and_b32_e32 v150, 7, v125
	v_cmp_ne_u32_e32 vcc, 0, v150
	v_add_u32_e32 v150, 1, v125
	v_and_b32_e32 v150, 7, v150
	v_cmp_ne_u32_e64 s[4:5], 0, v150
	v_cndmask_b32_e64 v148, 0, -2, vcc
	v_cndmask_b32_e64 v149, 0, -1, vcc
	v_lshl_add_u64 v[148:149], v[146:147], 0, v[148:149]
	v_cndmask_b32_e64 v150, 0, 16, s[4:5]
	v_mov_b32_e32 v151, 0
	v_lshl_add_u64 v[150:151], v[146:147], 0, v[150:151]
	s_mov_b64 s[4:5], 0x2000
	global_load_ushort v189, v[148:149], off
	global_load_ushort v197, v[150:151], off
	global_load_dwordx4 v[152:155], v[146:147], off
	v_lshl_add_u64 v[146:147], v[146:147], 0, s[4:5]
	v_lshl_add_u64 v[148:149], v[148:149], 0, s[4:5]
	v_lshl_add_u64 v[150:151], v[150:151], 0, s[4:5]
	global_load_ushort v190, v[148:149], off
	global_load_ushort v198, v[150:151], off
	global_load_dwordx4 v[156:159], v[146:147], off
	v_lshl_add_u64 v[146:147], v[146:147], 0, s[4:5]
	v_lshl_add_u64 v[148:149], v[148:149], 0, s[4:5]
	v_lshl_add_u64 v[150:151], v[150:151], 0, s[4:5]
	global_load_ushort v191, v[148:149], off
	global_load_ushort v199, v[150:151], off
	global_load_dwordx4 v[160:163], v[146:147], off
	v_lshl_add_u64 v[146:147], v[146:147], 0, s[4:5]
	v_lshl_add_u64 v[148:149], v[148:149], 0, s[4:5]
	v_lshl_add_u64 v[150:151], v[150:151], 0, s[4:5]
	global_load_ushort v192, v[148:149], off
	global_load_ushort v200, v[150:151], off
	global_load_dwordx4 v[164:167], v[146:147], off
	v_lshl_add_u64 v[146:147], v[146:147], 0, s[4:5]
	v_lshl_add_u64 v[148:149], v[148:149], 0, s[4:5]
	v_lshl_add_u64 v[150:151], v[150:151], 0, s[4:5]
	global_load_ushort v193, v[148:149], off
	global_load_ushort v201, v[150:151], off
	global_load_dwordx4 v[168:171], v[146:147], off
	v_lshl_add_u64 v[146:147], v[146:147], 0, s[4:5]
	v_lshl_add_u64 v[148:149], v[148:149], 0, s[4:5]
	v_lshl_add_u64 v[150:151], v[150:151], 0, s[4:5]
	global_load_ushort v194, v[148:149], off
	global_load_ushort v202, v[150:151], off
	global_load_dwordx4 v[172:175], v[146:147], off
	v_lshl_add_u64 v[146:147], v[146:147], 0, s[4:5]
	v_lshl_add_u64 v[148:149], v[148:149], 0, s[4:5]
	v_lshl_add_u64 v[150:151], v[150:151], 0, s[4:5]
	global_load_ushort v195, v[148:149], off
	global_load_ushort v203, v[150:151], off
	global_load_dwordx4 v[176:179], v[146:147], off
	v_lshl_add_u64 v[146:147], v[146:147], 0, s[4:5]
	v_lshl_add_u64 v[148:149], v[148:149], 0, s[4:5]
	v_lshl_add_u64 v[150:151], v[150:151], 0, s[4:5]
	global_load_ushort v196, v[148:149], off
	global_load_ushort v204, v[150:151], off
	global_load_dwordx4 v[180:183], v[146:147], off
	v_lshlrev_b32_e32 v2, 3, v24
	v_ashrrev_i32_e32 v5, 31, v4
	v_lshl_add_u64 v[4:5], v[4:5], 1, s[22:23]
	v_ashrrev_i32_e32 v3, 31, v2
	v_lshl_add_u64 v[10:11], v[2:3], 1, v[4:5]
	v_and_b32_e32 v3, 7, v24
	v_cmp_ne_u32_e32 vcc, 0, v3
	v_add_u32_e32 v3, 8, v2
	v_and_b32_e32 v12, 56, v3
	v_cmp_eq_u32_e64 s[4:5], 0, v12
	v_cndmask_b32_e64 v12, 0, -1, vcc
	v_mov_b32_e32 v13, v12
	v_cndmask_b32_e64 v2, v3, v2, s[4:5]
	v_ashrrev_i32_e32 v3, 31, v2
	v_lshl_add_u64 v[12:13], v[12:13], 1, v[10:11]
	v_lshl_add_u64 v[2:3], v[2:3], 1, v[4:5]
	s_waitcnt vmcnt(21)
	v_mov_b32_e32 v12, v189
	s_mov_b32 s2, 0x10100
	v_mov_b32_e32 v2, v197
	v_cndmask_b32_e64 v3, 1.0, 0, s[4:5]
	v_cndmask_b32_e64 v13, 0, 1.0, vcc
	s_movk_i32 s3, 0x2020
	s_mov_b32 s1, 0
	s_nop 0
	v_lshlrev_b32_e32 v12, 16, v12
	v_mul_f32_e32 v13, v13, v12
	s_nop 0
	v_lshlrev_b32_e32 v2, 16, v2
	v_mul_f32_e32 v15, v3, v2
	v_mov_b64_e32 v[2:3], v[152:153]
	v_mov_b64_e32 v[4:5], v[154:155]
	s_nop 0
	v_and_b32_e32 v22, 0xffff0000, v2
	v_mov_b32_e32 v12, v22
	v_lshlrev_b32_e32 v10, 16, v2
	v_lshlrev_b32_e32 v23, 16, v3
	v_pk_mul_f32 v[12:13], v[6:7], v[12:13]
	v_pk_mov_b32 v[2:3], v[2:3], v[4:5] op_sel:[1,0]
	v_pk_fma_f32 v[10:11], v[6:7], v[10:11], v[12:13] op_sel:[0,0,1] op_sel_hi:[1,0,0]
	v_and_b32_e32 v3, 16, v3
	v_and_b32_e32 v2, 0xffff0000, v2
	v_and_b32_e32 v17, 16, v5
	v_and_b32_e32 v16, 0xffff0000, v4
	v_lshlrev_b32_e32 v19, 16, v5
	v_and_b32_e32 v21, 0xffff0000, v5
	v_pk_fma_f32 v[10:11], v[0:1], v[22:23], v[10:11] op_sel_hi:[0,1,1]
	v_lshlrev_b32_e32 v5, 16, v4
	v_mov_b32_e32 v4, v2
	v_pk_mov_b32 v[2:3], v[22:23], v[2:3] op_sel:[1,0]
	v_pk_add_f32 v[12:13], v[8:9], v[10:11] op_sel_hi:[0,1]
	v_mov_b32_e32 v10, v7
	v_pk_mul_f32 v[2:3], v[6:7], v[2:3] op_sel_hi:[0,1]
	v_pk_fma_f32 v[2:3], v[10:11], v[22:23], v[2:3] op_sel_hi:[0,1,1]
	v_pk_fma_f32 v[2:3], v[0:1], v[4:5], v[2:3] op_sel_hi:[0,1,1]
	v_pk_add_f32 v[22:23], v[8:9], v[2:3] op_sel_hi:[0,1]
	v_pk_mov_b32 v[2:3], v[4:5], v[16:17] op_sel:[1,0]
	v_mov_b32_e32 v18, v16
	v_pk_mul_f32 v[2:3], v[6:7], v[2:3] op_sel_hi:[0,1]
	v_pk_fma_f32 v[2:3], v[10:11], v[4:5], v[2:3] op_sel_hi:[0,1,1]
	v_mov_b32_e32 v20, v19
	v_pk_fma_f32 v[2:3], v[0:1], v[18:19], v[2:3] op_sel_hi:[0,1,1]
	v_pk_add_f32 v[4:5], v[8:9], v[2:3] op_sel_hi:[0,1]
	v_pk_mul_f32 v[2:3], v[6:7], v[20:21] op_sel_hi:[0,1]
	v_pk_fma_f32 v[2:3], v[10:11], v[18:19], v[2:3] op_sel_hi:[0,1,1]
	v_mov_b32_e32 v14, v21
	v_pk_fma_f32 v[2:3], v[0:1], v[14:15], v[2:3] op_sel_hi:[0,1,1]
	v_pk_add_f32 v[14:15], v[8:9], v[2:3] op_sel_hi:[0,1]
	v_mul_i32_i24_e32 v9, 0x1010, v9
	v_lshlrev_b32_e32 v11, 4, v24
	v_cvt_pk_bf16_f32 v2, v12, v13
	v_cvt_pk_bf16_f32 v3, v22, v23
	v_cvt_pk_bf16_f32 v4, v4, v5
	v_cvt_pk_bf16_f32 v5, v14, v15
	v_add3_u32 v9, v9, v11, s2
	ds_write_b128 v9, v[2:5]
	v_add_u32_e32 v2, 0x200, v125
	v_ashrrev_i32_e32 v3, 31, v2
	v_add_u32_sdwa v3, v2, v3 dst_sel:DWORD dst_unused:UNUSED_PAD src0_sel:DWORD src1_sel:BYTE_3
	v_ashrrev_i32_e32 v9, 8, v3
	v_mul_i32_i24_e32 v3, 0x100, v9
	v_sub_u32_e32 v11, v2, v3
	v_lshlrev_b32_e32 v4, 11, v9
	v_lshlrev_b32_e32 v2, 3, v11
	v_ashrrev_i32_e32 v5, 31, v4
	v_lshl_add_u64 v[4:5], v[4:5], 1, s[22:23]
	v_ashrrev_i32_e32 v3, 31, v2
	v_lshl_add_u64 v[12:13], v[2:3], 1, v[4:5]
	v_and_b32_e32 v3, 7, v11
	v_cmp_ne_u32_e32 vcc, 0, v3
	v_add_u32_e32 v3, 8, v2
	v_and_b32_e32 v14, 56, v3
	v_cmp_eq_u32_e64 s[4:5], 0, v14
	v_cndmask_b32_e64 v14, 0, -1, vcc
	v_mov_b32_e32 v15, v14
	v_cndmask_b32_e64 v2, v3, v2, s[4:5]
	v_ashrrev_i32_e32 v3, 31, v2
	v_lshl_add_u64 v[14:15], v[14:15], 1, v[12:13]
	v_lshl_add_u64 v[2:3], v[2:3], 1, v[4:5]
	s_waitcnt vmcnt(18)
; DI float bf2f(bfu v) { return __uint_as_float(((unsigned)v) << 16); }
; DI unsigned pack2(float a, float b) { f32x2_t v = {a, b}; bf16x2_t r = __builtin_convertvector(v, bf16x2_t); return __builtin_bit_cast(unsigned, r); }
; DI float lo16(unsigned u) { return __uint_as_float(u << 16); }
; DI float hi16(unsigned u) { return __uint_as_float(u & 0xffff0000u); }
; template <int L>
; DI void hyena_job(const PX& p, int l, int c, unsigned char* smem) {
;     ...
; #pragma unroll
;   for (int ui = 0; ui < (16 * (L / 8)) / NTHR; ui++) {
;     const int u = tid + ui * NTHR;
;     const int b = u / (L / 8), s8 = (u % (L / 8)) * 8;
;     const bfu* zr = zv + b * L;
;     const uint4 mid = *(const uint4*)(zr + s8);
;     const bool lv = (s8 % RL != 0), rv = ((s8 + 8) % RL != 0);
;     const float lft = bf2f(zr[lv ? s8 - 1 : s8]) * (lv ? 1.f : 0.f);
;     const float rgt = bf2f(zr[rv ? s8 + 8 : s8]) * (rv ? 1.f : 0.f);
;     float z[10];
;     z[0] = lft; z[9] = rgt;
;     z[1] = lo16(mid.x); z[2] = hi16(mid.x); z[3] = lo16(mid.y); z[4] = hi16(mid.y);
;     z[5] = lo16(mid.z); z[6] = hi16(mid.z); z[7] = lo16(mid.w); z[8] = hi16(mid.w);
;     float o[8];
; #pragma unroll
;     for (int e = 0; e < 8; e++) o[e] = wv[0] * z[e] + wv[1] * z[e + 1] + wv[2] * z[e + 2] + wv[3];
;     uint4 pk;
;     pk.x = pack2(o[0], o[1]); pk.y = pack2(o[2], o[3]); pk.z = pack2(o[4], o[5]); pk.w = pack2(o[6], o[7]);
;     *(uint4*)(U + b * USTR + s8) = pk;
;   }
	v_mov_b32_e32 v14, v190
	s_nop 0
	v_mov_b32_e32 v2, v198
	v_cndmask_b32_e64 v3, 1.0, 0, s[4:5]
	v_cndmask_b32_e64 v15, 0, 1.0, vcc
	s_nop 0
	v_lshlrev_b32_e32 v14, 16, v14
	v_mul_f32_e32 v15, v15, v14
	s_nop 0
	v_lshlrev_b32_e32 v2, 16, v2
	v_mul_f32_e32 v17, v3, v2
	v_mov_b64_e32 v[2:3], v[156:157]
	v_mov_b64_e32 v[4:5], v[158:159]
	s_nop 0
	v_lshlrev_b32_e32 v16, 16, v2
	v_and_b32_e32 v22, 0xffff0000, v2
	v_lshlrev_b32_e32 v23, 16, v3
	v_pk_mov_b32 v[2:3], v[2:3], v[4:5] op_sel:[1,0]
	v_and_b32_e32 v13, 16, v5
	v_and_b32_e32 v3, 16, v3
	v_and_b32_e32 v2, 0xffff0000, v2
	v_and_b32_e32 v12, 0xffff0000, v4
	v_lshlrev_b32_e32 v19, 16, v5
	v_and_b32_e32 v21, 0xffff0000, v5
	v_lshlrev_b32_e32 v5, 16, v4
	v_mov_b32_e32 v4, v2
	v_pk_mov_b32 v[2:3], v[22:23], v[2:3] op_sel:[1,0]
	v_mov_b32_e32 v14, v22
	v_pk_mul_f32 v[2:3], v[6:7], v[2:3] op_sel_hi:[0,1]
	v_pk_mul_f32 v[14:15], v[6:7], v[14:15]
	v_pk_fma_f32 v[2:3], v[10:11], v[22:23], v[2:3] op_sel_hi:[0,1,1]
	v_pk_fma_f32 v[14:15], v[6:7], v[16:17], v[14:15] op_sel:[0,0,1] op_sel_hi:[1,0,0]
	v_pk_fma_f32 v[2:3], v[0:1], v[4:5], v[2:3] op_sel_hi:[0,1,1]
	v_pk_fma_f32 v[14:15], v[0:1], v[22:23], v[14:15] op_sel_hi:[0,1,1]
	v_pk_add_f32 v[22:23], v[8:9], v[2:3] op_sel_hi:[0,1]
	v_pk_mov_b32 v[2:3], v[4:5], v[12:13] op_sel:[1,0]
	v_mov_b32_e32 v18, v12
	v_pk_mul_f32 v[2:3], v[6:7], v[2:3] op_sel_hi:[0,1]
	v_pk_fma_f32 v[2:3], v[10:11], v[4:5], v[2:3] op_sel_hi:[0,1,1]
	v_mov_b32_e32 v20, v19
	v_pk_fma_f32 v[2:3], v[0:1], v[18:19], v[2:3] op_sel_hi:[0,1,1]
	v_pk_add_f32 v[4:5], v[8:9], v[2:3] op_sel_hi:[0,1]
	v_pk_mul_f32 v[2:3], v[6:7], v[20:21] op_sel_hi:[0,1]
	v_pk_fma_f32 v[2:3], v[10:11], v[18:19], v[2:3] op_sel_hi:[0,1,1]
	v_mov_b32_e32 v16, v21
	v_pk_fma_f32 v[2:3], v[0:1], v[16:17], v[2:3] op_sel_hi:[0,1,1]
	v_pk_add_f32 v[14:15], v[8:9], v[14:15] op_sel_hi:[0,1]
	v_pk_add_f32 v[12:13], v[8:9], v[2:3] op_sel_hi:[0,1]
	v_mul_i32_i24_e32 v9, 0x1010, v9
	v_lshlrev_b32_e32 v11, 4, v11
	v_cvt_pk_bf16_f32 v2, v14, v15
	v_cvt_pk_bf16_f32 v3, v22, v23
	v_cvt_pk_bf16_f32 v4, v4, v5
	v_cvt_pk_bf16_f32 v5, v12, v13
	v_add3_u32 v9, v9, v11, s2
	ds_write_b128 v9, v[2:5]
	v_add_u32_e32 v2, 0x400, v125
	v_ashrrev_i32_e32 v3, 31, v2
	v_add_u32_sdwa v3, v2, v3 dst_sel:DWORD dst_unused:UNUSED_PAD src0_sel:DWORD src1_sel:BYTE_3
	v_ashrrev_i32_e32 v9, 8, v3
	v_mul_i32_i24_e32 v3, 0x100, v9
	v_sub_u32_e32 v11, v2, v3
	v_lshlrev_b32_e32 v4, 11, v9
	v_lshlrev_b32_e32 v2, 3, v11
	v_ashrrev_i32_e32 v5, 31, v4
	v_lshl_add_u64 v[4:5], v[4:5], 1, s[22:23]
	v_ashrrev_i32_e32 v3, 31, v2
	v_lshl_add_u64 v[12:13], v[2:3], 1, v[4:5]
	v_and_b32_e32 v3, 7, v11
	v_cmp_ne_u32_e32 vcc, 0, v3
	v_add_u32_e32 v3, 8, v2
	v_and_b32_e32 v14, 56, v3
	v_cmp_eq_u32_e64 s[4:5], 0, v14
	v_cndmask_b32_e64 v14, 0, -1, vcc
	v_mov_b32_e32 v15, v14
	v_cndmask_b32_e64 v2, v3, v2, s[4:5]
	v_ashrrev_i32_e32 v3, 31, v2
	v_lshl_add_u64 v[14:15], v[14:15], 1, v[12:13]
	v_lshl_add_u64 v[2:3], v[2:3], 1, v[4:5]
	s_waitcnt vmcnt(15)
	v_mov_b32_e32 v14, v191
	s_nop 0
	v_mov_b32_e32 v2, v199
	v_cndmask_b32_e64 v3, 1.0, 0, s[4:5]
	v_cndmask_b32_e64 v15, 0, 1.0, vcc
	s_nop 0
	v_lshlrev_b32_e32 v14, 16, v14
	v_mul_f32_e32 v15, v15, v14
	s_nop 0
	v_lshlrev_b32_e32 v2, 16, v2
	v_mul_f32_e32 v17, v3, v2
	v_mov_b64_e32 v[2:3], v[160:161]
	v_mov_b64_e32 v[4:5], v[162:163]
	s_nop 0
	v_lshlrev_b32_e32 v16, 16, v2
	v_and_b32_e32 v22, 0xffff0000, v2
	v_lshlrev_b32_e32 v23, 16, v3
	v_pk_mov_b32 v[2:3], v[2:3], v[4:5] op_sel:[1,0]
	v_and_b32_e32 v13, 16, v5
	v_and_b32_e32 v3, 16, v3
	v_and_b32_e32 v2, 0xffff0000, v2
	v_and_b32_e32 v12, 0xffff0000, v4
	v_lshlrev_b32_e32 v19, 16, v5
	v_and_b32_e32 v21, 0xffff0000, v5
	v_lshlrev_b32_e32 v5, 16, v4
	v_mov_b32_e32 v4, v2
	v_pk_mov_b32 v[2:3], v[22:23], v[2:3] op_sel:[1,0]
	v_mov_b32_e32 v14, v22
	v_pk_mul_f32 v[2:3], v[6:7], v[2:3] op_sel_hi:[0,1]
	v_pk_mul_f32 v[14:15], v[6:7], v[14:15]
	v_pk_fma_f32 v[2:3], v[10:11], v[22:23], v[2:3] op_sel_hi:[0,1,1]
	v_pk_fma_f32 v[14:15], v[6:7], v[16:17], v[14:15] op_sel:[0,0,1] op_sel_hi:[1,0,0]
	v_pk_fma_f32 v[2:3], v[0:1], v[4:5], v[2:3] op_sel_hi:[0,1,1]
	v_pk_fma_f32 v[14:15], v[0:1], v[22:23], v[14:15] op_sel_hi:[0,1,1]
	v_pk_add_f32 v[22:23], v[8:9], v[2:3] op_sel_hi:[0,1]
	v_pk_mov_b32 v[2:3], v[4:5], v[12:13] op_sel:[1,0]
	v_mov_b32_e32 v18, v12
	v_pk_mul_f32 v[2:3], v[6:7], v[2:3] op_sel_hi:[0,1]
	v_pk_fma_f32 v[2:3], v[10:11], v[4:5], v[2:3] op_sel_hi:[0,1,1]
	v_mov_b32_e32 v20, v19
	v_pk_fma_f32 v[2:3], v[0:1], v[18:19], v[2:3] op_sel_hi:[0,1,1]
	v_pk_add_f32 v[4:5], v[8:9], v[2:3] op_sel_hi:[0,1]
	v_pk_mul_f32 v[2:3], v[6:7], v[20:21] op_sel_hi:[0,1]
	v_pk_fma_f32 v[2:3], v[10:11], v[18:19], v[2:3] op_sel_hi:[0,1,1]
	v_mov_b32_e32 v16, v21
	v_pk_fma_f32 v[2:3], v[0:1], v[16:17], v[2:3] op_sel_hi:[0,1,1]
	v_pk_add_f32 v[14:15], v[8:9], v[14:15] op_sel_hi:[0,1]
	v_pk_add_f32 v[12:13], v[8:9], v[2:3] op_sel_hi:[0,1]
	v_mul_i32_i24_e32 v9, 0x1010, v9
	v_lshlrev_b32_e32 v11, 4, v11
	v_cvt_pk_bf16_f32 v2, v14, v15
	v_cvt_pk_bf16_f32 v3, v22, v23
	v_cvt_pk_bf16_f32 v4, v4, v5
	v_cvt_pk_bf16_f32 v5, v12, v13
	v_add3_u32 v9, v9, v11, s2
	ds_write_b128 v9, v[2:5]
	v_add_u32_e32 v2, 0x600, v125
	v_ashrrev_i32_e32 v3, 31, v2
	v_add_u32_sdwa v3, v2, v3 dst_sel:DWORD dst_unused:UNUSED_PAD src0_sel:DWORD src1_sel:BYTE_3
	v_ashrrev_i32_e32 v9, 8, v3
	v_mul_i32_i24_e32 v3, 0x100, v9
	v_sub_u32_e32 v11, v2, v3
	v_lshlrev_b32_e32 v4, 11, v9
	v_lshlrev_b32_e32 v2, 3, v11
	v_ashrrev_i32_e32 v5, 31, v4
	v_lshl_add_u64 v[4:5], v[4:5], 1, s[22:23]
	v_ashrrev_i32_e32 v3, 31, v2
	v_lshl_add_u64 v[12:13], v[2:3], 1, v[4:5]
	v_and_b32_e32 v3, 7, v11
	v_cmp_ne_u32_e32 vcc, 0, v3
	v_add_u32_e32 v3, 8, v2
	v_and_b32_e32 v14, 56, v3
	v_cmp_eq_u32_e64 s[4:5], 0, v14
	v_cndmask_b32_e64 v14, 0, -1, vcc
	v_mov_b32_e32 v15, v14
	v_cndmask_b32_e64 v2, v3, v2, s[4:5]
	v_ashrrev_i32_e32 v3, 31, v2
	v_lshl_add_u64 v[14:15], v[14:15], 1, v[12:13]
	v_lshl_add_u64 v[2:3], v[2:3], 1, v[4:5]
	s_waitcnt vmcnt(12)
; DI float bf2f(bfu v) { return __uint_as_float(((unsigned)v) << 16); }
; DI unsigned pack2(float a, float b) { f32x2_t v = {a, b}; bf16x2_t r = __builtin_convertvector(v, bf16x2_t); return __builtin_bit_cast(unsigned, r); }
; DI float lo16(unsigned u) { return __uint_as_float(u << 16); }
; DI float hi16(unsigned u) { return __uint_as_float(u & 0xffff0000u); }
; template <int L>
; DI void hyena_job(const PX& p, int l, int c, unsigned char* smem) {
;     ...
; #pragma unroll
;   for (int ui = 0; ui < (16 * (L / 8)) / NTHR; ui++) {
;     const int u = tid + ui * NTHR;
;     const int b = u / (L / 8), s8 = (u % (L / 8)) * 8;
;     const bfu* zr = zv + b * L;
;     const uint4 mid = *(const uint4*)(zr + s8);
;     const bool lv = (s8 % RL != 0), rv = ((s8 + 8) % RL != 0);
;     const float lft = bf2f(zr[lv ? s8 - 1 : s8]) * (lv ? 1.f : 0.f);
;     const float rgt = bf2f(zr[rv ? s8 + 8 : s8]) * (rv ? 1.f : 0.f);
;     float z[10];
;     z[0] = lft; z[9] = rgt;
;     z[1] = lo16(mid.x); z[2] = hi16(mid.x); z[3] = lo16(mid.y); z[4] = hi16(mid.y);
;     z[5] = lo16(mid.z); z[6] = hi16(mid.z); z[7] = lo16(mid.w); z[8] = hi16(mid.w);
;     float o[8];
; #pragma unroll
;     for (int e = 0; e < 8; e++) o[e] = wv[0] * z[e] + wv[1] * z[e + 1] + wv[2] * z[e + 2] + wv[3];
;     uint4 pk;
;     pk.x = pack2(o[0], o[1]); pk.y = pack2(o[2], o[3]); pk.z = pack2(o[4], o[5]); pk.w = pack2(o[6], o[7]);
;     *(uint4*)(U + b * USTR + s8) = pk;
;   }
	v_mov_b32_e32 v14, v192
	s_nop 0
	v_mov_b32_e32 v2, v200
	v_cndmask_b32_e64 v3, 1.0, 0, s[4:5]
	v_cndmask_b32_e64 v15, 0, 1.0, vcc
	s_nop 0
	v_lshlrev_b32_e32 v14, 16, v14
	v_mul_f32_e32 v15, v15, v14
	s_nop 0
	v_lshlrev_b32_e32 v2, 16, v2
	v_mul_f32_e32 v17, v3, v2
	v_mov_b64_e32 v[2:3], v[164:165]
	v_mov_b64_e32 v[4:5], v[166:167]
	s_nop 0
	v_lshlrev_b32_e32 v16, 16, v2
	v_and_b32_e32 v22, 0xffff0000, v2
	v_lshlrev_b32_e32 v23, 16, v3
	v_pk_mov_b32 v[2:3], v[2:3], v[4:5] op_sel:[1,0]
	v_and_b32_e32 v13, 16, v5
	v_and_b32_e32 v3, 16, v3
	v_and_b32_e32 v2, 0xffff0000, v2
	v_and_b32_e32 v12, 0xffff0000, v4
	v_lshlrev_b32_e32 v19, 16, v5
	v_and_b32_e32 v21, 0xffff0000, v5
	v_lshlrev_b32_e32 v5, 16, v4
	v_mov_b32_e32 v4, v2
	v_pk_mov_b32 v[2:3], v[22:23], v[2:3] op_sel:[1,0]
	v_mov_b32_e32 v14, v22
	v_pk_mul_f32 v[2:3], v[6:7], v[2:3] op_sel_hi:[0,1]
	v_pk_mul_f32 v[14:15], v[6:7], v[14:15]
	v_pk_fma_f32 v[2:3], v[10:11], v[22:23], v[2:3] op_sel_hi:[0,1,1]
	v_pk_fma_f32 v[14:15], v[6:7], v[16:17], v[14:15] op_sel:[0,0,1] op_sel_hi:[1,0,0]
	v_pk_fma_f32 v[2:3], v[0:1], v[4:5], v[2:3] op_sel_hi:[0,1,1]
	v_pk_fma_f32 v[14:15], v[0:1], v[22:23], v[14:15] op_sel_hi:[0,1,1]
	v_pk_add_f32 v[22:23], v[8:9], v[2:3] op_sel_hi:[0,1]
	v_pk_mov_b32 v[2:3], v[4:5], v[12:13] op_sel:[1,0]
	v_mov_b32_e32 v18, v12
	v_pk_mul_f32 v[2:3], v[6:7], v[2:3] op_sel_hi:[0,1]
	v_pk_fma_f32 v[2:3], v[10:11], v[4:5], v[2:3] op_sel_hi:[0,1,1]
	v_mov_b32_e32 v20, v19
	v_pk_fma_f32 v[2:3], v[0:1], v[18:19], v[2:3] op_sel_hi:[0,1,1]
	v_pk_add_f32 v[4:5], v[8:9], v[2:3] op_sel_hi:[0,1]
	v_pk_mul_f32 v[2:3], v[6:7], v[20:21] op_sel_hi:[0,1]
	v_pk_fma_f32 v[2:3], v[10:11], v[18:19], v[2:3] op_sel_hi:[0,1,1]
	v_mov_b32_e32 v16, v21
	v_pk_fma_f32 v[2:3], v[0:1], v[16:17], v[2:3] op_sel_hi:[0,1,1]
	v_pk_add_f32 v[14:15], v[8:9], v[14:15] op_sel_hi:[0,1]
	v_pk_add_f32 v[12:13], v[8:9], v[2:3] op_sel_hi:[0,1]
	v_mul_i32_i24_e32 v9, 0x1010, v9
	v_lshlrev_b32_e32 v11, 4, v11
	v_cvt_pk_bf16_f32 v2, v14, v15
	v_cvt_pk_bf16_f32 v3, v22, v23
	v_cvt_pk_bf16_f32 v4, v4, v5
	v_cvt_pk_bf16_f32 v5, v12, v13
	v_add3_u32 v9, v9, v11, s2
	ds_write_b128 v9, v[2:5]
	v_add_u32_e32 v2, 0x800, v125
	v_ashrrev_i32_e32 v3, 31, v2
	v_add_u32_sdwa v3, v2, v3 dst_sel:DWORD dst_unused:UNUSED_PAD src0_sel:DWORD src1_sel:BYTE_3
	v_ashrrev_i32_e32 v9, 8, v3
	v_mul_i32_i24_e32 v3, 0x100, v9
	v_sub_u32_e32 v11, v2, v3
	v_lshlrev_b32_e32 v4, 11, v9
	v_lshlrev_b32_e32 v2, 3, v11
	v_ashrrev_i32_e32 v5, 31, v4
	v_lshl_add_u64 v[4:5], v[4:5], 1, s[22:23]
	v_ashrrev_i32_e32 v3, 31, v2
	v_lshl_add_u64 v[12:13], v[2:3], 1, v[4:5]
	v_and_b32_e32 v3, 7, v11
	v_cmp_ne_u32_e32 vcc, 0, v3
	v_add_u32_e32 v3, 8, v2
	v_and_b32_e32 v14, 56, v3
	v_cmp_eq_u32_e64 s[4:5], 0, v14
	v_cndmask_b32_e64 v14, 0, -1, vcc
	v_mov_b32_e32 v15, v14
	v_cndmask_b32_e64 v2, v3, v2, s[4:5]
	v_ashrrev_i32_e32 v3, 31, v2
	v_lshl_add_u64 v[14:15], v[14:15], 1, v[12:13]
	v_lshl_add_u64 v[2:3], v[2:3], 1, v[4:5]
	s_waitcnt vmcnt(9)
	v_mov_b32_e32 v14, v193
	s_nop 0
	v_mov_b32_e32 v2, v201
	v_cndmask_b32_e64 v3, 1.0, 0, s[4:5]
	v_cndmask_b32_e64 v15, 0, 1.0, vcc
	s_nop 0
	v_lshlrev_b32_e32 v14, 16, v14
	v_mul_f32_e32 v15, v15, v14
	s_nop 0
	v_lshlrev_b32_e32 v2, 16, v2
	v_mul_f32_e32 v17, v3, v2
	v_mov_b64_e32 v[2:3], v[168:169]
	v_mov_b64_e32 v[4:5], v[170:171]
	s_nop 0
	v_lshlrev_b32_e32 v16, 16, v2
	v_and_b32_e32 v22, 0xffff0000, v2
	v_lshlrev_b32_e32 v23, 16, v3
	v_pk_mov_b32 v[2:3], v[2:3], v[4:5] op_sel:[1,0]
	v_and_b32_e32 v13, 16, v5
	v_and_b32_e32 v3, 16, v3
	v_and_b32_e32 v2, 0xffff0000, v2
	v_and_b32_e32 v12, 0xffff0000, v4
	v_lshlrev_b32_e32 v19, 16, v5
	v_and_b32_e32 v21, 0xffff0000, v5
	v_lshlrev_b32_e32 v5, 16, v4
	v_mov_b32_e32 v4, v2
	v_pk_mov_b32 v[2:3], v[22:23], v[2:3] op_sel:[1,0]
	v_mov_b32_e32 v14, v22
	v_pk_mul_f32 v[2:3], v[6:7], v[2:3] op_sel_hi:[0,1]
	v_pk_mul_f32 v[14:15], v[6:7], v[14:15]
	v_pk_fma_f32 v[2:3], v[10:11], v[22:23], v[2:3] op_sel_hi:[0,1,1]
	v_pk_fma_f32 v[14:15], v[6:7], v[16:17], v[14:15] op_sel:[0,0,1] op_sel_hi:[1,0,0]
	v_pk_fma_f32 v[2:3], v[0:1], v[4:5], v[2:3] op_sel_hi:[0,1,1]
	v_pk_fma_f32 v[14:15], v[0:1], v[22:23], v[14:15] op_sel_hi:[0,1,1]
	v_pk_add_f32 v[22:23], v[8:9], v[2:3] op_sel_hi:[0,1]
	v_pk_mov_b32 v[2:3], v[4:5], v[12:13] op_sel:[1,0]
	v_mov_b32_e32 v18, v12
	v_pk_mul_f32 v[2:3], v[6:7], v[2:3] op_sel_hi:[0,1]
	v_pk_fma_f32 v[2:3], v[10:11], v[4:5], v[2:3] op_sel_hi:[0,1,1]
	v_mov_b32_e32 v20, v19
	v_pk_fma_f32 v[2:3], v[0:1], v[18:19], v[2:3] op_sel_hi:[0,1,1]
	v_pk_add_f32 v[4:5], v[8:9], v[2:3] op_sel_hi:[0,1]
	v_pk_mul_f32 v[2:3], v[6:7], v[20:21] op_sel_hi:[0,1]
	v_pk_fma_f32 v[2:3], v[10:11], v[18:19], v[2:3] op_sel_hi:[0,1,1]
	v_mov_b32_e32 v16, v21
	v_pk_fma_f32 v[2:3], v[0:1], v[16:17], v[2:3] op_sel_hi:[0,1,1]
	v_pk_add_f32 v[14:15], v[8:9], v[14:15] op_sel_hi:[0,1]
	v_pk_add_f32 v[12:13], v[8:9], v[2:3] op_sel_hi:[0,1]
	v_mul_i32_i24_e32 v9, 0x1010, v9
	v_lshlrev_b32_e32 v11, 4, v11
	v_cvt_pk_bf16_f32 v2, v14, v15
	v_cvt_pk_bf16_f32 v3, v22, v23
	v_cvt_pk_bf16_f32 v4, v4, v5
	v_cvt_pk_bf16_f32 v5, v12, v13
	v_add3_u32 v9, v9, v11, s2
	ds_write_b128 v9, v[2:5]
	v_add_u32_e32 v2, 0xa00, v125
	v_ashrrev_i32_e32 v3, 31, v2
	v_add_u32_sdwa v3, v2, v3 dst_sel:DWORD dst_unused:UNUSED_PAD src0_sel:DWORD src1_sel:BYTE_3
	v_ashrrev_i32_e32 v9, 8, v3
	v_mul_i32_i24_e32 v3, 0x100, v9
	v_sub_u32_e32 v11, v2, v3
	v_lshlrev_b32_e32 v4, 11, v9
	v_lshlrev_b32_e32 v2, 3, v11
	v_ashrrev_i32_e32 v5, 31, v4
	v_lshl_add_u64 v[4:5], v[4:5], 1, s[22:23]
	v_ashrrev_i32_e32 v3, 31, v2
	v_lshl_add_u64 v[12:13], v[2:3], 1, v[4:5]
	v_and_b32_e32 v3, 7, v11
	v_cmp_ne_u32_e32 vcc, 0, v3
	v_add_u32_e32 v3, 8, v2
	v_and_b32_e32 v14, 56, v3
	v_cmp_eq_u32_e64 s[4:5], 0, v14
	v_cndmask_b32_e64 v14, 0, -1, vcc
	v_mov_b32_e32 v15, v14
	v_cndmask_b32_e64 v2, v3, v2, s[4:5]
	v_ashrrev_i32_e32 v3, 31, v2
	v_lshl_add_u64 v[14:15], v[14:15], 1, v[12:13]
	v_lshl_add_u64 v[2:3], v[2:3], 1, v[4:5]
	s_waitcnt vmcnt(6)
; DI float bf2f(bfu v) { return __uint_as_float(((unsigned)v) << 16); }
; DI unsigned pack2(float a, float b) { f32x2_t v = {a, b}; bf16x2_t r = __builtin_convertvector(v, bf16x2_t); return __builtin_bit_cast(unsigned, r); }
; DI float lo16(unsigned u) { return __uint_as_float(u << 16); }
; DI float hi16(unsigned u) { return __uint_as_float(u & 0xffff0000u); }
; template <int L>
; DI void hyena_job(const PX& p, int l, int c, unsigned char* smem) {
;     ...
; #pragma unroll
;   for (int ui = 0; ui < (16 * (L / 8)) / NTHR; ui++) {
;     const int u = tid + ui * NTHR;
;     const int b = u / (L / 8), s8 = (u % (L / 8)) * 8;
;     const bfu* zr = zv + b * L;
;     const uint4 mid = *(const uint4*)(zr + s8);
;     const bool lv = (s8 % RL != 0), rv = ((s8 + 8) % RL != 0);
;     const float lft = bf2f(zr[lv ? s8 - 1 : s8]) * (lv ? 1.f : 0.f);
;     const float rgt = bf2f(zr[rv ? s8 + 8 : s8]) * (rv ? 1.f : 0.f);
;     float z[10];
;     z[0] = lft; z[9] = rgt;
;     z[1] = lo16(mid.x); z[2] = hi16(mid.x); z[3] = lo16(mid.y); z[4] = hi16(mid.y);
;     z[5] = lo16(mid.z); z[6] = hi16(mid.z); z[7] = lo16(mid.w); z[8] = hi16(mid.w);
;     float o[8];
; #pragma unroll
;     for (int e = 0; e < 8; e++) o[e] = wv[0] * z[e] + wv[1] * z[e + 1] + wv[2] * z[e + 2] + wv[3];
;     uint4 pk;
;     pk.x = pack2(o[0], o[1]); pk.y = pack2(o[2], o[3]); pk.z = pack2(o[4], o[5]); pk.w = pack2(o[6], o[7]);
;     *(uint4*)(U + b * USTR + s8) = pk;
;   }
	v_mov_b32_e32 v14, v194
	s_nop 0
	v_mov_b32_e32 v2, v202
	v_cndmask_b32_e64 v3, 1.0, 0, s[4:5]
	v_cndmask_b32_e64 v15, 0, 1.0, vcc
	s_nop 0
	v_lshlrev_b32_e32 v14, 16, v14
	v_mul_f32_e32 v15, v15, v14
	s_nop 0
	v_lshlrev_b32_e32 v2, 16, v2
	v_mul_f32_e32 v17, v3, v2
	v_mov_b64_e32 v[2:3], v[172:173]
	v_mov_b64_e32 v[4:5], v[174:175]
	s_nop 0
	v_lshlrev_b32_e32 v16, 16, v2
	v_and_b32_e32 v22, 0xffff0000, v2
	v_lshlrev_b32_e32 v23, 16, v3
	v_pk_mov_b32 v[2:3], v[2:3], v[4:5] op_sel:[1,0]
	v_and_b32_e32 v13, 16, v5
	v_and_b32_e32 v3, 16, v3
	v_and_b32_e32 v2, 0xffff0000, v2
	v_and_b32_e32 v12, 0xffff0000, v4
	v_lshlrev_b32_e32 v19, 16, v5
	v_and_b32_e32 v21, 0xffff0000, v5
	v_lshlrev_b32_e32 v5, 16, v4
	v_mov_b32_e32 v4, v2
	v_pk_mov_b32 v[2:3], v[22:23], v[2:3] op_sel:[1,0]
	v_mov_b32_e32 v14, v22
	v_pk_mul_f32 v[2:3], v[6:7], v[2:3] op_sel_hi:[0,1]
	v_pk_mul_f32 v[14:15], v[6:7], v[14:15]
	v_pk_fma_f32 v[2:3], v[10:11], v[22:23], v[2:3] op_sel_hi:[0,1,1]
	v_pk_fma_f32 v[14:15], v[6:7], v[16:17], v[14:15] op_sel:[0,0,1] op_sel_hi:[1,0,0]
	v_pk_fma_f32 v[2:3], v[0:1], v[4:5], v[2:3] op_sel_hi:[0,1,1]
	v_pk_fma_f32 v[14:15], v[0:1], v[22:23], v[14:15] op_sel_hi:[0,1,1]
	v_pk_add_f32 v[22:23], v[8:9], v[2:3] op_sel_hi:[0,1]
	v_pk_mov_b32 v[2:3], v[4:5], v[12:13] op_sel:[1,0]
	v_mov_b32_e32 v18, v12
	v_pk_mul_f32 v[2:3], v[6:7], v[2:3] op_sel_hi:[0,1]
	v_pk_fma_f32 v[2:3], v[10:11], v[4:5], v[2:3] op_sel_hi:[0,1,1]
	v_mov_b32_e32 v20, v19
	v_pk_fma_f32 v[2:3], v[0:1], v[18:19], v[2:3] op_sel_hi:[0,1,1]
	v_pk_add_f32 v[4:5], v[8:9], v[2:3] op_sel_hi:[0,1]
	v_pk_mul_f32 v[2:3], v[6:7], v[20:21] op_sel_hi:[0,1]
	v_pk_fma_f32 v[2:3], v[10:11], v[18:19], v[2:3] op_sel_hi:[0,1,1]
	v_mov_b32_e32 v16, v21
	v_pk_fma_f32 v[2:3], v[0:1], v[16:17], v[2:3] op_sel_hi:[0,1,1]
	v_pk_add_f32 v[14:15], v[8:9], v[14:15] op_sel_hi:[0,1]
	v_pk_add_f32 v[12:13], v[8:9], v[2:3] op_sel_hi:[0,1]
	v_mul_i32_i24_e32 v9, 0x1010, v9
	v_lshlrev_b32_e32 v11, 4, v11
	v_cvt_pk_bf16_f32 v2, v14, v15
	v_cvt_pk_bf16_f32 v3, v22, v23
	v_cvt_pk_bf16_f32 v4, v4, v5
	v_cvt_pk_bf16_f32 v5, v12, v13
	v_add3_u32 v9, v9, v11, s2
	ds_write_b128 v9, v[2:5]
	v_add_u32_e32 v2, 0xc00, v125
	v_ashrrev_i32_e32 v3, 31, v2
	v_add_u32_sdwa v3, v2, v3 dst_sel:DWORD dst_unused:UNUSED_PAD src0_sel:DWORD src1_sel:BYTE_3
	v_ashrrev_i32_e32 v9, 8, v3
	v_mul_i32_i24_e32 v3, 0x100, v9
	v_sub_u32_e32 v11, v2, v3
	v_lshlrev_b32_e32 v4, 11, v9
	v_lshlrev_b32_e32 v2, 3, v11
	v_ashrrev_i32_e32 v5, 31, v4
	v_lshl_add_u64 v[4:5], v[4:5], 1, s[22:23]
	v_ashrrev_i32_e32 v3, 31, v2
	v_lshl_add_u64 v[12:13], v[2:3], 1, v[4:5]
	v_and_b32_e32 v3, 7, v11
	v_cmp_ne_u32_e32 vcc, 0, v3
	v_add_u32_e32 v3, 8, v2
	v_and_b32_e32 v14, 56, v3
	v_cmp_eq_u32_e64 s[4:5], 0, v14
	v_cndmask_b32_e64 v14, 0, -1, vcc
	v_mov_b32_e32 v15, v14
	v_cndmask_b32_e64 v2, v3, v2, s[4:5]
	v_ashrrev_i32_e32 v3, 31, v2
	v_lshl_add_u64 v[14:15], v[14:15], 1, v[12:13]
	v_lshl_add_u64 v[2:3], v[2:3], 1, v[4:5]
	s_waitcnt vmcnt(3)
	v_mov_b32_e32 v14, v195
	s_nop 0
	v_mov_b32_e32 v2, v203
	v_cndmask_b32_e64 v3, 1.0, 0, s[4:5]
	v_cndmask_b32_e64 v15, 0, 1.0, vcc
	s_nop 0
	v_lshlrev_b32_e32 v14, 16, v14
	v_mul_f32_e32 v15, v15, v14
	s_nop 0
	v_lshlrev_b32_e32 v2, 16, v2
	v_mul_f32_e32 v17, v3, v2
	v_mov_b64_e32 v[2:3], v[176:177]
	v_mov_b64_e32 v[4:5], v[178:179]
	s_nop 0
	v_lshlrev_b32_e32 v16, 16, v2
	v_and_b32_e32 v22, 0xffff0000, v2
	v_lshlrev_b32_e32 v23, 16, v3
	v_pk_mov_b32 v[2:3], v[2:3], v[4:5] op_sel:[1,0]
	v_and_b32_e32 v13, 16, v5
	v_and_b32_e32 v3, 16, v3
	v_and_b32_e32 v2, 0xffff0000, v2
	v_and_b32_e32 v12, 0xffff0000, v4
	v_lshlrev_b32_e32 v19, 16, v5
	v_and_b32_e32 v21, 0xffff0000, v5
	v_lshlrev_b32_e32 v5, 16, v4
	v_mov_b32_e32 v4, v2
	v_pk_mov_b32 v[2:3], v[22:23], v[2:3] op_sel:[1,0]
	v_mov_b32_e32 v14, v22
	v_pk_mul_f32 v[2:3], v[6:7], v[2:3] op_sel_hi:[0,1]
	v_pk_mul_f32 v[14:15], v[6:7], v[14:15]
	v_pk_fma_f32 v[2:3], v[10:11], v[22:23], v[2:3] op_sel_hi:[0,1,1]
	v_pk_fma_f32 v[14:15], v[6:7], v[16:17], v[14:15] op_sel:[0,0,1] op_sel_hi:[1,0,0]
	v_pk_fma_f32 v[2:3], v[0:1], v[4:5], v[2:3] op_sel_hi:[0,1,1]
	v_pk_fma_f32 v[14:15], v[0:1], v[22:23], v[14:15] op_sel_hi:[0,1,1]
	v_pk_add_f32 v[22:23], v[8:9], v[2:3] op_sel_hi:[0,1]
	v_pk_mov_b32 v[2:3], v[4:5], v[12:13] op_sel:[1,0]
	v_mov_b32_e32 v18, v12
	v_pk_mul_f32 v[2:3], v[6:7], v[2:3] op_sel_hi:[0,1]
	v_pk_fma_f32 v[2:3], v[10:11], v[4:5], v[2:3] op_sel_hi:[0,1,1]
	v_mov_b32_e32 v20, v19
	v_pk_fma_f32 v[2:3], v[0:1], v[18:19], v[2:3] op_sel_hi:[0,1,1]
	v_pk_add_f32 v[4:5], v[8:9], v[2:3] op_sel_hi:[0,1]
	v_pk_mul_f32 v[2:3], v[6:7], v[20:21] op_sel_hi:[0,1]
	v_pk_fma_f32 v[2:3], v[10:11], v[18:19], v[2:3] op_sel_hi:[0,1,1]
	v_mov_b32_e32 v16, v21
	v_pk_fma_f32 v[2:3], v[0:1], v[16:17], v[2:3] op_sel_hi:[0,1,1]
	v_pk_add_f32 v[14:15], v[8:9], v[14:15] op_sel_hi:[0,1]
	v_pk_add_f32 v[12:13], v[8:9], v[2:3] op_sel_hi:[0,1]
	v_mul_i32_i24_e32 v9, 0x1010, v9
	v_lshlrev_b32_e32 v11, 4, v11
	v_cvt_pk_bf16_f32 v2, v14, v15
	v_cvt_pk_bf16_f32 v3, v22, v23
	v_cvt_pk_bf16_f32 v4, v4, v5
	v_cvt_pk_bf16_f32 v5, v12, v13
	v_add3_u32 v9, v9, v11, s2
	ds_write_b128 v9, v[2:5]
	v_add_u32_e32 v2, 0xe00, v125
	v_ashrrev_i32_e32 v3, 31, v2
	v_add_u32_sdwa v3, v2, v3 dst_sel:DWORD dst_unused:UNUSED_PAD src0_sel:DWORD src1_sel:BYTE_3
	v_ashrrev_i32_e32 v9, 8, v3
	v_mul_i32_i24_e32 v3, 0x100, v9
	v_sub_u32_e32 v24, v2, v3
	v_lshlrev_b32_e32 v4, 11, v9
	v_lshlrev_b32_e32 v2, 3, v24
	v_ashrrev_i32_e32 v5, 31, v4
	v_lshl_add_u64 v[4:5], v[4:5], 1, s[22:23]
	v_ashrrev_i32_e32 v3, 31, v2
	v_lshl_add_u64 v[14:15], v[2:3], 1, v[4:5]
	v_and_b32_e32 v3, 7, v24
	v_cmp_ne_u32_e32 vcc, 0, v3
	v_add_u32_e32 v3, 8, v2
	v_and_b32_e32 v11, 56, v3
	v_cmp_eq_u32_e64 s[4:5], 0, v11
	v_cndmask_b32_e64 v12, 0, -1, vcc
	v_mov_b32_e32 v13, v12
	v_cndmask_b32_e64 v2, v3, v2, s[4:5]
	v_ashrrev_i32_e32 v3, 31, v2
	v_lshl_add_u64 v[12:13], v[12:13], 1, v[14:15]
	v_lshl_add_u64 v[2:3], v[2:3], 1, v[4:5]
	s_waitcnt vmcnt(0)
; DI float bf2f(bfu v) { return __uint_as_float(((unsigned)v) << 16); }
; DI unsigned pack2(float a, float b) { f32x2_t v = {a, b}; bf16x2_t r = __builtin_convertvector(v, bf16x2_t); return __builtin_bit_cast(unsigned, r); }
; DI float lo16(unsigned u) { return __uint_as_float(u << 16); }
; DI float hi16(unsigned u) { return __uint_as_float(u & 0xffff0000u); }
; template <int L>
; DI void hyena_job(const PX& p, int l, int c, unsigned char* smem) {
;     ...
; #pragma unroll
;   for (int ui = 0; ui < (16 * (L / 8)) / NTHR; ui++) {
;     const int u = tid + ui * NTHR;
;     const int b = u / (L / 8), s8 = (u % (L / 8)) * 8;
;     const bfu* zr = zv + b * L;
;     const uint4 mid = *(const uint4*)(zr + s8);
;     const bool lv = (s8 % RL != 0), rv = ((s8 + 8) % RL != 0);
;     const float lft = bf2f(zr[lv ? s8 - 1 : s8]) * (lv ? 1.f : 0.f);
;     const float rgt = bf2f(zr[rv ? s8 + 8 : s8]) * (rv ? 1.f : 0.f);
;     float z[10];
;     z[0] = lft; z[9] = rgt;
;     z[1] = lo16(mid.x); z[2] = hi16(mid.x); z[3] = lo16(mid.y); z[4] = hi16(mid.y);
;     z[5] = lo16(mid.z); z[6] = hi16(mid.z); z[7] = lo16(mid.w); z[8] = hi16(mid.w);
;     float o[8];
; #pragma unroll
;     for (int e = 0; e < 8; e++) o[e] = wv[0] * z[e] + wv[1] * z[e + 1] + wv[2] * z[e + 2] + wv[3];
;     uint4 pk;
;     pk.x = pack2(o[0], o[1]); pk.y = pack2(o[2], o[3]); pk.z = pack2(o[4], o[5]); pk.w = pack2(o[6], o[7]);
;     *(uint4*)(U + b * USTR + s8) = pk;
;   }
;   __syncthreads();
;     ...
;       const int t0 = 16 * (w * TPW + m) + 4 * kq_o;
;       const bfu* zr = zx1 + b * L;
;       const uint2 mid = *(const uint2*)(zr + t0);
;       const bool lv = (t0 % RL != 0), rv = ((t0 + 4) % RL != 0);
;       const float lft = bf2f(zr[lv ? t0 - 1 : t0]) * (lv ? 1.f : 0.f);
;       const float rgt = bf2f(zr[rv ? t0 + 4 : t0]) * (rv ? 1.f : 0.f);
	v_mov_b32_e32 v11, v196
	s_nop 0
	v_mov_b32_e32 v2, v204
	v_cndmask_b32_e64 v12, 0, 1.0, vcc
	v_cndmask_b32_e64 v3, 1.0, 0, s[4:5]
	s_nop 0
	v_lshlrev_b32_e32 v11, 16, v11
	v_mul_f32_e32 v13, v12, v11
	s_nop 0
	v_lshlrev_b32_e32 v2, 16, v2
	v_mul_f32_e32 v11, v3, v2
	v_mov_b64_e32 v[2:3], v[180:181]
	v_mov_b64_e32 v[4:5], v[182:183]
	s_nop 0
	v_lshlrev_b32_e32 v20, 16, v2
	v_and_b32_e32 v22, 0xffff0000, v2
	v_lshlrev_b32_e32 v23, 16, v3
	v_pk_mov_b32 v[2:3], v[2:3], v[4:5] op_sel:[1,0]
	v_and_b32_e32 v15, 16, v5
	v_and_b32_e32 v3, 16, v3
	v_and_b32_e32 v2, 0xffff0000, v2
	v_and_b32_e32 v14, 0xffff0000, v4
	v_lshlrev_b32_e32 v17, 16, v5
	v_and_b32_e32 v19, 0xffff0000, v5
	v_lshlrev_b32_e32 v5, 16, v4
	v_mov_b32_e32 v4, v2
	v_pk_mov_b32 v[2:3], v[22:23], v[2:3] op_sel:[1,0]
	v_mov_b32_e32 v12, v22
	v_pk_mul_f32 v[2:3], v[6:7], v[2:3] op_sel_hi:[0,1]
	v_pk_fma_f32 v[2:3], v[10:11], v[22:23], v[2:3] op_sel_hi:[0,1,1]
	v_pk_mul_f32 v[12:13], v[6:7], v[12:13]
	v_pk_fma_f32 v[2:3], v[0:1], v[4:5], v[2:3] op_sel_hi:[0,1,1]
	v_pk_fma_f32 v[12:13], v[6:7], v[20:21], v[12:13] op_sel:[0,0,1] op_sel_hi:[1,0,0]
	v_pk_add_f32 v[20:21], v[8:9], v[2:3] op_sel_hi:[0,1]
	v_pk_mov_b32 v[2:3], v[4:5], v[14:15] op_sel:[1,0]
	v_mov_b32_e32 v16, v14
	v_pk_mul_f32 v[2:3], v[6:7], v[2:3] op_sel_hi:[0,1]
	v_pk_fma_f32 v[2:3], v[10:11], v[4:5], v[2:3] op_sel_hi:[0,1,1]
	v_mov_b32_e32 v18, v17
	v_pk_fma_f32 v[2:3], v[0:1], v[16:17], v[2:3] op_sel_hi:[0,1,1]
	v_pk_add_f32 v[4:5], v[8:9], v[2:3] op_sel_hi:[0,1]
	v_pk_mul_f32 v[2:3], v[6:7], v[18:19] op_sel_hi:[0,1]
	v_pk_fma_f32 v[2:3], v[10:11], v[16:17], v[2:3] op_sel_hi:[0,1,1]
	v_mov_b32_e32 v10, v19
	v_pk_fma_f32 v[2:3], v[0:1], v[10:11], v[2:3] op_sel_hi:[0,1,1]
	v_pk_fma_f32 v[12:13], v[0:1], v[22:23], v[12:13] op_sel_hi:[0,1,1]
	v_pk_add_f32 v[6:7], v[8:9], v[2:3] op_sel_hi:[0,1]
	v_pk_add_f32 v[12:13], v[8:9], v[12:13] op_sel_hi:[0,1]
	v_cvt_pk_bf16_f32 v4, v4, v5
	v_cvt_pk_bf16_f32 v5, v6, v7
	v_mul_i32_i24_e32 v0, 0x1010, v9
	v_lshlrev_b32_e32 v6, 4, v24
	v_cvt_pk_bf16_f32 v2, v12, v13
	v_cvt_pk_bf16_f32 v3, v20, v21
	v_add3_u32 v0, v0, v6, s2
	ds_write_b128 v0, v[2:5]
	v_mov_b32_e32 v2, v188
	v_mov_b32_e32 v250, s0
	v_mov_b32_e32 v251, 0x12000
	v_mad_u64_u32 v[248:249], s[4:5], v250, v251, 0
	v_readlane_b32 s4, v253, 29
	v_readlane_b32 s5, v253, 30
	v_and_b32_e32 v250, 15, v188
	v_lshlrev_b32_e32 v250, 12, v250
	v_lshrrev_b32_e32 v251, 6, v188
	v_lshl_add_u32 v250, v251, 9, v250
	v_bfe_u32 v251, v188, 4, 2
	v_lshl_add_u32 v250, v251, 3, v250
	v_mov_b32_e32 v251, 0
	v_lshl_add_u64 v[248:249], v[248:249], 0, s[4:5]
	v_lshl_add_u64 v[248:249], v[248:249], 0, v[250:251]
	global_load_dwordx4 v[152:155], v[248:249], off offset:-4
	global_load_dwordx4 v[156:159], v[248:249], off offset:28
	global_load_dwordx4 v[160:163], v[248:249], off offset:60
	global_load_dwordx4 v[164:167], v[248:249], off offset:92
	global_load_dwordx4 v[168:171], v[248:249], off offset:124
	global_load_dwordx4 v[172:175], v[248:249], off offset:156
	global_load_dwordx4 v[176:179], v[248:249], off offset:188
	global_load_dwordx4 v[180:183], v[248:249], off offset:220
	global_load_dwordx4 v[216:219], v[248:249], off offset:252
	global_load_dwordx4 v[220:223], v[248:249], off offset:284
	global_load_dwordx4 v[224:227], v[248:249], off offset:316
	global_load_dwordx4 v[228:231], v[248:249], off offset:348
	global_load_dwordx4 v[232:235], v[248:249], off offset:380
	global_load_dwordx4 v[236:239], v[248:249], off offset:412
	global_load_dwordx4 v[240:243], v[248:249], off offset:444
	global_load_dwordx4 v[244:247], v[248:249], off offset:476
	s_waitcnt lgkmcnt(0)
	s_barrier
	s_mov_b32 s2, 0xfffffe0
	v_bfe_u32 v3, v2, 4, 2
	v_bfe_u32 v6, v2, 3, 1
	v_lshrrev_b32_e32 v7, 1, v2
	v_lshlrev_b32_e32 v5, 4, v3
	v_or_b32_e32 v3, 0x100, v3
	v_and_or_b32 v7, v7, s2, v6
	v_sub_u32_e32 v3, v3, v7
	v_and_b32_e32 v4, 7, v2
	v_lshlrev_b32_e32 v3, 4, v3
	v_mad_u32_u24 v3, v4, s3, v3
	v_subrev_u32_e32 v7, 64, v3
	ds_read_b128 v[54:57], v7
	v_add_u32_e32 v7, 0xffffffa0, v3
	ds_read_b128 v[58:61], v7
	v_add_u32_e32 v7, 0xffffff80, v3
	ds_read_b128 v[62:65], v7
	v_add_u32_e32 v7, 0xffffff60, v3
	ds_read_b128 v[70:73], v7
	v_add_u32_e32 v7, 0xffffff40, v3
	ds_read_b128 v[66:69], v7
	v_add_u32_e32 v7, 0xffffff20, v3
	ds_read_b128 v[74:77], v7
	v_add_u32_e32 v7, 0xffffff00, v3
	ds_read_b128 v[78:81], v7
	v_add_u32_e32 v7, 0xfffffee0, v3
	ds_read_b128 v[98:101], v7
	v_add_u32_e32 v7, 0xfffffec0, v3
	ds_read_b128 v[86:89], v7
	v_add_u32_e32 v7, 0xfffffea0, v3
	ds_read_b128 v[106:109], v7
	v_add_u32_e32 v7, 0xfffffe80, v3
	ds_read_b128 v[82:85], v7
	v_add_u32_e32 v7, 0xfffffe60, v3
	ds_read_b128 v[102:105], v7
	v_add_u32_e32 v7, 0xfffffe40, v3
	v_add_u32_e32 v3, 0xfffffe20, v3
	v_and_b32_e32 v0, 15, v2
	ds_read_b128 v[90:93], v7
	ds_read_b128 v[110:113], v3
	v_mad_u32_u24 v3, v4, s3, v5
	v_lshlrev_b32_e32 v4, 4, v6
	v_lshlrev_b32_e32 v2, 3, v2
	v_sub_u32_e32 v3, v3, v4
	v_and_b32_e32 v2, 0xfffffe00, v2
	v_sub_u32_e32 v2, v3, v2
	s_movk_i32 s2, 0x1010
	v_add_u32_e32 v127, 0xfe0, v2
	v_mov_b32_e32 v2, 0
	v_mad_u32_u24 v0, v0, s2, v5
	v_mov_b32_e32 v3, v2
	v_mov_b32_e32 v4, v2
	v_mov_b32_e32 v5, v2
	v_mov_b32_e32 v6, v2
	v_mov_b32_e32 v7, v2
	v_mov_b32_e32 v8, v2
	v_mov_b32_e32 v9, v2
	v_mov_b32_e32 v10, v2
	v_mov_b32_e32 v11, v2
	v_mov_b32_e32 v12, v2
	v_mov_b32_e32 v13, v2
	v_mov_b32_e32 v14, v2
	v_mov_b32_e32 v15, v2
	v_mov_b32_e32 v16, v2
	v_mov_b32_e32 v17, v2
	v_mov_b32_e32 v18, v2
	v_mov_b32_e32 v19, v2
	v_mov_b32_e32 v20, v2
	v_mov_b32_e32 v21, v2
	v_mov_b32_e32 v22, v2
	v_mov_b32_e32 v23, v2
	v_mov_b32_e32 v24, v2
	v_mov_b32_e32 v25, v2
	v_mov_b32_e32 v26, v2
	v_mov_b32_e32 v27, v2
	v_mov_b32_e32 v28, v2
	v_mov_b32_e32 v29, v2
	v_mov_b32_e32 v30, v2
	v_mov_b32_e32 v31, v2
	v_mov_b32_e32 v32, v2
	v_mov_b32_e32 v33, v2
	v_mov_b32_e32 v34, v2
	v_mov_b32_e32 v35, v2
	v_mov_b32_e32 v36, v2
	v_mov_b32_e32 v37, v2
	v_mov_b32_e32 v38, v2
	v_mov_b32_e32 v39, v2
	v_mov_b32_e32 v40, v2
	v_mov_b32_e32 v41, v2
	v_mov_b32_e32 v42, v2
	v_mov_b32_e32 v43, v2
	v_mov_b32_e32 v44, v2
	v_mov_b32_e32 v45, v2
	v_mov_b32_e32 v46, v2
	v_mov_b32_e32 v47, v2
	v_mov_b32_e32 v48, v2
	v_mov_b32_e32 v49, v2
	v_mov_b32_e32 v50, v2
	v_mov_b32_e32 v51, v2
	v_mov_b32_e32 v52, v2
	v_mov_b32_e32 v53, v2
	v_mov_b32_e32 v94, v2
	v_mov_b32_e32 v95, v2
	v_mov_b32_e32 v96, v2
	v_mov_b32_e32 v97, v2
	v_mov_b32_e32 v114, v2
	v_mov_b32_e32 v115, v2
	v_mov_b32_e32 v116, v2
	v_mov_b32_e32 v117, v2
	v_mov_b32_e32 v118, v2
	v_mov_b32_e32 v119, v2
	v_mov_b32_e32 v120, v2
	v_mov_b32_e32 v121, v2
; DI f32x4 mfma16(bf16x8 a, bf16x8 b, f32x4 c) { return __builtin_amdgcn_mfma_f32_16x16x32_bf16(a, b, c, 0, 0, 0); }
; template <int L, int TPW>
; DI void hy_mfma(const PX& p, f32x4 (&acc)[TPW], const bfu* cp, const bfu* U) {
;     ...
;   if constexpr (TPW == 16) {
;     bf16x8 F[16];
; #pragma unroll
;     for (int m = 0; m < 16; m++) F[m] = *(const bf16x8*)(cpe + 8 * (qb0 - 2 * m));
; #pragma unroll 1
;     for (int k = 0; k < NS / 8; k++) {
; #pragma unroll
;       for (int j = 0; j < 8; j++) {
;         const int ss = 8 * k + j;
;         const int qb = qb0 + 4 * ss;
;         F[(0 - 2 * j) & 15] = *(const bf16x8*)(cpe + 8 * qb);
;         F[(1 - 2 * j) & 15] = *(const bf16x8*)(cpe + 8 * (qb - 2));
;         const bf16x8 bfr = *(const bf16x8*)(Ub + 32 * ss);
; #pragma unroll
;         for (int m = 0; m < 16; m++) acc[m] = mfma16(F[(m - 2 * j) & 15], bfr, acc[m]);
;       }
;     }
.LBB0_558:
	v_add_u32_e32 v133, s1, v0
	v_add_u32_e32 v129, 0x10100, v133
	ds_read_b128 v[138:141], v129
	v_add_u32_e32 v129, s1, v127
	v_add_u32_e32 v135, 0x10180, v133
	s_addk_i32 s1, 0x200
	s_cmpk_lg_i32 s1, 0x1000
	s_waitcnt lgkmcnt(0)
	v_mfma_f32_16x16x32_bf16 v[6:9], v[90:93], v[138:141], v[6:9]
	v_mfma_f32_16x16x32_bf16 v[90:93], v[110:113], v[138:141], v[2:5]
	s_nop 2
	ds_read_b128 v[2:5], v129 offset:32
	v_mfma_f32_16x16x32_bf16 v[142:145], v[58:61], v[138:141], v[50:53]
	s_nop 2
	ds_read_b128 v[50:53], v129
	s_waitcnt lgkmcnt(1)
	v_mfma_f32_16x16x32_bf16 v[110:113], v[2:5], v[138:141], v[118:121]
	s_nop 2
	v_add_u32_e32 v118, 0x10140, v133
	ds_read_b128 v[118:121], v118
	v_mfma_f32_16x16x32_bf16 v[94:97], v[54:57], v[138:141], v[94:97]
	v_mfma_f32_16x16x32_bf16 v[46:49], v[62:65], v[138:141], v[46:49]
	v_mfma_f32_16x16x32_bf16 v[42:45], v[70:73], v[138:141], v[42:45]
	v_mfma_f32_16x16x32_bf16 v[38:41], v[66:69], v[138:141], v[38:41]
	v_mfma_f32_16x16x32_bf16 v[34:37], v[74:77], v[138:141], v[34:37]
	v_mfma_f32_16x16x32_bf16 v[30:33], v[78:81], v[138:141], v[30:33]
	v_mfma_f32_16x16x32_bf16 v[26:29], v[98:101], v[138:141], v[26:29]
	v_mfma_f32_16x16x32_bf16 v[22:25], v[86:89], v[138:141], v[22:25]
	v_mfma_f32_16x16x32_bf16 v[18:21], v[106:109], v[138:141], v[18:21]
	v_mfma_f32_16x16x32_bf16 v[14:17], v[82:85], v[138:141], v[14:17]
	v_mfma_f32_16x16x32_bf16 v[10:13], v[102:105], v[138:141], v[10:13]
	s_waitcnt lgkmcnt(1)
	v_mfma_f32_16x16x32_bf16 v[114:117], v[50:53], v[138:141], v[114:117]
	s_waitcnt lgkmcnt(0)
	v_mfma_f32_16x16x32_bf16 v[138:141], v[50:53], v[118:121], v[142:145]
	v_mfma_f32_16x16x32_bf16 v[6:9], v[82:85], v[118:121], v[6:9]
	s_nop 1
	ds_read_b128 v[142:145], v135
	v_mfma_f32_16x16x32_bf16 v[82:85], v[102:105], v[118:121], v[90:93]
	v_add_u32_e32 v102, 0x101c0, v133
	s_nop 1
	ds_read_b128 v[90:93], v129 offset:96
	v_mfma_f32_16x16x32_bf16 v[14:17], v[86:89], v[118:121], v[14:17]
	s_waitcnt lgkmcnt(1)
	v_mfma_f32_16x16x32_bf16 v[6:9], v[86:89], v[142:145], v[6:9]
	s_waitcnt lgkmcnt(0)
	v_mfma_f32_16x16x32_bf16 v[86:89], v[90:93], v[118:121], v[110:113]
	s_nop 2
	ds_read_b128 v[110:113], v129 offset:64
	v_mfma_f32_16x16x32_bf16 v[94:97], v[2:5], v[118:121], v[94:97]
	v_mfma_f32_16x16x32_bf16 v[46:49], v[54:57], v[118:121], v[46:49]
	v_mfma_f32_16x16x32_bf16 v[42:45], v[58:61], v[118:121], v[42:45]
	v_mfma_f32_16x16x32_bf16 v[38:41], v[62:65], v[118:121], v[38:41]
	v_mfma_f32_16x16x32_bf16 v[34:37], v[70:73], v[118:121], v[34:37]
	v_mfma_f32_16x16x32_bf16 v[30:33], v[66:69], v[118:121], v[30:33]
	v_mfma_f32_16x16x32_bf16 v[26:29], v[74:77], v[118:121], v[26:29]
	v_mfma_f32_16x16x32_bf16 v[22:25], v[78:81], v[118:121], v[22:25]
	v_mfma_f32_16x16x32_bf16 v[18:21], v[98:101], v[118:121], v[18:21]
	v_mfma_f32_16x16x32_bf16 v[10:13], v[106:109], v[118:121], v[10:13]
	v_mfma_f32_16x16x32_bf16 v[82:85], v[106:109], v[142:145], v[82:85]
	s_waitcnt lgkmcnt(0)
	v_mfma_f32_16x16x32_bf16 v[106:109], v[110:113], v[118:121], v[114:117]
	ds_read_b128 v[118:121], v102
	ds_read_b128 v[102:105], v129 offset:128
	v_mfma_f32_16x16x32_bf16 v[14:17], v[78:81], v[142:145], v[14:17]
	s_waitcnt lgkmcnt(1)
	v_mfma_f32_16x16x32_bf16 v[6:9], v[78:81], v[118:121], v[6:9]
	v_mfma_f32_16x16x32_bf16 v[78:81], v[98:101], v[118:121], v[82:85]
	s_nop 2
	ds_read_b128 v[82:85], v129 offset:160
	v_mfma_f32_16x16x32_bf16 v[10:13], v[98:101], v[142:145], v[10:13]
	s_waitcnt lgkmcnt(0)
	v_mfma_f32_16x16x32_bf16 v[98:101], v[82:85], v[142:145], v[86:89]
	s_nop 2
	v_add_u32_e32 v86, 0x10200, v133
	v_mfma_f32_16x16x32_bf16 v[46:49], v[2:5], v[142:145], v[46:49]
	v_mfma_f32_16x16x32_bf16 v[42:45], v[50:53], v[142:145], v[42:45]
	v_mfma_f32_16x16x32_bf16 v[38:41], v[54:57], v[142:145], v[38:41]
	v_mfma_f32_16x16x32_bf16 v[34:37], v[58:61], v[142:145], v[34:37]
	v_mfma_f32_16x16x32_bf16 v[30:33], v[62:65], v[142:145], v[30:33]
	v_mfma_f32_16x16x32_bf16 v[26:29], v[70:73], v[142:145], v[26:29]
	v_mfma_f32_16x16x32_bf16 v[22:25], v[66:69], v[142:145], v[22:25]
	v_mfma_f32_16x16x32_bf16 v[18:21], v[74:77], v[142:145], v[18:21]
	v_mfma_f32_16x16x32_bf16 v[94:97], v[90:93], v[142:145], v[94:97]
	v_mfma_f32_16x16x32_bf16 v[114:117], v[110:113], v[142:145], v[138:141]
	v_mfma_f32_16x16x32_bf16 v[138:141], v[102:105], v[142:145], v[106:109]
	ds_read_b128 v[142:145], v86
	s_nop 1
	ds_read_b128 v[106:109], v129 offset:192
	ds_read_b128 v[86:89], v129 offset:224
	v_mfma_f32_16x16x32_bf16 v[14:17], v[66:69], v[118:121], v[14:17]
	s_waitcnt lgkmcnt(2)
	v_mfma_f32_16x16x32_bf16 v[6:9], v[66:69], v[142:145], v[6:9]
	v_mfma_f32_16x16x32_bf16 v[66:69], v[74:77], v[142:145], v[78:81]
	s_nop 2
	v_add_u32_e32 v78, 0x10240, v133
	v_mfma_f32_16x16x32_bf16 v[46:49], v[90:93], v[118:121], v[46:49]
	v_mfma_f32_16x16x32_bf16 v[42:45], v[110:113], v[118:121], v[42:45]
	v_mfma_f32_16x16x32_bf16 v[38:41], v[2:5], v[118:121], v[38:41]
	v_mfma_f32_16x16x32_bf16 v[34:37], v[50:53], v[118:121], v[34:37]
	v_mfma_f32_16x16x32_bf16 v[30:33], v[54:57], v[118:121], v[30:33]
	v_mfma_f32_16x16x32_bf16 v[26:29], v[58:61], v[118:121], v[26:29]
	v_mfma_f32_16x16x32_bf16 v[22:25], v[62:65], v[118:121], v[22:25]
	v_mfma_f32_16x16x32_bf16 v[18:21], v[70:73], v[118:121], v[18:21]
	v_mfma_f32_16x16x32_bf16 v[10:13], v[74:77], v[118:121], v[10:13]
	v_mfma_f32_16x16x32_bf16 v[94:97], v[82:85], v[118:121], v[94:97]
	v_mfma_f32_16x16x32_bf16 v[114:117], v[102:105], v[118:121], v[114:117]
	s_waitcnt lgkmcnt(0)
	v_mfma_f32_16x16x32_bf16 v[74:77], v[86:89], v[118:121], v[98:101]
	v_mfma_f32_16x16x32_bf16 v[118:121], v[106:109], v[118:121], v[138:141]
	s_nop 1
	ds_read_b128 v[98:101], v129 offset:256
	ds_read_b128 v[138:141], v78
	ds_read_b128 v[78:81], v129 offset:288
	v_mfma_f32_16x16x32_bf16 v[14:17], v[62:65], v[142:145], v[14:17]
	s_waitcnt lgkmcnt(1)
; DI f32x4 mfma16(bf16x8 a, bf16x8 b, f32x4 c) { return __builtin_amdgcn_mfma_f32_16x16x32_bf16(a, b, c, 0, 0, 0); }
; template <int L, int TPW>
; DI void hy_mfma(const PX& p, f32x4 (&acc)[TPW], const bfu* cp, const bfu* U) {
;     ...
;   if constexpr (TPW == 16) {
;     bf16x8 F[16];
; #pragma unroll
;     for (int m = 0; m < 16; m++) F[m] = *(const bf16x8*)(cpe + 8 * (qb0 - 2 * m));
; #pragma unroll 1
;     for (int k = 0; k < NS / 8; k++) {
; #pragma unroll
;       for (int j = 0; j < 8; j++) {
;         const int ss = 8 * k + j;
;         const int qb = qb0 + 4 * ss;
;         F[(0 - 2 * j) & 15] = *(const bf16x8*)(cpe + 8 * qb);
;         F[(1 - 2 * j) & 15] = *(const bf16x8*)(cpe + 8 * (qb - 2));
;         const bf16x8 bfr = *(const bf16x8*)(Ub + 32 * ss);
; #pragma unroll
;         for (int m = 0; m < 16; m++) acc[m] = mfma16(F[(m - 2 * j) & 15], bfr, acc[m]);
;       }
;     }
	v_mfma_f32_16x16x32_bf16 v[6:9], v[62:65], v[138:141], v[6:9]
	v_mfma_f32_16x16x32_bf16 v[62:65], v[70:73], v[138:141], v[66:69]
	s_nop 2
	v_add_u32_e32 v66, 0x10280, v133
	v_mfma_f32_16x16x32_bf16 v[46:49], v[82:85], v[142:145], v[46:49]
	v_mfma_f32_16x16x32_bf16 v[42:45], v[102:105], v[142:145], v[42:45]
	v_mfma_f32_16x16x32_bf16 v[38:41], v[90:93], v[142:145], v[38:41]
	v_mfma_f32_16x16x32_bf16 v[34:37], v[110:113], v[142:145], v[34:37]
	v_mfma_f32_16x16x32_bf16 v[30:33], v[2:5], v[142:145], v[30:33]
	v_mfma_f32_16x16x32_bf16 v[26:29], v[50:53], v[142:145], v[26:29]
	v_mfma_f32_16x16x32_bf16 v[22:25], v[54:57], v[142:145], v[22:25]
	v_mfma_f32_16x16x32_bf16 v[18:21], v[58:61], v[142:145], v[18:21]
	v_mfma_f32_16x16x32_bf16 v[10:13], v[70:73], v[142:145], v[10:13]
	v_mfma_f32_16x16x32_bf16 v[94:97], v[86:89], v[142:145], v[94:97]
	v_mfma_f32_16x16x32_bf16 v[114:117], v[106:109], v[142:145], v[114:117]
	s_waitcnt lgkmcnt(0)
	v_mfma_f32_16x16x32_bf16 v[70:73], v[78:81], v[142:145], v[74:77]
	v_mfma_f32_16x16x32_bf16 v[118:121], v[98:101], v[142:145], v[118:121]
	ds_read_b128 v[142:145], v66
	s_nop 0
	ds_read_b128 v[74:77], v129 offset:320
	ds_read_b128 v[66:69], v129 offset:352
	v_mfma_f32_16x16x32_bf16 v[14:17], v[54:57], v[138:141], v[14:17]
	s_waitcnt lgkmcnt(2)
	v_mfma_f32_16x16x32_bf16 v[6:9], v[54:57], v[142:145], v[6:9]
	v_mfma_f32_16x16x32_bf16 v[54:57], v[58:61], v[142:145], v[62:65]
	s_nop 2
	v_add_u32_e32 v62, 0x102c0, v133
	v_mfma_f32_16x16x32_bf16 v[46:49], v[86:89], v[138:141], v[46:49]
	v_mfma_f32_16x16x32_bf16 v[42:45], v[106:109], v[138:141], v[42:45]
	v_mfma_f32_16x16x32_bf16 v[38:41], v[82:85], v[138:141], v[38:41]
	v_mfma_f32_16x16x32_bf16 v[34:37], v[102:105], v[138:141], v[34:37]
	v_mfma_f32_16x16x32_bf16 v[30:33], v[90:93], v[138:141], v[30:33]
	v_mfma_f32_16x16x32_bf16 v[26:29], v[110:113], v[138:141], v[26:29]
	v_mfma_f32_16x16x32_bf16 v[22:25], v[2:5], v[138:141], v[22:25]
	v_mfma_f32_16x16x32_bf16 v[18:21], v[50:53], v[138:141], v[18:21]
	v_mfma_f32_16x16x32_bf16 v[10:13], v[58:61], v[138:141], v[10:13]
	v_mfma_f32_16x16x32_bf16 v[94:97], v[78:81], v[138:141], v[94:97]
	v_mfma_f32_16x16x32_bf16 v[114:117], v[98:101], v[138:141], v[114:117]
	s_waitcnt lgkmcnt(0)
	v_mfma_f32_16x16x32_bf16 v[58:61], v[66:69], v[138:141], v[70:73]
	v_mfma_f32_16x16x32_bf16 v[118:121], v[74:77], v[138:141], v[118:121]
	ds_read_b128 v[138:141], v62
	s_nop 0
	ds_read_b128 v[70:73], v129 offset:384
	ds_read_b128 v[62:65], v129 offset:416
	v_mfma_f32_16x16x32_bf16 v[14:17], v[2:5], v[142:145], v[14:17]
	s_waitcnt lgkmcnt(2)
	v_mfma_f32_16x16x32_bf16 v[6:9], v[2:5], v[138:141], v[6:9]
	v_mfma_f32_16x16x32_bf16 v[2:5], v[50:53], v[138:141], v[54:57]
	s_nop 2
	ds_read_b128 v[54:57], v129 offset:480
	s_waitcnt lgkmcnt(1)
	v_mfma_f32_16x16x32_bf16 v[58:61], v[62:65], v[142:145], v[58:61]
	v_mfma_f32_16x16x32_bf16 v[46:49], v[78:81], v[142:145], v[46:49]
	v_mfma_f32_16x16x32_bf16 v[42:45], v[98:101], v[142:145], v[42:45]
	v_mfma_f32_16x16x32_bf16 v[38:41], v[86:89], v[142:145], v[38:41]
	v_mfma_f32_16x16x32_bf16 v[34:37], v[106:109], v[142:145], v[34:37]
	v_mfma_f32_16x16x32_bf16 v[30:33], v[82:85], v[142:145], v[30:33]
	v_mfma_f32_16x16x32_bf16 v[26:29], v[102:105], v[142:145], v[26:29]
	v_mfma_f32_16x16x32_bf16 v[22:25], v[90:93], v[142:145], v[22:25]
	v_mfma_f32_16x16x32_bf16 v[18:21], v[110:113], v[142:145], v[18:21]
	v_mfma_f32_16x16x32_bf16 v[10:13], v[50:53], v[142:145], v[10:13]
	v_mfma_f32_16x16x32_bf16 v[94:97], v[66:69], v[142:145], v[94:97]
	v_mfma_f32_16x16x32_bf16 v[114:117], v[74:77], v[142:145], v[114:117]
	v_mfma_f32_16x16x32_bf16 v[142:145], v[70:73], v[142:145], v[118:121]
	s_waitcnt lgkmcnt(0)
	v_mfma_f32_16x16x32_bf16 v[118:121], v[54:57], v[138:141], v[58:61]
	s_nop 2
	ds_read_b128 v[58:61], v129 offset:448
	v_mfma_f32_16x16x32_bf16 v[46:49], v[66:69], v[138:141], v[46:49]
	v_mfma_f32_16x16x32_bf16 v[42:45], v[74:77], v[138:141], v[42:45]
	v_mfma_f32_16x16x32_bf16 v[38:41], v[78:81], v[138:141], v[38:41]
	v_mfma_f32_16x16x32_bf16 v[34:37], v[98:101], v[138:141], v[34:37]
	v_mfma_f32_16x16x32_bf16 v[30:33], v[86:89], v[138:141], v[30:33]
	v_mfma_f32_16x16x32_bf16 v[26:29], v[106:109], v[138:141], v[26:29]
	v_mfma_f32_16x16x32_bf16 v[22:25], v[82:85], v[138:141], v[22:25]
	v_mfma_f32_16x16x32_bf16 v[18:21], v[102:105], v[138:141], v[18:21]
	v_mfma_f32_16x16x32_bf16 v[14:17], v[90:93], v[138:141], v[14:17]
	v_mfma_f32_16x16x32_bf16 v[10:13], v[110:113], v[138:141], v[10:13]
	v_mfma_f32_16x16x32_bf16 v[94:97], v[62:65], v[138:141], v[94:97]
	v_mfma_f32_16x16x32_bf16 v[50:53], v[70:73], v[138:141], v[114:117]
	s_waitcnt lgkmcnt(0)
	v_mfma_f32_16x16x32_bf16 v[114:117], v[58:61], v[138:141], v[142:145]
	s_cbranch_scc1 .LBB0_558
; #define OPAQUE(x) asm volatile("" : "+v"(x))
; DI float bf2f(bfu v) { return __uint_as_float(((unsigned)v) << 16); }
; DI unsigned pack2(float a, float b) { f32x2_t v = {a, b}; bf16x2_t r = __builtin_convertvector(v, bf16x2_t); return __builtin_bit_cast(unsigned, r); }
; DI float lo16(unsigned u) { return __uint_as_float(u << 16); }
; DI float hi16(unsigned u) { return __uint_as_float(u & 0xffff0000u); }
; template <int L>
; DI void hyena_job(const PX& p, int l, int c, unsigned char* smem) {
;     ...
;     int kq_o = kq;
;     OPAQUE(kq_o);
; #pragma unroll
;     for (int m = 0; m < TPW; m++) {
;       const int t0 = 16 * (w * TPW + m) + 4 * kq_o;
;       const bfu* zr = zx1 + b * L;
;       const uint2 mid = *(const uint2*)(zr + t0);
;       const bool lv = (t0 % RL != 0), rv = ((t0 + 4) % RL != 0);
;       const float lft = bf2f(zr[lv ? t0 - 1 : t0]) * (lv ? 1.f : 0.f);
;       const float rgt = bf2f(zr[rv ? t0 + 4 : t0]) * (rv ? 1.f : 0.f);
;       float z[6];
;       z[0] = lft; z[5] = rgt; z[1] = lo16(mid.x); z[2] = hi16(mid.x); z[3] = lo16(mid.y); z[4] = hi16(mid.y);
;       const uint2 vu = *(const uint2*)(U + b * USTR + t0);
;       const float vv[4] = {lo16(vu.x), hi16(vu.x), lo16(vu.y), hi16(vu.y)};
;       float y[4];
; #pragma unroll
;       for (int r = 0; r < 4; r++) {
;         const float x1 = w1[0] * z[r] + w1[1] * z[r + 1] + w1[2] * z[r + 2] + w1[3];
;         y[r] = x1 * (acc[m][r] + bias0 * vv[r]);
;       }
;       y1pk[m].x = pack2(y[0], y[1]);
;       y1pk[m].y = pack2(y[2], y[3]);
;     }
	s_waitcnt vmcnt(0)
	s_mul_hi_i32 s1, s0, 0x12000
	s_mul_i32 s0, s0, 0x12000
	v_readlane_b32 s2, v253, 29
	v_readlane_b32 s3, v253, 30
	s_add_u32 s0, s2, s0
	v_and_b32_e32 v68, 15, v125
	v_ashrrev_i32_e32 v69, 6, v125
	s_addc_u32 s1, s3, s1
	v_bfe_u32 v125, v125, 4, 2
	v_lshlrev_b32_e32 v0, 12, v68
	v_mov_b32_e32 v54, v125
	v_lshlrev_b32_e32 v127, 8, v69
	v_lshl_add_u64 v[64:65], s[0:1], 0, v[0:1]
	s_movk_i32 s0, 0x1010
	v_mov_b32_e32 v0, 0x10100
	v_mad_u32_u24 v70, v68, s0, v0
	v_lshl_add_u32 v66, v54, 2, v127
	v_and_b32_e32 v0, 15, v54
	v_cmp_ne_u32_e32 vcc, 0, v0
	v_add_u32_e32 v0, 4, v66
	v_and_b32_e32 v54, 60, v0
	v_ashrrev_i32_e32 v67, 31, v66
	v_cmp_eq_u32_e64 s[4:5], 0, v54
	v_cndmask_b32_e64 v54, 0, -1, vcc
	v_lshl_add_u64 v[62:63], v[66:67], 1, v[64:65]
	v_mov_b32_e32 v55, v54
	v_lshl_add_u64 v[54:55], v[54:55], 1, v[62:63]
	v_lshrrev_b32_e32 v54, 16, v152
	v_cndmask_b32_e64 v71, 0, 1.0, vcc
	v_mov_b32_e32 v74, v153
	v_mov_b32_e32 v75, v154
	v_lshl_add_u32 v67, v66, 1, v70
	v_lshl_add_u32 v129, v69, 9, v70
	s_add_u32 s24, s24, 0x600000
	s_movk_i32 s0, 0x1000
	s_addc_u32 s25, s25, 0
	v_mov_b32_e32 v78, v161
	v_mov_b32_e32 v79, v162
	s_nop 0
	v_lshlrev_b32_e32 v54, 16, v54
	v_mul_f32_e32 v59, v71, v54
	v_cndmask_b32_e64 v54, v0, v66, s[4:5]
	v_ashrrev_i32_e32 v55, 31, v54
	v_lshl_add_u64 v[54:55], v[54:55], 1, v[64:65]
	v_and_b32_e32 v0, 0xffff, v155
	v_cndmask_b32_e64 v54, 1.0, 0, s[4:5]
	s_nop 0
	v_and_b32_e32 v76, 0xffff0000, v74
	v_mov_b32_e32 v58, v76
	v_pk_mul_f32 v[58:59], v[130:131], v[58:59]
	v_lshlrev_b32_e32 v77, 16, v75
	v_and_b32_e32 v75, 0xffff0000, v75
	v_mov_b32_e32 v60, v75
	s_nop 0
	v_and_b32_e32 v80, 0xffff0000, v78
	v_lshlrev_b32_e32 v81, 16, v79
	v_and_b32_e32 v79, 0xffff0000, v79
	s_nop 0
	v_lshlrev_b32_e32 v0, 16, v0
	v_mul_f32_e32 v61, v54, v0
	ds_read2_b64 v[54:57], v67 offset1:4
	v_lshlrev_b32_e32 v0, 16, v74
	v_pk_fma_f32 v[58:59], v[130:131], v[0:1], v[58:59] op_sel:[0,0,1] op_sel_hi:[1,0,0]
	v_mov_b32_e32 v74, v77
	v_pk_fma_f32 v[58:59], v[134:135], v[76:77], v[58:59] op_sel_hi:[0,1,1]
	s_waitcnt lgkmcnt(0)
	v_lshlrev_b32_e32 v72, 16, v54
	v_and_b32_e32 v73, 0xffff0000, v54
	v_pk_fma_f32 v[72:73], v[136:137], v[72:73], v[118:119] op_sel_hi:[0,1,1]
	v_pk_add_f32 v[58:59], v[132:133], v[58:59] op_sel_hi:[0,1]
	v_pk_mul_f32 v[58:59], v[58:59], v[72:73]
	v_mov_b32_e32 v0, v131
	v_pk_mul_f32 v[72:73], v[130:131], v[74:75] op_sel_hi:[0,1]
	v_pk_fma_f32 v[72:73], v[0:1], v[76:77], v[72:73] op_sel_hi:[0,1,1]
	v_lshlrev_b32_e32 v54, 16, v55
	v_and_b32_e32 v55, 0xffff0000, v55
	v_pk_fma_f32 v[60:61], v[134:135], v[60:61], v[72:73] op_sel_hi:[0,1,1]
	v_pk_add_f32 v[60:61], v[132:133], v[60:61] op_sel_hi:[0,1]
	v_pk_fma_f32 v[54:55], v[136:137], v[54:55], v[120:121] op_sel_hi:[0,1,1]
	v_pk_mul_f32 v[54:55], v[54:55], v[60:61]
	v_add_u32_e32 v60, 16, v66
	v_cvt_pk_bf16_f32 v58, v58, v59
	v_cvt_pk_bf16_f32 v59, v54, v55
	v_and_b32_e32 v54, 60, v60
	v_add_u32_e32 v61, 20, v66
	v_cmp_ne_u32_e64 s[4:5], 0, v54
	v_and_b32_e32 v54, 60, v61
	v_cmp_eq_u32_e64 s[6:7], 0, v54
	v_subbrev_co_u32_e64 v54, s[8:9], 0, v60, s[4:5]
	v_ashrrev_i32_e32 v55, 31, v54
	v_lshl_add_u64 v[54:55], v[54:55], 1, v[64:65]
	v_lshrrev_b32_e32 v54, 16, v156
	v_cndmask_b32_e64 v60, v61, v60, s[6:7]
	v_ashrrev_i32_e32 v61, 31, v60
	v_lshl_add_u64 v[60:61], v[60:61], 1, v[64:65]
	v_mov_b32_e32 v74, v157
	v_mov_b32_e32 v75, v158
	v_cndmask_b32_e64 v55, 0, 1.0, s[4:5]
	v_lshlrev_b32_e32 v72, 16, v56
	v_and_b32_e32 v73, 0xffff0000, v56
	v_pk_fma_f32 v[72:73], v[136:137], v[72:73], v[114:115] op_sel_hi:[0,1,1]
	v_lshlrev_b32_e32 v56, 16, v57
	v_and_b32_e32 v57, 0xffff0000, v57
	v_pk_fma_f32 v[56:57], v[136:137], v[56:57], v[116:117] op_sel_hi:[0,1,1]
	s_nop 0
	v_lshlrev_b32_e32 v54, 16, v54
	v_mul_f32_e32 v55, v55, v54
	v_and_b32_e32 v54, 0xffff, v159
	v_cndmask_b32_e64 v60, 1.0, 0, s[6:7]
	s_nop 0
	v_and_b32_e32 v76, 0xffff0000, v74
	v_lshlrev_b32_e32 v77, 16, v75
	v_and_b32_e32 v75, 0xffff0000, v75
	s_nop 0
	v_lshlrev_b32_e32 v54, 16, v54
	v_mul_f32_e32 v61, v60, v54
	v_mov_b32_e32 v54, v76
	v_lshlrev_b32_e32 v60, 16, v74
	v_pk_mul_f32 v[54:55], v[130:131], v[54:55]
	v_mov_b32_e32 v74, v77
	v_pk_fma_f32 v[54:55], v[130:131], v[60:61], v[54:55] op_sel:[0,0,1] op_sel_hi:[1,0,0]
	v_mov_b32_e32 v60, v75
	v_pk_fma_f32 v[54:55], v[134:135], v[76:77], v[54:55] op_sel_hi:[0,1,1]
	v_pk_add_f32 v[54:55], v[132:133], v[54:55] op_sel_hi:[0,1]
	v_pk_mul_f32 v[54:55], v[54:55], v[72:73]
	v_pk_mul_f32 v[72:73], v[130:131], v[74:75] op_sel_hi:[0,1]
	v_pk_fma_f32 v[72:73], v[0:1], v[76:77], v[72:73] op_sel_hi:[0,1,1]
	v_pk_fma_f32 v[60:61], v[134:135], v[60:61], v[72:73] op_sel_hi:[0,1,1]
	v_pk_add_f32 v[60:61], v[132:133], v[60:61] op_sel_hi:[0,1]
	v_pk_mul_f32 v[56:57], v[56:57], v[60:61]
	v_cvt_pk_bf16_f32 v60, v54, v55
	v_cvt_pk_bf16_f32 v61, v56, v57
	v_add_u32_e32 v56, 32, v66
	v_and_b32_e32 v54, 60, v56
	v_add_u32_e32 v57, 36, v66
	v_cmp_ne_u32_e64 s[4:5], 0, v54
	v_and_b32_e32 v54, 60, v57
	v_cmp_eq_u32_e64 s[6:7], 0, v54
	v_subbrev_co_u32_e64 v54, s[8:9], 0, v56, s[4:5]
	v_ashrrev_i32_e32 v55, 31, v54
	v_lshl_add_u64 v[54:55], v[54:55], 1, v[64:65]
	v_lshrrev_b32_e32 v54, 16, v160
	v_cndmask_b32_e64 v55, 0, 1.0, s[4:5]
	v_mov_b32_e32 v72, v80
	v_lshlrev_b32_e32 v74, 16, v78
	v_mov_b32_e32 v78, v81
	s_nop 0
	v_lshlrev_b32_e32 v54, 16, v54
	v_mul_f32_e32 v73, v55, v54
	v_cndmask_b32_e64 v54, v57, v56, s[6:7]
	v_ashrrev_i32_e32 v55, 31, v54
	v_lshl_add_u64 v[54:55], v[54:55], 1, v[64:65]
	v_and_b32_e32 v54, 0xffff, v163
	v_cndmask_b32_e64 v55, 1.0, 0, s[6:7]
	v_pk_mul_f32 v[72:73], v[130:131], v[72:73]
	s_nop 0
	v_lshlrev_b32_e32 v54, 16, v54
	v_mul_f32_e32 v75, v55, v54
	ds_read2_b64 v[54:57], v67 offset0:8 offset1:12
	v_pk_fma_f32 v[72:73], v[130:131], v[74:75], v[72:73] op_sel:[0,0,1] op_sel_hi:[1,0,0]
	v_mov_b32_e32 v74, v79
	v_pk_fma_f32 v[72:73], v[134:135], v[80:81], v[72:73] op_sel_hi:[0,1,1]
	v_pk_add_f32 v[72:73], v[132:133], v[72:73] op_sel_hi:[0,1]
	s_waitcnt lgkmcnt(0)
; DI float bf2f(bfu v) { return __uint_as_float(((unsigned)v) << 16); }
; DI unsigned pack2(float a, float b) { f32x2_t v = {a, b}; bf16x2_t r = __builtin_convertvector(v, bf16x2_t); return __builtin_bit_cast(unsigned, r); }
; DI float lo16(unsigned u) { return __uint_as_float(u << 16); }
; DI float hi16(unsigned u) { return __uint_as_float(u & 0xffff0000u); }
; template <int L>
; DI void hyena_job(const PX& p, int l, int c, unsigned char* smem) {
;     ...
;     for (int m = 0; m < TPW; m++) {
;       const int t0 = 16 * (w * TPW + m) + 4 * kq_o;
;       const bfu* zr = zx1 + b * L;
;       const uint2 mid = *(const uint2*)(zr + t0);
;       const bool lv = (t0 % RL != 0), rv = ((t0 + 4) % RL != 0);
;       const float lft = bf2f(zr[lv ? t0 - 1 : t0]) * (lv ? 1.f : 0.f);
;       const float rgt = bf2f(zr[rv ? t0 + 4 : t0]) * (rv ? 1.f : 0.f);
;       float z[6];
;       z[0] = lft; z[5] = rgt; z[1] = lo16(mid.x); z[2] = hi16(mid.x); z[3] = lo16(mid.y); z[4] = hi16(mid.y);
;       const uint2 vu = *(const uint2*)(U + b * USTR + t0);
;       const float vv[4] = {lo16(vu.x), hi16(vu.x), lo16(vu.y), hi16(vu.y)};
;       float y[4];
; #pragma unroll
;       for (int r = 0; r < 4; r++) {
;         const float x1 = w1[0] * z[r] + w1[1] * z[r + 1] + w1[2] * z[r + 2] + w1[3];
;         y[r] = x1 * (acc[m][r] + bias0 * vv[r]);
;       }
;       y1pk[m].x = pack2(y[0], y[1]);
;       y1pk[m].y = pack2(y[2], y[3]);
;     }
	v_lshlrev_b32_e32 v76, 16, v54
	v_and_b32_e32 v77, 0xffff0000, v54
	v_pk_fma_f32 v[76:77], v[136:137], v[76:77], v[94:95] op_sel_hi:[0,1,1]
	v_pk_mul_f32 v[72:73], v[72:73], v[76:77]
	v_pk_mul_f32 v[76:77], v[130:131], v[78:79] op_sel_hi:[0,1]
	v_pk_fma_f32 v[76:77], v[0:1], v[80:81], v[76:77] op_sel_hi:[0,1,1]
	v_lshlrev_b32_e32 v54, 16, v55
	v_and_b32_e32 v55, 0xffff0000, v55
	v_pk_fma_f32 v[74:75], v[134:135], v[74:75], v[76:77] op_sel_hi:[0,1,1]
	v_pk_add_f32 v[74:75], v[132:133], v[74:75] op_sel_hi:[0,1]
	v_pk_fma_f32 v[54:55], v[136:137], v[54:55], v[96:97] op_sel_hi:[0,1,1]
	v_pk_mul_f32 v[74:75], v[54:55], v[74:75]
	v_cvt_pk_bf16_f32 v54, v72, v73
	v_cvt_pk_bf16_f32 v55, v74, v75
	v_add_u32_e32 v74, 48, v66
	v_and_b32_e32 v72, 60, v74
	v_add_u32_e32 v75, 52, v66
	v_cmp_ne_u32_e64 s[4:5], 0, v72
	v_and_b32_e32 v72, 60, v75
	v_cmp_eq_u32_e64 s[6:7], 0, v72
	v_subbrev_co_u32_e64 v72, s[8:9], 0, v74, s[4:5]
	v_ashrrev_i32_e32 v73, 31, v72
	v_lshl_add_u64 v[72:73], v[72:73], 1, v[64:65]
	v_lshrrev_b32_e32 v72, 16, v164
	v_cndmask_b32_e64 v74, v75, v74, s[6:7]
	v_ashrrev_i32_e32 v75, 31, v74
	v_lshl_add_u64 v[74:75], v[74:75], 1, v[64:65]
	v_mov_b32_e32 v78, v165
	v_mov_b32_e32 v79, v166
	v_cndmask_b32_e64 v73, 0, 1.0, s[4:5]
	v_lshlrev_b32_e32 v76, 16, v56
	v_and_b32_e32 v77, 0xffff0000, v56
	v_pk_fma_f32 v[50:51], v[136:137], v[76:77], v[50:51] op_sel_hi:[0,1,1]
	v_lshlrev_b32_e32 v56, 16, v57
	v_and_b32_e32 v57, 0xffff0000, v57
	v_pk_fma_f32 v[52:53], v[136:137], v[56:57], v[52:53] op_sel_hi:[0,1,1]
	s_nop 0
	v_lshlrev_b32_e32 v72, 16, v72
	v_mul_f32_e32 v73, v73, v72
	v_and_b32_e32 v72, 0xffff, v167
	v_cndmask_b32_e64 v74, 1.0, 0, s[6:7]
	s_nop 0
	v_and_b32_e32 v80, 0xffff0000, v78
	v_lshlrev_b32_e32 v81, 16, v79
	v_and_b32_e32 v79, 0xffff0000, v79
	s_nop 0
	v_lshlrev_b32_e32 v72, 16, v72
	v_mul_f32_e32 v75, v74, v72
	v_mov_b32_e32 v72, v80
	v_lshlrev_b32_e32 v74, 16, v78
	v_pk_mul_f32 v[72:73], v[130:131], v[72:73]
	v_mov_b32_e32 v78, v81
	v_pk_fma_f32 v[72:73], v[130:131], v[74:75], v[72:73] op_sel:[0,0,1] op_sel_hi:[1,0,0]
	v_mov_b32_e32 v74, v79
	v_pk_fma_f32 v[72:73], v[134:135], v[80:81], v[72:73] op_sel_hi:[0,1,1]
	v_pk_add_f32 v[72:73], v[132:133], v[72:73] op_sel_hi:[0,1]
	v_pk_mul_f32 v[50:51], v[72:73], v[50:51]
	v_pk_mul_f32 v[72:73], v[130:131], v[78:79] op_sel_hi:[0,1]
	v_pk_fma_f32 v[72:73], v[0:1], v[80:81], v[72:73] op_sel_hi:[0,1,1]
	v_pk_fma_f32 v[72:73], v[134:135], v[74:75], v[72:73] op_sel_hi:[0,1,1]
	v_pk_add_f32 v[72:73], v[132:133], v[72:73] op_sel_hi:[0,1]
	v_pk_mul_f32 v[52:53], v[52:53], v[72:73]
	v_cvt_pk_bf16_f32 v56, v50, v51
	v_cvt_pk_bf16_f32 v57, v52, v53
	v_add_u32_e32 v53, 0x44, v66
	v_add_u32_e32 v52, 64, v66
	v_and_b32_e32 v50, 60, v53
	v_cmp_eq_u32_e64 s[4:5], 0, v50
	v_subbrev_co_u32_e64 v50, s[6:7], 0, v52, vcc
	v_ashrrev_i32_e32 v51, 31, v50
	v_lshl_add_u64 v[50:51], v[50:51], 1, v[64:65]
	v_lshrrev_b32_e32 v50, 16, v168
	s_nop 0
	v_mov_b32_e32 v78, v169
	v_mov_b32_e32 v79, v170
	s_nop 0
	v_lshlrev_b32_e32 v50, 16, v50
	v_mul_f32_e32 v73, v71, v50
	v_cndmask_b32_e64 v50, v53, v52, s[4:5]
	v_ashrrev_i32_e32 v51, 31, v50
	v_lshl_add_u64 v[50:51], v[50:51], 1, v[64:65]
	v_and_b32_e32 v50, 0xffff, v171
	v_cndmask_b32_e64 v51, 1.0, 0, s[4:5]
	s_nop 0
	v_and_b32_e32 v80, 0xffff0000, v78
	v_mov_b32_e32 v72, v80
	v_lshlrev_b32_e32 v74, 16, v78
	v_pk_mul_f32 v[72:73], v[130:131], v[72:73]
	v_lshlrev_b32_e32 v81, 16, v79
	v_and_b32_e32 v79, 0xffff0000, v79
	v_mov_b32_e32 v78, v81
	s_nop 0
	v_lshlrev_b32_e32 v50, 16, v50
	v_mul_f32_e32 v75, v51, v50
	ds_read2_b64 v[50:53], v67 offset0:16 offset1:20
	v_pk_fma_f32 v[72:73], v[130:131], v[74:75], v[72:73] op_sel:[0,0,1] op_sel_hi:[1,0,0]
	v_mov_b32_e32 v74, v79
	v_pk_fma_f32 v[72:73], v[134:135], v[80:81], v[72:73] op_sel_hi:[0,1,1]
	v_pk_add_f32 v[72:73], v[132:133], v[72:73] op_sel_hi:[0,1]
	s_waitcnt lgkmcnt(0)
	v_lshlrev_b32_e32 v76, 16, v50
	v_and_b32_e32 v77, 0xffff0000, v50
	v_pk_fma_f32 v[46:47], v[136:137], v[76:77], v[46:47] op_sel_hi:[0,1,1]
	v_pk_mul_f32 v[46:47], v[72:73], v[46:47]
	v_pk_mul_f32 v[72:73], v[130:131], v[78:79] op_sel_hi:[0,1]
	v_pk_fma_f32 v[72:73], v[0:1], v[80:81], v[72:73] op_sel_hi:[0,1,1]
	v_lshlrev_b32_e32 v50, 16, v51
	v_and_b32_e32 v51, 0xffff0000, v51
	v_pk_fma_f32 v[72:73], v[134:135], v[74:75], v[72:73] op_sel_hi:[0,1,1]
	v_pk_add_f32 v[72:73], v[132:133], v[72:73] op_sel_hi:[0,1]
	v_pk_fma_f32 v[48:49], v[136:137], v[50:51], v[48:49] op_sel_hi:[0,1,1]
	v_pk_mul_f32 v[48:49], v[48:49], v[72:73]
	v_add_u32_e32 v50, 0x50, v66
	v_cvt_pk_bf16_f32 v46, v46, v47
	v_cvt_pk_bf16_f32 v47, v48, v49
	v_and_b32_e32 v48, 60, v50
	v_add_u32_e32 v51, 0x54, v66
	v_cmp_ne_u32_e64 s[4:5], 0, v48
	v_and_b32_e32 v48, 60, v51
	v_cmp_eq_u32_e64 s[6:7], 0, v48
	v_subbrev_co_u32_e64 v48, s[8:9], 0, v50, s[4:5]
	v_ashrrev_i32_e32 v49, 31, v48
	v_lshl_add_u64 v[48:49], v[48:49], 1, v[64:65]
	v_lshrrev_b32_e32 v48, 16, v172
	v_cndmask_b32_e64 v50, v51, v50, s[6:7]
	v_ashrrev_i32_e32 v51, 31, v50
	v_lshl_add_u64 v[50:51], v[50:51], 1, v[64:65]
	v_mov_b32_e32 v74, v173
	v_mov_b32_e32 v75, v174
	v_cndmask_b32_e64 v49, 0, 1.0, s[4:5]
	v_lshlrev_b32_e32 v72, 16, v52
	v_and_b32_e32 v73, 0xffff0000, v52
	v_pk_fma_f32 v[42:43], v[136:137], v[72:73], v[42:43] op_sel_hi:[0,1,1]
	v_lshlrev_b32_e32 v52, 16, v53
	v_and_b32_e32 v53, 0xffff0000, v53
	v_pk_fma_f32 v[44:45], v[136:137], v[52:53], v[44:45] op_sel_hi:[0,1,1]
	s_nop 0
	v_lshlrev_b32_e32 v48, 16, v48
	v_mul_f32_e32 v49, v49, v48
	v_and_b32_e32 v48, 0xffff, v175
	v_cndmask_b32_e64 v50, 1.0, 0, s[6:7]
	s_nop 0
	v_and_b32_e32 v76, 0xffff0000, v74
	v_lshlrev_b32_e32 v77, 16, v75
; DI float bf2f(bfu v) { return __uint_as_float(((unsigned)v) << 16); }
; DI unsigned pack2(float a, float b) { f32x2_t v = {a, b}; bf16x2_t r = __builtin_convertvector(v, bf16x2_t); return __builtin_bit_cast(unsigned, r); }
; DI float lo16(unsigned u) { return __uint_as_float(u << 16); }
; DI float hi16(unsigned u) { return __uint_as_float(u & 0xffff0000u); }
; template <int L>
; DI void hyena_job(const PX& p, int l, int c, unsigned char* smem) {
;     ...
;     for (int m = 0; m < TPW; m++) {
;       const int t0 = 16 * (w * TPW + m) + 4 * kq_o;
;       const bfu* zr = zx1 + b * L;
;       const uint2 mid = *(const uint2*)(zr + t0);
;       const bool lv = (t0 % RL != 0), rv = ((t0 + 4) % RL != 0);
;       const float lft = bf2f(zr[lv ? t0 - 1 : t0]) * (lv ? 1.f : 0.f);
;       const float rgt = bf2f(zr[rv ? t0 + 4 : t0]) * (rv ? 1.f : 0.f);
;       float z[6];
;       z[0] = lft; z[5] = rgt; z[1] = lo16(mid.x); z[2] = hi16(mid.x); z[3] = lo16(mid.y); z[4] = hi16(mid.y);
;       const uint2 vu = *(const uint2*)(U + b * USTR + t0);
;       const float vv[4] = {lo16(vu.x), hi16(vu.x), lo16(vu.y), hi16(vu.y)};
;       float y[4];
; #pragma unroll
;       for (int r = 0; r < 4; r++) {
;         const float x1 = w1[0] * z[r] + w1[1] * z[r + 1] + w1[2] * z[r + 2] + w1[3];
;         y[r] = x1 * (acc[m][r] + bias0 * vv[r]);
;       }
;       y1pk[m].x = pack2(y[0], y[1]);
;       y1pk[m].y = pack2(y[2], y[3]);
;     }
	v_and_b32_e32 v75, 0xffff0000, v75
	s_nop 0
	v_lshlrev_b32_e32 v48, 16, v48
	v_mul_f32_e32 v51, v50, v48
	v_mov_b32_e32 v48, v76
	v_lshlrev_b32_e32 v50, 16, v74
	v_pk_mul_f32 v[48:49], v[130:131], v[48:49]
	v_mov_b32_e32 v74, v77
	v_pk_fma_f32 v[48:49], v[130:131], v[50:51], v[48:49] op_sel:[0,0,1] op_sel_hi:[1,0,0]
	v_mov_b32_e32 v50, v75
	v_pk_fma_f32 v[48:49], v[134:135], v[76:77], v[48:49] op_sel_hi:[0,1,1]
	v_pk_add_f32 v[48:49], v[132:133], v[48:49] op_sel_hi:[0,1]
	v_pk_mul_f32 v[42:43], v[48:49], v[42:43]
	v_pk_mul_f32 v[48:49], v[130:131], v[74:75] op_sel_hi:[0,1]
	v_pk_fma_f32 v[48:49], v[0:1], v[76:77], v[48:49] op_sel_hi:[0,1,1]
	v_pk_fma_f32 v[48:49], v[134:135], v[50:51], v[48:49] op_sel_hi:[0,1,1]
	v_pk_add_f32 v[48:49], v[132:133], v[48:49] op_sel_hi:[0,1]
	v_pk_mul_f32 v[44:45], v[44:45], v[48:49]
	v_add_u32_e32 v48, 0x60, v66
	v_cvt_pk_bf16_f32 v42, v42, v43
	v_cvt_pk_bf16_f32 v43, v44, v45
	v_and_b32_e32 v44, 60, v48
	v_add_u32_e32 v49, 0x64, v66
	v_cmp_ne_u32_e64 s[4:5], 0, v44
	v_and_b32_e32 v44, 60, v49
	v_cmp_eq_u32_e64 s[6:7], 0, v44
	v_subbrev_co_u32_e64 v44, s[8:9], 0, v48, s[4:5]
	v_ashrrev_i32_e32 v45, 31, v44
	v_lshl_add_u64 v[44:45], v[44:45], 1, v[64:65]
	v_lshrrev_b32_e32 v44, 16, v176
	v_cndmask_b32_e64 v48, v49, v48, s[6:7]
	v_ashrrev_i32_e32 v49, 31, v48
	v_lshl_add_u64 v[48:49], v[48:49], 1, v[64:65]
	v_mov_b32_e32 v74, v177
	v_mov_b32_e32 v75, v178
	v_cndmask_b32_e64 v45, 0, 1.0, s[4:5]
	s_nop 0
	v_lshlrev_b32_e32 v44, 16, v44
	v_mul_f32_e32 v45, v45, v44
	v_and_b32_e32 v44, 0xffff, v179
	v_cndmask_b32_e64 v48, 1.0, 0, s[6:7]
	s_nop 0
	v_and_b32_e32 v76, 0xffff0000, v74
	v_lshlrev_b32_e32 v52, 16, v74
	v_lshlrev_b32_e32 v77, 16, v75
	v_and_b32_e32 v75, 0xffff0000, v75
	v_mov_b32_e32 v74, v77
	s_nop 0
	v_lshlrev_b32_e32 v44, 16, v44
	v_mul_f32_e32 v53, v48, v44
	ds_read2_b64 v[48:51], v67 offset0:24 offset1:28
	v_mov_b32_e32 v44, v76
	v_pk_mul_f32 v[44:45], v[130:131], v[44:45]
	s_waitcnt lgkmcnt(0)
	v_lshlrev_b32_e32 v72, 16, v48
	v_pk_fma_f32 v[44:45], v[130:131], v[52:53], v[44:45] op_sel:[0,0,1] op_sel_hi:[1,0,0]
	v_and_b32_e32 v73, 0xffff0000, v48
	v_pk_fma_f32 v[44:45], v[134:135], v[76:77], v[44:45] op_sel_hi:[0,1,1]
	v_pk_fma_f32 v[38:39], v[136:137], v[72:73], v[38:39] op_sel_hi:[0,1,1]
	v_pk_add_f32 v[44:45], v[132:133], v[44:45] op_sel_hi:[0,1]
	v_pk_mul_f32 v[38:39], v[44:45], v[38:39]
	v_pk_mul_f32 v[44:45], v[130:131], v[74:75] op_sel_hi:[0,1]
	v_pk_fma_f32 v[44:45], v[0:1], v[76:77], v[44:45] op_sel_hi:[0,1,1]
	v_mov_b32_e32 v52, v75
	v_lshlrev_b32_e32 v48, 16, v49
	v_and_b32_e32 v49, 0xffff0000, v49
	v_pk_fma_f32 v[44:45], v[134:135], v[52:53], v[44:45] op_sel_hi:[0,1,1]
	v_pk_add_f32 v[44:45], v[132:133], v[44:45] op_sel_hi:[0,1]
	v_pk_fma_f32 v[40:41], v[136:137], v[48:49], v[40:41] op_sel_hi:[0,1,1]
	v_pk_mul_f32 v[40:41], v[40:41], v[44:45]
	v_add_u32_e32 v44, 0x70, v66
	v_cvt_pk_bf16_f32 v38, v38, v39
	v_cvt_pk_bf16_f32 v39, v40, v41
	v_and_b32_e32 v40, 60, v44
	v_add_u32_e32 v45, 0x74, v66
	v_cmp_ne_u32_e64 s[4:5], 0, v40
	v_and_b32_e32 v40, 60, v45
	v_cmp_eq_u32_e64 s[6:7], 0, v40
	v_subbrev_co_u32_e64 v40, s[8:9], 0, v44, s[4:5]
	v_ashrrev_i32_e32 v41, 31, v40
	v_lshl_add_u64 v[40:41], v[40:41], 1, v[64:65]
	v_lshrrev_b32_e32 v40, 16, v180
	v_cndmask_b32_e64 v44, v45, v44, s[6:7]
	v_ashrrev_i32_e32 v45, 31, v44
	v_lshl_add_u64 v[44:45], v[44:45], 1, v[64:65]
	v_mov_b32_e32 v52, v181
	v_mov_b32_e32 v53, v182
	v_cndmask_b32_e64 v41, 0, 1.0, s[4:5]
	v_lshlrev_b32_e32 v48, 16, v50
	v_and_b32_e32 v49, 0xffff0000, v50
	v_pk_fma_f32 v[34:35], v[136:137], v[48:49], v[34:35] op_sel_hi:[0,1,1]
	v_lshlrev_b32_e32 v50, 16, v51
	v_and_b32_e32 v51, 0xffff0000, v51
	v_pk_fma_f32 v[36:37], v[136:137], v[50:51], v[36:37] op_sel_hi:[0,1,1]
	s_nop 0
	v_lshlrev_b32_e32 v40, 16, v40
	v_mul_f32_e32 v41, v41, v40
	v_and_b32_e32 v40, 0xffff, v183
	v_cndmask_b32_e64 v44, 1.0, 0, s[6:7]
	s_nop 0
	v_and_b32_e32 v72, 0xffff0000, v52
	v_lshlrev_b32_e32 v73, 16, v53
	v_and_b32_e32 v53, 0xffff0000, v53
	s_nop 0
	v_lshlrev_b32_e32 v40, 16, v40
	v_mul_f32_e32 v45, v44, v40
	v_mov_b32_e32 v40, v72
	v_lshlrev_b32_e32 v44, 16, v52
	v_pk_mul_f32 v[40:41], v[130:131], v[40:41]
	v_mov_b32_e32 v52, v73
	v_pk_fma_f32 v[40:41], v[130:131], v[44:45], v[40:41] op_sel:[0,0,1] op_sel_hi:[1,0,0]
	v_mov_b32_e32 v44, v53
	v_pk_fma_f32 v[40:41], v[134:135], v[72:73], v[40:41] op_sel_hi:[0,1,1]
	v_pk_add_f32 v[40:41], v[132:133], v[40:41] op_sel_hi:[0,1]
	v_pk_mul_f32 v[34:35], v[40:41], v[34:35]
	v_pk_mul_f32 v[40:41], v[130:131], v[52:53] op_sel_hi:[0,1]
	v_pk_fma_f32 v[40:41], v[0:1], v[72:73], v[40:41] op_sel_hi:[0,1,1]
	v_pk_fma_f32 v[40:41], v[134:135], v[44:45], v[40:41] op_sel_hi:[0,1,1]
	v_pk_add_f32 v[40:41], v[132:133], v[40:41] op_sel_hi:[0,1]
	v_pk_mul_f32 v[36:37], v[36:37], v[40:41]
	v_cvt_pk_bf16_f32 v40, v34, v35
	v_cvt_pk_bf16_f32 v41, v36, v37
	v_add_u32_e32 v37, 0x84, v66
	v_add_u32_e32 v36, 0x80, v66
	v_and_b32_e32 v34, 60, v37
	v_cmp_eq_u32_e64 s[4:5], 0, v34
	v_subbrev_co_u32_e64 v34, s[6:7], 0, v36, vcc
	v_ashrrev_i32_e32 v35, 31, v34
	v_lshl_add_u64 v[34:35], v[34:35], 1, v[64:65]
	v_lshrrev_b32_e32 v34, 16, v216
	s_nop 0
	v_mov_b32_e32 v52, v217
	v_mov_b32_e32 v53, v218
	s_nop 0
	v_lshlrev_b32_e32 v34, 16, v34
	v_mul_f32_e32 v45, v71, v34
	v_cndmask_b32_e64 v34, v37, v36, s[4:5]
	v_ashrrev_i32_e32 v35, 31, v34
	v_lshl_add_u64 v[34:35], v[34:35], 1, v[64:65]
	v_and_b32_e32 v34, 0xffff, v219
	v_cndmask_b32_e64 v35, 1.0, 0, s[4:5]
	s_nop 0
	v_and_b32_e32 v72, 0xffff0000, v52
	v_mov_b32_e32 v44, v72
	v_lshlrev_b32_e32 v48, 16, v52
	v_pk_mul_f32 v[44:45], v[130:131], v[44:45]
	v_lshlrev_b32_e32 v73, 16, v53
	v_and_b32_e32 v53, 0xffff0000, v53
	v_mov_b32_e32 v52, v73
	s_nop 0
	v_lshlrev_b32_e32 v34, 16, v34
	v_mul_f32_e32 v49, v35, v34
	ds_read2_b64 v[34:37], v67 offset0:32 offset1:36
	v_pk_fma_f32 v[44:45], v[130:131], v[48:49], v[44:45] op_sel:[0,0,1] op_sel_hi:[1,0,0]
	v_mov_b32_e32 v48, v53
	v_pk_fma_f32 v[44:45], v[134:135], v[72:73], v[44:45] op_sel_hi:[0,1,1]
	v_pk_add_f32 v[44:45], v[132:133], v[44:45] op_sel_hi:[0,1]
	s_waitcnt lgkmcnt(0)
; DI float bf2f(bfu v) { return __uint_as_float(((unsigned)v) << 16); }
; DI unsigned pack2(float a, float b) { f32x2_t v = {a, b}; bf16x2_t r = __builtin_convertvector(v, bf16x2_t); return __builtin_bit_cast(unsigned, r); }
; DI float lo16(unsigned u) { return __uint_as_float(u << 16); }
; DI float hi16(unsigned u) { return __uint_as_float(u & 0xffff0000u); }
; template <int L>
; DI void hyena_job(const PX& p, int l, int c, unsigned char* smem) {
;     ...
;     for (int m = 0; m < TPW; m++) {
;       const int t0 = 16 * (w * TPW + m) + 4 * kq_o;
;       const bfu* zr = zx1 + b * L;
;       const uint2 mid = *(const uint2*)(zr + t0);
;       const bool lv = (t0 % RL != 0), rv = ((t0 + 4) % RL != 0);
;       const float lft = bf2f(zr[lv ? t0 - 1 : t0]) * (lv ? 1.f : 0.f);
;       const float rgt = bf2f(zr[rv ? t0 + 4 : t0]) * (rv ? 1.f : 0.f);
;       float z[6];
;       z[0] = lft; z[5] = rgt; z[1] = lo16(mid.x); z[2] = hi16(mid.x); z[3] = lo16(mid.y); z[4] = hi16(mid.y);
;       const uint2 vu = *(const uint2*)(U + b * USTR + t0);
;       const float vv[4] = {lo16(vu.x), hi16(vu.x), lo16(vu.y), hi16(vu.y)};
;       float y[4];
; #pragma unroll
;       for (int r = 0; r < 4; r++) {
;         const float x1 = w1[0] * z[r] + w1[1] * z[r + 1] + w1[2] * z[r + 2] + w1[3];
;         y[r] = x1 * (acc[m][r] + bias0 * vv[r]);
;       }
;       y1pk[m].x = pack2(y[0], y[1]);
;       y1pk[m].y = pack2(y[2], y[3]);
;     }
	v_lshlrev_b32_e32 v50, 16, v34
	v_and_b32_e32 v51, 0xffff0000, v34
	v_pk_fma_f32 v[30:31], v[136:137], v[50:51], v[30:31] op_sel_hi:[0,1,1]
	v_pk_mul_f32 v[30:31], v[44:45], v[30:31]
	v_pk_mul_f32 v[44:45], v[130:131], v[52:53] op_sel_hi:[0,1]
	v_pk_fma_f32 v[44:45], v[0:1], v[72:73], v[44:45] op_sel_hi:[0,1,1]
	v_lshlrev_b32_e32 v34, 16, v35
	v_and_b32_e32 v35, 0xffff0000, v35
	v_pk_fma_f32 v[44:45], v[134:135], v[48:49], v[44:45] op_sel_hi:[0,1,1]
	v_pk_add_f32 v[44:45], v[132:133], v[44:45] op_sel_hi:[0,1]
	v_pk_fma_f32 v[32:33], v[136:137], v[34:35], v[32:33] op_sel_hi:[0,1,1]
	v_pk_mul_f32 v[32:33], v[32:33], v[44:45]
	v_add_u32_e32 v34, 0x90, v66
	v_cvt_pk_bf16_f32 v30, v30, v31
	v_cvt_pk_bf16_f32 v31, v32, v33
	v_and_b32_e32 v32, 60, v34
	v_add_u32_e32 v35, 0x94, v66
	v_cmp_ne_u32_e64 s[4:5], 0, v32
	v_and_b32_e32 v32, 60, v35
	v_cmp_eq_u32_e64 s[6:7], 0, v32
	v_subbrev_co_u32_e64 v32, s[8:9], 0, v34, s[4:5]
	v_ashrrev_i32_e32 v33, 31, v32
	v_lshl_add_u64 v[32:33], v[32:33], 1, v[64:65]
	v_lshrrev_b32_e32 v32, 16, v220
	v_cndmask_b32_e64 v34, v35, v34, s[6:7]
	v_ashrrev_i32_e32 v35, 31, v34
	v_lshl_add_u64 v[34:35], v[34:35], 1, v[64:65]
	v_mov_b32_e32 v48, v221
	v_mov_b32_e32 v49, v222
	v_cndmask_b32_e64 v33, 0, 1.0, s[4:5]
	v_lshlrev_b32_e32 v44, 16, v36
	v_and_b32_e32 v45, 0xffff0000, v36
	v_pk_fma_f32 v[26:27], v[136:137], v[44:45], v[26:27] op_sel_hi:[0,1,1]
	v_lshlrev_b32_e32 v36, 16, v37
	v_and_b32_e32 v37, 0xffff0000, v37
	v_pk_fma_f32 v[28:29], v[136:137], v[36:37], v[28:29] op_sel_hi:[0,1,1]
	s_nop 0
	v_lshlrev_b32_e32 v32, 16, v32
	v_mul_f32_e32 v33, v33, v32
	v_and_b32_e32 v32, 0xffff, v223
	v_cndmask_b32_e64 v34, 1.0, 0, s[6:7]
	s_nop 0
	v_and_b32_e32 v50, 0xffff0000, v48
	v_lshlrev_b32_e32 v51, 16, v49
	v_and_b32_e32 v49, 0xffff0000, v49
	s_nop 0
	v_lshlrev_b32_e32 v32, 16, v32
	v_mul_f32_e32 v35, v34, v32
	v_mov_b32_e32 v32, v50
	v_lshlrev_b32_e32 v34, 16, v48
	v_pk_mul_f32 v[32:33], v[130:131], v[32:33]
	v_mov_b32_e32 v48, v51
	v_pk_fma_f32 v[32:33], v[130:131], v[34:35], v[32:33] op_sel:[0,0,1] op_sel_hi:[1,0,0]
	v_mov_b32_e32 v34, v49
	v_pk_fma_f32 v[32:33], v[134:135], v[50:51], v[32:33] op_sel_hi:[0,1,1]
	v_pk_add_f32 v[32:33], v[132:133], v[32:33] op_sel_hi:[0,1]
	v_pk_mul_f32 v[26:27], v[32:33], v[26:27]
	v_pk_mul_f32 v[32:33], v[130:131], v[48:49] op_sel_hi:[0,1]
	v_pk_fma_f32 v[32:33], v[0:1], v[50:51], v[32:33] op_sel_hi:[0,1,1]
	v_pk_fma_f32 v[32:33], v[134:135], v[34:35], v[32:33] op_sel_hi:[0,1,1]
	v_pk_add_f32 v[32:33], v[132:133], v[32:33] op_sel_hi:[0,1]
	v_pk_mul_f32 v[28:29], v[28:29], v[32:33]
	v_add_u32_e32 v32, 0xa0, v66
	v_cvt_pk_bf16_f32 v26, v26, v27
	v_cvt_pk_bf16_f32 v27, v28, v29
	v_and_b32_e32 v28, 60, v32
	v_add_u32_e32 v33, 0xa4, v66
	v_cmp_ne_u32_e64 s[4:5], 0, v28
	v_and_b32_e32 v28, 60, v33
	v_cmp_eq_u32_e64 s[6:7], 0, v28
	v_subbrev_co_u32_e64 v28, s[8:9], 0, v32, s[4:5]
	v_ashrrev_i32_e32 v29, 31, v28
	v_lshl_add_u64 v[28:29], v[28:29], 1, v[64:65]
	v_lshrrev_b32_e32 v28, 16, v224
	v_cndmask_b32_e64 v32, v33, v32, s[6:7]
	v_ashrrev_i32_e32 v33, 31, v32
	v_lshl_add_u64 v[32:33], v[32:33], 1, v[64:65]
	v_mov_b32_e32 v48, v225
	v_mov_b32_e32 v49, v226
	v_cndmask_b32_e64 v29, 0, 1.0, s[4:5]
	s_nop 0
	v_lshlrev_b32_e32 v28, 16, v28
	v_mul_f32_e32 v29, v29, v28
	v_and_b32_e32 v28, 0xffff, v227
	v_cndmask_b32_e64 v32, 1.0, 0, s[6:7]
	s_nop 0
	v_and_b32_e32 v50, 0xffff0000, v48
	v_lshlrev_b32_e32 v36, 16, v48
	v_lshlrev_b32_e32 v51, 16, v49
	v_and_b32_e32 v49, 0xffff0000, v49
	v_mov_b32_e32 v48, v51
	s_nop 0
	v_lshlrev_b32_e32 v28, 16, v28
	v_mul_f32_e32 v37, v32, v28
	ds_read2_b64 v[32:35], v67 offset0:40 offset1:44
	v_mov_b32_e32 v28, v50
	v_pk_mul_f32 v[28:29], v[130:131], v[28:29]
	s_waitcnt lgkmcnt(0)
	v_lshlrev_b32_e32 v44, 16, v32
	v_pk_fma_f32 v[28:29], v[130:131], v[36:37], v[28:29] op_sel:[0,0,1] op_sel_hi:[1,0,0]
	v_and_b32_e32 v45, 0xffff0000, v32
	v_pk_fma_f32 v[28:29], v[134:135], v[50:51], v[28:29] op_sel_hi:[0,1,1]
	v_pk_fma_f32 v[22:23], v[136:137], v[44:45], v[22:23] op_sel_hi:[0,1,1]
	v_pk_add_f32 v[28:29], v[132:133], v[28:29] op_sel_hi:[0,1]
	v_pk_mul_f32 v[22:23], v[28:29], v[22:23]
	v_pk_mul_f32 v[28:29], v[130:131], v[48:49] op_sel_hi:[0,1]
	v_pk_fma_f32 v[28:29], v[0:1], v[50:51], v[28:29] op_sel_hi:[0,1,1]
	v_mov_b32_e32 v36, v49
	v_lshlrev_b32_e32 v32, 16, v33
	v_and_b32_e32 v33, 0xffff0000, v33
	v_pk_fma_f32 v[28:29], v[134:135], v[36:37], v[28:29] op_sel_hi:[0,1,1]
	v_pk_add_f32 v[28:29], v[132:133], v[28:29] op_sel_hi:[0,1]
	v_pk_fma_f32 v[24:25], v[136:137], v[32:33], v[24:25] op_sel_hi:[0,1,1]
	v_pk_mul_f32 v[24:25], v[24:25], v[28:29]
	v_add_u32_e32 v28, 0xb0, v66
	v_cvt_pk_bf16_f32 v22, v22, v23
	v_cvt_pk_bf16_f32 v23, v24, v25
	v_and_b32_e32 v24, 60, v28
	v_add_u32_e32 v29, 0xb4, v66
	v_cmp_ne_u32_e64 s[4:5], 0, v24
	v_and_b32_e32 v24, 60, v29
	v_cmp_eq_u32_e64 s[6:7], 0, v24
	v_subbrev_co_u32_e64 v24, s[8:9], 0, v28, s[4:5]
	v_ashrrev_i32_e32 v25, 31, v24
	v_lshl_add_u64 v[24:25], v[24:25], 1, v[64:65]
	v_lshrrev_b32_e32 v24, 16, v228
	v_cndmask_b32_e64 v28, v29, v28, s[6:7]
	v_ashrrev_i32_e32 v29, 31, v28
	v_lshl_add_u64 v[28:29], v[28:29], 1, v[64:65]
	v_mov_b32_e32 v36, v229
	v_mov_b32_e32 v37, v230
	v_cndmask_b32_e64 v25, 0, 1.0, s[4:5]
	v_lshlrev_b32_e32 v32, 16, v34
	v_and_b32_e32 v33, 0xffff0000, v34
	v_pk_fma_f32 v[18:19], v[136:137], v[32:33], v[18:19] op_sel_hi:[0,1,1]
	v_lshlrev_b32_e32 v34, 16, v35
	v_and_b32_e32 v35, 0xffff0000, v35
	v_pk_fma_f32 v[20:21], v[136:137], v[34:35], v[20:21] op_sel_hi:[0,1,1]
	s_nop 0
	v_lshlrev_b32_e32 v24, 16, v24
	v_mul_f32_e32 v25, v25, v24
	v_and_b32_e32 v24, 0xffff, v231
	v_cndmask_b32_e64 v28, 1.0, 0, s[6:7]
; DI float bf2f(bfu v) { return __uint_as_float(((unsigned)v) << 16); }
; DI unsigned pack2(float a, float b) { f32x2_t v = {a, b}; bf16x2_t r = __builtin_convertvector(v, bf16x2_t); return __builtin_bit_cast(unsigned, r); }
; DI float lo16(unsigned u) { return __uint_as_float(u << 16); }
; DI float hi16(unsigned u) { return __uint_as_float(u & 0xffff0000u); }
; template <int L>
; DI void hyena_job(const PX& p, int l, int c, unsigned char* smem) {
;     ...
;     for (int m = 0; m < TPW; m++) {
;       const int t0 = 16 * (w * TPW + m) + 4 * kq_o;
;       const bfu* zr = zx1 + b * L;
;       const uint2 mid = *(const uint2*)(zr + t0);
;       const bool lv = (t0 % RL != 0), rv = ((t0 + 4) % RL != 0);
;       const float lft = bf2f(zr[lv ? t0 - 1 : t0]) * (lv ? 1.f : 0.f);
;       const float rgt = bf2f(zr[rv ? t0 + 4 : t0]) * (rv ? 1.f : 0.f);
;       float z[6];
;       z[0] = lft; z[5] = rgt; z[1] = lo16(mid.x); z[2] = hi16(mid.x); z[3] = lo16(mid.y); z[4] = hi16(mid.y);
;       const uint2 vu = *(const uint2*)(U + b * USTR + t0);
;       const float vv[4] = {lo16(vu.x), hi16(vu.x), lo16(vu.y), hi16(vu.y)};
;       float y[4];
; #pragma unroll
;       for (int r = 0; r < 4; r++) {
;         const float x1 = w1[0] * z[r] + w1[1] * z[r + 1] + w1[2] * z[r + 2] + w1[3];
;         y[r] = x1 * (acc[m][r] + bias0 * vv[r]);
;       }
;       y1pk[m].x = pack2(y[0], y[1]);
;       y1pk[m].y = pack2(y[2], y[3]);
;     }
	s_nop 0
	v_and_b32_e32 v44, 0xffff0000, v36
	v_lshlrev_b32_e32 v45, 16, v37
	v_and_b32_e32 v37, 0xffff0000, v37
	s_nop 0
	v_lshlrev_b32_e32 v24, 16, v24
	v_mul_f32_e32 v29, v28, v24
	v_mov_b32_e32 v24, v44
	v_lshlrev_b32_e32 v28, 16, v36
	v_pk_mul_f32 v[24:25], v[130:131], v[24:25]
	v_mov_b32_e32 v36, v45
	v_pk_fma_f32 v[24:25], v[130:131], v[28:29], v[24:25] op_sel:[0,0,1] op_sel_hi:[1,0,0]
	v_mov_b32_e32 v28, v37
	v_pk_fma_f32 v[24:25], v[134:135], v[44:45], v[24:25] op_sel_hi:[0,1,1]
	v_pk_add_f32 v[24:25], v[132:133], v[24:25] op_sel_hi:[0,1]
	v_pk_mul_f32 v[18:19], v[24:25], v[18:19]
	v_pk_mul_f32 v[24:25], v[130:131], v[36:37] op_sel_hi:[0,1]
	v_pk_fma_f32 v[24:25], v[0:1], v[44:45], v[24:25] op_sel_hi:[0,1,1]
	v_pk_fma_f32 v[24:25], v[134:135], v[28:29], v[24:25] op_sel_hi:[0,1,1]
	v_pk_add_f32 v[24:25], v[132:133], v[24:25] op_sel_hi:[0,1]
	v_pk_mul_f32 v[20:21], v[20:21], v[24:25]
	v_cvt_pk_bf16_f32 v24, v18, v19
	v_cvt_pk_bf16_f32 v25, v20, v21
	v_add_u32_e32 v21, 0xc4, v66
	v_add_u32_e32 v20, 0xc0, v66
	v_and_b32_e32 v18, 60, v21
	v_cmp_eq_u32_e64 s[4:5], 0, v18
	v_subbrev_co_u32_e32 v18, vcc, 0, v20, vcc
	v_ashrrev_i32_e32 v19, 31, v18
	v_lshl_add_u64 v[18:19], v[18:19], 1, v[64:65]
	v_lshrrev_b32_e32 v18, 16, v232
	s_nop 0
	v_mov_b32_e32 v36, v233
	v_mov_b32_e32 v37, v234
	s_nop 0
	v_lshlrev_b32_e32 v18, 16, v18
	v_mul_f32_e32 v29, v71, v18
	v_cndmask_b32_e64 v18, v21, v20, s[4:5]
	v_ashrrev_i32_e32 v19, 31, v18
	v_lshl_add_u64 v[18:19], v[18:19], 1, v[64:65]
	v_and_b32_e32 v18, 0xffff, v235
	v_cndmask_b32_e64 v19, 1.0, 0, s[4:5]
	s_nop 0
	v_and_b32_e32 v44, 0xffff0000, v36
	v_mov_b32_e32 v28, v44
	v_lshlrev_b32_e32 v32, 16, v36
	v_pk_mul_f32 v[28:29], v[130:131], v[28:29]
	v_lshlrev_b32_e32 v45, 16, v37
	v_and_b32_e32 v37, 0xffff0000, v37
	v_mov_b32_e32 v36, v45
	s_nop 0
	v_lshlrev_b32_e32 v18, 16, v18
	v_mul_f32_e32 v33, v19, v18
	ds_read2_b64 v[18:21], v67 offset0:48 offset1:52
	v_pk_fma_f32 v[28:29], v[130:131], v[32:33], v[28:29] op_sel:[0,0,1] op_sel_hi:[1,0,0]
	v_mov_b32_e32 v32, v37
	v_pk_fma_f32 v[28:29], v[134:135], v[44:45], v[28:29] op_sel_hi:[0,1,1]
	v_pk_add_f32 v[28:29], v[132:133], v[28:29] op_sel_hi:[0,1]
	s_waitcnt lgkmcnt(0)
	v_lshlrev_b32_e32 v34, 16, v18
	v_and_b32_e32 v35, 0xffff0000, v18
	v_pk_fma_f32 v[14:15], v[136:137], v[34:35], v[14:15] op_sel_hi:[0,1,1]
	v_pk_mul_f32 v[14:15], v[28:29], v[14:15]
	v_pk_mul_f32 v[28:29], v[130:131], v[36:37] op_sel_hi:[0,1]
	v_pk_fma_f32 v[28:29], v[0:1], v[44:45], v[28:29] op_sel_hi:[0,1,1]
	v_lshlrev_b32_e32 v18, 16, v19
	v_and_b32_e32 v19, 0xffff0000, v19
	v_pk_fma_f32 v[28:29], v[134:135], v[32:33], v[28:29] op_sel_hi:[0,1,1]
	v_pk_add_f32 v[28:29], v[132:133], v[28:29] op_sel_hi:[0,1]
	v_pk_fma_f32 v[16:17], v[136:137], v[18:19], v[16:17] op_sel_hi:[0,1,1]
	v_pk_mul_f32 v[16:17], v[16:17], v[28:29]
	v_add_u32_e32 v18, 0xd0, v66
	v_cvt_pk_bf16_f32 v14, v14, v15
	v_cvt_pk_bf16_f32 v15, v16, v17
	v_and_b32_e32 v16, 60, v18
	v_add_u32_e32 v19, 0xd4, v66
	v_cmp_ne_u32_e32 vcc, 0, v16
	v_and_b32_e32 v16, 60, v19
	v_cmp_eq_u32_e64 s[4:5], 0, v16
	v_subbrev_co_u32_e64 v16, s[6:7], 0, v18, vcc
	v_ashrrev_i32_e32 v17, 31, v16
	v_lshl_add_u64 v[16:17], v[16:17], 1, v[64:65]
	v_lshrrev_b32_e32 v16, 16, v236
	v_cndmask_b32_e64 v18, v19, v18, s[4:5]
	v_ashrrev_i32_e32 v19, 31, v18
	v_lshl_add_u64 v[18:19], v[18:19], 1, v[64:65]
	v_mov_b32_e32 v32, v237
	v_mov_b32_e32 v33, v238
	v_cndmask_b32_e64 v17, 0, 1.0, vcc
	v_lshlrev_b32_e32 v28, 16, v20
	v_and_b32_e32 v29, 0xffff0000, v20
	v_pk_fma_f32 v[10:11], v[136:137], v[28:29], v[10:11] op_sel_hi:[0,1,1]
	v_lshlrev_b32_e32 v20, 16, v21
	v_and_b32_e32 v21, 0xffff0000, v21
	v_pk_fma_f32 v[12:13], v[136:137], v[20:21], v[12:13] op_sel_hi:[0,1,1]
	s_nop 0
	v_lshlrev_b32_e32 v16, 16, v16
	v_mul_f32_e32 v17, v17, v16
	v_and_b32_e32 v16, 0xffff, v239
	v_cndmask_b32_e64 v18, 1.0, 0, s[4:5]
	s_nop 0
	v_and_b32_e32 v34, 0xffff0000, v32
	v_lshlrev_b32_e32 v35, 16, v33
	v_and_b32_e32 v33, 0xffff0000, v33
	s_nop 0
	v_lshlrev_b32_e32 v16, 16, v16
	v_mul_f32_e32 v19, v18, v16
	v_mov_b32_e32 v16, v34
	v_lshlrev_b32_e32 v18, 16, v32
	v_pk_mul_f32 v[16:17], v[130:131], v[16:17]
	v_mov_b32_e32 v32, v35
	v_pk_fma_f32 v[16:17], v[130:131], v[18:19], v[16:17] op_sel:[0,0,1] op_sel_hi:[1,0,0]
	v_mov_b32_e32 v18, v33
	v_pk_fma_f32 v[16:17], v[134:135], v[34:35], v[16:17] op_sel_hi:[0,1,1]
	v_pk_add_f32 v[16:17], v[132:133], v[16:17] op_sel_hi:[0,1]
	v_pk_mul_f32 v[10:11], v[16:17], v[10:11]
	v_pk_mul_f32 v[16:17], v[130:131], v[32:33] op_sel_hi:[0,1]
	v_pk_fma_f32 v[16:17], v[0:1], v[34:35], v[16:17] op_sel_hi:[0,1,1]
	v_pk_fma_f32 v[16:17], v[134:135], v[18:19], v[16:17] op_sel_hi:[0,1,1]
	v_pk_add_f32 v[16:17], v[132:133], v[16:17] op_sel_hi:[0,1]
	v_pk_mul_f32 v[12:13], v[12:13], v[16:17]
	v_add_u32_e32 v16, 0xe0, v66
	v_cvt_pk_bf16_f32 v10, v10, v11
	v_cvt_pk_bf16_f32 v11, v12, v13
	v_and_b32_e32 v12, 60, v16
	v_add_u32_e32 v17, 0xe4, v66
	v_cmp_ne_u32_e32 vcc, 0, v12
	v_and_b32_e32 v12, 60, v17
	v_cmp_eq_u32_e64 s[4:5], 0, v12
	v_subbrev_co_u32_e64 v12, s[6:7], 0, v16, vcc
	v_ashrrev_i32_e32 v13, 31, v12
	v_lshl_add_u64 v[12:13], v[12:13], 1, v[64:65]
	v_lshrrev_b32_e32 v12, 16, v240
	v_cndmask_b32_e64 v16, v17, v16, s[4:5]
	v_ashrrev_i32_e32 v17, 31, v16
	v_lshl_add_u64 v[16:17], v[16:17], 1, v[64:65]
	v_mov_b32_e32 v32, v241
	v_mov_b32_e32 v33, v242
	v_cndmask_b32_e64 v13, 0, 1.0, vcc
	ds_read2_b64 v[18:21], v67 offset0:56 offset1:60
	s_waitcnt lgkmcnt(0)
; DI float bf2f(bfu v) { return __uint_as_float(((unsigned)v) << 16); }
; DI unsigned pack2(float a, float b) { f32x2_t v = {a, b}; bf16x2_t r = __builtin_convertvector(v, bf16x2_t); return __builtin_bit_cast(unsigned, r); }
; DI float lo16(unsigned u) { return __uint_as_float(u << 16); }
; DI float hi16(unsigned u) { return __uint_as_float(u & 0xffff0000u); }
; template <int L>
; DI void hyena_job(const PX& p, int l, int c, unsigned char* smem) {
;     ...
;     for (int m = 0; m < TPW; m++) {
;       const int t0 = 16 * (w * TPW + m) + 4 * kq_o;
;       const bfu* zr = zx1 + b * L;
;       const uint2 mid = *(const uint2*)(zr + t0);
;       const bool lv = (t0 % RL != 0), rv = ((t0 + 4) % RL != 0);
;       const float lft = bf2f(zr[lv ? t0 - 1 : t0]) * (lv ? 1.f : 0.f);
;       const float rgt = bf2f(zr[rv ? t0 + 4 : t0]) * (rv ? 1.f : 0.f);
;       float z[6];
;       z[0] = lft; z[5] = rgt; z[1] = lo16(mid.x); z[2] = hi16(mid.x); z[3] = lo16(mid.y); z[4] = hi16(mid.y);
;       const uint2 vu = *(const uint2*)(U + b * USTR + t0);
;       const float vv[4] = {lo16(vu.x), hi16(vu.x), lo16(vu.y), hi16(vu.y)};
;       float y[4];
; #pragma unroll
;       for (int r = 0; r < 4; r++) {
;         const float x1 = w1[0] * z[r] + w1[1] * z[r + 1] + w1[2] * z[r + 2] + w1[3];
;         y[r] = x1 * (acc[m][r] + bias0 * vv[r]);
;       }
;       y1pk[m].x = pack2(y[0], y[1]);
;       y1pk[m].y = pack2(y[2], y[3]);
;     }
;   }
;   __syncthreads();
; #pragma unroll
;   for (int m = 0; m < TPW; m++) *(uint2*)(U + b * USTR + 16 * (w * TPW + m) + 4 * kq) = y1pk[m];
;   hy_fill_copies<L>(p, Rg + (size_t)768 * (2 * L), cp);
;     ...
;       const int t0 = 16 * (w * TPW + m) + 4 * kq_o;
;       const bfu* zr = zx2 + b * L;
;       const uint2 mid = *(const uint2*)(zr + t0);
	v_lshlrev_b32_e32 v28, 16, v18
	v_and_b32_e32 v29, 0xffff0000, v18
	v_pk_fma_f32 v[6:7], v[136:137], v[28:29], v[6:7] op_sel_hi:[0,1,1]
	v_lshlrev_b32_e32 v18, 16, v19
	v_and_b32_e32 v19, 0xffff0000, v19
	v_pk_fma_f32 v[8:9], v[136:137], v[18:19], v[8:9] op_sel_hi:[0,1,1]
	v_lshlrev_b32_e32 v18, 16, v20
	v_and_b32_e32 v19, 0xffff0000, v20
	v_pk_fma_f32 v[2:3], v[136:137], v[18:19], v[2:3] op_sel_hi:[0,1,1]
	v_mov_b32_e32 v18, 0
	s_nop 0
	v_lshlrev_b32_e32 v12, 16, v12
	v_mul_f32_e32 v13, v13, v12
	v_and_b32_e32 v12, 0xffff, v243
	v_cndmask_b32_e64 v16, 1.0, 0, s[4:5]
	s_nop 0
	v_and_b32_e32 v34, 0xffff0000, v32
	v_lshlrev_b32_e32 v35, 16, v33
	v_and_b32_e32 v33, 0xffff0000, v33
	s_nop 0
	v_lshlrev_b32_e32 v12, 16, v12
	v_mul_f32_e32 v17, v16, v12
	v_mov_b32_e32 v12, v34
	v_lshlrev_b32_e32 v16, 16, v32
	v_pk_mul_f32 v[12:13], v[130:131], v[12:13]
	v_mov_b32_e32 v32, v35
	v_pk_fma_f32 v[12:13], v[130:131], v[16:17], v[12:13] op_sel:[0,0,1] op_sel_hi:[1,0,0]
	v_mov_b32_e32 v16, v33
	v_pk_fma_f32 v[12:13], v[134:135], v[34:35], v[12:13] op_sel_hi:[0,1,1]
	v_pk_add_f32 v[12:13], v[132:133], v[12:13] op_sel_hi:[0,1]
	v_pk_mul_f32 v[6:7], v[12:13], v[6:7]
	v_pk_mul_f32 v[12:13], v[130:131], v[32:33] op_sel_hi:[0,1]
	v_pk_fma_f32 v[12:13], v[0:1], v[34:35], v[12:13] op_sel_hi:[0,1,1]
	v_pk_fma_f32 v[12:13], v[134:135], v[16:17], v[12:13] op_sel_hi:[0,1,1]
	v_pk_add_f32 v[12:13], v[132:133], v[12:13] op_sel_hi:[0,1]
	v_pk_mul_f32 v[8:9], v[8:9], v[12:13]
	v_add_u32_e32 v12, 0xf0, v66
	v_cvt_pk_bf16_f32 v6, v6, v7
	v_cvt_pk_bf16_f32 v7, v8, v9
	v_and_b32_e32 v8, 60, v12
	v_add_u32_e32 v13, 0xf4, v66
	v_cmp_ne_u32_e32 vcc, 0, v8
	v_and_b32_e32 v8, 60, v13
	v_cmp_eq_u32_e64 s[4:5], 0, v8
	v_subbrev_co_u32_e64 v8, s[6:7], 0, v12, vcc
	v_ashrrev_i32_e32 v9, 31, v8
	v_lshl_add_u64 v[8:9], v[8:9], 1, v[64:65]
	v_lshrrev_b32_e32 v8, 16, v244
	v_cndmask_b32_e64 v12, v13, v12, s[4:5]
	v_ashrrev_i32_e32 v13, 31, v12
	v_cndmask_b32_e64 v9, 0, 1.0, vcc
	v_lshl_add_u64 v[12:13], v[12:13], 1, v[64:65]
	s_nop 0
	v_lshlrev_b32_e32 v8, 16, v8
	v_mul_f32_e32 v9, v9, v8
	v_and_b32_e32 v8, 0xffff, v247
	v_cndmask_b32_e64 v12, 1.0, 0, s[4:5]
	v_and_b32_e32 v13, 0xffff0000, v21
	s_nop 0
	v_lshlrev_b32_e32 v8, 16, v8
	v_mul_f32_e32 v17, v12, v8
	v_lshlrev_b32_e32 v12, 16, v21
	v_mov_b32_e32 v20, v245
	v_mov_b32_e32 v21, v246
	v_pk_fma_f32 v[4:5], v[136:137], v[12:13], v[4:5] op_sel_hi:[0,1,1]
	s_barrier
	s_nop 0
	v_mov_b32_e32 v250, s70
	v_mov_b32_e32 v251, 0x12000
	v_mad_u64_u32 v[248:249], s[4:5], v250, v251, 0
	v_readlane_b32 s4, v253, 29
	v_readlane_b32 s5, v253, 30
	v_and_b32_e32 v250, 15, v188
	v_lshlrev_b32_e32 v250, 12, v250
	v_lshrrev_b32_e32 v251, 6, v188
	v_lshl_add_u32 v250, v251, 9, v250
	v_bfe_u32 v251, v188, 4, 2
	v_lshl_add_u32 v250, v251, 3, v250
	v_mov_b32_e32 v251, 0
	v_lshl_add_u64 v[248:249], v[248:249], 0, s[4:5]
	v_lshl_add_u64 v[248:249], v[248:249], 0, v[250:251]
	global_load_dwordx4 v[152:155], v[248:249], off offset:-4
	global_load_dwordx4 v[156:159], v[248:249], off offset:28
	global_load_dwordx4 v[160:163], v[248:249], off offset:60
	global_load_dwordx4 v[164:167], v[248:249], off offset:92
	global_load_dwordx4 v[168:171], v[248:249], off offset:124
	global_load_dwordx4 v[172:175], v[248:249], off offset:156
	global_load_dwordx4 v[176:179], v[248:249], off offset:188
	global_load_dwordx4 v[180:183], v[248:249], off offset:220
	global_load_dwordx4 v[216:219], v[248:249], off offset:252
	global_load_dwordx4 v[220:223], v[248:249], off offset:284
	global_load_dwordx4 v[224:227], v[248:249], off offset:316
	global_load_dwordx4 v[228:231], v[248:249], off offset:348
	global_load_dwordx4 v[232:235], v[248:249], off offset:380
	global_load_dwordx4 v[236:239], v[248:249], off offset:412
	global_load_dwordx4 v[240:243], v[248:249], off offset:444
	global_load_dwordx4 v[244:247], v[248:249], off offset:476
	v_and_b32_e32 v28, 0xffff0000, v20
	v_mov_b32_e32 v8, v28
	v_lshlrev_b32_e32 v16, 16, v20
	v_pk_mul_f32 v[8:9], v[130:131], v[8:9]
	v_lshlrev_b32_e32 v29, 16, v21
	v_pk_fma_f32 v[8:9], v[130:131], v[16:17], v[8:9] op_sel:[0,0,1] op_sel_hi:[1,0,0]
	v_and_b32_e32 v21, 0xffff0000, v21
	v_pk_fma_f32 v[8:9], v[134:135], v[28:29], v[8:9] op_sel_hi:[0,1,1]
	v_mov_b32_e32 v20, v29
	v_pk_add_f32 v[8:9], v[132:133], v[8:9] op_sel_hi:[0,1]
	v_pk_mul_f32 v[2:3], v[8:9], v[2:3]
	v_pk_mul_f32 v[8:9], v[130:131], v[20:21] op_sel_hi:[0,1]
	v_pk_fma_f32 v[8:9], v[0:1], v[28:29], v[8:9] op_sel_hi:[0,1,1]
	v_mov_b32_e32 v16, v21
	v_pk_fma_f32 v[8:9], v[134:135], v[16:17], v[8:9] op_sel_hi:[0,1,1]
	v_pk_add_f32 v[8:9], v[132:133], v[8:9] op_sel_hi:[0,1]
	v_pk_mul_f32 v[4:5], v[4:5], v[8:9]
	v_cvt_pk_bf16_f32 v2, v2, v3
	v_lshl_add_u32 v0, v125, 3, v129
	v_cvt_pk_bf16_f32 v3, v4, v5
	ds_write2_b64 v0, v[58:59], v[60:61] offset1:4
	ds_write2_b64 v0, v[54:55], v[56:57] offset0:8 offset1:12
	ds_write2_b64 v0, v[46:47], v[42:43] offset0:16 offset1:20
	ds_write2_b64 v0, v[38:39], v[40:41] offset0:24 offset1:28
	ds_write2_b64 v0, v[30:31], v[26:27] offset0:32 offset1:36
	ds_write2_b64 v0, v[22:23], v[24:25] offset0:40 offset1:44
	ds_write2_b64 v0, v[14:15], v[10:11] offset0:48 offset1:52
	ds_write2_b64 v0, v[6:7], v[2:3] offset0:56 offset1:60
	v_mov_b32_e32 v2, v188
	v_mov_b32_e32 v0, 0
	v_cmp_gt_i32_e32 vcc, s0, v2
	s_and_saveexec_b64 s[4:5], vcc
	s_cbranch_execz .LBB0_561
	v_ashrrev_i32_e32 v3, 31, v2
	v_lshl_add_u64 v[4:5], v[2:3], 1, s[24:25]
	global_load_ushort v18, v[4:5], off

; DI f32x4 mfma16(bf16x8 a, bf16x8 b, f32x4 c) { return __builtin_amdgcn_mfma_f32_16x16x32_bf16(a, b, c, 0, 0, 0); }
; template <int L, int TPW>
; DI void hy_mfma(const PX& p, f32x4 (&acc)[TPW], const bfu* cp, const bfu* U) {
;     ...
;     for (int k = 0; k < NS / 8; k++) {
; #pragma unroll
;       for (int j = 0; j < 8; j++) {
;         const int ss = 8 * k + j;
;         const int qb = qb0 + 4 * ss;
;         F[(0 - 2 * j) & 15] = *(const bf16x8*)(cpe + 8 * qb);
;         F[(1 - 2 * j) & 15] = *(const bf16x8*)(cpe + 8 * (qb - 2));
;         const bf16x8 bfr = *(const bf16x8*)(Ub + 32 * ss);
; #pragma unroll
;         for (int m = 0; m < 16; m++) acc[m] = mfma16(F[(m - 2 * j) & 15], bfr, acc[m]);
;       }
.LBB0_584:
	v_add_u32_e32 v133, s0, v130
	v_add_u32_e32 v132, 0x10100, v133
	ds_read_b128 v[134:137], v132
	v_add_u32_e32 v132, s0, v131
	s_addk_i32 s0, 0x200
	s_cmpk_lg_i32 s0, 0x1000
	s_waitcnt lgkmcnt(0)
	v_mfma_f32_16x16x32_bf16 v[6:9], v[74:77], v[134:137], v[6:9]
	v_mfma_f32_16x16x32_bf16 v[74:77], v[82:85], v[134:137], v[2:5]
	s_nop 2
	ds_read_b128 v[2:5], v132 offset:32
	v_mfma_f32_16x16x32_bf16 v[138:141], v[62:65], v[134:137], v[50:53]
	s_nop 2
	ds_read_b128 v[50:53], v132
	s_waitcnt lgkmcnt(1)
	v_mfma_f32_16x16x32_bf16 v[82:85], v[2:5], v[134:137], v[118:121]
	s_nop 2
	v_add_u32_e32 v118, 0x10140, v133
	ds_read_b128 v[118:121], v118
	v_mfma_f32_16x16x32_bf16 v[14:17], v[86:89], v[134:137], v[14:17]
	s_waitcnt lgkmcnt(0)
	v_mfma_f32_16x16x32_bf16 v[6:9], v[86:89], v[118:121], v[6:9]
	v_add_u32_e32 v86, 0x10180, v133
	v_mfma_f32_16x16x32_bf16 v[54:57], v[58:61], v[134:137], v[54:57]
	v_mfma_f32_16x16x32_bf16 v[46:49], v[66:69], v[134:137], v[46:49]
	v_mfma_f32_16x16x32_bf16 v[42:45], v[90:93], v[134:137], v[42:45]
	v_mfma_f32_16x16x32_bf16 v[38:41], v[70:73], v[134:137], v[38:41]
	v_mfma_f32_16x16x32_bf16 v[34:37], v[78:81], v[134:137], v[34:37]
	v_mfma_f32_16x16x32_bf16 v[30:33], v[98:101], v[134:137], v[30:33]
	v_mfma_f32_16x16x32_bf16 v[26:29], v[110:113], v[134:137], v[26:29]
	v_mfma_f32_16x16x32_bf16 v[22:25], v[102:105], v[134:137], v[22:25]
	v_mfma_f32_16x16x32_bf16 v[18:21], v[106:109], v[134:137], v[18:21]
	v_mfma_f32_16x16x32_bf16 v[10:13], v[94:97], v[134:137], v[10:13]
	v_mfma_f32_16x16x32_bf16 v[114:117], v[50:53], v[134:137], v[114:117]
	v_mfma_f32_16x16x32_bf16 v[134:137], v[50:53], v[118:121], v[138:141]
	s_nop 2
	ds_read_b128 v[138:141], v86
	v_mfma_f32_16x16x32_bf16 v[74:77], v[94:97], v[118:121], v[74:77]
	s_waitcnt lgkmcnt(0)
	v_mfma_f32_16x16x32_bf16 v[86:89], v[106:109], v[138:141], v[74:77]
	v_mfma_f32_16x16x32_bf16 v[14:17], v[102:105], v[118:121], v[14:17]
	s_nop 4
	ds_read_b128 v[74:77], v132 offset:96
	s_waitcnt lgkmcnt(0)
	v_mfma_f32_16x16x32_bf16 v[94:97], v[74:77], v[118:121], v[82:85]
	s_nop 2
	ds_read_b128 v[82:85], v132 offset:64
	v_mfma_f32_16x16x32_bf16 v[6:9], v[102:105], v[138:141], v[6:9]
	s_waitcnt lgkmcnt(0)
	v_mfma_f32_16x16x32_bf16 v[102:105], v[82:85], v[118:121], v[114:117]
	s_nop 2
	v_add_u32_e32 v114, 0x101c0, v133
	ds_read_b128 v[114:117], v114
	v_mfma_f32_16x16x32_bf16 v[22:25], v[98:101], v[118:121], v[22:25]
	v_mfma_f32_16x16x32_bf16 v[14:17], v[98:101], v[138:141], v[14:17]
	s_waitcnt lgkmcnt(0)
	v_mfma_f32_16x16x32_bf16 v[6:9], v[98:101], v[114:117], v[6:9]
	v_mfma_f32_16x16x32_bf16 v[98:101], v[110:113], v[114:117], v[86:89]
	s_nop 2
	ds_read_b128 v[86:89], v132 offset:160
	v_mfma_f32_16x16x32_bf16 v[10:13], v[106:109], v[118:121], v[10:13]
	v_mfma_f32_16x16x32_bf16 v[18:21], v[110:113], v[118:121], v[18:21]
	v_mfma_f32_16x16x32_bf16 v[10:13], v[110:113], v[138:141], v[10:13]
	s_waitcnt lgkmcnt(0)
	v_mfma_f32_16x16x32_bf16 v[110:113], v[86:89], v[138:141], v[94:97]
	s_nop 2
	ds_read_b128 v[94:97], v132 offset:128
	v_mfma_f32_16x16x32_bf16 v[54:57], v[2:5], v[118:121], v[54:57]
	v_mfma_f32_16x16x32_bf16 v[46:49], v[58:61], v[118:121], v[46:49]
	v_mfma_f32_16x16x32_bf16 v[42:45], v[62:65], v[118:121], v[42:45]
	v_mfma_f32_16x16x32_bf16 v[38:41], v[66:69], v[118:121], v[38:41]
	v_mfma_f32_16x16x32_bf16 v[34:37], v[90:93], v[118:121], v[34:37]
	v_mfma_f32_16x16x32_bf16 v[30:33], v[70:73], v[118:121], v[30:33]
	v_mfma_f32_16x16x32_bf16 v[26:29], v[78:81], v[118:121], v[26:29]
	v_mfma_f32_16x16x32_bf16 v[106:109], v[82:85], v[138:141], v[134:137]
	s_waitcnt lgkmcnt(0)
	v_mfma_f32_16x16x32_bf16 v[118:121], v[94:97], v[138:141], v[102:105]
	s_nop 2
	v_add_u32_e32 v102, 0x10200, v133
	v_mfma_f32_16x16x32_bf16 v[46:49], v[2:5], v[138:141], v[46:49]
	v_mfma_f32_16x16x32_bf16 v[42:45], v[50:53], v[138:141], v[42:45]
	v_mfma_f32_16x16x32_bf16 v[38:41], v[58:61], v[138:141], v[38:41]
	v_mfma_f32_16x16x32_bf16 v[34:37], v[62:65], v[138:141], v[34:37]
	v_mfma_f32_16x16x32_bf16 v[30:33], v[66:69], v[138:141], v[30:33]
	v_mfma_f32_16x16x32_bf16 v[26:29], v[90:93], v[138:141], v[26:29]
	v_mfma_f32_16x16x32_bf16 v[22:25], v[70:73], v[138:141], v[22:25]
	v_mfma_f32_16x16x32_bf16 v[18:21], v[78:81], v[138:141], v[18:21]
	v_mfma_f32_16x16x32_bf16 v[54:57], v[74:77], v[138:141], v[54:57]
	ds_read_b128 v[138:141], v102
	v_mfma_f32_16x16x32_bf16 v[134:137], v[94:97], v[114:117], v[106:109]
	s_nop 2
	ds_read_b128 v[106:109], v132 offset:192
	ds_read_b128 v[102:105], v132 offset:224
	v_mfma_f32_16x16x32_bf16 v[14:17], v[70:73], v[114:117], v[14:17]
	s_waitcnt lgkmcnt(2)
	v_mfma_f32_16x16x32_bf16 v[6:9], v[70:73], v[138:141], v[6:9]
	v_mfma_f32_16x16x32_bf16 v[70:73], v[78:81], v[138:141], v[98:101]
	s_nop 2
	v_add_u32_e32 v98, 0x10240, v133
	v_mfma_f32_16x16x32_bf16 v[46:49], v[74:77], v[114:117], v[46:49]
	v_mfma_f32_16x16x32_bf16 v[42:45], v[82:85], v[114:117], v[42:45]
	v_mfma_f32_16x16x32_bf16 v[38:41], v[2:5], v[114:117], v[38:41]
	v_mfma_f32_16x16x32_bf16 v[34:37], v[50:53], v[114:117], v[34:37]
	v_mfma_f32_16x16x32_bf16 v[30:33], v[58:61], v[114:117], v[30:33]
	v_mfma_f32_16x16x32_bf16 v[26:29], v[62:65], v[114:117], v[26:29]
	v_mfma_f32_16x16x32_bf16 v[22:25], v[66:69], v[114:117], v[22:25]
	v_mfma_f32_16x16x32_bf16 v[18:21], v[90:93], v[114:117], v[18:21]
	v_mfma_f32_16x16x32_bf16 v[10:13], v[78:81], v[114:117], v[10:13]
	v_mfma_f32_16x16x32_bf16 v[54:57], v[86:89], v[114:117], v[54:57]
	s_waitcnt lgkmcnt(0)
; DI f32x4 mfma16(bf16x8 a, bf16x8 b, f32x4 c) { return __builtin_amdgcn_mfma_f32_16x16x32_bf16(a, b, c, 0, 0, 0); }
; template <int L, int TPW>
; DI void hy_mfma(const PX& p, f32x4 (&acc)[TPW], const bfu* cp, const bfu* U) {
;     ...
;     for (int k = 0; k < NS / 8; k++) {
; #pragma unroll
;       for (int j = 0; j < 8; j++) {
;         const int ss = 8 * k + j;
;         const int qb = qb0 + 4 * ss;
;         F[(0 - 2 * j) & 15] = *(const bf16x8*)(cpe + 8 * qb);
;         F[(1 - 2 * j) & 15] = *(const bf16x8*)(cpe + 8 * (qb - 2));
;         const bf16x8 bfr = *(const bf16x8*)(Ub + 32 * ss);
; #pragma unroll
;         for (int m = 0; m < 16; m++) acc[m] = mfma16(F[(m - 2 * j) & 15], bfr, acc[m]);
;       }
	v_mfma_f32_16x16x32_bf16 v[78:81], v[102:105], v[114:117], v[110:113]
	v_mfma_f32_16x16x32_bf16 v[114:117], v[106:109], v[114:117], v[118:121]
	s_nop 1
	ds_read_b128 v[110:113], v132 offset:256
	v_mfma_f32_16x16x32_bf16 v[118:121], v[106:109], v[138:141], v[134:137]
	s_nop 2
	ds_read_b128 v[134:137], v98
	ds_read_b128 v[98:101], v132 offset:288
	v_mfma_f32_16x16x32_bf16 v[14:17], v[66:69], v[138:141], v[14:17]
	s_waitcnt lgkmcnt(1)
	v_mfma_f32_16x16x32_bf16 v[6:9], v[66:69], v[134:137], v[6:9]
	v_mfma_f32_16x16x32_bf16 v[66:69], v[90:93], v[134:137], v[70:73]
	s_nop 2
	v_add_u32_e32 v70, 0x10280, v133
	v_mfma_f32_16x16x32_bf16 v[10:13], v[90:93], v[138:141], v[10:13]
	v_mfma_f32_16x16x32_bf16 v[90:93], v[110:113], v[138:141], v[114:117]
	v_mfma_f32_16x16x32_bf16 v[114:117], v[110:113], v[134:137], v[118:121]
	s_nop 2
	ds_read_b128 v[118:121], v70
	ds_read_b128 v[70:73], v132 offset:352
	s_waitcnt lgkmcnt(2)
	v_mfma_f32_16x16x32_bf16 v[78:81], v[98:101], v[138:141], v[78:81]
	v_mfma_f32_16x16x32_bf16 v[22:25], v[58:61], v[138:141], v[22:25]
	v_mfma_f32_16x16x32_bf16 v[18:21], v[62:65], v[138:141], v[18:21]
	v_mfma_f32_16x16x32_bf16 v[14:17], v[58:61], v[134:137], v[14:17]
	v_mfma_f32_16x16x32_bf16 v[10:13], v[62:65], v[134:137], v[10:13]
	s_waitcnt lgkmcnt(1)
	v_mfma_f32_16x16x32_bf16 v[6:9], v[58:61], v[118:121], v[6:9]
	v_mfma_f32_16x16x32_bf16 v[58:61], v[62:65], v[118:121], v[66:69]
	s_waitcnt lgkmcnt(0)
	v_mfma_f32_16x16x32_bf16 v[62:65], v[70:73], v[134:137], v[78:81]
	s_nop 0
	v_add_u32_e32 v66, 0x102c0, v133
	s_nop 0
	ds_read_b128 v[78:81], v132 offset:320
	v_mfma_f32_16x16x32_bf16 v[46:49], v[86:89], v[138:141], v[46:49]
	v_mfma_f32_16x16x32_bf16 v[42:45], v[94:97], v[138:141], v[42:45]
	v_mfma_f32_16x16x32_bf16 v[38:41], v[74:77], v[138:141], v[38:41]
	v_mfma_f32_16x16x32_bf16 v[34:37], v[82:85], v[138:141], v[34:37]
	v_mfma_f32_16x16x32_bf16 v[30:33], v[2:5], v[138:141], v[30:33]
	v_mfma_f32_16x16x32_bf16 v[26:29], v[50:53], v[138:141], v[26:29]
	v_mfma_f32_16x16x32_bf16 v[54:57], v[102:105], v[138:141], v[54:57]
	ds_read_b128 v[138:141], v66
	ds_read_b128 v[66:69], v132 offset:416
	v_mfma_f32_16x16x32_bf16 v[46:49], v[102:105], v[134:137], v[46:49]
	v_mfma_f32_16x16x32_bf16 v[42:45], v[106:109], v[134:137], v[42:45]
	v_mfma_f32_16x16x32_bf16 v[38:41], v[86:89], v[134:137], v[38:41]
	v_mfma_f32_16x16x32_bf16 v[34:37], v[94:97], v[134:137], v[34:37]
	v_mfma_f32_16x16x32_bf16 v[30:33], v[74:77], v[134:137], v[30:33]
	v_mfma_f32_16x16x32_bf16 v[26:29], v[82:85], v[134:137], v[26:29]
	v_mfma_f32_16x16x32_bf16 v[22:25], v[2:5], v[134:137], v[22:25]
	v_mfma_f32_16x16x32_bf16 v[18:21], v[50:53], v[134:137], v[18:21]
	v_mfma_f32_16x16x32_bf16 v[54:57], v[98:101], v[134:137], v[54:57]
	v_mfma_f32_16x16x32_bf16 v[14:17], v[2:5], v[118:121], v[14:17]
	s_waitcnt lgkmcnt(2)
	v_mfma_f32_16x16x32_bf16 v[134:137], v[78:81], v[134:137], v[90:93]
	s_waitcnt lgkmcnt(1)
	v_mfma_f32_16x16x32_bf16 v[6:9], v[2:5], v[138:141], v[6:9]
	s_nop 0
	ds_read_b128 v[90:93], v132 offset:384
	v_mfma_f32_16x16x32_bf16 v[2:5], v[50:53], v[138:141], v[58:61]
	s_nop 2
	ds_read_b128 v[58:61], v132 offset:480
	s_waitcnt lgkmcnt(2)
	v_mfma_f32_16x16x32_bf16 v[62:65], v[66:69], v[118:121], v[62:65]
	v_mfma_f32_16x16x32_bf16 v[46:49], v[98:101], v[118:121], v[46:49]
	v_mfma_f32_16x16x32_bf16 v[42:45], v[110:113], v[118:121], v[42:45]
	v_mfma_f32_16x16x32_bf16 v[38:41], v[102:105], v[118:121], v[38:41]
	v_mfma_f32_16x16x32_bf16 v[34:37], v[106:109], v[118:121], v[34:37]
	v_mfma_f32_16x16x32_bf16 v[30:33], v[86:89], v[118:121], v[30:33]
	v_mfma_f32_16x16x32_bf16 v[26:29], v[94:97], v[118:121], v[26:29]
	v_mfma_f32_16x16x32_bf16 v[22:25], v[74:77], v[118:121], v[22:25]
	v_mfma_f32_16x16x32_bf16 v[18:21], v[82:85], v[118:121], v[18:21]
	v_mfma_f32_16x16x32_bf16 v[10:13], v[50:53], v[118:121], v[10:13]
	v_mfma_f32_16x16x32_bf16 v[54:57], v[70:73], v[118:121], v[54:57]
	v_mfma_f32_16x16x32_bf16 v[114:117], v[78:81], v[118:121], v[114:117]
	s_waitcnt lgkmcnt(1)
	v_mfma_f32_16x16x32_bf16 v[134:137], v[90:93], v[118:121], v[134:137]
	s_waitcnt lgkmcnt(0)
	v_mfma_f32_16x16x32_bf16 v[118:121], v[58:61], v[138:141], v[62:65]
	s_nop 2
	ds_read_b128 v[62:65], v132 offset:448
	v_mfma_f32_16x16x32_bf16 v[46:49], v[70:73], v[138:141], v[46:49]
	v_mfma_f32_16x16x32_bf16 v[42:45], v[78:81], v[138:141], v[42:45]
	v_mfma_f32_16x16x32_bf16 v[38:41], v[98:101], v[138:141], v[38:41]
	v_mfma_f32_16x16x32_bf16 v[34:37], v[110:113], v[138:141], v[34:37]
	v_mfma_f32_16x16x32_bf16 v[30:33], v[102:105], v[138:141], v[30:33]
	v_mfma_f32_16x16x32_bf16 v[26:29], v[106:109], v[138:141], v[26:29]
	v_mfma_f32_16x16x32_bf16 v[22:25], v[86:89], v[138:141], v[22:25]
	v_mfma_f32_16x16x32_bf16 v[18:21], v[94:97], v[138:141], v[18:21]
	v_mfma_f32_16x16x32_bf16 v[14:17], v[74:77], v[138:141], v[14:17]
	v_mfma_f32_16x16x32_bf16 v[10:13], v[82:85], v[138:141], v[10:13]
	v_mfma_f32_16x16x32_bf16 v[54:57], v[66:69], v[138:141], v[54:57]
	v_mfma_f32_16x16x32_bf16 v[50:53], v[90:93], v[138:141], v[114:117]
	s_waitcnt lgkmcnt(0)
	v_mfma_f32_16x16x32_bf16 v[114:117], v[62:65], v[138:141], v[134:137]
	s_cbranch_scc1 .LBB0_584
; #define OPAQUE(x) asm volatile("" : "+v"(x))
; DI float bf2f(bfu v) { return __uint_as_float(((unsigned)v) << 16); }
; DI unsigned pack2(float a, float b) { f32x2_t v = {a, b}; bf16x2_t r = __builtin_convertvector(v, bf16x2_t); return __builtin_bit_cast(unsigned, r); }
; DI float lo16(unsigned u) { return __uint_as_float(u << 16); }
; DI float hi16(unsigned u) { return __uint_as_float(u & 0xffff0000u); }
; template <int L>
; DI void hyena_job(const PX& p, int l, int c, unsigned char* smem) {
;     ...
;     bfu* yrow = (bfu*)zv;
;     int kq_o = kq;
;     OPAQUE(kq_o);
; #pragma unroll
;     for (int m = 0; m < TPW; m++) {
;       const int t0 = 16 * (w * TPW + m) + 4 * kq_o;
;       const bfu* zr = zx2 + b * L;
;       const uint2 mid = *(const uint2*)(zr + t0);
;       const bool lv = (t0 % RL != 0), rv = ((t0 + 4) % RL != 0);
;       const float lft = bf2f(zr[lv ? t0 - 1 : t0]) * (lv ? 1.f : 0.f);
;       const float rgt = bf2f(zr[rv ? t0 + 4 : t0]) * (rv ? 1.f : 0.f);
;       float z[6];
;       z[0] = lft; z[5] = rgt; z[1] = lo16(mid.x); z[2] = hi16(mid.x); z[3] = lo16(mid.y); z[4] = hi16(mid.y);
;       const uint2 vu = *(const uint2*)(U + b * USTR + t0);
;       const float vv[4] = {lo16(vu.x), hi16(vu.x), lo16(vu.y), hi16(vu.y)};
;       float y2[4];
; #pragma unroll
;       for (int r = 0; r < 4; r++) {
;         const float x2 = w2[0] * z[r] + w2[1] * z[r + 1] + w2[2] * z[r + 2] + w2[3];
;         y2[r] = x2 * (acc[m][r] + bias1 * vv[r]);
;       }
;       uint2 o2; o2.x = pack2(y2[0], y2[1]); o2.y = pack2(y2[2], y2[3]);
;       *(uint2*)(yrow + b * L + t0) = o2;
	s_waitcnt vmcnt(0)
	s_mul_hi_i32 s1, s70, 0x12000
	s_mul_i32 s70, s70, 0x12000
	v_readlane_b32 s2, v253, 29
	v_readlane_b32 s3, v253, 30
	s_add_u32 s0, s2, s70
	s_addc_u32 s1, s3, s1
	v_lshlrev_b32_e32 v0, 1, v0
	v_lshl_add_u64 v[64:65], s[0:1], 0, v[0:1]
	v_lshl_add_u32 v66, v125, 2, v127
	v_lshl_add_u64 v[62:63], s[22:23], 0, v[0:1]
	v_and_b32_e32 v0, 15, v125
	v_cmp_ne_u32_e32 vcc, 0, v0
	v_add_u32_e32 v0, 4, v66
	v_ashrrev_i32_e32 v67, 31, v66
	v_and_b32_e32 v58, 60, v0
	v_lshlrev_b64 v[70:71], 1, v[66:67]
	v_cmp_eq_u32_e64 s[4:5], 0, v58
	v_cndmask_b32_e64 v58, 0, -1, vcc
	v_lshl_add_u64 v[68:69], v[64:65], 0, v[70:71]
	v_mov_b32_e32 v59, v58
	v_lshl_add_u64 v[58:59], v[58:59], 1, v[68:69]
	v_lshrrev_b32_e32 v58, 16, v152
	v_cndmask_b32_e64 v74, 0, 1.0, vcc
	v_mov_b32_e32 v80, v153
	v_mov_b32_e32 v81, v154
	v_lshl_add_u32 v67, v125, 3, v129
	v_lshl_add_u64 v[62:63], v[62:63], 0, v[70:71]
	v_add_u32_e32 v70, 16, v66
	v_add_u32_e32 v71, 20, v66
	s_mov_b64 s[0:1], 0x1e0
	s_nop 0
	v_lshlrev_b32_e32 v58, 16, v58
	v_mul_f32_e32 v73, v74, v58
	v_cndmask_b32_e64 v58, v0, v66, s[4:5]
	v_ashrrev_i32_e32 v59, 31, v58
	v_lshl_add_u64 v[58:59], v[58:59], 1, v[64:65]
	v_and_b32_e32 v0, 0xffff, v155
	v_cndmask_b32_e64 v58, 1.0, 0, s[4:5]
	s_nop 0
	v_and_b32_e32 v82, 0xffff0000, v80
	v_mov_b32_e32 v72, v82
	v_pk_mul_f32 v[72:73], v[122:123], v[72:73]
	v_lshlrev_b32_e32 v83, 16, v81
	v_and_b32_e32 v81, 0xffff0000, v81
	v_mov_b32_e32 v76, v81
	s_nop 0
	v_lshlrev_b32_e32 v0, 16, v0
	v_mul_f32_e32 v77, v58, v0
	ds_read2_b64 v[58:61], v67 offset1:4
	v_lshlrev_b32_e32 v0, 16, v80
	v_pk_fma_f32 v[72:73], v[122:123], v[0:1], v[72:73] op_sel:[0,0,1] op_sel_hi:[1,0,0]
	v_mov_b32_e32 v80, v83
	v_pk_fma_f32 v[72:73], v[126:127], v[82:83], v[72:73] op_sel_hi:[0,1,1]
	s_waitcnt lgkmcnt(0)
	v_lshlrev_b32_e32 v78, 16, v58
	v_and_b32_e32 v79, 0xffff0000, v58
	v_pk_fma_f32 v[78:79], v[128:129], v[78:79], v[118:119] op_sel_hi:[0,1,1]
	v_pk_add_f32 v[72:73], v[124:125], v[72:73] op_sel_hi:[0,1]
	v_pk_mul_f32 v[72:73], v[72:73], v[78:79]
	v_mov_b32_e32 v0, v123
	v_pk_mul_f32 v[78:79], v[122:123], v[80:81] op_sel_hi:[0,1]
	v_pk_fma_f32 v[78:79], v[0:1], v[82:83], v[78:79] op_sel_hi:[0,1,1]
	v_lshlrev_b32_e32 v58, 16, v59
	v_and_b32_e32 v59, 0xffff0000, v59
	v_pk_fma_f32 v[76:77], v[126:127], v[76:77], v[78:79] op_sel_hi:[0,1,1]
	v_pk_add_f32 v[76:77], v[124:125], v[76:77] op_sel_hi:[0,1]
	v_pk_fma_f32 v[58:59], v[128:129], v[58:59], v[120:121] op_sel_hi:[0,1,1]
	v_pk_mul_f32 v[58:59], v[58:59], v[76:77]
	v_cvt_pk_bf16_f32 v72, v72, v73
	v_cvt_pk_bf16_f32 v73, v58, v59
	v_and_b32_e32 v58, 60, v70
	v_cmp_ne_u32_e64 s[4:5], 0, v58
	v_and_b32_e32 v58, 60, v71
	v_cmp_eq_u32_e64 s[6:7], 0, v58
	v_subbrev_co_u32_e64 v58, s[8:9], 0, v70, s[4:5]
	v_ashrrev_i32_e32 v59, 31, v58
	global_store_dwordx2 v[62:63], v[72:73], off
	v_lshl_add_u64 v[58:59], v[58:59], 1, v[64:65]
	v_lshrrev_b32_e32 v58, 16, v156
	v_cndmask_b32_e64 v70, v71, v70, s[6:7]
	v_ashrrev_i32_e32 v71, 31, v70
	v_lshl_add_u64 v[70:71], v[70:71], 1, v[64:65]
	v_mov_b32_e32 v76, v157
	v_mov_b32_e32 v77, v158
	v_cndmask_b32_e64 v59, 0, 1.0, s[4:5]
	v_lshlrev_b32_e32 v72, 16, v60
	v_and_b32_e32 v73, 0xffff0000, v60
	v_pk_fma_f32 v[72:73], v[128:129], v[72:73], v[114:115] op_sel_hi:[0,1,1]
	v_lshlrev_b32_e32 v60, 16, v61
	v_and_b32_e32 v61, 0xffff0000, v61
	v_pk_fma_f32 v[60:61], v[128:129], v[60:61], v[116:117] op_sel_hi:[0,1,1]
	s_nop 0
	v_lshlrev_b32_e32 v58, 16, v58
	v_mul_f32_e32 v59, v59, v58
	v_and_b32_e32 v58, 0xffff, v159
	v_cndmask_b32_e64 v70, 1.0, 0, s[6:7]
	s_nop 0
	v_and_b32_e32 v78, 0xffff0000, v76
	v_lshlrev_b32_e32 v79, 16, v77
	v_and_b32_e32 v77, 0xffff0000, v77
	s_nop 0
	v_lshlrev_b32_e32 v58, 16, v58
	v_mul_f32_e32 v71, v70, v58
	v_mov_b32_e32 v58, v78
	v_lshlrev_b32_e32 v70, 16, v76
	v_pk_mul_f32 v[58:59], v[122:123], v[58:59]
	v_mov_b32_e32 v76, v79
	v_pk_fma_f32 v[58:59], v[122:123], v[70:71], v[58:59] op_sel:[0,0,1] op_sel_hi:[1,0,0]
	v_mov_b32_e32 v70, v77
	v_pk_fma_f32 v[58:59], v[126:127], v[78:79], v[58:59] op_sel_hi:[0,1,1]
	v_pk_add_f32 v[58:59], v[124:125], v[58:59] op_sel_hi:[0,1]
	v_pk_mul_f32 v[58:59], v[58:59], v[72:73]
	v_pk_mul_f32 v[72:73], v[122:123], v[76:77] op_sel_hi:[0,1]
	v_pk_fma_f32 v[72:73], v[0:1], v[78:79], v[72:73] op_sel_hi:[0,1,1]
	v_pk_fma_f32 v[70:71], v[126:127], v[70:71], v[72:73] op_sel_hi:[0,1,1]
	v_pk_add_f32 v[70:71], v[124:125], v[70:71] op_sel_hi:[0,1]
	v_pk_mul_f32 v[60:61], v[60:61], v[70:71]
	v_cvt_pk_bf16_f32 v58, v58, v59
	v_cvt_pk_bf16_f32 v59, v60, v61
	v_add_u32_e32 v60, 32, v66
	global_store_dwordx2 v[62:63], v[58:59], off offset:32
	v_and_b32_e32 v58, 60, v60
	v_add_u32_e32 v61, 36, v66
	v_cmp_ne_u32_e64 s[4:5], 0, v58
	v_and_b32_e32 v58, 60, v61
	v_cmp_eq_u32_e64 s[6:7], 0, v58
	v_subbrev_co_u32_e64 v58, s[8:9], 0, v60, s[4:5]
	v_ashrrev_i32_e32 v59, 31, v58
	v_lshl_add_u64 v[58:59], v[58:59], 1, v[64:65]
	v_lshrrev_b32_e32 v58, 16, v160
	s_nop 0
	v_mov_b32_e32 v78, v161
	v_mov_b32_e32 v79, v162
	v_cndmask_b32_e64 v59, 0, 1.0, s[4:5]
	s_nop 0
	v_lshlrev_b32_e32 v58, 16, v58
	v_mul_f32_e32 v73, v59, v58
	v_cndmask_b32_e64 v58, v61, v60, s[6:7]
	v_ashrrev_i32_e32 v59, 31, v58
	v_lshl_add_u64 v[58:59], v[58:59], 1, v[64:65]
	v_and_b32_e32 v58, 0xffff, v163
	v_cndmask_b32_e64 v59, 1.0, 0, s[6:7]
	s_nop 0
	v_and_b32_e32 v80, 0xffff0000, v78
	v_mov_b32_e32 v72, v80
	v_lshlrev_b32_e32 v70, 16, v78
	v_pk_mul_f32 v[72:73], v[122:123], v[72:73]
	v_lshlrev_b32_e32 v81, 16, v79
	v_and_b32_e32 v79, 0xffff0000, v79
	v_mov_b32_e32 v78, v81
	s_nop 0
	v_lshlrev_b32_e32 v58, 16, v58
	v_mul_f32_e32 v71, v59, v58
	ds_read2_b64 v[58:61], v67 offset0:8 offset1:12
	v_pk_fma_f32 v[72:73], v[122:123], v[70:71], v[72:73] op_sel:[0,0,1] op_sel_hi:[1,0,0]
	v_mov_b32_e32 v70, v79
	v_pk_fma_f32 v[72:73], v[126:127], v[80:81], v[72:73] op_sel_hi:[0,1,1]
	v_pk_add_f32 v[72:73], v[124:125], v[72:73] op_sel_hi:[0,1]
	s_waitcnt lgkmcnt(0)
; DI float bf2f(bfu v) { return __uint_as_float(((unsigned)v) << 16); }
; DI unsigned pack2(float a, float b) { f32x2_t v = {a, b}; bf16x2_t r = __builtin_convertvector(v, bf16x2_t); return __builtin_bit_cast(unsigned, r); }
; DI float lo16(unsigned u) { return __uint_as_float(u << 16); }
; DI float hi16(unsigned u) { return __uint_as_float(u & 0xffff0000u); }
; template <int L>
; DI void hyena_job(const PX& p, int l, int c, unsigned char* smem) {
;     ...
;     for (int m = 0; m < TPW; m++) {
;       const int t0 = 16 * (w * TPW + m) + 4 * kq_o;
;       const bfu* zr = zx2 + b * L;
;       const uint2 mid = *(const uint2*)(zr + t0);
;       const bool lv = (t0 % RL != 0), rv = ((t0 + 4) % RL != 0);
;       const float lft = bf2f(zr[lv ? t0 - 1 : t0]) * (lv ? 1.f : 0.f);
;       const float rgt = bf2f(zr[rv ? t0 + 4 : t0]) * (rv ? 1.f : 0.f);
;       float z[6];
;       z[0] = lft; z[5] = rgt; z[1] = lo16(mid.x); z[2] = hi16(mid.x); z[3] = lo16(mid.y); z[4] = hi16(mid.y);
;       const uint2 vu = *(const uint2*)(U + b * USTR + t0);
;       const float vv[4] = {lo16(vu.x), hi16(vu.x), lo16(vu.y), hi16(vu.y)};
;       float y2[4];
; #pragma unroll
;       for (int r = 0; r < 4; r++) {
;         const float x2 = w2[0] * z[r] + w2[1] * z[r + 1] + w2[2] * z[r + 2] + w2[3];
;         y2[r] = x2 * (acc[m][r] + bias1 * vv[r]);
;       }
;       uint2 o2; o2.x = pack2(y2[0], y2[1]); o2.y = pack2(y2[2], y2[3]);
;       *(uint2*)(yrow + b * L + t0) = o2;
	v_lshlrev_b32_e32 v76, 16, v58
	v_and_b32_e32 v77, 0xffff0000, v58
	v_pk_fma_f32 v[54:55], v[128:129], v[76:77], v[54:55] op_sel_hi:[0,1,1]
	v_pk_mul_f32 v[54:55], v[72:73], v[54:55]
	v_pk_mul_f32 v[72:73], v[122:123], v[78:79] op_sel_hi:[0,1]
	v_pk_fma_f32 v[72:73], v[0:1], v[80:81], v[72:73] op_sel_hi:[0,1,1]
	v_lshlrev_b32_e32 v58, 16, v59
	v_and_b32_e32 v59, 0xffff0000, v59
	v_pk_fma_f32 v[70:71], v[126:127], v[70:71], v[72:73] op_sel_hi:[0,1,1]
	v_pk_add_f32 v[70:71], v[124:125], v[70:71] op_sel_hi:[0,1]
	v_pk_fma_f32 v[56:57], v[128:129], v[58:59], v[56:57] op_sel_hi:[0,1,1]
	v_pk_mul_f32 v[56:57], v[56:57], v[70:71]
	v_cvt_pk_bf16_f32 v54, v54, v55
	v_cvt_pk_bf16_f32 v55, v56, v57
	v_add_u32_e32 v56, 48, v66
	global_store_dwordx2 v[62:63], v[54:55], off offset:64
	v_and_b32_e32 v54, 60, v56
	v_add_u32_e32 v58, 52, v66
	v_cmp_ne_u32_e64 s[4:5], 0, v54
	v_and_b32_e32 v54, 60, v58
	v_cmp_eq_u32_e64 s[6:7], 0, v54
	v_subbrev_co_u32_e64 v54, s[8:9], 0, v56, s[4:5]
	v_ashrrev_i32_e32 v55, 31, v54
	v_lshl_add_u64 v[54:55], v[54:55], 1, v[64:65]
	v_lshrrev_b32_e32 v54, 16, v164
	v_cndmask_b32_e64 v55, 0, 1.0, s[4:5]
	v_lshlrev_b32_e32 v70, 16, v60
	v_and_b32_e32 v71, 0xffff0000, v60
	v_and_b32_e32 v59, 0xffff0000, v61
	v_pk_fma_f32 v[50:51], v[128:129], v[70:71], v[50:51] op_sel_hi:[0,1,1]
	s_nop 0
	v_lshlrev_b32_e32 v54, 16, v54
	v_mul_f32_e32 v57, v55, v54
	v_cndmask_b32_e64 v54, v58, v56, s[6:7]
	v_ashrrev_i32_e32 v55, 31, v54
	v_lshl_add_u64 v[54:55], v[54:55], 1, v[64:65]
	v_and_b32_e32 v54, 0xffff, v167
	v_lshlrev_b32_e32 v58, 16, v61
	v_mov_b32_e32 v60, v165
	v_mov_b32_e32 v61, v166
	v_cndmask_b32_e64 v55, 1.0, 0, s[6:7]
	v_pk_fma_f32 v[52:53], v[128:129], v[58:59], v[52:53] op_sel_hi:[0,1,1]
	s_nop 0
	v_lshlrev_b32_e32 v54, 16, v54
	v_mul_f32_e32 v55, v55, v54
	s_nop 0
	v_and_b32_e32 v72, 0xffff0000, v60
	v_mov_b32_e32 v56, v72
	v_lshlrev_b32_e32 v54, 16, v60
	v_pk_mul_f32 v[56:57], v[122:123], v[56:57]
	v_lshlrev_b32_e32 v73, 16, v61
	v_pk_fma_f32 v[56:57], v[122:123], v[54:55], v[56:57] op_sel:[0,0,1] op_sel_hi:[1,0,0]
	v_and_b32_e32 v61, 0xffff0000, v61
	v_pk_fma_f32 v[56:57], v[126:127], v[72:73], v[56:57] op_sel_hi:[0,1,1]
	v_mov_b32_e32 v60, v73
	v_pk_add_f32 v[56:57], v[124:125], v[56:57] op_sel_hi:[0,1]
	v_pk_mul_f32 v[50:51], v[56:57], v[50:51]
	v_pk_mul_f32 v[56:57], v[122:123], v[60:61] op_sel_hi:[0,1]
	v_pk_fma_f32 v[56:57], v[0:1], v[72:73], v[56:57] op_sel_hi:[0,1,1]
	v_mov_b32_e32 v54, v61
	v_pk_fma_f32 v[54:55], v[126:127], v[54:55], v[56:57] op_sel_hi:[0,1,1]
	v_pk_add_f32 v[54:55], v[124:125], v[54:55] op_sel_hi:[0,1]
	v_pk_mul_f32 v[52:53], v[52:53], v[54:55]
	v_cvt_pk_bf16_f32 v50, v50, v51
	v_cvt_pk_bf16_f32 v51, v52, v53
	v_add_u32_e32 v53, 0x44, v66
	global_store_dwordx2 v[62:63], v[50:51], off offset:96
	v_add_u32_e32 v52, 64, v66
	v_and_b32_e32 v50, 60, v53
	v_cmp_eq_u32_e64 s[4:5], 0, v50
	v_subbrev_co_u32_e64 v50, s[6:7], 0, v52, vcc
	v_ashrrev_i32_e32 v51, 31, v50
	v_lshl_add_u64 v[50:51], v[50:51], 1, v[64:65]
	v_lshrrev_b32_e32 v50, 16, v168
	s_nop 0
	v_mov_b32_e32 v60, v169
	v_mov_b32_e32 v61, v170
	s_nop 0
	v_lshlrev_b32_e32 v50, 16, v50
	v_mul_f32_e32 v55, v74, v50
	v_cndmask_b32_e64 v50, v53, v52, s[4:5]
	v_ashrrev_i32_e32 v51, 31, v50
	v_lshl_add_u64 v[50:51], v[50:51], 1, v[64:65]
	v_and_b32_e32 v50, 0xffff, v171
	v_cndmask_b32_e64 v51, 1.0, 0, s[4:5]
	s_nop 0
	v_and_b32_e32 v70, 0xffff0000, v60
	v_mov_b32_e32 v54, v70
	v_lshlrev_b32_e32 v56, 16, v60
	v_pk_mul_f32 v[54:55], v[122:123], v[54:55]
	v_lshlrev_b32_e32 v71, 16, v61
	v_and_b32_e32 v61, 0xffff0000, v61
	v_mov_b32_e32 v60, v71
	s_nop 0
	v_lshlrev_b32_e32 v50, 16, v50
	v_mul_f32_e32 v57, v51, v50
	ds_read2_b64 v[50:53], v67 offset0:16 offset1:20
	v_pk_fma_f32 v[54:55], v[122:123], v[56:57], v[54:55] op_sel:[0,0,1] op_sel_hi:[1,0,0]
	v_mov_b32_e32 v56, v61
	v_pk_fma_f32 v[54:55], v[126:127], v[70:71], v[54:55] op_sel_hi:[0,1,1]
	v_pk_add_f32 v[54:55], v[124:125], v[54:55] op_sel_hi:[0,1]
	s_waitcnt lgkmcnt(0)
	v_lshlrev_b32_e32 v58, 16, v50
	v_and_b32_e32 v59, 0xffff0000, v50
	v_pk_fma_f32 v[46:47], v[128:129], v[58:59], v[46:47] op_sel_hi:[0,1,1]
	v_pk_mul_f32 v[46:47], v[54:55], v[46:47]
	v_pk_mul_f32 v[54:55], v[122:123], v[60:61] op_sel_hi:[0,1]
	v_pk_fma_f32 v[54:55], v[0:1], v[70:71], v[54:55] op_sel_hi:[0,1,1]
	v_lshlrev_b32_e32 v50, 16, v51
	v_and_b32_e32 v51, 0xffff0000, v51
	v_pk_fma_f32 v[54:55], v[126:127], v[56:57], v[54:55] op_sel_hi:[0,1,1]
	v_pk_add_f32 v[54:55], v[124:125], v[54:55] op_sel_hi:[0,1]
	v_pk_fma_f32 v[48:49], v[128:129], v[50:51], v[48:49] op_sel_hi:[0,1,1]
	v_pk_mul_f32 v[48:49], v[48:49], v[54:55]
	v_cvt_pk_bf16_f32 v46, v46, v47
	v_cvt_pk_bf16_f32 v47, v48, v49
	v_add_u32_e32 v48, 0x50, v66
	global_store_dwordx2 v[62:63], v[46:47], off offset:128
	v_and_b32_e32 v46, 60, v48
	v_add_u32_e32 v49, 0x54, v66
	v_cmp_ne_u32_e64 s[4:5], 0, v46
	v_and_b32_e32 v46, 60, v49
	v_cmp_eq_u32_e64 s[6:7], 0, v46
	v_subbrev_co_u32_e64 v46, s[8:9], 0, v48, s[4:5]
	v_ashrrev_i32_e32 v47, 31, v46
	v_lshl_add_u64 v[46:47], v[46:47], 1, v[64:65]
	v_lshrrev_b32_e32 v46, 16, v172
	v_cndmask_b32_e64 v48, v49, v48, s[6:7]
	v_ashrrev_i32_e32 v49, 31, v48
	v_lshl_add_u64 v[48:49], v[48:49], 1, v[64:65]
	v_mov_b32_e32 v54, v173
	v_mov_b32_e32 v55, v174
	v_cndmask_b32_e64 v47, 0, 1.0, s[4:5]
	v_lshlrev_b32_e32 v50, 16, v52
	v_and_b32_e32 v51, 0xffff0000, v52
	v_pk_fma_f32 v[42:43], v[128:129], v[50:51], v[42:43] op_sel_hi:[0,1,1]
	v_lshlrev_b32_e32 v52, 16, v53
	v_and_b32_e32 v53, 0xffff0000, v53
	v_pk_fma_f32 v[44:45], v[128:129], v[52:53], v[44:45] op_sel_hi:[0,1,1]
	v_mov_b32_e32 v52, v177
	v_mov_b32_e32 v53, v178
	s_nop 0
; DI float bf2f(bfu v) { return __uint_as_float(((unsigned)v) << 16); }
; DI unsigned pack2(float a, float b) { f32x2_t v = {a, b}; bf16x2_t r = __builtin_convertvector(v, bf16x2_t); return __builtin_bit_cast(unsigned, r); }
; DI float lo16(unsigned u) { return __uint_as_float(u << 16); }
; DI float hi16(unsigned u) { return __uint_as_float(u & 0xffff0000u); }
; template <int L>
; DI void hyena_job(const PX& p, int l, int c, unsigned char* smem) {
;     ...
;     for (int m = 0; m < TPW; m++) {
;       const int t0 = 16 * (w * TPW + m) + 4 * kq_o;
;       const bfu* zr = zx2 + b * L;
;       const uint2 mid = *(const uint2*)(zr + t0);
;       const bool lv = (t0 % RL != 0), rv = ((t0 + 4) % RL != 0);
;       const float lft = bf2f(zr[lv ? t0 - 1 : t0]) * (lv ? 1.f : 0.f);
;       const float rgt = bf2f(zr[rv ? t0 + 4 : t0]) * (rv ? 1.f : 0.f);
;       float z[6];
;       z[0] = lft; z[5] = rgt; z[1] = lo16(mid.x); z[2] = hi16(mid.x); z[3] = lo16(mid.y); z[4] = hi16(mid.y);
;       const uint2 vu = *(const uint2*)(U + b * USTR + t0);
;       const float vv[4] = {lo16(vu.x), hi16(vu.x), lo16(vu.y), hi16(vu.y)};
;       float y2[4];
; #pragma unroll
;       for (int r = 0; r < 4; r++) {
;         const float x2 = w2[0] * z[r] + w2[1] * z[r + 1] + w2[2] * z[r + 2] + w2[3];
;         y2[r] = x2 * (acc[m][r] + bias1 * vv[r]);
;       }
;       uint2 o2; o2.x = pack2(y2[0], y2[1]); o2.y = pack2(y2[2], y2[3]);
;       *(uint2*)(yrow + b * L + t0) = o2;
	v_lshlrev_b32_e32 v46, 16, v46
	v_mul_f32_e32 v47, v47, v46
	v_and_b32_e32 v46, 0xffff, v175
	v_cndmask_b32_e64 v48, 1.0, 0, s[6:7]
	s_nop 0
	v_and_b32_e32 v56, 0xffff0000, v54
	v_lshlrev_b32_e32 v57, 16, v55
	v_and_b32_e32 v55, 0xffff0000, v55
	s_nop 0
	v_lshlrev_b32_e32 v46, 16, v46
	v_mul_f32_e32 v49, v48, v46
	v_mov_b32_e32 v46, v56
	v_lshlrev_b32_e32 v48, 16, v54
	v_pk_mul_f32 v[46:47], v[122:123], v[46:47]
	v_mov_b32_e32 v54, v57
	v_pk_fma_f32 v[46:47], v[122:123], v[48:49], v[46:47] op_sel:[0,0,1] op_sel_hi:[1,0,0]
	v_mov_b32_e32 v48, v55
	v_pk_fma_f32 v[46:47], v[126:127], v[56:57], v[46:47] op_sel_hi:[0,1,1]
	v_pk_add_f32 v[46:47], v[124:125], v[46:47] op_sel_hi:[0,1]
	v_pk_mul_f32 v[42:43], v[46:47], v[42:43]
	v_pk_mul_f32 v[46:47], v[122:123], v[54:55] op_sel_hi:[0,1]
	v_pk_fma_f32 v[46:47], v[0:1], v[56:57], v[46:47] op_sel_hi:[0,1,1]
	v_pk_fma_f32 v[46:47], v[126:127], v[48:49], v[46:47] op_sel_hi:[0,1,1]
	v_pk_add_f32 v[46:47], v[124:125], v[46:47] op_sel_hi:[0,1]
	v_pk_mul_f32 v[44:45], v[44:45], v[46:47]
	v_cvt_pk_bf16_f32 v42, v42, v43
	v_cvt_pk_bf16_f32 v43, v44, v45
	v_add_u32_e32 v44, 0x60, v66
	global_store_dwordx2 v[62:63], v[42:43], off offset:160
	v_and_b32_e32 v42, 60, v44
	v_add_u32_e32 v45, 0x64, v66
	v_cmp_ne_u32_e64 s[4:5], 0, v42
	v_and_b32_e32 v42, 60, v45
	v_cmp_eq_u32_e64 s[6:7], 0, v42
	v_subbrev_co_u32_e64 v42, s[8:9], 0, v44, s[4:5]
	v_ashrrev_i32_e32 v43, 31, v42
	v_lshl_add_u64 v[42:43], v[42:43], 1, v[64:65]
	v_lshrrev_b32_e32 v42, 16, v176
	v_cndmask_b32_e64 v43, 0, 1.0, s[4:5]
	v_and_b32_e32 v54, 0xffff0000, v52
	v_mov_b32_e32 v48, v54
	v_lshlrev_b32_e32 v46, 16, v52
	v_lshlrev_b32_e32 v55, 16, v53
	v_and_b32_e32 v53, 0xffff0000, v53
	v_mov_b32_e32 v52, v55
	s_nop 0
	v_lshlrev_b32_e32 v42, 16, v42
	v_mul_f32_e32 v49, v43, v42
	v_cndmask_b32_e64 v42, v45, v44, s[6:7]
	v_ashrrev_i32_e32 v43, 31, v42
	v_lshl_add_u64 v[42:43], v[42:43], 1, v[64:65]
	v_and_b32_e32 v42, 0xffff, v179
	v_cndmask_b32_e64 v43, 1.0, 0, s[6:7]
	v_pk_mul_f32 v[48:49], v[122:123], v[48:49]
	s_nop 0
	v_lshlrev_b32_e32 v42, 16, v42
	v_mul_f32_e32 v47, v43, v42
	ds_read2_b64 v[42:45], v67 offset0:24 offset1:28
	v_pk_fma_f32 v[48:49], v[122:123], v[46:47], v[48:49] op_sel:[0,0,1] op_sel_hi:[1,0,0]
	v_mov_b32_e32 v46, v53
	v_pk_fma_f32 v[48:49], v[126:127], v[54:55], v[48:49] op_sel_hi:[0,1,1]
	v_pk_add_f32 v[48:49], v[124:125], v[48:49] op_sel_hi:[0,1]
	s_waitcnt lgkmcnt(0)
	v_lshlrev_b32_e32 v50, 16, v42
	v_and_b32_e32 v51, 0xffff0000, v42
	v_pk_fma_f32 v[38:39], v[128:129], v[50:51], v[38:39] op_sel_hi:[0,1,1]
	v_pk_mul_f32 v[38:39], v[48:49], v[38:39]
	v_pk_mul_f32 v[48:49], v[122:123], v[52:53] op_sel_hi:[0,1]
	v_pk_fma_f32 v[48:49], v[0:1], v[54:55], v[48:49] op_sel_hi:[0,1,1]
	v_lshlrev_b32_e32 v42, 16, v43
	v_and_b32_e32 v43, 0xffff0000, v43
	v_pk_fma_f32 v[46:47], v[126:127], v[46:47], v[48:49] op_sel_hi:[0,1,1]
	v_pk_add_f32 v[46:47], v[124:125], v[46:47] op_sel_hi:[0,1]
	v_pk_fma_f32 v[40:41], v[128:129], v[42:43], v[40:41] op_sel_hi:[0,1,1]
	v_pk_mul_f32 v[40:41], v[40:41], v[46:47]
	v_cvt_pk_bf16_f32 v38, v38, v39
	v_cvt_pk_bf16_f32 v39, v40, v41
	v_add_u32_e32 v40, 0x70, v66
	global_store_dwordx2 v[62:63], v[38:39], off offset:192
	v_and_b32_e32 v38, 60, v40
	v_add_u32_e32 v42, 0x74, v66
	v_cmp_ne_u32_e64 s[4:5], 0, v38
	v_and_b32_e32 v38, 60, v42
	v_cmp_eq_u32_e64 s[6:7], 0, v38
	v_subbrev_co_u32_e64 v38, s[8:9], 0, v40, s[4:5]
	v_ashrrev_i32_e32 v39, 31, v38
	v_lshl_add_u64 v[38:39], v[38:39], 1, v[64:65]
	v_lshrrev_b32_e32 v38, 16, v180
	v_cndmask_b32_e64 v39, 0, 1.0, s[4:5]
	v_lshlrev_b32_e32 v46, 16, v44
	v_and_b32_e32 v47, 0xffff0000, v44
	v_and_b32_e32 v43, 0xffff0000, v45
	v_pk_fma_f32 v[34:35], v[128:129], v[46:47], v[34:35] op_sel_hi:[0,1,1]
	s_nop 0
	v_lshlrev_b32_e32 v38, 16, v38
	v_mul_f32_e32 v41, v39, v38
	v_cndmask_b32_e64 v38, v42, v40, s[6:7]
	v_ashrrev_i32_e32 v39, 31, v38
	v_lshl_add_u64 v[38:39], v[38:39], 1, v[64:65]
	v_and_b32_e32 v38, 0xffff, v183
	v_lshlrev_b32_e32 v42, 16, v45
	v_mov_b32_e32 v44, v181
	v_mov_b32_e32 v45, v182
	v_cndmask_b32_e64 v39, 1.0, 0, s[6:7]
	v_pk_fma_f32 v[36:37], v[128:129], v[42:43], v[36:37] op_sel_hi:[0,1,1]
	s_nop 0
	v_lshlrev_b32_e32 v38, 16, v38
	v_mul_f32_e32 v39, v39, v38
	s_nop 0
	v_and_b32_e32 v48, 0xffff0000, v44
	v_mov_b32_e32 v40, v48
	v_lshlrev_b32_e32 v38, 16, v44
	v_pk_mul_f32 v[40:41], v[122:123], v[40:41]
	v_lshlrev_b32_e32 v49, 16, v45
	v_pk_fma_f32 v[40:41], v[122:123], v[38:39], v[40:41] op_sel:[0,0,1] op_sel_hi:[1,0,0]
	v_and_b32_e32 v45, 0xffff0000, v45
	v_pk_fma_f32 v[40:41], v[126:127], v[48:49], v[40:41] op_sel_hi:[0,1,1]
	v_mov_b32_e32 v44, v49
	v_pk_add_f32 v[40:41], v[124:125], v[40:41] op_sel_hi:[0,1]
	v_pk_mul_f32 v[34:35], v[40:41], v[34:35]
	v_pk_mul_f32 v[40:41], v[122:123], v[44:45] op_sel_hi:[0,1]
	v_pk_fma_f32 v[40:41], v[0:1], v[48:49], v[40:41] op_sel_hi:[0,1,1]
	v_mov_b32_e32 v38, v45
	v_pk_fma_f32 v[38:39], v[126:127], v[38:39], v[40:41] op_sel_hi:[0,1,1]
	v_pk_add_f32 v[38:39], v[124:125], v[38:39] op_sel_hi:[0,1]
	v_pk_mul_f32 v[36:37], v[36:37], v[38:39]
	v_cvt_pk_bf16_f32 v34, v34, v35
	v_cvt_pk_bf16_f32 v35, v36, v37
	v_add_u32_e32 v37, 0x84, v66
	global_store_dwordx2 v[62:63], v[34:35], off offset:224
	v_add_u32_e32 v36, 0x80, v66
	v_and_b32_e32 v34, 60, v37
	v_cmp_eq_u32_e64 s[4:5], 0, v34
	v_subbrev_co_u32_e64 v34, s[6:7], 0, v36, vcc
	v_ashrrev_i32_e32 v35, 31, v34
	v_lshl_add_u64 v[34:35], v[34:35], 1, v[64:65]
	v_lshrrev_b32_e32 v34, 16, v216
	s_nop 0
	v_mov_b32_e32 v44, v217
	v_mov_b32_e32 v45, v218
	s_nop 0
	v_lshlrev_b32_e32 v34, 16, v34
	v_mul_f32_e32 v39, v74, v34
	v_cndmask_b32_e64 v34, v37, v36, s[4:5]
	v_ashrrev_i32_e32 v35, 31, v34
	v_lshl_add_u64 v[34:35], v[34:35], 1, v[64:65]
	v_and_b32_e32 v34, 0xffff, v219
	v_cndmask_b32_e64 v35, 1.0, 0, s[4:5]
	s_nop 0
	v_and_b32_e32 v46, 0xffff0000, v44
	v_mov_b32_e32 v38, v46
	v_lshlrev_b32_e32 v40, 16, v44
	v_pk_mul_f32 v[38:39], v[122:123], v[38:39]
	v_lshlrev_b32_e32 v47, 16, v45
	v_and_b32_e32 v45, 0xffff0000, v45
	v_mov_b32_e32 v44, v47
	s_nop 0
	v_lshlrev_b32_e32 v34, 16, v34
	v_mul_f32_e32 v41, v35, v34
	ds_read2_b64 v[34:37], v67 offset0:32 offset1:36
	v_pk_fma_f32 v[38:39], v[122:123], v[40:41], v[38:39] op_sel:[0,0,1] op_sel_hi:[1,0,0]
	v_mov_b32_e32 v40, v45
	v_pk_fma_f32 v[38:39], v[126:127], v[46:47], v[38:39] op_sel_hi:[0,1,1]
	v_pk_add_f32 v[38:39], v[124:125], v[38:39] op_sel_hi:[0,1]
	s_waitcnt lgkmcnt(0)
; DI float bf2f(bfu v) { return __uint_as_float(((unsigned)v) << 16); }
; DI unsigned pack2(float a, float b) { f32x2_t v = {a, b}; bf16x2_t r = __builtin_convertvector(v, bf16x2_t); return __builtin_bit_cast(unsigned, r); }
; DI float lo16(unsigned u) { return __uint_as_float(u << 16); }
; DI float hi16(unsigned u) { return __uint_as_float(u & 0xffff0000u); }
; template <int L>
; DI void hyena_job(const PX& p, int l, int c, unsigned char* smem) {
;     ...
;     for (int m = 0; m < TPW; m++) {
;       const int t0 = 16 * (w * TPW + m) + 4 * kq_o;
;       const bfu* zr = zx2 + b * L;
;       const uint2 mid = *(const uint2*)(zr + t0);
;       const bool lv = (t0 % RL != 0), rv = ((t0 + 4) % RL != 0);
;       const float lft = bf2f(zr[lv ? t0 - 1 : t0]) * (lv ? 1.f : 0.f);
;       const float rgt = bf2f(zr[rv ? t0 + 4 : t0]) * (rv ? 1.f : 0.f);
;       float z[6];
;       z[0] = lft; z[5] = rgt; z[1] = lo16(mid.x); z[2] = hi16(mid.x); z[3] = lo16(mid.y); z[4] = hi16(mid.y);
;       const uint2 vu = *(const uint2*)(U + b * USTR + t0);
;       const float vv[4] = {lo16(vu.x), hi16(vu.x), lo16(vu.y), hi16(vu.y)};
;       float y2[4];
; #pragma unroll
;       for (int r = 0; r < 4; r++) {
;         const float x2 = w2[0] * z[r] + w2[1] * z[r + 1] + w2[2] * z[r + 2] + w2[3];
;         y2[r] = x2 * (acc[m][r] + bias1 * vv[r]);
;       }
;       uint2 o2; o2.x = pack2(y2[0], y2[1]); o2.y = pack2(y2[2], y2[3]);
;       *(uint2*)(yrow + b * L + t0) = o2;
	v_lshlrev_b32_e32 v42, 16, v34
	v_and_b32_e32 v43, 0xffff0000, v34
	v_pk_fma_f32 v[30:31], v[128:129], v[42:43], v[30:31] op_sel_hi:[0,1,1]
	v_pk_mul_f32 v[30:31], v[38:39], v[30:31]
	v_pk_mul_f32 v[38:39], v[122:123], v[44:45] op_sel_hi:[0,1]
	v_pk_fma_f32 v[38:39], v[0:1], v[46:47], v[38:39] op_sel_hi:[0,1,1]
	v_lshlrev_b32_e32 v34, 16, v35
	v_and_b32_e32 v35, 0xffff0000, v35
	v_pk_fma_f32 v[38:39], v[126:127], v[40:41], v[38:39] op_sel_hi:[0,1,1]
	v_pk_add_f32 v[38:39], v[124:125], v[38:39] op_sel_hi:[0,1]
	v_pk_fma_f32 v[32:33], v[128:129], v[34:35], v[32:33] op_sel_hi:[0,1,1]
	v_pk_mul_f32 v[32:33], v[32:33], v[38:39]
	v_cvt_pk_bf16_f32 v30, v30, v31
	v_cvt_pk_bf16_f32 v31, v32, v33
	v_add_u32_e32 v32, 0x90, v66
	global_store_dwordx2 v[62:63], v[30:31], off offset:256
	v_and_b32_e32 v30, 60, v32
	v_add_u32_e32 v33, 0x94, v66
	v_cmp_ne_u32_e64 s[4:5], 0, v30
	v_and_b32_e32 v30, 60, v33
	v_cmp_eq_u32_e64 s[6:7], 0, v30
	v_subbrev_co_u32_e64 v30, s[8:9], 0, v32, s[4:5]
	v_ashrrev_i32_e32 v31, 31, v30
	v_lshl_add_u64 v[30:31], v[30:31], 1, v[64:65]
	v_lshrrev_b32_e32 v30, 16, v220
	v_cndmask_b32_e64 v32, v33, v32, s[6:7]
	v_ashrrev_i32_e32 v33, 31, v32
	v_lshl_add_u64 v[32:33], v[32:33], 1, v[64:65]
	v_mov_b32_e32 v38, v221
	v_mov_b32_e32 v39, v222
	v_cndmask_b32_e64 v31, 0, 1.0, s[4:5]
	v_lshlrev_b32_e32 v34, 16, v36
	v_and_b32_e32 v35, 0xffff0000, v36
	v_pk_fma_f32 v[26:27], v[128:129], v[34:35], v[26:27] op_sel_hi:[0,1,1]
	v_lshlrev_b32_e32 v36, 16, v37
	v_and_b32_e32 v37, 0xffff0000, v37
	v_pk_fma_f32 v[28:29], v[128:129], v[36:37], v[28:29] op_sel_hi:[0,1,1]
	v_mov_b32_e32 v36, v225
	v_mov_b32_e32 v37, v226
	s_nop 0
	v_lshlrev_b32_e32 v30, 16, v30
	v_mul_f32_e32 v31, v31, v30
	v_and_b32_e32 v30, 0xffff, v223
	v_cndmask_b32_e64 v32, 1.0, 0, s[6:7]
	s_nop 0
	v_and_b32_e32 v40, 0xffff0000, v38
	v_lshlrev_b32_e32 v41, 16, v39
	v_and_b32_e32 v39, 0xffff0000, v39
	s_nop 0
	v_lshlrev_b32_e32 v30, 16, v30
	v_mul_f32_e32 v33, v32, v30
	v_mov_b32_e32 v30, v40
	v_lshlrev_b32_e32 v32, 16, v38
	v_pk_mul_f32 v[30:31], v[122:123], v[30:31]
	v_mov_b32_e32 v38, v41
	v_pk_fma_f32 v[30:31], v[122:123], v[32:33], v[30:31] op_sel:[0,0,1] op_sel_hi:[1,0,0]
	v_mov_b32_e32 v32, v39
	v_pk_fma_f32 v[30:31], v[126:127], v[40:41], v[30:31] op_sel_hi:[0,1,1]
	v_pk_add_f32 v[30:31], v[124:125], v[30:31] op_sel_hi:[0,1]
	v_pk_mul_f32 v[26:27], v[30:31], v[26:27]
	v_pk_mul_f32 v[30:31], v[122:123], v[38:39] op_sel_hi:[0,1]
	v_pk_fma_f32 v[30:31], v[0:1], v[40:41], v[30:31] op_sel_hi:[0,1,1]
	v_pk_fma_f32 v[30:31], v[126:127], v[32:33], v[30:31] op_sel_hi:[0,1,1]
	v_pk_add_f32 v[30:31], v[124:125], v[30:31] op_sel_hi:[0,1]
	v_pk_mul_f32 v[28:29], v[28:29], v[30:31]
	v_cvt_pk_bf16_f32 v26, v26, v27
	v_cvt_pk_bf16_f32 v27, v28, v29
	v_add_u32_e32 v28, 0xa0, v66
	global_store_dwordx2 v[62:63], v[26:27], off offset:288
	v_and_b32_e32 v26, 60, v28
	v_add_u32_e32 v29, 0xa4, v66
	v_cmp_ne_u32_e64 s[4:5], 0, v26
	v_and_b32_e32 v26, 60, v29
	v_cmp_eq_u32_e64 s[6:7], 0, v26
	v_subbrev_co_u32_e64 v26, s[8:9], 0, v28, s[4:5]
	v_ashrrev_i32_e32 v27, 31, v26
	v_lshl_add_u64 v[26:27], v[26:27], 1, v[64:65]
	v_lshrrev_b32_e32 v26, 16, v224
	v_cndmask_b32_e64 v27, 0, 1.0, s[4:5]
	v_and_b32_e32 v38, 0xffff0000, v36
	v_mov_b32_e32 v32, v38
	v_lshlrev_b32_e32 v30, 16, v36
	v_lshlrev_b32_e32 v39, 16, v37
	v_and_b32_e32 v37, 0xffff0000, v37
	v_mov_b32_e32 v36, v39
	s_nop 0
	v_lshlrev_b32_e32 v26, 16, v26
	v_mul_f32_e32 v33, v27, v26
	v_cndmask_b32_e64 v26, v29, v28, s[6:7]
	v_ashrrev_i32_e32 v27, 31, v26
	v_lshl_add_u64 v[26:27], v[26:27], 1, v[64:65]
	v_and_b32_e32 v26, 0xffff, v227
	v_cndmask_b32_e64 v27, 1.0, 0, s[6:7]
	v_pk_mul_f32 v[32:33], v[122:123], v[32:33]
	s_nop 0
	v_lshlrev_b32_e32 v26, 16, v26
	v_mul_f32_e32 v31, v27, v26
	ds_read2_b64 v[26:29], v67 offset0:40 offset1:44
	v_pk_fma_f32 v[32:33], v[122:123], v[30:31], v[32:33] op_sel:[0,0,1] op_sel_hi:[1,0,0]
	v_mov_b32_e32 v30, v37
	v_pk_fma_f32 v[32:33], v[126:127], v[38:39], v[32:33] op_sel_hi:[0,1,1]
	v_pk_add_f32 v[32:33], v[124:125], v[32:33] op_sel_hi:[0,1]
	s_waitcnt lgkmcnt(0)
	v_lshlrev_b32_e32 v34, 16, v26
	v_and_b32_e32 v35, 0xffff0000, v26
	v_pk_fma_f32 v[22:23], v[128:129], v[34:35], v[22:23] op_sel_hi:[0,1,1]
	v_pk_mul_f32 v[22:23], v[32:33], v[22:23]
	v_pk_mul_f32 v[32:33], v[122:123], v[36:37] op_sel_hi:[0,1]
	v_pk_fma_f32 v[32:33], v[0:1], v[38:39], v[32:33] op_sel_hi:[0,1,1]
	v_lshlrev_b32_e32 v26, 16, v27
	v_and_b32_e32 v27, 0xffff0000, v27
	v_pk_fma_f32 v[30:31], v[126:127], v[30:31], v[32:33] op_sel_hi:[0,1,1]
	v_pk_add_f32 v[30:31], v[124:125], v[30:31] op_sel_hi:[0,1]
	v_pk_fma_f32 v[24:25], v[128:129], v[26:27], v[24:25] op_sel_hi:[0,1,1]
	v_pk_mul_f32 v[24:25], v[24:25], v[30:31]
	v_cvt_pk_bf16_f32 v22, v22, v23
	v_cvt_pk_bf16_f32 v23, v24, v25
	v_add_u32_e32 v24, 0xb0, v66
	global_store_dwordx2 v[62:63], v[22:23], off offset:320
	v_and_b32_e32 v22, 60, v24
	v_add_u32_e32 v26, 0xb4, v66
	v_cmp_ne_u32_e64 s[4:5], 0, v22
	v_and_b32_e32 v22, 60, v26
	v_cmp_eq_u32_e64 s[6:7], 0, v22
	v_subbrev_co_u32_e64 v22, s[8:9], 0, v24, s[4:5]
	v_ashrrev_i32_e32 v23, 31, v22
	v_lshl_add_u64 v[22:23], v[22:23], 1, v[64:65]
	v_lshrrev_b32_e32 v22, 16, v228
	v_cndmask_b32_e64 v23, 0, 1.0, s[4:5]
	v_lshlrev_b32_e32 v30, 16, v28
	v_and_b32_e32 v31, 0xffff0000, v28
	v_and_b32_e32 v27, 0xffff0000, v29
	v_pk_fma_f32 v[18:19], v[128:129], v[30:31], v[18:19] op_sel_hi:[0,1,1]
	s_nop 0
	v_lshlrev_b32_e32 v22, 16, v22
	v_mul_f32_e32 v25, v23, v22
	v_cndmask_b32_e64 v22, v26, v24, s[6:7]
	v_ashrrev_i32_e32 v23, 31, v22
	v_lshl_add_u64 v[22:23], v[22:23], 1, v[64:65]
	v_and_b32_e32 v22, 0xffff, v231
	v_lshlrev_b32_e32 v26, 16, v29
; DI float bf2f(bfu v) { return __uint_as_float(((unsigned)v) << 16); }
; DI unsigned pack2(float a, float b) { f32x2_t v = {a, b}; bf16x2_t r = __builtin_convertvector(v, bf16x2_t); return __builtin_bit_cast(unsigned, r); }
; DI float lo16(unsigned u) { return __uint_as_float(u << 16); }
; DI float hi16(unsigned u) { return __uint_as_float(u & 0xffff0000u); }
; template <int L>
; DI void hyena_job(const PX& p, int l, int c, unsigned char* smem) {
;     ...
;     for (int m = 0; m < TPW; m++) {
;       const int t0 = 16 * (w * TPW + m) + 4 * kq_o;
;       const bfu* zr = zx2 + b * L;
;       const uint2 mid = *(const uint2*)(zr + t0);
;       const bool lv = (t0 % RL != 0), rv = ((t0 + 4) % RL != 0);
;       const float lft = bf2f(zr[lv ? t0 - 1 : t0]) * (lv ? 1.f : 0.f);
;       const float rgt = bf2f(zr[rv ? t0 + 4 : t0]) * (rv ? 1.f : 0.f);
;       float z[6];
;       z[0] = lft; z[5] = rgt; z[1] = lo16(mid.x); z[2] = hi16(mid.x); z[3] = lo16(mid.y); z[4] = hi16(mid.y);
;       const uint2 vu = *(const uint2*)(U + b * USTR + t0);
;       const float vv[4] = {lo16(vu.x), hi16(vu.x), lo16(vu.y), hi16(vu.y)};
;       float y2[4];
; #pragma unroll
;       for (int r = 0; r < 4; r++) {
;         const float x2 = w2[0] * z[r] + w2[1] * z[r + 1] + w2[2] * z[r + 2] + w2[3];
;         y2[r] = x2 * (acc[m][r] + bias1 * vv[r]);
;       }
;       uint2 o2; o2.x = pack2(y2[0], y2[1]); o2.y = pack2(y2[2], y2[3]);
;       *(uint2*)(yrow + b * L + t0) = o2;
	v_mov_b32_e32 v28, v229
	v_mov_b32_e32 v29, v230
	v_cndmask_b32_e64 v23, 1.0, 0, s[6:7]
	v_pk_fma_f32 v[20:21], v[128:129], v[26:27], v[20:21] op_sel_hi:[0,1,1]
	s_nop 0
	v_lshlrev_b32_e32 v22, 16, v22
	v_mul_f32_e32 v23, v23, v22
	s_nop 0
	v_and_b32_e32 v32, 0xffff0000, v28
	v_mov_b32_e32 v24, v32
	v_lshlrev_b32_e32 v22, 16, v28
	v_pk_mul_f32 v[24:25], v[122:123], v[24:25]
	v_lshlrev_b32_e32 v33, 16, v29
	v_pk_fma_f32 v[24:25], v[122:123], v[22:23], v[24:25] op_sel:[0,0,1] op_sel_hi:[1,0,0]
	v_and_b32_e32 v29, 0xffff0000, v29
	v_pk_fma_f32 v[24:25], v[126:127], v[32:33], v[24:25] op_sel_hi:[0,1,1]
	v_mov_b32_e32 v28, v33
	v_pk_add_f32 v[24:25], v[124:125], v[24:25] op_sel_hi:[0,1]
	v_pk_mul_f32 v[18:19], v[24:25], v[18:19]
	v_pk_mul_f32 v[24:25], v[122:123], v[28:29] op_sel_hi:[0,1]
	v_pk_fma_f32 v[24:25], v[0:1], v[32:33], v[24:25] op_sel_hi:[0,1,1]
	v_mov_b32_e32 v22, v29
	v_pk_fma_f32 v[22:23], v[126:127], v[22:23], v[24:25] op_sel_hi:[0,1,1]
	v_pk_add_f32 v[22:23], v[124:125], v[22:23] op_sel_hi:[0,1]
	v_pk_mul_f32 v[20:21], v[20:21], v[22:23]
	v_cvt_pk_bf16_f32 v18, v18, v19
	v_cvt_pk_bf16_f32 v19, v20, v21
	v_add_u32_e32 v21, 0xc4, v66
	global_store_dwordx2 v[62:63], v[18:19], off offset:352
	v_add_u32_e32 v20, 0xc0, v66
	v_and_b32_e32 v18, 60, v21
	v_cmp_eq_u32_e64 s[4:5], 0, v18
	v_subbrev_co_u32_e32 v18, vcc, 0, v20, vcc
	v_ashrrev_i32_e32 v19, 31, v18
	v_lshl_add_u64 v[18:19], v[18:19], 1, v[64:65]
	v_lshrrev_b32_e32 v18, 16, v232
	s_nop 0
	v_mov_b32_e32 v28, v233
	v_mov_b32_e32 v29, v234
	s_nop 0
	v_lshlrev_b32_e32 v18, 16, v18
	v_mul_f32_e32 v23, v74, v18
	v_cndmask_b32_e64 v18, v21, v20, s[4:5]
	v_ashrrev_i32_e32 v19, 31, v18
	v_lshl_add_u64 v[18:19], v[18:19], 1, v[64:65]
	v_and_b32_e32 v18, 0xffff, v235
	v_cndmask_b32_e64 v19, 1.0, 0, s[4:5]
	s_nop 0
	v_and_b32_e32 v30, 0xffff0000, v28
	v_mov_b32_e32 v22, v30
	v_lshlrev_b32_e32 v24, 16, v28
	v_pk_mul_f32 v[22:23], v[122:123], v[22:23]
	v_lshlrev_b32_e32 v31, 16, v29
	v_and_b32_e32 v29, 0xffff0000, v29
	v_mov_b32_e32 v28, v31
	s_nop 0
	v_lshlrev_b32_e32 v18, 16, v18
	v_mul_f32_e32 v25, v19, v18
	ds_read2_b64 v[18:21], v67 offset0:48 offset1:52
	v_pk_fma_f32 v[22:23], v[122:123], v[24:25], v[22:23] op_sel:[0,0,1] op_sel_hi:[1,0,0]
	v_mov_b32_e32 v24, v29
	v_pk_fma_f32 v[22:23], v[126:127], v[30:31], v[22:23] op_sel_hi:[0,1,1]
	v_pk_add_f32 v[22:23], v[124:125], v[22:23] op_sel_hi:[0,1]
	s_waitcnt lgkmcnt(0)
	v_lshlrev_b32_e32 v26, 16, v18
	v_and_b32_e32 v27, 0xffff0000, v18
	v_pk_fma_f32 v[14:15], v[128:129], v[26:27], v[14:15] op_sel_hi:[0,1,1]
	v_pk_mul_f32 v[14:15], v[22:23], v[14:15]
	v_pk_mul_f32 v[22:23], v[122:123], v[28:29] op_sel_hi:[0,1]
	v_pk_fma_f32 v[22:23], v[0:1], v[30:31], v[22:23] op_sel_hi:[0,1,1]
	v_lshlrev_b32_e32 v18, 16, v19
	v_and_b32_e32 v19, 0xffff0000, v19
	v_pk_fma_f32 v[22:23], v[126:127], v[24:25], v[22:23] op_sel_hi:[0,1,1]
	v_pk_add_f32 v[22:23], v[124:125], v[22:23] op_sel_hi:[0,1]
	v_pk_fma_f32 v[16:17], v[128:129], v[18:19], v[16:17] op_sel_hi:[0,1,1]
	v_pk_mul_f32 v[16:17], v[16:17], v[22:23]
	v_cvt_pk_bf16_f32 v14, v14, v15
	v_cvt_pk_bf16_f32 v15, v16, v17
	v_add_u32_e32 v16, 0xd0, v66
	global_store_dwordx2 v[62:63], v[14:15], off offset:384
	v_and_b32_e32 v14, 60, v16
	v_add_u32_e32 v17, 0xd4, v66
	v_cmp_ne_u32_e32 vcc, 0, v14
	v_and_b32_e32 v14, 60, v17
	v_cmp_eq_u32_e64 s[4:5], 0, v14
	v_subbrev_co_u32_e64 v14, s[6:7], 0, v16, vcc
	v_ashrrev_i32_e32 v15, 31, v14
	v_lshl_add_u64 v[14:15], v[14:15], 1, v[64:65]
	v_lshrrev_b32_e32 v14, 16, v236
	v_cndmask_b32_e64 v16, v17, v16, s[4:5]
	v_ashrrev_i32_e32 v17, 31, v16
	v_lshl_add_u64 v[16:17], v[16:17], 1, v[64:65]
	v_mov_b32_e32 v22, v237
	v_mov_b32_e32 v23, v238
	v_cndmask_b32_e64 v15, 0, 1.0, vcc
	v_lshlrev_b32_e32 v18, 16, v20
	v_and_b32_e32 v19, 0xffff0000, v20
	v_pk_fma_f32 v[10:11], v[128:129], v[18:19], v[10:11] op_sel_hi:[0,1,1]
	v_lshlrev_b32_e32 v20, 16, v21
	v_and_b32_e32 v21, 0xffff0000, v21
	v_pk_fma_f32 v[12:13], v[128:129], v[20:21], v[12:13] op_sel_hi:[0,1,1]
	v_mov_b32_e32 v20, v241
	v_mov_b32_e32 v21, v242
	s_nop 0
	v_lshlrev_b32_e32 v14, 16, v14
	v_mul_f32_e32 v15, v15, v14
	v_and_b32_e32 v14, 0xffff, v239
	v_cndmask_b32_e64 v16, 1.0, 0, s[4:5]
	s_nop 0
	v_and_b32_e32 v24, 0xffff0000, v22
	v_lshlrev_b32_e32 v25, 16, v23
	v_and_b32_e32 v23, 0xffff0000, v23
	s_nop 0
	v_lshlrev_b32_e32 v14, 16, v14
	v_mul_f32_e32 v17, v16, v14
	v_mov_b32_e32 v14, v24
	v_lshlrev_b32_e32 v16, 16, v22
	v_pk_mul_f32 v[14:15], v[122:123], v[14:15]
	v_mov_b32_e32 v22, v25
	v_pk_fma_f32 v[14:15], v[122:123], v[16:17], v[14:15] op_sel:[0,0,1] op_sel_hi:[1,0,0]
	v_mov_b32_e32 v16, v23
	v_pk_fma_f32 v[14:15], v[126:127], v[24:25], v[14:15] op_sel_hi:[0,1,1]
	v_pk_add_f32 v[14:15], v[124:125], v[14:15] op_sel_hi:[0,1]
	v_pk_mul_f32 v[10:11], v[14:15], v[10:11]
	v_pk_mul_f32 v[14:15], v[122:123], v[22:23] op_sel_hi:[0,1]
	v_pk_fma_f32 v[14:15], v[0:1], v[24:25], v[14:15] op_sel_hi:[0,1,1]
	v_pk_fma_f32 v[14:15], v[126:127], v[16:17], v[14:15] op_sel_hi:[0,1,1]
	v_pk_add_f32 v[14:15], v[124:125], v[14:15] op_sel_hi:[0,1]
	v_pk_mul_f32 v[12:13], v[12:13], v[14:15]
	v_cvt_pk_bf16_f32 v10, v10, v11
	v_cvt_pk_bf16_f32 v11, v12, v13
	v_add_u32_e32 v12, 0xe0, v66
	global_store_dwordx2 v[62:63], v[10:11], off offset:416
	v_and_b32_e32 v10, 60, v12
	v_add_u32_e32 v13, 0xe4, v66
	v_cmp_ne_u32_e32 vcc, 0, v10
	v_and_b32_e32 v10, 60, v13
	v_cmp_eq_u32_e64 s[4:5], 0, v10
	v_subbrev_co_u32_e64 v10, s[6:7], 0, v12, vcc
	v_ashrrev_i32_e32 v11, 31, v10
	v_lshl_add_u64 v[10:11], v[10:11], 1, v[64:65]
	v_lshrrev_b32_e32 v10, 16, v240
	v_cndmask_b32_e64 v11, 0, 1.0, vcc
	v_and_b32_e32 v22, 0xffff0000, v20
	v_mov_b32_e32 v16, v22
	v_lshlrev_b32_e32 v14, 16, v20
	v_lshlrev_b32_e32 v23, 16, v21
	v_and_b32_e32 v21, 0xffff0000, v21
	v_mov_b32_e32 v20, v23
	s_nop 0
	v_lshlrev_b32_e32 v10, 16, v10
	v_mul_f32_e32 v17, v11, v10
	v_cndmask_b32_e64 v10, v13, v12, s[4:5]
	v_ashrrev_i32_e32 v11, 31, v10
	v_lshl_add_u64 v[10:11], v[10:11], 1, v[64:65]
	v_and_b32_e32 v10, 0xffff, v243
	v_cndmask_b32_e64 v11, 1.0, 0, s[4:5]
	v_pk_mul_f32 v[16:17], v[122:123], v[16:17]
	s_nop 0
	v_lshlrev_b32_e32 v10, 16, v10
	v_mul_f32_e32 v15, v11, v10
	ds_read2_b64 v[10:13], v67 offset0:56 offset1:60
	v_pk_fma_f32 v[16:17], v[122:123], v[14:15], v[16:17] op_sel:[0,0,1] op_sel_hi:[1,0,0]
	v_mov_b32_e32 v14, v21
	v_pk_fma_f32 v[16:17], v[126:127], v[22:23], v[16:17] op_sel_hi:[0,1,1]
	v_pk_add_f32 v[16:17], v[124:125], v[16:17] op_sel_hi:[0,1]
	s_waitcnt lgkmcnt(0)
; DI float bf2f(bfu v) { return __uint_as_float(((unsigned)v) << 16); }
; DI unsigned pack2(float a, float b) { f32x2_t v = {a, b}; bf16x2_t r = __builtin_convertvector(v, bf16x2_t); return __builtin_bit_cast(unsigned, r); }
; DI float lo16(unsigned u) { return __uint_as_float(u << 16); }
; DI float hi16(unsigned u) { return __uint_as_float(u & 0xffff0000u); }
; template <int L>
; DI void hyena_job(const PX& p, int l, int c, unsigned char* smem) {
;     ...
;     for (int m = 0; m < TPW; m++) {
;       const int t0 = 16 * (w * TPW + m) + 4 * kq_o;
;       const bfu* zr = zx2 + b * L;
;       const uint2 mid = *(const uint2*)(zr + t0);
;       const bool lv = (t0 % RL != 0), rv = ((t0 + 4) % RL != 0);
;       const float lft = bf2f(zr[lv ? t0 - 1 : t0]) * (lv ? 1.f : 0.f);
;       const float rgt = bf2f(zr[rv ? t0 + 4 : t0]) * (rv ? 1.f : 0.f);
;       float z[6];
;       z[0] = lft; z[5] = rgt; z[1] = lo16(mid.x); z[2] = hi16(mid.x); z[3] = lo16(mid.y); z[4] = hi16(mid.y);
;       const uint2 vu = *(const uint2*)(U + b * USTR + t0);
;       const float vv[4] = {lo16(vu.x), hi16(vu.x), lo16(vu.y), hi16(vu.y)};
;       float y2[4];
; #pragma unroll
;       for (int r = 0; r < 4; r++) {
;         const float x2 = w2[0] * z[r] + w2[1] * z[r + 1] + w2[2] * z[r + 2] + w2[3];
;         y2[r] = x2 * (acc[m][r] + bias1 * vv[r]);
;       }
;       uint2 o2; o2.x = pack2(y2[0], y2[1]); o2.y = pack2(y2[2], y2[3]);
;       *(uint2*)(yrow + b * L + t0) = o2;
;     }
	v_lshlrev_b32_e32 v18, 16, v10
	v_and_b32_e32 v19, 0xffff0000, v10
	v_pk_fma_f32 v[6:7], v[128:129], v[18:19], v[6:7] op_sel_hi:[0,1,1]
	v_pk_mul_f32 v[6:7], v[16:17], v[6:7]
	v_pk_mul_f32 v[16:17], v[122:123], v[20:21] op_sel_hi:[0,1]
	v_pk_fma_f32 v[16:17], v[0:1], v[22:23], v[16:17] op_sel_hi:[0,1,1]
	v_lshlrev_b32_e32 v10, 16, v11
	v_and_b32_e32 v11, 0xffff0000, v11
	v_pk_fma_f32 v[14:15], v[126:127], v[14:15], v[16:17] op_sel_hi:[0,1,1]
	v_pk_add_f32 v[14:15], v[124:125], v[14:15] op_sel_hi:[0,1]
	v_pk_fma_f32 v[8:9], v[128:129], v[10:11], v[8:9] op_sel_hi:[0,1,1]
	v_pk_mul_f32 v[8:9], v[8:9], v[14:15]
	v_add_u32_e32 v0, 0xf0, v66
	v_cvt_pk_bf16_f32 v6, v6, v7
	v_cvt_pk_bf16_f32 v7, v8, v9
	v_and_b32_e32 v8, 60, v0
	v_add_u32_e32 v10, 0xf4, v66
	v_cmp_ne_u32_e32 vcc, 0, v8
	v_and_b32_e32 v8, 60, v10
	v_cmp_eq_u32_e64 s[4:5], 0, v8
	v_subbrev_co_u32_e64 v8, s[6:7], 0, v0, vcc
	v_ashrrev_i32_e32 v9, 31, v8
	v_cndmask_b32_e64 v10, v10, v0, s[4:5]
	global_store_dwordx2 v[62:63], v[6:7], off offset:448
	v_lshl_add_u64 v[8:9], v[8:9], 1, v[64:65]
	v_ashrrev_i32_e32 v11, 31, v10
	v_lshrrev_b32_e32 v8, 16, v244
	v_lshl_add_u64 v[10:11], v[10:11], 1, v[64:65]
	v_mov_b32_e32 v6, v245
	v_mov_b32_e32 v7, v246
	v_and_b32_e32 v0, 0xffff, v247
	v_cndmask_b32_e64 v9, 0, 1.0, vcc
	v_lshlrev_b32_e32 v14, 16, v12
	v_and_b32_e32 v15, 0xffff0000, v12
	v_pk_fma_f32 v[2:3], v[128:129], v[14:15], v[2:3] op_sel_hi:[0,1,1]
	v_and_b32_e32 v10, 0xffff0000, v13
	v_mov_b32_e32 v129, v126
	v_lshlrev_b32_e32 v12, 16, v13
	v_mul_f32_e32 v12, v128, v12
	v_mov_b32_e32 v13, v124
	s_nop 0
	v_lshlrev_b32_e32 v8, 16, v8
	v_mul_f32_e32 v9, v9, v8
	v_cndmask_b32_e64 v8, 1.0, 0, s[4:5]
	s_nop 0
	v_lshlrev_b32_e32 v0, 16, v0
	v_mul_f32_e32 v11, v8, v0
	v_and_b32_e32 v8, 0xffff0000, v6
	v_lshlrev_b32_e32 v0, 16, v6
	v_lshlrev_b32_e32 v6, 16, v7
	v_pk_mul_f32 v[16:17], v[122:123], v[8:9]
	v_mov_b32_e32 v9, v6
	v_pk_fma_f32 v[16:17], v[122:123], v[0:1], v[16:17] op_sel:[0,0,1] op_sel_hi:[1,0,0]
	v_and_b32_e32 v7, 0xffff0000, v7
	v_pk_fma_f32 v[14:15], v[126:127], v[8:9], v[16:17] op_sel_hi:[0,1,1]
	v_pk_add_f32 v[14:15], v[124:125], v[14:15] op_sel_hi:[0,1]
	v_pk_mul_f32 v[14:15], v[14:15], v[2:3]
	v_mov_b32_e32 v2, v122
	v_mov_b32_e32 v3, v126
	v_pk_mul_f32 v[2:3], v[2:3], v[6:7]
	v_mov_b32_e32 v9, v122
	v_fma_f32 v0, v123, v8, v2
	v_add_f32_e32 v0, v3, v0
	v_add_f32_e32 v2, v124, v0
	v_mov_b32_e32 v8, v123
	v_mul_f32_e32 v0, v123, v6
	v_pk_fma_f32 v[6:7], v[8:9], v[6:7], v[0:1] op_sel_hi:[1,1,0]
	v_cvt_pk_bf16_f32 v0, v14, v15
	v_mov_b32_e32 v6, v5
	v_pk_fma_f32 v[6:7], v[128:129], v[10:11], v[6:7]
	global_store_dword v[62:63], v0, off offset:480
	v_mov_b32_e32 v5, v7
	v_pk_add_f32 v[4:5], v[4:5], v[12:13]
	v_mov_b32_e32 v3, v6
	v_pk_mul_f32 v[2:3], v[2:3], v[4:5]
	v_lshl_add_u64 v[6:7], v[62:63], 0, s[0:1]
	s_branch .LBB0_515

; __global__ void __launch_bounds__(NTHR) mega(P p0, int ph_lo, int ph_hi) {
;   PX p;
;   *(P*)&p = p0;
;   p.wv = __builtin_amdgcn_readfirstlane((int)(threadIdx.x >> 6));
;   __shared__ __attribute__((aligned(16))) unsigned char smem[SMEM_BYTES];
	.amdhsa_kernel _Z4mega1Pii
		.amdhsa_group_segment_fixed_size 160000
		.amdhsa_private_segment_fixed_size 0
		.amdhsa_kernarg_size 608
		.amdhsa_user_sgpr_count 2
		.amdhsa_user_sgpr_dispatch_ptr 0
		.amdhsa_user_sgpr_queue_ptr 0
		.amdhsa_user_sgpr_kernarg_segment_ptr 1
		.amdhsa_user_sgpr_dispatch_id 0
		.amdhsa_user_sgpr_kernarg_preload_length 0
		.amdhsa_user_sgpr_kernarg_preload_offset 0
		.amdhsa_user_sgpr_private_segment_size 0
		.amdhsa_uses_dynamic_stack 0
		.amdhsa_enable_private_segment 0
		.amdhsa_system_sgpr_workgroup_id_x 1
		.amdhsa_system_sgpr_workgroup_id_y 0
		.amdhsa_system_sgpr_workgroup_id_z 0
		.amdhsa_system_sgpr_workgroup_info 0
		.amdhsa_system_vgpr_workitem_id 2
		.amdhsa_next_free_vgpr 256
		.amdhsa_next_free_sgpr 100
		.amdhsa_accum_offset 256
		.amdhsa_reserve_vcc 1
		.amdhsa_float_round_mode_32 0
		.amdhsa_float_round_mode_16_64 0
		.amdhsa_float_denorm_mode_32 3
		.amdhsa_float_denorm_mode_16_64 3
		.amdhsa_dx10_clamp 1
		.amdhsa_ieee_mode 1
		.amdhsa_fp16_overflow 0
		.amdhsa_tg_split 0
		.amdhsa_exception_fp_ieee_invalid_op 0
		.amdhsa_exception_fp_denorm_src 0
		.amdhsa_exception_fp_ieee_div_zero 0
		.amdhsa_exception_fp_ieee_overflow 0
		.amdhsa_exception_fp_ieee_underflow 0
		.amdhsa_exception_fp_ieee_inexact 0
		.amdhsa_exception_int_div_zero 0
	.end_amdhsa_kernel

; __global__ void __launch_bounds__(NTHR) mega(P p0, int ph_lo, int ph_hi) {
;   PX p;
;   *(P*)&p = p0;
;   p.wv = __builtin_amdgcn_readfirstlane((int)(threadIdx.x >> 6));
;   __shared__ __attribute__((aligned(16))) unsigned char smem[SMEM_BYTES];
amdhsa.kernels:
  - .agpr_count:     0
    .args:
      - .offset:         0
        .size:           344
        .value_kind:     by_value
      - .offset:         344
        .size:           4
        .value_kind:     by_value
      - .offset:         348
        .size:           4
        .value_kind:     by_value
      - .offset:         352
        .size:           4
        .value_kind:     hidden_block_count_x
      - .offset:         356
        .size:           4
        .value_kind:     hidden_block_count_y
      - .offset:         360
        .size:           4
        .value_kind:     hidden_block_count_z
      - .offset:         364
        .size:           2
        .value_kind:     hidden_group_size_x
      - .offset:         366
        .size:           2
        .value_kind:     hidden_group_size_y
      - .offset:         368
        .size:           2
        .value_kind:     hidden_group_size_z
      - .offset:         370
        .size:           2
        .value_kind:     hidden_remainder_x
      - .offset:         372
        .size:           2
        .value_kind:     hidden_remainder_y
      - .offset:         374
        .size:           2
        .value_kind:     hidden_remainder_z
      - .offset:         392
        .size:           8
        .value_kind:     hidden_global_offset_x
      - .offset:         400
        .size:           8
        .value_kind:     hidden_global_offset_y
      - .offset:         408
        .size:           8
        .value_kind:     hidden_global_offset_z
      - .offset:         416
        .size:           2
        .value_kind:     hidden_grid_dims
      - .offset:         440
        .size:           8
        .value_kind:     hidden_multigrid_sync_arg
    .group_segment_fixed_size: 160000
    .kernarg_segment_align: 8
    .kernarg_segment_size: 608
    .language:       OpenCL C
    .language_version:
      - 2
      - 0
    .max_flat_workgroup_size: 512
    .name:           _Z4mega1Pii
    .private_segment_fixed_size: 0
    .sgpr_count:     106
    .sgpr_spill_count: 387
    .symbol:         _Z4mega1Pii.kd
    .uniform_work_group_size: 1
    .uses_dynamic_stack: false
    .vgpr_count:     256
    .vgpr_spill_count: 0
    .wavefront_size: 64
